# peer_topk layer-0: first-half fragment loads issued up front with counted vmcnt (were 16 load->wait->MFMA round trips); dynamic selects via wave-private LDS table
# speedup vs baseline: 1.0107x; 1.0077x over previous
; #define MFMA(a, b, c) __builtin_amdgcn_mfma_f32_32x32x16_bf16((a), (b), (c), 0, 0, 0)
; DI unsigned f2ord(float f) { const unsigned u = __float_as_uint(f); return (u & 0x80000000u) ? ~u : (u | 0x80000000u); }
; DI void peer_topk_phase(const bf16_t* __restrict__ qpk, const bf16_t* __restrict__ subk, int* __restrict__ eidx, float* __restrict__ gout) {
;     ...
;         for (int c = 0; c < 2; ++c) {
;             f32x16 acc[4];
; #pragma unroll
;             for (int nb = 0; nb < 4; ++nb)
; #pragma unroll
;                 for (int i = 0; i < 16; ++i) acc[nb][i] = 0.f;
;             const bf16_t* qp = qpk + (size_t)(t0 + r) * 1024 + hh * 128 + c * 64 + h * 8;
;             const bf16_t* kp = subk + ((size_t)(hh * 2 + c) * 128 + r) * 64 + h * 8;
; #pragma unroll
;             for (int ks = 0; ks < 4; ++ks) {
;                 const bf16x8 qfr = *(const bf16x8*)(qp + ks * 16);
; #pragma unroll
;                 for (int nb = 0; nb < 4; ++nb) {
;                     const bf16x8 kf = *(const bf16x8*)(kp + nb * 32 * 64 + ks * 16);
;                     acc[nb] = MFMA(kf, qfr, acc[nb]);
;                 }
;             }
;             unsigned key[64];
; #pragma unroll
;             for (int nb = 0; nb < 4; ++nb)
; #pragma unroll
;                 for (int i = 0; i < 16; ++i) {
;                     const int n = nb * 32 + (i & 3) + 8 * (i >> 2) + 4 * h;
;                     key[nb * 16 + i] = (f2ord(acc[nb][i]) & ~127u) | (unsigned)(127 - n);
.LBB0_466:
	v_and_or_b32 v80, v154, s21, v84
	v_ashrrev_i32_e32 v81, 31, v80
	v_and_b32_e32 v156, 7, v1
	v_lshlrev_b64 v[2:3], 11, v[80:81]
	v_lshl_add_u64 v[2:3], s[40:41], 0, v[2:3]
	v_lshlrev_b32_e32 v74, 8, v156
	v_lshl_add_u64 v[2:3], v[2:3], 0, v[74:75]
	v_mov_b32_e32 v79, v75
	v_lshl_add_u64 v[66:67], v[2:3], 0, v[78:79]
	v_lshl_or_b32 v74, v156, 15, v155
	v_lshl_add_u64 v[68:69], v[76:77], 0, v[74:75]
	v_add_co_u32_e32 v72, vcc, s24, v68
	s_nop 1
	v_addc_co_u32_e32 v73, vcc, 0, v69, vcc
	v_add_co_u32_e32 v82, vcc, s25, v68
	s_nop 1
	v_addc_co_u32_e32 v83, vcc, 0, v69, vcc
	v_add_co_u32_e32 v166, vcc, s27, v68
	s_nop 1
	v_addc_co_u32_e32 v167, vcc, 0, v69, vcc
	v_add_co_u32_e32 v70, vcc, s4, v68
	s_nop 1
	v_addc_co_u32_e32 v71, vcc, 0, v69, vcc
	global_load_dwordx4 v[2:5], v[66:67], off
	global_load_dwordx4 v[6:9], v[68:69], off
	global_load_dwordx4 v[162:165], v[72:73], off
	global_load_dwordx4 v[198:201], v[82:83], off
	global_load_dwordx4 v[210:213], v[166:167], off
	global_load_dwordx4 v[158:161], v[66:67], off offset:32
	global_load_dwordx4 v[214:217], v[68:69], off offset:32
	global_load_dwordx4 v[218:221], v[72:73], off offset:32
	global_load_dwordx4 v[222:225], v[82:83], off offset:32
	global_load_dwordx4 v[226:229], v[166:167], off offset:32
	global_load_dwordx4 v[182:185], v[66:67], off offset:64
	global_load_dwordx4 v[232:235], v[68:69], off offset:64
	global_load_dwordx4 v[236:239], v[72:73], off offset:64
	global_load_dwordx4 v[240:243], v[82:83], off offset:64
	global_load_dwordx4 v[244:247], v[166:167], off offset:64
	global_load_dwordx4 v[186:189], v[66:67], off offset:96
	global_load_dwordx4 v[248:251], v[68:69], off offset:96
	s_waitcnt vmcnt(15)
	v_mfma_f32_32x32x16_bf16 v[50:65], v[6:9], v[2:5], 0
	s_waitcnt vmcnt(14)
	v_mfma_f32_32x32x16_bf16 v[34:49], v[162:165], v[2:5], 0
	s_waitcnt vmcnt(13)
	v_mfma_f32_32x32x16_bf16 v[18:33], v[198:201], v[2:5], 0
	s_waitcnt vmcnt(12)
	v_mfma_f32_32x32x16_bf16 v[2:17], v[210:213], v[2:5], 0
	global_load_dwordx4 v[162:165], v[72:73], off offset:96
	global_load_dwordx4 v[198:201], v[82:83], off offset:96
	global_load_dwordx4 v[210:213], v[166:167], off offset:96
	s_waitcnt vmcnt(13)
	v_mfma_f32_32x32x16_bf16 v[50:65], v[214:217], v[158:161], v[50:65]
	s_waitcnt vmcnt(12)
	v_mfma_f32_32x32x16_bf16 v[34:49], v[218:221], v[158:161], v[34:49]
	s_waitcnt vmcnt(11)
	v_mfma_f32_32x32x16_bf16 v[18:33], v[222:225], v[158:161], v[18:33]
	s_waitcnt vmcnt(10)
	v_mfma_f32_32x32x16_bf16 v[2:17], v[226:229], v[158:161], v[2:17]
	s_waitcnt vmcnt(8)
	v_mfma_f32_32x32x16_bf16 v[50:65], v[232:235], v[182:185], v[50:65]
	s_waitcnt vmcnt(7)
	v_mfma_f32_32x32x16_bf16 v[34:49], v[236:239], v[182:185], v[34:49]
	s_waitcnt vmcnt(6)
	v_mfma_f32_32x32x16_bf16 v[18:33], v[240:243], v[182:185], v[18:33]
	s_waitcnt vmcnt(5)
	v_mfma_f32_32x32x16_bf16 v[2:17], v[244:247], v[182:185], v[2:17]
	s_waitcnt vmcnt(3)
	v_mfma_f32_32x32x16_bf16 v[50:65], v[248:251], v[186:189], v[50:65]
	s_nop 11
	v_not_b32_e32 v72, v50
	v_or_b32_e32 v73, 0x80000000, v50
	v_cmp_gt_i32_e32 vcc, 0, v50
	s_waitcnt vmcnt(2)
	v_mfma_f32_32x32x16_bf16 v[34:49], v[162:165], v[186:189], v[34:49]
	v_cndmask_b32_e32 v50, v73, v72, vcc
	v_not_b32_e32 v72, v51
	v_or_b32_e32 v73, 0x80000000, v51
	v_cmp_gt_i32_e32 vcc, 0, v51
	v_and_or_b32 v50, v50, s42, v85
	s_nop 0
	v_cndmask_b32_e32 v51, v73, v72, vcc
	v_not_b32_e32 v72, v52
	v_or_b32_e32 v73, 0x80000000, v52
	v_cmp_gt_i32_e32 vcc, 0, v52
	v_and_or_b32 v51, v51, s42, v86
	s_waitcnt vmcnt(1)
	v_mfma_f32_32x32x16_bf16 v[18:33], v[198:201], v[186:189], v[18:33]
	v_cndmask_b32_e32 v52, v73, v72, vcc
	v_not_b32_e32 v72, v53
	v_or_b32_e32 v73, 0x80000000, v53
	v_cmp_gt_i32_e32 vcc, 0, v53
	v_and_or_b32 v52, v52, s42, v87
	s_nop 0
	v_cndmask_b32_e32 v53, v73, v72, vcc
	v_not_b32_e32 v72, v54
	v_or_b32_e32 v73, 0x80000000, v54
	v_cmp_gt_i32_e32 vcc, 0, v54
	v_and_or_b32 v53, v53, s42, v88
	s_waitcnt vmcnt(0)
	v_mfma_f32_32x32x16_bf16 v[2:17], v[210:213], v[186:189], v[2:17]
	v_cndmask_b32_e32 v54, v73, v72, vcc
	v_not_b32_e32 v72, v55
	v_or_b32_e32 v73, 0x80000000, v55
	v_cmp_gt_i32_e32 vcc, 0, v55
	v_and_or_b32 v54, v54, s42, v89
	s_nop 0
	v_cndmask_b32_e32 v55, v73, v72, vcc
	v_not_b32_e32 v72, v56
	v_or_b32_e32 v73, 0x80000000, v56
	v_cmp_gt_i32_e32 vcc, 0, v56
	v_and_or_b32 v55, v55, s42, v90
	s_nop 0
	v_cndmask_b32_e32 v56, v73, v72, vcc
	v_not_b32_e32 v72, v57
	v_or_b32_e32 v73, 0x80000000, v57
	v_cmp_gt_i32_e32 vcc, 0, v57
	v_and_or_b32 v56, v56, s42, v91
	s_nop 0
	v_cndmask_b32_e32 v57, v73, v72, vcc
	v_not_b32_e32 v72, v58
	v_or_b32_e32 v73, 0x80000000, v58
	v_cmp_gt_i32_e32 vcc, 0, v58
	v_and_or_b32 v57, v57, s42, v92
	s_nop 0
	v_cndmask_b32_e32 v58, v73, v72, vcc
	v_not_b32_e32 v72, v59
	v_or_b32_e32 v73, 0x80000000, v59
	v_cmp_gt_i32_e32 vcc, 0, v59
	v_and_or_b32 v58, v58, s42, v93
	s_nop 0
	v_cndmask_b32_e32 v59, v73, v72, vcc
	v_not_b32_e32 v72, v60
	v_or_b32_e32 v73, 0x80000000, v60
	v_cmp_gt_i32_e32 vcc, 0, v60
	v_and_or_b32 v59, v59, s42, v94
	s_nop 0
	v_cndmask_b32_e32 v60, v73, v72, vcc
	v_not_b32_e32 v72, v61
	v_or_b32_e32 v73, 0x80000000, v61
	v_cmp_gt_i32_e32 vcc, 0, v61
	v_and_or_b32 v60, v60, s42, v95
	s_nop 0
	v_cndmask_b32_e32 v61, v73, v72, vcc
	v_not_b32_e32 v72, v62
	v_or_b32_e32 v73, 0x80000000, v62
	v_cmp_gt_i32_e32 vcc, 0, v62
	v_and_or_b32 v61, v61, s42, v96
	s_nop 0
	v_cndmask_b32_e32 v62, v73, v72, vcc
	v_not_b32_e32 v72, v63
	v_or_b32_e32 v73, 0x80000000, v63
	v_cmp_gt_i32_e32 vcc, 0, v63
	v_and_or_b32 v62, v62, s42, v97
	s_nop 0
	v_cndmask_b32_e32 v63, v73, v72, vcc
	v_not_b32_e32 v72, v64
	v_or_b32_e32 v73, 0x80000000, v64
	v_cmp_gt_i32_e32 vcc, 0, v64
; DI unsigned f2ord(float f) { const unsigned u = __float_as_uint(f); return (u & 0x80000000u) ? ~u : (u | 0x80000000u); }
; DI void peer_topk_phase(const bf16_t* __restrict__ qpk, const bf16_t* __restrict__ subk, int* __restrict__ eidx, float* __restrict__ gout) {
;     ...
;             unsigned key[64];
; #pragma unroll
;             for (int nb = 0; nb < 4; ++nb)
; #pragma unroll
;                 for (int i = 0; i < 16; ++i) {
;                     const int n = nb * 32 + (i & 3) + 8 * (i >> 2) + 4 * h;
;                     key[nb * 16 + i] = (f2ord(acc[nb][i]) & ~127u) | (unsigned)(127 - n);
;                 }
	v_and_or_b32 v63, v63, s42, v98
	s_nop 0
	v_cndmask_b32_e32 v64, v73, v72, vcc
	v_not_b32_e32 v72, v65
	v_or_b32_e32 v73, 0x80000000, v65
	v_cmp_gt_i32_e32 vcc, 0, v65
	v_and_or_b32 v64, v64, s42, v99
	s_nop 0
	v_cndmask_b32_e32 v65, v73, v72, vcc
	v_not_b32_e32 v72, v34
	v_or_b32_e32 v73, 0x80000000, v34
	v_cmp_gt_i32_e32 vcc, 0, v34
	v_and_or_b32 v65, v65, s42, v100
	s_nop 0
	v_cndmask_b32_e32 v34, v73, v72, vcc
	v_not_b32_e32 v72, v35
	v_or_b32_e32 v73, 0x80000000, v35
	v_cmp_gt_i32_e32 vcc, 0, v35
	v_and_or_b32 v34, v34, s42, v101
	s_nop 0
	v_cndmask_b32_e32 v35, v73, v72, vcc
	v_not_b32_e32 v72, v36
	v_or_b32_e32 v73, 0x80000000, v36
	v_cmp_gt_i32_e32 vcc, 0, v36
	v_and_or_b32 v35, v35, s42, v102
	s_nop 0
	v_cndmask_b32_e32 v36, v73, v72, vcc
	v_not_b32_e32 v72, v37
	v_or_b32_e32 v73, 0x80000000, v37
	v_cmp_gt_i32_e32 vcc, 0, v37
	v_and_or_b32 v36, v36, s42, v103
	s_nop 0
	v_cndmask_b32_e32 v37, v73, v72, vcc
	v_not_b32_e32 v72, v38
	v_or_b32_e32 v73, 0x80000000, v38
	v_cmp_gt_i32_e32 vcc, 0, v38
	v_and_or_b32 v37, v37, s42, v104
	s_nop 0
	v_cndmask_b32_e32 v38, v73, v72, vcc
	v_not_b32_e32 v72, v39
	v_or_b32_e32 v73, 0x80000000, v39
	v_cmp_gt_i32_e32 vcc, 0, v39
	v_and_or_b32 v38, v38, s42, v105
	s_nop 0
	v_cndmask_b32_e32 v39, v73, v72, vcc
	v_not_b32_e32 v72, v40
	v_or_b32_e32 v73, 0x80000000, v40
	v_cmp_gt_i32_e32 vcc, 0, v40
	v_and_or_b32 v39, v39, s42, v106
	s_nop 0
	v_cndmask_b32_e32 v40, v73, v72, vcc
	v_not_b32_e32 v72, v41
	v_or_b32_e32 v73, 0x80000000, v41
	v_cmp_gt_i32_e32 vcc, 0, v41
	v_and_or_b32 v40, v40, s42, v107
	s_nop 0
	v_cndmask_b32_e32 v41, v73, v72, vcc
	v_not_b32_e32 v72, v42
	v_or_b32_e32 v73, 0x80000000, v42
	v_cmp_gt_i32_e32 vcc, 0, v42
	v_and_or_b32 v41, v41, s42, v108
	s_nop 0
	v_cndmask_b32_e32 v42, v73, v72, vcc
	v_not_b32_e32 v72, v43
	v_or_b32_e32 v73, 0x80000000, v43
	v_cmp_gt_i32_e32 vcc, 0, v43
	v_and_or_b32 v42, v42, s42, v109
	s_nop 0
	v_cndmask_b32_e32 v43, v73, v72, vcc
	v_not_b32_e32 v72, v44
	v_or_b32_e32 v73, 0x80000000, v44
	v_cmp_gt_i32_e32 vcc, 0, v44
	v_and_or_b32 v43, v43, s42, v110
	s_nop 0
	v_cndmask_b32_e32 v44, v73, v72, vcc
	v_not_b32_e32 v72, v45
	v_or_b32_e32 v73, 0x80000000, v45
	v_cmp_gt_i32_e32 vcc, 0, v45
	v_and_or_b32 v44, v44, s42, v111
	s_nop 0
	v_cndmask_b32_e32 v45, v73, v72, vcc
	v_not_b32_e32 v72, v46
	v_or_b32_e32 v73, 0x80000000, v46
	v_cmp_gt_i32_e32 vcc, 0, v46
	v_and_or_b32 v45, v45, s42, v112
	s_nop 0
	v_cndmask_b32_e32 v46, v73, v72, vcc
	v_not_b32_e32 v72, v47
	v_or_b32_e32 v73, 0x80000000, v47
	v_cmp_gt_i32_e32 vcc, 0, v47
	v_and_or_b32 v46, v46, s42, v113
	s_nop 0
	v_cndmask_b32_e32 v47, v73, v72, vcc
	v_not_b32_e32 v72, v48
	v_or_b32_e32 v73, 0x80000000, v48
	v_cmp_gt_i32_e32 vcc, 0, v48
	v_and_or_b32 v47, v47, s42, v114
	s_nop 0
	v_cndmask_b32_e32 v48, v73, v72, vcc
	v_not_b32_e32 v72, v49
	v_or_b32_e32 v73, 0x80000000, v49
	v_cmp_gt_i32_e32 vcc, 0, v49
	v_and_or_b32 v48, v48, s42, v115
	s_nop 0
	v_cndmask_b32_e32 v49, v73, v72, vcc
	v_not_b32_e32 v72, v18
	v_or_b32_e32 v73, 0x80000000, v18
	v_cmp_gt_i32_e32 vcc, 0, v18
	v_and_or_b32 v49, v49, s42, v116
	s_nop 0
	v_cndmask_b32_e32 v18, v73, v72, vcc
	v_not_b32_e32 v72, v19
	v_or_b32_e32 v73, 0x80000000, v19
	v_cmp_gt_i32_e32 vcc, 0, v19
	v_and_or_b32 v18, v18, s42, v117
	s_nop 0
	v_cndmask_b32_e32 v19, v73, v72, vcc
	v_not_b32_e32 v72, v20
	v_or_b32_e32 v73, 0x80000000, v20
	v_cmp_gt_i32_e32 vcc, 0, v20
	v_and_or_b32 v19, v19, s42, v118
	s_nop 0
	v_cndmask_b32_e32 v20, v73, v72, vcc
	v_not_b32_e32 v72, v21
	v_or_b32_e32 v73, 0x80000000, v21
	v_cmp_gt_i32_e32 vcc, 0, v21
	v_and_or_b32 v20, v20, s42, v119
	s_nop 0
	v_cndmask_b32_e32 v21, v73, v72, vcc
	v_not_b32_e32 v72, v22
	v_or_b32_e32 v73, 0x80000000, v22
	v_cmp_gt_i32_e32 vcc, 0, v22
	v_and_or_b32 v21, v21, s42, v120
	s_nop 0
	v_cndmask_b32_e32 v22, v73, v72, vcc
	v_not_b32_e32 v72, v23
	v_or_b32_e32 v73, 0x80000000, v23
	v_cmp_gt_i32_e32 vcc, 0, v23
	v_and_or_b32 v22, v22, s42, v121
	s_nop 0
	v_cndmask_b32_e32 v23, v73, v72, vcc
	v_not_b32_e32 v72, v24
	v_or_b32_e32 v73, 0x80000000, v24
	v_cmp_gt_i32_e32 vcc, 0, v24
	v_and_or_b32 v23, v23, s42, v122
	s_nop 0
	v_cndmask_b32_e32 v24, v73, v72, vcc
	v_not_b32_e32 v72, v25
	v_or_b32_e32 v73, 0x80000000, v25
	v_cmp_gt_i32_e32 vcc, 0, v25
	v_and_or_b32 v24, v24, s42, v123
	s_nop 0
	v_cndmask_b32_e32 v25, v73, v72, vcc
	v_not_b32_e32 v72, v26
	v_or_b32_e32 v73, 0x80000000, v26
	v_cmp_gt_i32_e32 vcc, 0, v26
	v_and_or_b32 v25, v25, s42, v124
	s_nop 0
	v_cndmask_b32_e32 v26, v73, v72, vcc
	v_not_b32_e32 v72, v27
	v_or_b32_e32 v73, 0x80000000, v27
	v_cmp_gt_i32_e32 vcc, 0, v27
	v_and_or_b32 v26, v26, s42, v125
	s_nop 0
	v_cndmask_b32_e32 v27, v73, v72, vcc
	v_not_b32_e32 v72, v28
	v_or_b32_e32 v73, 0x80000000, v28
	v_cmp_gt_i32_e32 vcc, 0, v28
	v_and_or_b32 v27, v27, s42, v126
	s_nop 0
	v_cndmask_b32_e32 v28, v73, v72, vcc
	v_not_b32_e32 v72, v29
	v_or_b32_e32 v73, 0x80000000, v29
	v_cmp_gt_i32_e32 vcc, 0, v29
	v_and_or_b32 v28, v28, s42, v127
	s_nop 0
	v_cndmask_b32_e32 v29, v73, v72, vcc
	v_not_b32_e32 v72, v30
	v_or_b32_e32 v73, 0x80000000, v30
	v_cmp_gt_i32_e32 vcc, 0, v30
	v_and_or_b32 v29, v29, s42, v128
	s_nop 0
	v_cndmask_b32_e32 v30, v73, v72, vcc
	v_not_b32_e32 v72, v31
	v_or_b32_e32 v73, 0x80000000, v31
	v_cmp_gt_i32_e32 vcc, 0, v31
	v_and_or_b32 v30, v30, s42, v129
	s_nop 0
	v_cndmask_b32_e32 v31, v73, v72, vcc
	v_not_b32_e32 v72, v32
	v_or_b32_e32 v73, 0x80000000, v32
	v_cmp_gt_i32_e32 vcc, 0, v32
	v_and_or_b32 v31, v31, s42, v130
	s_nop 0
	v_cndmask_b32_e32 v32, v73, v72, vcc
	v_not_b32_e32 v72, v33
	v_or_b32_e32 v73, 0x80000000, v33
	v_cmp_gt_i32_e32 vcc, 0, v33
	v_and_or_b32 v32, v32, s42, v131
; DI unsigned f2ord(float f) { const unsigned u = __float_as_uint(f); return (u & 0x80000000u) ? ~u : (u | 0x80000000u); }
; DI void peer_topk_phase(const bf16_t* __restrict__ qpk, const bf16_t* __restrict__ subk, int* __restrict__ eidx, float* __restrict__ gout) {
;     ...
;             unsigned key[64];
; #pragma unroll
;             for (int nb = 0; nb < 4; ++nb)
; #pragma unroll
;                 for (int i = 0; i < 16; ++i) {
;                     const int n = nb * 32 + (i & 3) + 8 * (i >> 2) + 4 * h;
;                     key[nb * 16 + i] = (f2ord(acc[nb][i]) & ~127u) | (unsigned)(127 - n);
;                 }
;             unsigned g0[16], g1[16], g2[16], g3[16];
; #pragma unroll
;             for (int i = 0; i < 16; ++i) { g0[i] = key[i]; g1[i] = key[16 + i]; g2[i] = key[32 + i]; g3[i] = key[48 + i]; }
; #pragma unroll
;             for (int n = 0; n < 63; ++n) { cex(g0[SORT16[n][0]], g0[SORT16[n][1]]); cex(g1[SORT16[n][0]], g1[SORT16[n][1]]); cex(g2[SORT16[n][0]], g2[SORT16[n][1]]); cex(g3[SORT16[n][0]], g3[SORT16[n][1]]); }
	s_nop 0
	v_cndmask_b32_e32 v33, v73, v72, vcc
	v_not_b32_e32 v72, v2
	v_or_b32_e32 v73, 0x80000000, v2
	v_cmp_gt_i32_e32 vcc, 0, v2
	v_and_or_b32 v33, v33, s42, v132
	s_nop 0
	v_cndmask_b32_e32 v2, v73, v72, vcc
	v_not_b32_e32 v72, v3
	v_or_b32_e32 v73, 0x80000000, v3
	v_cmp_gt_i32_e32 vcc, 0, v3
	v_and_or_b32 v2, v2, s42, v133
	s_nop 0
	v_cndmask_b32_e32 v3, v73, v72, vcc
	v_not_b32_e32 v72, v4
	v_or_b32_e32 v73, 0x80000000, v4
	v_cmp_gt_i32_e32 vcc, 0, v4
	v_and_or_b32 v3, v3, s42, v134
	s_nop 0
	v_cndmask_b32_e32 v4, v73, v72, vcc
	v_not_b32_e32 v72, v5
	v_or_b32_e32 v73, 0x80000000, v5
	v_cmp_gt_i32_e32 vcc, 0, v5
	v_and_or_b32 v4, v4, s42, v135
	s_nop 0
	v_cndmask_b32_e32 v5, v73, v72, vcc
	v_not_b32_e32 v72, v6
	v_or_b32_e32 v73, 0x80000000, v6
	v_cmp_gt_i32_e32 vcc, 0, v6
	v_and_or_b32 v5, v5, s42, v136
	s_nop 0
	v_cndmask_b32_e32 v6, v73, v72, vcc
	v_not_b32_e32 v72, v7
	v_or_b32_e32 v73, 0x80000000, v7
	v_cmp_gt_i32_e32 vcc, 0, v7
	v_and_or_b32 v6, v6, s42, v137
	s_nop 0
	v_cndmask_b32_e32 v7, v73, v72, vcc
	v_not_b32_e32 v72, v8
	v_or_b32_e32 v73, 0x80000000, v8
	v_cmp_gt_i32_e32 vcc, 0, v8
	v_and_or_b32 v7, v7, s42, v138
	s_nop 0
	v_cndmask_b32_e32 v8, v73, v72, vcc
	v_not_b32_e32 v72, v9
	v_or_b32_e32 v73, 0x80000000, v9
	v_cmp_gt_i32_e32 vcc, 0, v9
	v_and_or_b32 v8, v8, s42, v139
	s_nop 0
	v_cndmask_b32_e32 v9, v73, v72, vcc
	v_not_b32_e32 v72, v10
	v_or_b32_e32 v73, 0x80000000, v10
	v_cmp_gt_i32_e32 vcc, 0, v10
	v_and_or_b32 v9, v9, s42, v140
	s_nop 0
	v_cndmask_b32_e32 v10, v73, v72, vcc
	v_not_b32_e32 v72, v11
	v_or_b32_e32 v73, 0x80000000, v11
	v_cmp_gt_i32_e32 vcc, 0, v11
	v_and_or_b32 v10, v10, s42, v141
	s_nop 0
	v_cndmask_b32_e32 v11, v73, v72, vcc
	v_not_b32_e32 v72, v12
	v_or_b32_e32 v73, 0x80000000, v12
	v_cmp_gt_i32_e32 vcc, 0, v12
	v_and_or_b32 v11, v11, s42, v142
	s_nop 0
	v_cndmask_b32_e32 v12, v73, v72, vcc
	v_not_b32_e32 v72, v13
	v_or_b32_e32 v73, 0x80000000, v13
	v_cmp_gt_i32_e32 vcc, 0, v13
	v_and_or_b32 v12, v12, s42, v143
	s_nop 0
	v_cndmask_b32_e32 v13, v73, v72, vcc
	v_not_b32_e32 v72, v14
	v_or_b32_e32 v73, 0x80000000, v14
	v_cmp_gt_i32_e32 vcc, 0, v14
	v_and_or_b32 v13, v13, s42, v144
	s_nop 0
	v_cndmask_b32_e32 v14, v73, v72, vcc
	v_not_b32_e32 v72, v15
	v_or_b32_e32 v73, 0x80000000, v15
	v_cmp_gt_i32_e32 vcc, 0, v15
	v_and_or_b32 v14, v14, s42, v145
	s_nop 0
	v_cndmask_b32_e32 v15, v73, v72, vcc
	v_not_b32_e32 v72, v16
	v_or_b32_e32 v73, 0x80000000, v16
	v_cmp_gt_i32_e32 vcc, 0, v16
	v_and_or_b32 v15, v15, s42, v149
	s_nop 0
	v_cndmask_b32_e32 v16, v73, v72, vcc
	v_not_b32_e32 v72, v17
	v_or_b32_e32 v73, 0x80000000, v17
	v_cmp_gt_i32_e32 vcc, 0, v17
	v_and_or_b32 v16, v16, s42, v152
	s_nop 0
	v_cndmask_b32_e32 v17, v73, v72, vcc
	v_max_u32_e32 v72, v50, v51
	v_min_u32_e32 v50, v50, v51
	v_max_u32_e32 v51, v34, v35
	v_min_u32_e32 v34, v34, v35
	v_max_u32_e32 v35, v18, v19
	v_min_u32_e32 v18, v18, v19
	v_max_u32_e32 v19, v2, v3
	v_min_u32_e32 v2, v2, v3
	v_max_u32_e32 v3, v52, v53
	v_min_u32_e32 v52, v52, v53
	v_max_u32_e32 v53, v36, v37
	v_min_u32_e32 v36, v36, v37
	v_max_u32_e32 v37, v20, v21
	v_min_u32_e32 v20, v20, v21
	v_max_u32_e32 v21, v4, v5
	v_min_u32_e32 v4, v4, v5
	v_max_u32_e32 v5, v72, v3
	v_min_u32_e32 v3, v72, v3
	v_max_u32_e32 v72, v51, v53
	v_min_u32_e32 v51, v51, v53
	v_max_u32_e32 v53, v35, v37
	v_min_u32_e32 v35, v35, v37
	v_max_u32_e32 v37, v19, v21
	v_min_u32_e32 v19, v19, v21
	v_max_u32_e32 v21, v50, v52
	v_min_u32_e32 v50, v50, v52
	v_max_u32_e32 v52, v34, v36
	v_min_u32_e32 v34, v34, v36
	v_max_u32_e32 v36, v18, v20
	v_min_u32_e32 v18, v18, v20
	v_max_u32_e32 v20, v2, v4
	v_min_u32_e32 v2, v2, v4
	v_max_u32_e32 v4, v21, v3
	v_min_u32_e32 v3, v21, v3
	v_max_u32_e32 v21, v52, v51
	v_min_u32_e32 v51, v52, v51
	v_max_u32_e32 v52, v36, v35
	v_min_u32_e32 v35, v36, v35
	v_max_u32_e32 v36, v20, v19
	v_min_u32_e32 v19, v20, v19
	v_max_u32_e32 v20, v54, v55
	v_min_u32_e32 v54, v54, v55
	v_max_u32_e32 v55, v38, v39
	v_min_u32_e32 v38, v38, v39
	v_max_u32_e32 v39, v22, v23
	v_min_u32_e32 v22, v22, v23
	v_max_u32_e32 v23, v6, v7
	v_min_u32_e32 v6, v6, v7
	v_max_u32_e32 v7, v56, v57
	v_min_u32_e32 v56, v56, v57
	v_max_u32_e32 v57, v40, v41
	v_min_u32_e32 v40, v40, v41
	v_max_u32_e32 v41, v24, v25
	v_min_u32_e32 v24, v24, v25
	v_max_u32_e32 v25, v8, v9
	v_min_u32_e32 v8, v8, v9
	v_max_u32_e32 v9, v20, v7
	v_min_u32_e32 v7, v20, v7
	v_max_u32_e32 v20, v55, v57
	v_min_u32_e32 v55, v55, v57
	v_max_u32_e32 v57, v39, v41
	v_min_u32_e32 v39, v39, v41
	v_max_u32_e32 v41, v23, v25
	v_min_u32_e32 v23, v23, v25
	v_max_u32_e32 v25, v54, v56
	v_min_u32_e32 v54, v54, v56
	v_max_u32_e32 v56, v38, v40
	v_min_u32_e32 v38, v38, v40
	v_max_u32_e32 v40, v22, v24
	v_min_u32_e32 v22, v22, v24
	v_max_u32_e32 v24, v6, v8
	v_min_u32_e32 v6, v6, v8
	v_max_u32_e32 v8, v25, v7
	v_min_u32_e32 v7, v25, v7
	v_max_u32_e32 v25, v56, v55
	v_min_u32_e32 v55, v56, v55
	v_max_u32_e32 v56, v40, v39
	v_min_u32_e32 v39, v40, v39
	v_max_u32_e32 v40, v24, v23
	v_min_u32_e32 v23, v24, v23
	v_max_u32_e32 v24, v5, v9
	v_min_u32_e32 v5, v5, v9
	v_max_u32_e32 v9, v72, v20
	v_min_u32_e32 v20, v72, v20
	v_max_u32_e32 v72, v53, v57
	v_min_u32_e32 v53, v53, v57
	v_max_u32_e32 v57, v37, v41
	v_min_u32_e32 v37, v37, v41
	v_max_u32_e32 v41, v3, v7
	v_min_u32_e32 v3, v3, v7
	v_max_u32_e32 v7, v51, v55
	v_min_u32_e32 v51, v51, v55
	v_max_u32_e32 v55, v35, v39
	v_min_u32_e32 v35, v35, v39
	v_max_u32_e32 v39, v19, v23
	v_min_u32_e32 v19, v19, v23
	v_max_u32_e32 v23, v41, v5
	v_min_u32_e32 v5, v41, v5
	v_max_u32_e32 v41, v7, v20
	v_min_u32_e32 v7, v7, v20
	v_max_u32_e32 v20, v55, v53
	v_min_u32_e32 v53, v55, v53
	v_max_u32_e32 v55, v39, v37
; DI void peer_topk_phase(const bf16_t* __restrict__ qpk, const bf16_t* __restrict__ subk, int* __restrict__ eidx, float* __restrict__ gout) {
;     ...
; #pragma unroll
;             for (int n = 0; n < 63; ++n) { cex(g0[SORT16[n][0]], g0[SORT16[n][1]]); cex(g1[SORT16[n][0]], g1[SORT16[n][1]]); cex(g2[SORT16[n][0]], g2[SORT16[n][1]]); cex(g3[SORT16[n][0]], g3[SORT16[n][1]]); }
;             merge_top16(g0, g1); merge_top16(g2, g3); merge_top16(g0, g2);
	v_min_u32_e32 v37, v39, v37
	v_max_u32_e32 v39, v4, v8
	v_min_u32_e32 v4, v4, v8
	v_max_u32_e32 v8, v21, v25
	v_min_u32_e32 v21, v21, v25
	v_max_u32_e32 v25, v52, v56
	v_min_u32_e32 v52, v52, v56
	v_max_u32_e32 v56, v36, v40
	v_min_u32_e32 v36, v36, v40
	v_max_u32_e32 v40, v50, v54
	v_min_u32_e32 v50, v50, v54
	v_max_u32_e32 v54, v34, v38
	v_min_u32_e32 v34, v34, v38
	v_max_u32_e32 v38, v18, v22
	v_min_u32_e32 v18, v18, v22
	v_max_u32_e32 v22, v2, v6
	v_min_u32_e32 v2, v2, v6
	v_max_u32_e32 v6, v40, v4
	v_min_u32_e32 v4, v40, v4
	v_max_u32_e32 v40, v54, v21
	v_min_u32_e32 v21, v54, v21
	v_max_u32_e32 v54, v38, v52
	v_min_u32_e32 v38, v38, v52
	v_max_u32_e32 v52, v22, v36
	v_min_u32_e32 v22, v22, v36
	v_max_u32_e32 v36, v39, v23
	v_min_u32_e32 v23, v39, v23
	v_max_u32_e32 v39, v8, v41
	v_min_u32_e32 v8, v8, v41
	v_max_u32_e32 v41, v25, v20
	v_min_u32_e32 v20, v25, v20
	v_max_u32_e32 v25, v56, v55
	v_min_u32_e32 v55, v56, v55
	v_max_u32_e32 v56, v6, v5
	v_min_u32_e32 v5, v6, v5
	v_max_u32_e32 v6, v40, v7
	v_min_u32_e32 v7, v40, v7
	v_max_u32_e32 v40, v54, v53
	v_min_u32_e32 v53, v54, v53
	v_max_u32_e32 v54, v52, v37
	v_min_u32_e32 v37, v52, v37
	v_max_u32_e32 v52, v4, v3
	v_min_u32_e32 v3, v4, v3
	v_max_u32_e32 v4, v21, v51
	v_min_u32_e32 v21, v21, v51
	v_max_u32_e32 v51, v38, v35
	v_min_u32_e32 v35, v38, v35
	v_max_u32_e32 v38, v22, v19
	v_min_u32_e32 v19, v22, v19
	v_max_u32_e32 v22, v58, v59
	v_min_u32_e32 v58, v58, v59
	v_max_u32_e32 v59, v42, v43
	v_min_u32_e32 v42, v42, v43
	v_max_u32_e32 v43, v26, v27
	v_min_u32_e32 v26, v26, v27
	v_max_u32_e32 v27, v10, v11
	v_min_u32_e32 v10, v10, v11
	v_max_u32_e32 v11, v60, v61
	v_min_u32_e32 v60, v60, v61
	v_max_u32_e32 v61, v44, v45
	v_min_u32_e32 v44, v44, v45
	v_max_u32_e32 v45, v28, v29
	v_min_u32_e32 v28, v28, v29
	v_max_u32_e32 v29, v12, v13
	v_min_u32_e32 v12, v12, v13
	v_and_or_b32 v17, v17, s42, v153
	v_max_u32_e32 v13, v22, v11
	v_min_u32_e32 v11, v22, v11
	v_max_u32_e32 v22, v59, v61
	v_min_u32_e32 v59, v59, v61
	v_max_u32_e32 v61, v43, v45
	v_min_u32_e32 v43, v43, v45
	v_max_u32_e32 v45, v27, v29
	v_min_u32_e32 v27, v27, v29
	v_max_u32_e32 v29, v58, v60
	v_min_u32_e32 v58, v58, v60
	v_max_u32_e32 v60, v42, v44
	v_min_u32_e32 v42, v42, v44
	v_max_u32_e32 v44, v26, v28
	v_min_u32_e32 v26, v26, v28
	v_max_u32_e32 v28, v10, v12
	v_min_u32_e32 v10, v10, v12
	v_max_u32_e32 v12, v29, v11
	v_min_u32_e32 v11, v29, v11
	v_max_u32_e32 v29, v60, v59
	v_min_u32_e32 v59, v60, v59
	v_max_u32_e32 v60, v44, v43
	v_min_u32_e32 v43, v44, v43
	v_max_u32_e32 v44, v28, v27
	v_min_u32_e32 v27, v28, v27
	v_max_u32_e32 v28, v62, v63
	v_min_u32_e32 v62, v62, v63
	v_max_u32_e32 v63, v46, v47
	v_min_u32_e32 v46, v46, v47
	v_max_u32_e32 v47, v30, v31
	v_min_u32_e32 v30, v30, v31
	v_max_u32_e32 v31, v14, v15
	v_min_u32_e32 v14, v14, v15
	v_max_u32_e32 v15, v64, v65
	v_min_u32_e32 v64, v64, v65
	v_max_u32_e32 v65, v48, v49
	v_min_u32_e32 v48, v48, v49
	v_max_u32_e32 v49, v32, v33
	v_min_u32_e32 v32, v32, v33
	v_max_u32_e32 v33, v16, v17
	v_min_u32_e32 v16, v16, v17
	v_max_u32_e32 v17, v28, v15
	v_min_u32_e32 v15, v28, v15
	v_max_u32_e32 v28, v63, v65
	v_min_u32_e32 v63, v63, v65
	v_max_u32_e32 v65, v47, v49
	v_min_u32_e32 v47, v47, v49
	v_max_u32_e32 v49, v31, v33
	v_min_u32_e32 v31, v31, v33
	v_max_u32_e32 v33, v62, v64
	v_min_u32_e32 v62, v62, v64
	v_max_u32_e32 v64, v46, v48
	v_min_u32_e32 v46, v46, v48
	v_max_u32_e32 v48, v30, v32
	v_min_u32_e32 v30, v30, v32
	v_max_u32_e32 v32, v14, v16
	v_min_u32_e32 v14, v14, v16
	v_max_u32_e32 v16, v33, v15
	v_min_u32_e32 v15, v33, v15
	v_max_u32_e32 v33, v64, v63
	v_min_u32_e32 v63, v64, v63
	v_max_u32_e32 v64, v48, v47
	v_min_u32_e32 v47, v48, v47
	v_max_u32_e32 v48, v32, v31
	v_min_u32_e32 v31, v32, v31
	v_max_u32_e32 v32, v13, v17
	v_min_u32_e32 v13, v13, v17
	v_max_u32_e32 v17, v22, v28
	v_min_u32_e32 v22, v22, v28
	v_max_u32_e32 v28, v61, v65
	v_min_u32_e32 v61, v61, v65
	v_max_u32_e32 v65, v45, v49
	v_min_u32_e32 v45, v45, v49
	v_max_u32_e32 v49, v11, v15
	v_min_u32_e32 v11, v11, v15
	v_max_u32_e32 v15, v59, v63
	v_min_u32_e32 v59, v59, v63
	v_max_u32_e32 v63, v43, v47
	v_min_u32_e32 v43, v43, v47
	v_max_u32_e32 v47, v27, v31
	v_min_u32_e32 v27, v27, v31
	v_max_u32_e32 v31, v49, v13
	v_min_u32_e32 v13, v49, v13
	v_max_u32_e32 v49, v15, v22
	v_min_u32_e32 v15, v15, v22
	v_max_u32_e32 v22, v63, v61
	v_min_u32_e32 v61, v63, v61
	v_max_u32_e32 v63, v47, v45
	v_min_u32_e32 v45, v47, v45
	v_max_u32_e32 v47, v12, v16
	v_min_u32_e32 v12, v12, v16
	v_max_u32_e32 v16, v29, v33
	v_min_u32_e32 v29, v29, v33
	v_max_u32_e32 v33, v60, v64
	v_min_u32_e32 v60, v60, v64
	v_max_u32_e32 v64, v44, v48
	v_min_u32_e32 v44, v44, v48
	v_max_u32_e32 v48, v58, v62
	v_min_u32_e32 v58, v58, v62
	v_max_u32_e32 v62, v42, v46
	v_min_u32_e32 v42, v42, v46
	v_max_u32_e32 v46, v26, v30
	v_min_u32_e32 v26, v26, v30
	v_max_u32_e32 v30, v10, v14
	v_min_u32_e32 v10, v10, v14
	v_max_u32_e32 v14, v48, v12
	v_min_u32_e32 v12, v48, v12
	v_max_u32_e32 v48, v62, v29
	v_min_u32_e32 v29, v62, v29
	v_max_u32_e32 v62, v46, v60
	v_min_u32_e32 v46, v46, v60
	v_max_u32_e32 v60, v30, v44
	v_min_u32_e32 v30, v30, v44
	v_max_u32_e32 v44, v47, v31
	v_min_u32_e32 v31, v47, v31
	v_max_u32_e32 v47, v16, v49
	v_min_u32_e32 v16, v16, v49
	v_max_u32_e32 v49, v33, v22
	v_min_u32_e32 v22, v33, v22
	v_max_u32_e32 v33, v64, v63
	v_min_u32_e32 v63, v64, v63
	v_max_u32_e32 v64, v14, v13
	v_min_u32_e32 v13, v14, v13
	v_max_u32_e32 v14, v48, v15
	v_min_u32_e32 v15, v48, v15
	v_max_u32_e32 v48, v62, v61
	v_min_u32_e32 v61, v62, v61
	v_max_u32_e32 v62, v60, v45
	v_min_u32_e32 v45, v60, v45
	v_max_u32_e32 v60, v12, v11
; DI void merge_top16(unsigned (&A)[16], const unsigned (&B)[16]) {
; #pragma unroll
;     for (int i = 0; i < 16; ++i) A[i] = max(A[i], B[15 - i]);
; #pragma unroll
;     for (int n = 0; n < 32; ++n) cex(A[BMERGE16[n][0]], A[BMERGE16[n][1]]);
; }
; DI void peer_topk_phase(const bf16_t* __restrict__ qpk, const bf16_t* __restrict__ subk, int* __restrict__ eidx, float* __restrict__ gout) {
;     ...
; #pragma unroll
;             for (int n = 0; n < 63; ++n) { cex(g0[SORT16[n][0]], g0[SORT16[n][1]]); cex(g1[SORT16[n][0]], g1[SORT16[n][1]]); cex(g2[SORT16[n][0]], g2[SORT16[n][1]]); cex(g3[SORT16[n][0]], g3[SORT16[n][1]]); }
;             merge_top16(g0, g1); merge_top16(g2, g3); merge_top16(g0, g2);
	v_min_u32_e32 v11, v12, v11
	v_max_u32_e32 v12, v29, v59
	v_min_u32_e32 v29, v29, v59
	v_max_u32_e32 v59, v46, v43
	v_min_u32_e32 v43, v46, v43
	v_max_u32_e32 v46, v30, v27
	v_min_u32_e32 v27, v30, v27
	v_min_u32_e32 v30, v24, v32
	v_min_u32_e32 v73, v9, v17
	v_min_u32_e32 v74, v72, v28
	v_min_u32_e32 v79, v57, v65
	v_max_u32_e32 v82, v5, v13
	v_min_u32_e32 v5, v5, v13
	v_max_u32_e32 v13, v7, v15
	v_min_u32_e32 v7, v7, v15
	v_max_u32_e32 v15, v53, v61
	v_min_u32_e32 v53, v53, v61
	v_max_u32_e32 v61, v37, v45
	v_min_u32_e32 v37, v37, v45
	v_max_u32_e32 v45, v82, v30
	v_min_u32_e32 v30, v82, v30
	v_max_u32_e32 v82, v13, v73
	v_min_u32_e32 v13, v13, v73
	v_max_u32_e32 v73, v15, v74
	v_min_u32_e32 v15, v15, v74
	v_max_u32_e32 v74, v61, v79
	v_min_u32_e32 v61, v61, v79
	v_max_u32_e32 v79, v23, v31
	v_min_u32_e32 v23, v23, v31
	v_max_u32_e32 v31, v8, v16
	v_min_u32_e32 v8, v8, v16
	v_max_u32_e32 v16, v20, v22
	v_min_u32_e32 v20, v20, v22
	v_max_u32_e32 v22, v55, v63
	v_min_u32_e32 v55, v55, v63
	v_max_u32_e32 v63, v3, v11
	v_min_u32_e32 v3, v3, v11
	v_max_u32_e32 v11, v21, v29
	v_min_u32_e32 v21, v21, v29
	v_max_u32_e32 v29, v35, v43
	v_min_u32_e32 v35, v35, v43
	v_max_u32_e32 v43, v19, v27
	v_min_u32_e32 v19, v19, v27
	v_max_u32_e32 v27, v63, v23
	v_min_u32_e32 v23, v63, v23
	v_max_u32_e32 v63, v11, v8
	v_min_u32_e32 v8, v11, v8
	v_max_u32_e32 v11, v29, v20
	v_min_u32_e32 v20, v29, v20
	v_max_u32_e32 v29, v43, v55
	v_min_u32_e32 v43, v43, v55
	v_max_u32_e32 v55, v79, v45
	v_min_u32_e32 v45, v79, v45
	v_max_u32_e32 v79, v31, v82
	v_min_u32_e32 v31, v31, v82
	v_max_u32_e32 v82, v16, v73
	v_min_u32_e32 v16, v16, v73
	v_max_u32_e32 v73, v22, v74
	v_min_u32_e32 v22, v22, v74
	v_max_u32_e32 v74, v27, v30
	v_min_u32_e32 v27, v27, v30
	v_max_u32_e32 v30, v63, v13
	v_min_u32_e32 v13, v63, v13
	v_max_u32_e32 v63, v11, v15
	v_min_u32_e32 v11, v11, v15
	v_max_u32_e32 v15, v29, v61
	v_min_u32_e32 v29, v29, v61
	v_max_u32_e32 v61, v23, v5
	v_min_u32_e32 v5, v23, v5
	v_max_u32_e32 v23, v8, v7
	v_min_u32_e32 v7, v8, v7
	v_max_u32_e32 v8, v20, v53
	v_min_u32_e32 v20, v20, v53
	v_max_u32_e32 v53, v43, v37
	v_min_u32_e32 v37, v43, v37
	v_max_u32_e32 v43, v36, v44
	v_min_u32_e32 v36, v36, v44
	v_max_u32_e32 v44, v39, v47
	v_min_u32_e32 v39, v39, v47
	v_max_u32_e32 v47, v41, v49
	v_min_u32_e32 v41, v41, v49
	v_max_u32_e32 v49, v25, v33
	v_min_u32_e32 v25, v25, v33
	v_max_u32_e32 v33, v52, v60
	v_min_u32_e32 v52, v52, v60
	v_max_u32_e32 v60, v4, v12
	v_min_u32_e32 v4, v4, v12
	v_max_u32_e32 v12, v51, v59
	v_min_u32_e32 v51, v51, v59
	v_max_u32_e32 v59, v38, v46
	v_min_u32_e32 v38, v38, v46
	v_max_u32_e32 v46, v33, v36
	v_min_u32_e32 v33, v33, v36
	v_max_u32_e32 v36, v60, v39
	v_min_u32_e32 v39, v60, v39
	v_max_u32_e32 v60, v12, v41
	v_min_u32_e32 v12, v12, v41
	v_max_u32_e32 v41, v59, v25
	v_min_u32_e32 v25, v59, v25
	v_max_u32_e32 v59, v56, v64
	v_min_u32_e32 v56, v56, v64
	v_max_u32_e32 v64, v6, v14
	v_min_u32_e32 v6, v6, v14
	v_max_u32_e32 v14, v40, v48
	v_min_u32_e32 v40, v40, v48
	v_max_u32_e32 v48, v54, v62
	v_min_u32_e32 v54, v54, v62
	v_max_u32_e32 v62, v50, v58
	v_min_u32_e32 v50, v50, v58
	v_max_u32_e32 v58, v34, v42
	v_min_u32_e32 v34, v34, v42
	v_max_u32_e32 v42, v18, v26
	v_min_u32_e32 v18, v18, v26
	v_max_u32_e32 v26, v2, v10
	v_min_u32_e32 v2, v2, v10
	v_max_u32_e32 v10, v62, v56
	v_min_u32_e32 v56, v62, v56
	v_max_u32_e32 v62, v58, v6
	v_min_u32_e32 v6, v58, v6
	v_max_u32_e32 v58, v42, v40
	v_min_u32_e32 v40, v42, v40
	v_max_u32_e32 v42, v26, v54
	v_min_u32_e32 v26, v26, v54
	v_max_u32_e32 v54, v59, v46
	v_min_u32_e32 v46, v59, v46
	v_max_u32_e32 v59, v64, v36
	v_min_u32_e32 v36, v64, v36
	v_max_u32_e32 v64, v14, v60
	v_min_u32_e32 v14, v14, v60
	v_max_u32_e32 v60, v48, v41
	v_min_u32_e32 v41, v48, v41
	v_max_u32_e32 v48, v10, v33
	v_min_u32_e32 v10, v10, v33
	v_max_u32_e32 v33, v62, v39
	v_min_u32_e32 v39, v62, v39
	v_max_u32_e32 v62, v58, v12
	v_min_u32_e32 v12, v58, v12
	v_max_u32_e32 v58, v42, v25
	v_min_u32_e32 v25, v42, v25
	v_max_u32_e32 v42, v56, v52
	v_min_u32_e32 v52, v56, v52
	v_max_u32_e32 v56, v6, v4
	v_min_u32_e32 v4, v6, v4
	v_max_u32_e32 v6, v40, v51
	v_min_u32_e32 v40, v40, v51
	v_max_u32_e32 v51, v26, v38
	v_min_u32_e32 v26, v26, v38
	v_min_u32_e32 v38, v43, v55
	v_min_u32_e32 v83, v44, v79
	v_min_u32_e32 v157, v47, v82
	v_min_u32_e32 v158, v49, v73
	v_min_u32_e32 v159, v54, v45
	v_min_u32_e32 v160, v59, v31
	v_min_u32_e32 v161, v64, v16
	v_min_u32_e32 v162, v60, v22
	v_min_u32_e32 v163, v46, v74
	v_min_u32_e32 v164, v36, v30
	v_min_u32_e32 v165, v14, v63
	v_min_u32_e32 v166, v41, v15
	v_min_u32_e32 v167, v48, v27
	v_min_u32_e32 v168, v33, v13
	v_min_u32_e32 v169, v62, v11
	v_min_u32_e32 v182, v58, v29
	v_min_u32_e32 v183, v10, v61
	v_min_u32_e32 v184, v39, v23
	v_min_u32_e32 v185, v12, v8
	v_min_u32_e32 v186, v25, v53
	v_min_u32_e32 v187, v42, v5
	v_min_u32_e32 v188, v56, v7
	v_min_u32_e32 v189, v6, v20
	v_min_u32_e32 v190, v51, v37
	v_min_u32_e32 v191, v52, v3
	v_min_u32_e32 v198, v4, v21
	v_min_u32_e32 v199, v40, v35
	v_min_u32_e32 v200, v26, v19
	v_max3_u32 v24, v24, v32, v34
	v_max3_u32 v32, v43, v55, v198
	v_max3_u32 v4, v38, v4, v21
	v_max3_u32 v21, v54, v45, v188
	v_max3_u32 v7, v159, v56, v7
	v_max3_u32 v34, v46, v74, v184
	v_max3_u32 v23, v163, v39, v23
	v_max3_u32 v27, v48, v27, v168
	v_max3_u32 v13, v167, v33, v13
	v_max3_u32 v10, v10, v61, v164
	v_max3_u32 v30, v183, v36, v30
	v_max3_u32 v5, v42, v5, v160
	v_max3_u32 v31, v187, v59, v31
	v_max3_u32 v3, v52, v3, v83
	v_max3_u32 v33, v191, v44, v79
	v_max3_u32 v9, v50, v9, v17
	v_max3_u32 v2, v72, v28, v2
	v_max3_u32 v28, v47, v82, v200
	v_max3_u32 v19, v157, v26, v19
; DI void merge_top16(unsigned (&A)[16], const unsigned (&B)[16]) {
; #pragma unroll
;     for (int i = 0; i < 16; ++i) A[i] = max(A[i], B[15 - i]);
; #pragma unroll
;     for (int n = 0; n < 32; ++n) cex(A[BMERGE16[n][0]], A[BMERGE16[n][1]]);
; }
; DI void peer_topk_phase(const bf16_t* __restrict__ qpk, const bf16_t* __restrict__ subk, int* __restrict__ eidx, float* __restrict__ gout) {
;     ...
;             merge_top16(g0, g1); merge_top16(g2, g3); merge_top16(g0, g2);
;             unsigned pb[16];
; #pragma unroll
;             for (int i = 0; i < 16; ++i) pb[i] = (unsigned)__shfl_xor((int)g0[i], 32);
;             merge_top16(g0, pb);
	v_max3_u32 v16, v64, v16, v190
	v_max3_u32 v26, v161, v51, v37
	v_max3_u32 v14, v14, v63, v186
	v_max3_u32 v25, v165, v25, v53
	v_max3_u32 v11, v62, v11, v182
	v_max3_u32 v29, v169, v58, v29
	v_max3_u32 v8, v12, v8, v166
	v_max3_u32 v12, v185, v41, v15
	v_max3_u32 v6, v6, v20, v162
	v_max3_u32 v15, v189, v60, v22
	v_max3_u32 v20, v40, v35, v158
	v_max3_u32 v22, v199, v49, v73
	v_max3_u32 v18, v18, v57, v65
	v_max_u32_e32 v17, v24, v13
	v_min_u32_e32 v13, v24, v13
	v_max_u32_e32 v24, v32, v10
	v_min_u32_e32 v10, v32, v10
	v_max_u32_e32 v32, v4, v30
	v_min_u32_e32 v4, v4, v30
	v_max_u32_e32 v30, v21, v5
	v_min_u32_e32 v5, v21, v5
	v_max_u32_e32 v21, v7, v31
	v_min_u32_e32 v7, v7, v31
	v_max_u32_e32 v31, v34, v3
	v_min_u32_e32 v3, v34, v3
	v_max_u32_e32 v34, v23, v33
	v_min_u32_e32 v23, v23, v33
	v_max_u32_e32 v33, v27, v9
	v_min_u32_e32 v9, v27, v9
	v_max_u32_e32 v35, v2, v29
	v_min_u32_e32 v2, v2, v29
	v_max_u32_e32 v29, v28, v8
	v_min_u32_e32 v8, v28, v8
	v_max_u32_e32 v28, v19, v12
	v_min_u32_e32 v12, v19, v12
	v_max_u32_e32 v19, v16, v6
	v_min_u32_e32 v6, v16, v6
	v_max_u32_e32 v16, v26, v15
	v_min_u32_e32 v15, v26, v15
	v_max_u32_e32 v26, v14, v20
	v_min_u32_e32 v14, v14, v20
	v_max_u32_e32 v20, v25, v22
	v_min_u32_e32 v22, v25, v22
	v_max_u32_e32 v25, v11, v18
	v_min_u32_e32 v11, v11, v18
	v_max_u32_e32 v27, v17, v21
	v_min_u32_e32 v17, v17, v21
	v_max_u32_e32 v21, v24, v31
	v_min_u32_e32 v24, v24, v31
	v_max_u32_e32 v31, v32, v34
	v_min_u32_e32 v32, v32, v34
	v_max_u32_e32 v34, v30, v33
	v_min_u32_e32 v30, v30, v33
	v_max_u32_e32 v33, v13, v7
	v_min_u32_e32 v7, v13, v7
	v_max_u32_e32 v13, v10, v3
	v_min_u32_e32 v3, v10, v3
	v_max_u32_e32 v10, v4, v23
	v_min_u32_e32 v4, v4, v23
	v_max_u32_e32 v23, v5, v9
	v_min_u32_e32 v5, v5, v9
	v_max_u32_e32 v18, v35, v16
	v_min_u32_e32 v16, v35, v16
	v_max_u32_e32 v35, v29, v26
	v_min_u32_e32 v26, v29, v26
	v_max_u32_e32 v29, v28, v20
	v_min_u32_e32 v20, v28, v20
	v_max_u32_e32 v28, v19, v25
	v_min_u32_e32 v19, v19, v25
	v_max_u32_e32 v25, v2, v15
	v_min_u32_e32 v2, v2, v15
	v_max_u32_e32 v15, v8, v14
	v_min_u32_e32 v8, v8, v14
	v_max_u32_e32 v14, v12, v22
	v_min_u32_e32 v12, v12, v22
	v_max_u32_e32 v22, v6, v11
	v_min_u32_e32 v6, v6, v11
	v_max_u32_e32 v9, v27, v31
	v_min_u32_e32 v27, v27, v31
	v_max_u32_e32 v31, v21, v34
	v_min_u32_e32 v21, v21, v34
	v_max_u32_e32 v34, v17, v32
	v_min_u32_e32 v17, v17, v32
	v_max_u32_e32 v32, v24, v30
	v_min_u32_e32 v24, v24, v30
	v_max_u32_e32 v30, v33, v10
	v_min_u32_e32 v10, v33, v10
	v_max_u32_e32 v33, v13, v23
	v_min_u32_e32 v13, v13, v23
	v_max_u32_e32 v23, v7, v4
	v_min_u32_e32 v4, v7, v4
	v_max_u32_e32 v7, v3, v5
	v_min_u32_e32 v3, v3, v5
	v_max_u32_e32 v11, v18, v29
	v_min_u32_e32 v18, v18, v29
	v_max_u32_e32 v29, v35, v28
	v_min_u32_e32 v28, v35, v28
	v_max_u32_e32 v35, v16, v20
	v_min_u32_e32 v16, v16, v20
	v_max_u32_e32 v20, v26, v19
	v_min_u32_e32 v19, v26, v19
	v_max_u32_e32 v26, v25, v14
	v_min_u32_e32 v14, v25, v14
	v_max_u32_e32 v25, v15, v22
	v_min_u32_e32 v15, v15, v22
	v_max_u32_e32 v22, v2, v12
	v_min_u32_e32 v2, v2, v12
	v_max_u32_e32 v12, v8, v6
	v_min_u32_e32 v6, v8, v6
	v_min_u32_e32 v5, v9, v31
	v_min_u32_e32 v36, v27, v21
	v_min_u32_e32 v38, v34, v32
	v_min_u32_e32 v39, v17, v24
	v_min_u32_e32 v42, v30, v33
	v_min_u32_e32 v43, v10, v13
	v_min_u32_e32 v44, v23, v7
	v_min_u32_e32 v45, v4, v3
	v_min_u32_e32 v8, v11, v29
	v_min_u32_e32 v37, v18, v28
	v_min_u32_e32 v40, v35, v20
	v_min_u32_e32 v41, v16, v19
	v_min_u32_e32 v46, v26, v25
	v_min_u32_e32 v47, v14, v15
	v_min_u32_e32 v48, v22, v12
	v_min_u32_e32 v49, v2, v6
	v_max3_u32 v9, v9, v31, v49
	v_max3_u32 v2, v5, v2, v6
	v_max3_u32 v5, v27, v21, v48
	v_max3_u32 v6, v36, v22, v12
	v_max3_u32 v12, v34, v32, v47
	v_max3_u32 v14, v38, v14, v15
	v_max3_u32 v15, v17, v24, v46
	v_max3_u32 v17, v39, v26, v25
	v_max3_u32 v21, v30, v33, v41
	v_max3_u32 v16, v42, v16, v19
	v_max3_u32 v10, v10, v13, v40
	v_max3_u32 v13, v43, v35, v20
	v_max3_u32 v7, v23, v7, v37
	v_max3_u32 v18, v44, v18, v28
	v_max3_u32 v3, v4, v3, v8
	v_max3_u32 v4, v45, v11, v29
	v_max_u32_e32 v8, v9, v21
	v_min_u32_e32 v9, v9, v21
	v_max_u32_e32 v11, v2, v16
	v_min_u32_e32 v2, v2, v16
	v_max_u32_e32 v16, v5, v10
	v_min_u32_e32 v5, v5, v10
	v_max_u32_e32 v10, v6, v13
	v_min_u32_e32 v6, v6, v13
	v_max_u32_e32 v13, v12, v7
	v_min_u32_e32 v7, v12, v7
	v_max_u32_e32 v12, v14, v18
	v_min_u32_e32 v14, v14, v18
	v_max_u32_e32 v18, v15, v3
	v_min_u32_e32 v3, v15, v3
	v_max_u32_e32 v15, v17, v4
	v_min_u32_e32 v4, v17, v4
	v_max_u32_e32 v17, v8, v13
	v_min_u32_e32 v8, v8, v13
	v_max_u32_e32 v13, v11, v12
	v_min_u32_e32 v11, v11, v12
	v_max_u32_e32 v12, v16, v18
	v_min_u32_e32 v16, v16, v18
	v_max_u32_e32 v18, v10, v15
	v_min_u32_e32 v10, v10, v15
	v_max_u32_e32 v15, v9, v7
	v_min_u32_e32 v7, v9, v7
	v_max_u32_e32 v9, v2, v14
	v_min_u32_e32 v2, v2, v14
	v_max_u32_e32 v14, v5, v3
	v_min_u32_e32 v3, v5, v3
	v_max_u32_e32 v5, v6, v4
	v_min_u32_e32 v4, v6, v4
	v_max_u32_e32 v6, v17, v12
	v_min_u32_e32 v12, v17, v12
	v_max_u32_e32 v17, v13, v18
	v_min_u32_e32 v13, v13, v18
	v_max_u32_e32 v18, v8, v16
	v_min_u32_e32 v8, v8, v16
	v_max_u32_e32 v16, v11, v10
	v_min_u32_e32 v10, v11, v10
	v_max_u32_e32 v11, v15, v14
	v_min_u32_e32 v14, v15, v14
	v_max_u32_e32 v15, v9, v5
	v_min_u32_e32 v5, v9, v5
	v_max_u32_e32 v9, v7, v3
	v_min_u32_e32 v3, v7, v3
	v_max_u32_e32 v7, v2, v4
	v_min_u32_e32 v2, v2, v4
	v_max_u32_e32 v4, v6, v17
	v_min_u32_e32 v6, v6, v17
	v_max_u32_e32 v17, v12, v13
	v_min_u32_e32 v12, v12, v13
	v_max_u32_e32 v13, v18, v16
	v_min_u32_e32 v16, v18, v16
	v_max_u32_e32 v18, v8, v10
	v_min_u32_e32 v8, v8, v10
	v_max_u32_e32 v10, v11, v15
	v_min_u32_e32 v11, v11, v15
	v_max_u32_e32 v15, v14, v5
	v_min_u32_e32 v5, v14, v5
	v_max_u32_e32 v14, v9, v7
	v_min_u32_e32 v7, v9, v7
	v_max_u32_e32 v9, v3, v2
	v_min_u32_e32 v2, v3, v2
	ds_bpermute_b32 v3, v173, v4
	ds_bpermute_b32 v19, v173, v6
	ds_bpermute_b32 v20, v173, v17
	ds_bpermute_b32 v21, v173, v12
	ds_bpermute_b32 v22, v173, v13
	ds_bpermute_b32 v23, v173, v16
	ds_bpermute_b32 v24, v173, v18
	ds_bpermute_b32 v25, v173, v8
	ds_bpermute_b32 v26, v173, v10
	ds_bpermute_b32 v27, v173, v11
	ds_bpermute_b32 v28, v173, v15
	ds_bpermute_b32 v29, v173, v5
	ds_bpermute_b32 v30, v173, v14
	ds_bpermute_b32 v31, v173, v7
	ds_bpermute_b32 v32, v173, v9
	ds_bpermute_b32 v33, v173, v2
	s_waitcnt lgkmcnt(4)
; #define MFMA(a, b, c) __builtin_amdgcn_mfma_f32_32x32x16_bf16((a), (b), (c), 0, 0, 0)
; DI void merge_top16(unsigned (&A)[16], const unsigned (&B)[16]) {
; #pragma unroll
;     for (int i = 0; i < 16; ++i) A[i] = max(A[i], B[15 - i]);
; #pragma unroll
;     for (int n = 0; n < 32; ++n) cex(A[BMERGE16[n][0]], A[BMERGE16[n][1]]);
; }
; DI void peer_topk_phase(const bf16_t* __restrict__ qpk, const bf16_t* __restrict__ subk, int* __restrict__ eidx, float* __restrict__ gout) {
;     ...
;         for (int c = 0; c < 2; ++c) {
;             f32x16 acc[4];
; #pragma unroll
;             for (int nb = 0; nb < 4; ++nb)
; #pragma unroll
;                 for (int i = 0; i < 16; ++i) acc[nb][i] = 0.f;
;             const bf16_t* qp = qpk + (size_t)(t0 + r) * 1024 + hh * 128 + c * 64 + h * 8;
;             const bf16_t* kp = subk + ((size_t)(hh * 2 + c) * 128 + r) * 64 + h * 8;
; #pragma unroll
;             for (int ks = 0; ks < 4; ++ks) {
;                 const bf16x8 qfr = *(const bf16x8*)(qp + ks * 16);
; #pragma unroll
;                 for (int nb = 0; nb < 4; ++nb) {
;                     const bf16x8 kf = *(const bf16x8*)(kp + nb * 32 * 64 + ks * 16);
;                     acc[nb] = MFMA(kf, qfr, acc[nb]);
;                 }
	v_max_u32_e32 v13, v13, v29
	s_waitcnt lgkmcnt(3)
	v_max_u32_e32 v12, v12, v30
	s_waitcnt lgkmcnt(2)
	v_max_u32_e32 v17, v17, v31
	s_waitcnt lgkmcnt(1)
	v_max_u32_e32 v6, v6, v32
	s_waitcnt lgkmcnt(0)
	v_max_u32_e32 v4, v4, v33
	v_max_u32_e32 v16, v16, v28
	v_max_u32_e32 v18, v18, v27
	v_max_u32_e32 v8, v8, v26
	v_max_u32_e32 v10, v10, v25
	v_max_u32_e32 v11, v11, v24
	v_max_u32_e32 v15, v15, v23
	v_max_u32_e32 v5, v5, v22
	v_max_u32_e32 v14, v14, v21
	v_max_u32_e32 v7, v7, v20
	v_max_u32_e32 v9, v9, v19
	v_max_u32_e32 v2, v2, v3
	v_max_u32_e32 v3, v4, v10
	v_min_u32_e32 v4, v4, v10
	v_max_u32_e32 v10, v6, v11
	v_min_u32_e32 v6, v6, v11
	v_max_u32_e32 v11, v17, v15
	v_min_u32_e32 v15, v17, v15
	v_max_u32_e32 v17, v12, v5
	v_min_u32_e32 v5, v12, v5
	v_max_u32_e32 v12, v13, v14
	v_min_u32_e32 v13, v13, v14
	v_max_u32_e32 v14, v16, v7
	v_min_u32_e32 v7, v16, v7
	v_max_u32_e32 v16, v18, v9
	v_min_u32_e32 v9, v18, v9
	v_max_u32_e32 v18, v8, v2
	v_min_u32_e32 v2, v8, v2
	v_max_u32_e32 v8, v3, v12
	v_min_u32_e32 v3, v3, v12
	v_max_u32_e32 v12, v10, v14
	v_min_u32_e32 v10, v10, v14
	v_max_u32_e32 v14, v11, v16
	v_min_u32_e32 v11, v11, v16
	v_max_u32_e32 v16, v17, v18
	v_min_u32_e32 v17, v17, v18
	v_max_u32_e32 v18, v4, v13
	v_min_u32_e32 v4, v4, v13
	v_max_u32_e32 v13, v6, v7
	v_min_u32_e32 v6, v6, v7
	v_max_u32_e32 v7, v15, v9
	v_min_u32_e32 v9, v15, v9
	v_max_u32_e32 v15, v5, v2
	v_min_u32_e32 v2, v5, v2
	v_max_u32_e32 v5, v8, v14
	v_min_u32_e32 v8, v8, v14
	v_max_u32_e32 v14, v12, v16
	v_min_u32_e32 v12, v12, v16
	v_max_u32_e32 v16, v3, v11
	v_min_u32_e32 v3, v3, v11
	v_max_u32_e32 v11, v10, v17
	v_min_u32_e32 v10, v10, v17
	v_max_u32_e32 v17, v18, v7
	v_min_u32_e32 v7, v18, v7
	v_max_u32_e32 v18, v13, v15
	v_min_u32_e32 v13, v13, v15
	v_max_u32_e32 v15, v4, v9
	v_min_u32_e32 v4, v4, v9
	v_max_u32_e32 v9, v6, v2
	v_min_u32_e32 v2, v6, v2
	v_max_u32_e32 v168, v5, v14
	v_min_u32_e32 v182, v5, v14
	v_max_u32_e32 v164, v3, v10
	v_min_u32_e32 v163, v3, v10
	v_max_u32_e32 v79, v4, v2
	v_min_u32_e32 v74, v4, v2
	global_load_dwordx4 v[50:53], v[66:67], off offset:128
	global_load_dwordx4 v[2:5], v[70:71], off
	v_add_co_u32_e32 v72, vcc, s43, v68
	s_waitcnt vmcnt(0)
	v_mfma_f32_32x32x16_bf16 v[34:49], v[2:5], v[50:53], 0
	v_addc_co_u32_e32 v73, vcc, 0, v69, vcc
	v_add_co_u32_e32 v82, vcc, s52, v68
	v_max_u32_e32 v162, v17, v18
	s_nop 0
	v_addc_co_u32_e32 v83, vcc, 0, v69, vcc
	global_load_dwordx4 v[2:5], v[82:83], off offset:-4096
	v_add_co_u32_e32 v198, vcc, s53, v68
	v_min_u32_e32 v161, v17, v18
	s_nop 0
	v_addc_co_u32_e32 v199, vcc, 0, v69, vcc
	global_load_dwordx4 v[54:57], v[198:199], off
	s_waitcnt vmcnt(1)
	v_mfma_f32_32x32x16_bf16 v[18:33], v[2:5], v[50:53], 0
	global_load_dwordx4 v[2:5], v[82:83], off
	global_load_dwordx4 v[184:187], v[66:67], off offset:160
	global_load_dwordx4 v[188:191], v[70:71], off offset:32
	v_max_u32_e32 v169, v8, v12
	v_min_u32_e32 v167, v8, v12
	v_max_u32_e32 v166, v16, v11
	v_min_u32_e32 v165, v16, v11
	v_max_u32_e32 v160, v7, v13
	s_waitcnt vmcnt(0)
	v_mfma_f32_32x32x16_bf16 v[34:49], v[188:191], v[184:187], v[34:49]
	global_load_dwordx4 v[188:191], v[72:73], off offset:32
	v_min_u32_e32 v159, v7, v13
	v_max_u32_e32 v158, v15, v9
	v_min_u32_e32 v157, v15, v9
	s_waitcnt vmcnt(0)
	v_mfma_f32_32x32x16_bf16 v[18:33], v[188:191], v[184:187], v[18:33]
	global_load_dwordx4 v[188:191], v[82:83], off offset:32
	v_mfma_f32_32x32x16_bf16 v[2:17], v[2:5], v[50:53], 0
	s_waitcnt vmcnt(0)
	v_mfma_f32_32x32x16_bf16 v[2:17], v[188:191], v[184:187], v[2:17]
	global_load_dwordx4 v[188:191], v[198:199], off offset:32
	v_mfma_f32_32x32x16_bf16 v[50:65], v[54:57], v[50:53], 0
	s_waitcnt vmcnt(0)
	v_mfma_f32_32x32x16_bf16 v[50:65], v[188:191], v[184:187], v[50:65]
	global_load_dwordx4 v[184:187], v[66:67], off offset:192
	global_load_dwordx4 v[188:191], v[70:71], off offset:64
	s_waitcnt vmcnt(0)
	v_mfma_f32_32x32x16_bf16 v[34:49], v[188:191], v[184:187], v[34:49]
	global_load_dwordx4 v[188:191], v[72:73], off offset:64
	s_waitcnt vmcnt(0)
	v_mfma_f32_32x32x16_bf16 v[18:33], v[188:191], v[184:187], v[18:33]
	global_load_dwordx4 v[188:191], v[82:83], off offset:64
	s_waitcnt vmcnt(0)
	v_mfma_f32_32x32x16_bf16 v[2:17], v[188:191], v[184:187], v[2:17]
	global_load_dwordx4 v[188:191], v[198:199], off offset:64
	s_waitcnt vmcnt(0)
	v_mfma_f32_32x32x16_bf16 v[50:65], v[188:191], v[184:187], v[50:65]
	global_load_dwordx4 v[66:69], v[66:67], off offset:224
	s_nop 0
	global_load_dwordx4 v[184:187], v[70:71], off offset:96
	s_nop 0
	global_load_dwordx4 v[70:73], v[72:73], off offset:96
	s_waitcnt vmcnt(0)
	v_mfma_f32_32x32x16_bf16 v[18:33], v[70:73], v[66:69], v[18:33]
	global_load_dwordx4 v[70:73], v[82:83], off offset:96
	s_waitcnt vmcnt(0)
	v_mfma_f32_32x32x16_bf16 v[2:17], v[70:73], v[66:69], v[2:17]
	global_load_dwordx4 v[70:73], v[198:199], off offset:96
	v_mfma_f32_32x32x16_bf16 v[34:49], v[184:187], v[66:69], v[34:49]
	s_waitcnt vmcnt(0)
; #define MFMA(a, b, c) __builtin_amdgcn_mfma_f32_32x32x16_bf16((a), (b), (c), 0, 0, 0)
; DI unsigned f2ord(float f) { const unsigned u = __float_as_uint(f); return (u & 0x80000000u) ? ~u : (u | 0x80000000u); }
; DI void peer_topk_phase(const bf16_t* __restrict__ qpk, const bf16_t* __restrict__ subk, int* __restrict__ eidx, float* __restrict__ gout) {
;     ...
;                     acc[nb] = MFMA(kf, qfr, acc[nb]);
;                 }
;             }
;             unsigned key[64];
; #pragma unroll
;             for (int nb = 0; nb < 4; ++nb)
; #pragma unroll
;                 for (int i = 0; i < 16; ++i) {
;                     const int n = nb * 32 + (i & 3) + 8 * (i >> 2) + 4 * h;
;                     key[nb * 16 + i] = (f2ord(acc[nb][i]) & ~127u) | (unsigned)(127 - n);
;                 }
	v_mfma_f32_32x32x16_bf16 v[50:65], v[70:73], v[66:69], v[50:65]
	s_nop 9
	v_not_b32_e32 v66, v34
	v_or_b32_e32 v67, 0x80000000, v34
	v_cmp_gt_i32_e32 vcc, 0, v34
	s_nop 1
	v_cndmask_b32_e32 v34, v67, v66, vcc
	v_not_b32_e32 v66, v35
	v_or_b32_e32 v67, 0x80000000, v35
	v_cmp_gt_i32_e32 vcc, 0, v35
	v_and_or_b32 v34, v34, s42, v85
	s_nop 0
	v_cndmask_b32_e32 v35, v67, v66, vcc
	v_not_b32_e32 v66, v36
	v_or_b32_e32 v67, 0x80000000, v36
	v_cmp_gt_i32_e32 vcc, 0, v36
	v_and_or_b32 v35, v35, s42, v86
	s_nop 0
	v_cndmask_b32_e32 v36, v67, v66, vcc
	v_not_b32_e32 v66, v37
	v_or_b32_e32 v67, 0x80000000, v37
	v_cmp_gt_i32_e32 vcc, 0, v37
	v_and_or_b32 v36, v36, s42, v87
	s_nop 0
	v_cndmask_b32_e32 v37, v67, v66, vcc
	v_not_b32_e32 v66, v38
	v_or_b32_e32 v67, 0x80000000, v38
	v_cmp_gt_i32_e32 vcc, 0, v38
	v_and_or_b32 v37, v37, s42, v88
	s_nop 0
	v_cndmask_b32_e32 v38, v67, v66, vcc
	v_not_b32_e32 v66, v39
	v_or_b32_e32 v67, 0x80000000, v39
	v_cmp_gt_i32_e32 vcc, 0, v39
	v_and_or_b32 v38, v38, s42, v89
	s_nop 0
	v_cndmask_b32_e32 v39, v67, v66, vcc
	v_not_b32_e32 v66, v40
	v_or_b32_e32 v67, 0x80000000, v40
	v_cmp_gt_i32_e32 vcc, 0, v40
	v_and_or_b32 v39, v39, s42, v90
	s_nop 0
	v_cndmask_b32_e32 v40, v67, v66, vcc
	v_not_b32_e32 v66, v41
	v_or_b32_e32 v67, 0x80000000, v41
	v_cmp_gt_i32_e32 vcc, 0, v41
	v_and_or_b32 v40, v40, s42, v91
	s_nop 0
	v_cndmask_b32_e32 v41, v67, v66, vcc
	v_not_b32_e32 v66, v42
	v_or_b32_e32 v67, 0x80000000, v42
	v_cmp_gt_i32_e32 vcc, 0, v42
	v_and_or_b32 v41, v41, s42, v92
	s_nop 0
	v_cndmask_b32_e32 v42, v67, v66, vcc
	v_not_b32_e32 v66, v43
	v_or_b32_e32 v67, 0x80000000, v43
	v_cmp_gt_i32_e32 vcc, 0, v43
	v_and_or_b32 v42, v42, s42, v93
	s_nop 0
	v_cndmask_b32_e32 v43, v67, v66, vcc
	v_not_b32_e32 v66, v44
	v_or_b32_e32 v67, 0x80000000, v44
	v_cmp_gt_i32_e32 vcc, 0, v44
	v_and_or_b32 v43, v43, s42, v94
	s_nop 0
	v_cndmask_b32_e32 v44, v67, v66, vcc
	v_not_b32_e32 v66, v45
	v_or_b32_e32 v67, 0x80000000, v45
	v_cmp_gt_i32_e32 vcc, 0, v45
	v_and_or_b32 v44, v44, s42, v95
	s_nop 0
	v_cndmask_b32_e32 v45, v67, v66, vcc
	v_not_b32_e32 v66, v46
	v_or_b32_e32 v67, 0x80000000, v46
	v_cmp_gt_i32_e32 vcc, 0, v46
	v_and_or_b32 v45, v45, s42, v96
	s_nop 0
	v_cndmask_b32_e32 v46, v67, v66, vcc
	v_not_b32_e32 v66, v47
	v_or_b32_e32 v67, 0x80000000, v47
	v_cmp_gt_i32_e32 vcc, 0, v47
	v_and_or_b32 v46, v46, s42, v97
	s_nop 0
	v_cndmask_b32_e32 v47, v67, v66, vcc
	v_not_b32_e32 v66, v48
	v_or_b32_e32 v67, 0x80000000, v48
	v_cmp_gt_i32_e32 vcc, 0, v48
	v_and_or_b32 v47, v47, s42, v98
	s_nop 0
	v_cndmask_b32_e32 v48, v67, v66, vcc
	v_not_b32_e32 v66, v49
	v_or_b32_e32 v67, 0x80000000, v49
	v_cmp_gt_i32_e32 vcc, 0, v49
	v_and_or_b32 v48, v48, s42, v99
	s_nop 0
	v_cndmask_b32_e32 v49, v67, v66, vcc
	v_not_b32_e32 v66, v18
	v_or_b32_e32 v67, 0x80000000, v18
	v_cmp_gt_i32_e32 vcc, 0, v18
	v_and_or_b32 v49, v49, s42, v100
	s_nop 0
	v_cndmask_b32_e32 v18, v67, v66, vcc
	v_not_b32_e32 v66, v19
	v_or_b32_e32 v67, 0x80000000, v19
	v_cmp_gt_i32_e32 vcc, 0, v19
	v_and_or_b32 v18, v18, s42, v101
	s_nop 0
	v_cndmask_b32_e32 v19, v67, v66, vcc
	v_not_b32_e32 v66, v20
	v_or_b32_e32 v67, 0x80000000, v20
	v_cmp_gt_i32_e32 vcc, 0, v20
	v_and_or_b32 v19, v19, s42, v102
	s_nop 0
	v_cndmask_b32_e32 v20, v67, v66, vcc
	v_not_b32_e32 v66, v21
	v_or_b32_e32 v67, 0x80000000, v21
	v_cmp_gt_i32_e32 vcc, 0, v21
	v_and_or_b32 v20, v20, s42, v103
	s_nop 0
	v_cndmask_b32_e32 v21, v67, v66, vcc
	v_not_b32_e32 v66, v22
	v_or_b32_e32 v67, 0x80000000, v22
	v_cmp_gt_i32_e32 vcc, 0, v22
	v_and_or_b32 v21, v21, s42, v104
	s_nop 0
	v_cndmask_b32_e32 v22, v67, v66, vcc
	v_not_b32_e32 v66, v23
	v_or_b32_e32 v67, 0x80000000, v23
	v_cmp_gt_i32_e32 vcc, 0, v23
	v_and_or_b32 v22, v22, s42, v105
	s_nop 0
	v_cndmask_b32_e32 v23, v67, v66, vcc
	v_not_b32_e32 v66, v24
	v_or_b32_e32 v67, 0x80000000, v24
	v_cmp_gt_i32_e32 vcc, 0, v24
	v_and_or_b32 v23, v23, s42, v106
	s_nop 0
	v_cndmask_b32_e32 v24, v67, v66, vcc
	v_not_b32_e32 v66, v25
	v_or_b32_e32 v67, 0x80000000, v25
	v_cmp_gt_i32_e32 vcc, 0, v25
	v_and_or_b32 v24, v24, s42, v107
	s_nop 0
	v_cndmask_b32_e32 v25, v67, v66, vcc
	v_not_b32_e32 v66, v26
	v_or_b32_e32 v67, 0x80000000, v26
	v_cmp_gt_i32_e32 vcc, 0, v26
	v_and_or_b32 v25, v25, s42, v108
	s_nop 0
	v_cndmask_b32_e32 v26, v67, v66, vcc
	v_not_b32_e32 v66, v27
	v_or_b32_e32 v67, 0x80000000, v27
	v_cmp_gt_i32_e32 vcc, 0, v27
	v_and_or_b32 v26, v26, s42, v109
	s_nop 0
	v_cndmask_b32_e32 v27, v67, v66, vcc
	v_not_b32_e32 v66, v28
	v_or_b32_e32 v67, 0x80000000, v28
	v_cmp_gt_i32_e32 vcc, 0, v28
	v_and_or_b32 v27, v27, s42, v110
	s_nop 0
	v_cndmask_b32_e32 v28, v67, v66, vcc
	v_not_b32_e32 v66, v29
	v_or_b32_e32 v67, 0x80000000, v29
	v_cmp_gt_i32_e32 vcc, 0, v29
	v_and_or_b32 v28, v28, s42, v111
	s_nop 0
	v_cndmask_b32_e32 v29, v67, v66, vcc
	v_not_b32_e32 v66, v30
	v_or_b32_e32 v67, 0x80000000, v30
	v_cmp_gt_i32_e32 vcc, 0, v30
	v_and_or_b32 v29, v29, s42, v112
	s_nop 0
	v_cndmask_b32_e32 v30, v67, v66, vcc
	v_not_b32_e32 v66, v31
	v_or_b32_e32 v67, 0x80000000, v31
	v_cmp_gt_i32_e32 vcc, 0, v31
	v_and_or_b32 v30, v30, s42, v113
	s_nop 0
	v_cndmask_b32_e32 v31, v67, v66, vcc
	v_not_b32_e32 v66, v32
	v_or_b32_e32 v67, 0x80000000, v32
	v_cmp_gt_i32_e32 vcc, 0, v32
	v_and_or_b32 v31, v31, s42, v114
	s_nop 0
	v_cndmask_b32_e32 v32, v67, v66, vcc
	v_not_b32_e32 v66, v33
	v_or_b32_e32 v67, 0x80000000, v33
	v_cmp_gt_i32_e32 vcc, 0, v33
	v_and_or_b32 v32, v32, s42, v115
	s_nop 0
	v_cndmask_b32_e32 v33, v67, v66, vcc
	v_not_b32_e32 v66, v2
	v_or_b32_e32 v67, 0x80000000, v2
	v_cmp_gt_i32_e32 vcc, 0, v2
	v_and_or_b32 v33, v33, s42, v116
	s_nop 0
	v_cndmask_b32_e32 v2, v67, v66, vcc
; DI unsigned f2ord(float f) { const unsigned u = __float_as_uint(f); return (u & 0x80000000u) ? ~u : (u | 0x80000000u); }
; DI void peer_topk_phase(const bf16_t* __restrict__ qpk, const bf16_t* __restrict__ subk, int* __restrict__ eidx, float* __restrict__ gout) {
;     ...
;             unsigned key[64];
; #pragma unroll
;             for (int nb = 0; nb < 4; ++nb)
; #pragma unroll
;                 for (int i = 0; i < 16; ++i) {
;                     const int n = nb * 32 + (i & 3) + 8 * (i >> 2) + 4 * h;
;                     key[nb * 16 + i] = (f2ord(acc[nb][i]) & ~127u) | (unsigned)(127 - n);
;                 }
;             unsigned g0[16], g1[16], g2[16], g3[16];
; #pragma unroll
;             for (int i = 0; i < 16; ++i) { g0[i] = key[i]; g1[i] = key[16 + i]; g2[i] = key[32 + i]; g3[i] = key[48 + i]; }
; #pragma unroll
;             for (int n = 0; n < 63; ++n) { cex(g0[SORT16[n][0]], g0[SORT16[n][1]]); cex(g1[SORT16[n][0]], g1[SORT16[n][1]]); cex(g2[SORT16[n][0]], g2[SORT16[n][1]]); cex(g3[SORT16[n][0]], g3[SORT16[n][1]]); }
	v_not_b32_e32 v66, v3
	v_or_b32_e32 v67, 0x80000000, v3
	v_cmp_gt_i32_e32 vcc, 0, v3
	v_and_or_b32 v2, v2, s42, v117
	s_nop 0
	v_cndmask_b32_e32 v3, v67, v66, vcc
	v_not_b32_e32 v66, v4
	v_or_b32_e32 v67, 0x80000000, v4
	v_cmp_gt_i32_e32 vcc, 0, v4
	v_and_or_b32 v3, v3, s42, v118
	s_nop 0
	v_cndmask_b32_e32 v4, v67, v66, vcc
	v_not_b32_e32 v66, v5
	v_or_b32_e32 v67, 0x80000000, v5
	v_cmp_gt_i32_e32 vcc, 0, v5
	v_and_or_b32 v4, v4, s42, v119
	s_nop 0
	v_cndmask_b32_e32 v5, v67, v66, vcc
	v_not_b32_e32 v66, v6
	v_or_b32_e32 v67, 0x80000000, v6
	v_cmp_gt_i32_e32 vcc, 0, v6
	v_and_or_b32 v5, v5, s42, v120
	s_nop 0
	v_cndmask_b32_e32 v6, v67, v66, vcc
	v_not_b32_e32 v66, v7
	v_or_b32_e32 v67, 0x80000000, v7
	v_cmp_gt_i32_e32 vcc, 0, v7
	v_and_or_b32 v6, v6, s42, v121
	s_nop 0
	v_cndmask_b32_e32 v7, v67, v66, vcc
	v_not_b32_e32 v66, v8
	v_or_b32_e32 v67, 0x80000000, v8
	v_cmp_gt_i32_e32 vcc, 0, v8
	v_and_or_b32 v7, v7, s42, v122
	s_nop 0
	v_cndmask_b32_e32 v8, v67, v66, vcc
	v_not_b32_e32 v66, v9
	v_or_b32_e32 v67, 0x80000000, v9
	v_cmp_gt_i32_e32 vcc, 0, v9
	v_and_or_b32 v8, v8, s42, v123
	s_nop 0
	v_cndmask_b32_e32 v9, v67, v66, vcc
	v_not_b32_e32 v66, v10
	v_or_b32_e32 v67, 0x80000000, v10
	v_cmp_gt_i32_e32 vcc, 0, v10
	v_and_or_b32 v9, v9, s42, v124
	s_nop 0
	v_cndmask_b32_e32 v10, v67, v66, vcc
	v_not_b32_e32 v66, v11
	v_or_b32_e32 v67, 0x80000000, v11
	v_cmp_gt_i32_e32 vcc, 0, v11
	v_and_or_b32 v10, v10, s42, v125
	s_nop 0
	v_cndmask_b32_e32 v11, v67, v66, vcc
	v_not_b32_e32 v66, v12
	v_or_b32_e32 v67, 0x80000000, v12
	v_cmp_gt_i32_e32 vcc, 0, v12
	v_and_or_b32 v11, v11, s42, v126
	s_nop 0
	v_cndmask_b32_e32 v12, v67, v66, vcc
	v_not_b32_e32 v66, v13
	v_or_b32_e32 v67, 0x80000000, v13
	v_cmp_gt_i32_e32 vcc, 0, v13
	v_and_or_b32 v12, v12, s42, v127
	s_nop 0
	v_cndmask_b32_e32 v13, v67, v66, vcc
	v_not_b32_e32 v66, v14
	v_or_b32_e32 v67, 0x80000000, v14
	v_cmp_gt_i32_e32 vcc, 0, v14
	v_and_or_b32 v13, v13, s42, v128
	s_nop 0
	v_cndmask_b32_e32 v14, v67, v66, vcc
	v_not_b32_e32 v66, v15
	v_or_b32_e32 v67, 0x80000000, v15
	v_cmp_gt_i32_e32 vcc, 0, v15
	v_and_or_b32 v14, v14, s42, v129
	s_nop 0
	v_cndmask_b32_e32 v15, v67, v66, vcc
	v_not_b32_e32 v66, v16
	v_or_b32_e32 v67, 0x80000000, v16
	v_cmp_gt_i32_e32 vcc, 0, v16
	v_and_or_b32 v15, v15, s42, v130
	s_nop 0
	v_cndmask_b32_e32 v16, v67, v66, vcc
	v_not_b32_e32 v66, v17
	v_or_b32_e32 v67, 0x80000000, v17
	v_cmp_gt_i32_e32 vcc, 0, v17
	v_and_or_b32 v16, v16, s42, v131
	s_nop 0
	v_cndmask_b32_e32 v17, v67, v66, vcc
	v_not_b32_e32 v66, v50
	v_or_b32_e32 v67, 0x80000000, v50
	v_cmp_gt_i32_e32 vcc, 0, v50
	v_and_or_b32 v17, v17, s42, v132
	s_nop 0
	v_cndmask_b32_e32 v50, v67, v66, vcc
	v_not_b32_e32 v66, v51
	v_or_b32_e32 v67, 0x80000000, v51
	v_cmp_gt_i32_e32 vcc, 0, v51
	v_and_or_b32 v50, v50, s42, v133
	s_nop 0
	v_cndmask_b32_e32 v51, v67, v66, vcc
	v_not_b32_e32 v66, v52
	v_or_b32_e32 v67, 0x80000000, v52
	v_cmp_gt_i32_e32 vcc, 0, v52
	v_and_or_b32 v51, v51, s42, v134
	s_nop 0
	v_cndmask_b32_e32 v52, v67, v66, vcc
	v_not_b32_e32 v66, v53
	v_or_b32_e32 v67, 0x80000000, v53
	v_cmp_gt_i32_e32 vcc, 0, v53
	v_and_or_b32 v52, v52, s42, v135
	s_nop 0
	v_cndmask_b32_e32 v53, v67, v66, vcc
	v_not_b32_e32 v66, v54
	v_or_b32_e32 v67, 0x80000000, v54
	v_cmp_gt_i32_e32 vcc, 0, v54
	v_and_or_b32 v53, v53, s42, v136
	s_nop 0
	v_cndmask_b32_e32 v54, v67, v66, vcc
	v_not_b32_e32 v66, v55
	v_or_b32_e32 v67, 0x80000000, v55
	v_cmp_gt_i32_e32 vcc, 0, v55
	v_and_or_b32 v54, v54, s42, v137
	s_nop 0
	v_cndmask_b32_e32 v55, v67, v66, vcc
	v_not_b32_e32 v66, v56
	v_or_b32_e32 v67, 0x80000000, v56
	v_cmp_gt_i32_e32 vcc, 0, v56
	v_and_or_b32 v55, v55, s42, v138
	s_nop 0
	v_cndmask_b32_e32 v56, v67, v66, vcc
	v_not_b32_e32 v66, v57
	v_or_b32_e32 v67, 0x80000000, v57
	v_cmp_gt_i32_e32 vcc, 0, v57
	v_and_or_b32 v56, v56, s42, v139
	s_nop 0
	v_cndmask_b32_e32 v57, v67, v66, vcc
	v_not_b32_e32 v66, v58
	v_or_b32_e32 v67, 0x80000000, v58
	v_cmp_gt_i32_e32 vcc, 0, v58
	v_and_or_b32 v57, v57, s42, v140
	s_nop 0
	v_cndmask_b32_e32 v58, v67, v66, vcc
	v_not_b32_e32 v66, v59
	v_or_b32_e32 v67, 0x80000000, v59
	v_cmp_gt_i32_e32 vcc, 0, v59
	v_and_or_b32 v58, v58, s42, v141
	s_nop 0
	v_cndmask_b32_e32 v59, v67, v66, vcc
	v_not_b32_e32 v66, v60
	v_or_b32_e32 v67, 0x80000000, v60
	v_cmp_gt_i32_e32 vcc, 0, v60
	v_and_or_b32 v59, v59, s42, v142
	s_nop 0
	v_cndmask_b32_e32 v60, v67, v66, vcc
	v_not_b32_e32 v66, v61
	v_or_b32_e32 v67, 0x80000000, v61
	v_cmp_gt_i32_e32 vcc, 0, v61
	v_and_or_b32 v60, v60, s42, v143
	s_nop 0
	v_cndmask_b32_e32 v61, v67, v66, vcc
	v_not_b32_e32 v66, v62
	v_or_b32_e32 v67, 0x80000000, v62
	v_cmp_gt_i32_e32 vcc, 0, v62
	v_and_or_b32 v61, v61, s42, v144
	s_nop 0
	v_cndmask_b32_e32 v62, v67, v66, vcc
	v_not_b32_e32 v66, v63
	v_or_b32_e32 v67, 0x80000000, v63
	v_cmp_gt_i32_e32 vcc, 0, v63
	v_and_or_b32 v62, v62, s42, v145
	s_nop 0
	v_cndmask_b32_e32 v63, v67, v66, vcc
	v_not_b32_e32 v66, v64
	v_or_b32_e32 v67, 0x80000000, v64
	v_cmp_gt_i32_e32 vcc, 0, v64
	v_and_or_b32 v63, v63, s42, v149
	s_nop 0
	v_cndmask_b32_e32 v64, v67, v66, vcc
	v_not_b32_e32 v66, v65
	v_or_b32_e32 v67, 0x80000000, v65
	v_cmp_gt_i32_e32 vcc, 0, v65
	v_and_or_b32 v64, v64, s42, v152
	s_nop 0
	v_cndmask_b32_e32 v65, v67, v66, vcc
	v_max_u32_e32 v66, v34, v35
	v_min_u32_e32 v34, v34, v35
	v_max_u32_e32 v35, v18, v19
	v_min_u32_e32 v18, v18, v19
	v_max_u32_e32 v19, v2, v3
	v_min_u32_e32 v2, v2, v3
	v_max_u32_e32 v3, v50, v51
	v_min_u32_e32 v50, v50, v51
	v_max_u32_e32 v51, v36, v37
	v_min_u32_e32 v36, v36, v37
	v_max_u32_e32 v37, v20, v21
	v_min_u32_e32 v20, v20, v21
	v_max_u32_e32 v21, v4, v5
	v_min_u32_e32 v4, v4, v5
	v_max_u32_e32 v5, v52, v53
; DI void peer_topk_phase(const bf16_t* __restrict__ qpk, const bf16_t* __restrict__ subk, int* __restrict__ eidx, float* __restrict__ gout) {
;     ...
; #pragma unroll
;             for (int n = 0; n < 63; ++n) { cex(g0[SORT16[n][0]], g0[SORT16[n][1]]); cex(g1[SORT16[n][0]], g1[SORT16[n][1]]); cex(g2[SORT16[n][0]], g2[SORT16[n][1]]); cex(g3[SORT16[n][0]], g3[SORT16[n][1]]); }
;             merge_top16(g0, g1); merge_top16(g2, g3); merge_top16(g0, g2);
	v_min_u32_e32 v52, v52, v53
	v_max_u32_e32 v53, v66, v51
	v_min_u32_e32 v51, v66, v51
	v_max_u32_e32 v66, v35, v37
	v_min_u32_e32 v35, v35, v37
	v_max_u32_e32 v37, v19, v21
	v_min_u32_e32 v19, v19, v21
	v_max_u32_e32 v21, v3, v5
	v_min_u32_e32 v3, v3, v5
	v_max_u32_e32 v5, v34, v36
	v_min_u32_e32 v34, v34, v36
	v_max_u32_e32 v36, v18, v20
	v_min_u32_e32 v18, v18, v20
	v_max_u32_e32 v20, v2, v4
	v_min_u32_e32 v2, v2, v4
	v_max_u32_e32 v4, v50, v52
	v_min_u32_e32 v50, v50, v52
	v_max_u32_e32 v52, v5, v51
	v_min_u32_e32 v5, v5, v51
	v_max_u32_e32 v51, v36, v35
	v_min_u32_e32 v35, v36, v35
	v_max_u32_e32 v36, v20, v19
	v_min_u32_e32 v19, v20, v19
	v_max_u32_e32 v20, v4, v3
	v_min_u32_e32 v3, v4, v3
	v_max_u32_e32 v4, v38, v39
	v_min_u32_e32 v38, v38, v39
	v_max_u32_e32 v39, v22, v23
	v_min_u32_e32 v22, v22, v23
	v_max_u32_e32 v23, v6, v7
	v_min_u32_e32 v6, v6, v7
	v_max_u32_e32 v7, v54, v55
	v_min_u32_e32 v54, v54, v55
	v_max_u32_e32 v55, v40, v41
	v_min_u32_e32 v40, v40, v41
	v_max_u32_e32 v41, v24, v25
	v_min_u32_e32 v24, v24, v25
	v_max_u32_e32 v25, v8, v9
	v_min_u32_e32 v8, v8, v9
	v_max_u32_e32 v9, v56, v57
	v_min_u32_e32 v56, v56, v57
	v_max_u32_e32 v57, v4, v55
	v_min_u32_e32 v4, v4, v55
	v_max_u32_e32 v55, v39, v41
	v_min_u32_e32 v39, v39, v41
	v_max_u32_e32 v41, v23, v25
	v_min_u32_e32 v23, v23, v25
	v_max_u32_e32 v25, v7, v9
	v_min_u32_e32 v7, v7, v9
	v_max_u32_e32 v9, v38, v40
	v_min_u32_e32 v38, v38, v40
	v_max_u32_e32 v40, v22, v24
	v_min_u32_e32 v22, v22, v24
	v_max_u32_e32 v24, v6, v8
	v_min_u32_e32 v6, v6, v8
	v_max_u32_e32 v8, v54, v56
	v_min_u32_e32 v54, v54, v56
	v_max_u32_e32 v56, v9, v4
	v_min_u32_e32 v4, v9, v4
	v_max_u32_e32 v9, v40, v39
	v_min_u32_e32 v39, v40, v39
	v_max_u32_e32 v40, v24, v23
	v_min_u32_e32 v23, v24, v23
	v_max_u32_e32 v24, v8, v7
	v_min_u32_e32 v7, v8, v7
	v_max_u32_e32 v8, v53, v57
	v_min_u32_e32 v53, v53, v57
	v_max_u32_e32 v57, v66, v55
	v_min_u32_e32 v55, v66, v55
	v_max_u32_e32 v66, v37, v41
	v_min_u32_e32 v37, v37, v41
	v_max_u32_e32 v41, v21, v25
	v_min_u32_e32 v21, v21, v25
	v_max_u32_e32 v25, v5, v4
	v_min_u32_e32 v4, v5, v4
	v_max_u32_e32 v5, v35, v39
	v_min_u32_e32 v35, v35, v39
	v_max_u32_e32 v39, v19, v23
	v_min_u32_e32 v19, v19, v23
	v_max_u32_e32 v23, v3, v7
	v_min_u32_e32 v3, v3, v7
	v_max_u32_e32 v7, v25, v53
	v_min_u32_e32 v25, v25, v53
	v_max_u32_e32 v53, v5, v55
	v_min_u32_e32 v5, v5, v55
	v_max_u32_e32 v55, v39, v37
	v_min_u32_e32 v37, v39, v37
	v_max_u32_e32 v39, v23, v21
	v_min_u32_e32 v21, v23, v21
	v_max_u32_e32 v23, v52, v56
	v_min_u32_e32 v52, v52, v56
	v_max_u32_e32 v56, v51, v9
	v_min_u32_e32 v9, v51, v9
	v_max_u32_e32 v51, v36, v40
	v_min_u32_e32 v36, v36, v40
	v_max_u32_e32 v40, v20, v24
	v_min_u32_e32 v20, v20, v24
	v_max_u32_e32 v24, v34, v38
	v_min_u32_e32 v34, v34, v38
	v_max_u32_e32 v38, v18, v22
	v_min_u32_e32 v18, v18, v22
	v_max_u32_e32 v22, v2, v6
	v_min_u32_e32 v2, v2, v6
	v_max_u32_e32 v6, v50, v54
	v_min_u32_e32 v50, v50, v54
	v_max_u32_e32 v54, v24, v52
	v_min_u32_e32 v24, v24, v52
	v_max_u32_e32 v52, v38, v9
	v_min_u32_e32 v9, v38, v9
	v_max_u32_e32 v38, v22, v36
	v_min_u32_e32 v22, v22, v36
	v_max_u32_e32 v36, v6, v20
	v_min_u32_e32 v6, v6, v20
	v_max_u32_e32 v20, v23, v7
	v_min_u32_e32 v7, v23, v7
	v_max_u32_e32 v23, v56, v53
	v_min_u32_e32 v53, v56, v53
	v_max_u32_e32 v56, v51, v55
	v_min_u32_e32 v51, v51, v55
	v_max_u32_e32 v55, v40, v39
	v_min_u32_e32 v39, v40, v39
	v_max_u32_e32 v40, v54, v25
	v_min_u32_e32 v25, v54, v25
	v_max_u32_e32 v54, v52, v5
	v_min_u32_e32 v5, v52, v5
	v_max_u32_e32 v52, v38, v37
	v_min_u32_e32 v37, v38, v37
	v_max_u32_e32 v38, v36, v21
	v_min_u32_e32 v21, v36, v21
	v_max_u32_e32 v36, v24, v4
	v_min_u32_e32 v4, v24, v4
	v_max_u32_e32 v24, v9, v35
	v_min_u32_e32 v9, v9, v35
	v_max_u32_e32 v35, v22, v19
	v_min_u32_e32 v19, v22, v19
	v_max_u32_e32 v22, v6, v3
	v_min_u32_e32 v3, v6, v3
	v_max_u32_e32 v6, v42, v43
	v_min_u32_e32 v42, v42, v43
	v_max_u32_e32 v43, v26, v27
	v_min_u32_e32 v26, v26, v27
	v_max_u32_e32 v27, v10, v11
	v_min_u32_e32 v10, v10, v11
	v_max_u32_e32 v11, v58, v59
	v_min_u32_e32 v58, v58, v59
	v_max_u32_e32 v59, v44, v45
	v_min_u32_e32 v44, v44, v45
	v_max_u32_e32 v45, v28, v29
	v_min_u32_e32 v28, v28, v29
	v_max_u32_e32 v29, v12, v13
	v_min_u32_e32 v12, v12, v13
	v_max_u32_e32 v13, v60, v61
	v_min_u32_e32 v60, v60, v61
	v_and_or_b32 v65, v65, s42, v153
	v_max_u32_e32 v61, v6, v59
	v_min_u32_e32 v6, v6, v59
	v_max_u32_e32 v59, v43, v45
	v_min_u32_e32 v43, v43, v45
	v_max_u32_e32 v45, v27, v29
	v_min_u32_e32 v27, v27, v29
	v_max_u32_e32 v29, v11, v13
	v_min_u32_e32 v11, v11, v13
	v_max_u32_e32 v13, v42, v44
	v_min_u32_e32 v42, v42, v44
	v_max_u32_e32 v44, v26, v28
	v_min_u32_e32 v26, v26, v28
	v_max_u32_e32 v28, v10, v12
	v_min_u32_e32 v10, v10, v12
	v_max_u32_e32 v12, v58, v60
	v_min_u32_e32 v58, v58, v60
	v_max_u32_e32 v60, v13, v6
	v_min_u32_e32 v6, v13, v6
	v_max_u32_e32 v13, v44, v43
	v_min_u32_e32 v43, v44, v43
	v_max_u32_e32 v44, v28, v27
	v_min_u32_e32 v27, v28, v27
	v_max_u32_e32 v28, v12, v11
	v_min_u32_e32 v11, v12, v11
	v_max_u32_e32 v12, v46, v47
	v_min_u32_e32 v46, v46, v47
	v_max_u32_e32 v47, v30, v31
	v_min_u32_e32 v30, v30, v31
	v_max_u32_e32 v31, v14, v15
	v_min_u32_e32 v14, v14, v15
	v_max_u32_e32 v15, v62, v63
	v_min_u32_e32 v62, v62, v63
	v_max_u32_e32 v63, v48, v49
	v_min_u32_e32 v48, v48, v49
	v_max_u32_e32 v49, v32, v33
	v_min_u32_e32 v32, v32, v33
	v_max_u32_e32 v33, v16, v17
	v_min_u32_e32 v16, v16, v17
	v_max_u32_e32 v17, v64, v65
	v_min_u32_e32 v64, v64, v65
	v_max_u32_e32 v65, v12, v63
	v_min_u32_e32 v12, v12, v63
	v_max_u32_e32 v63, v47, v49
	v_min_u32_e32 v47, v47, v49
; DI void merge_top16(unsigned (&A)[16], const unsigned (&B)[16]) {
; #pragma unroll
;     for (int i = 0; i < 16; ++i) A[i] = max(A[i], B[15 - i]);
; #pragma unroll
;     for (int n = 0; n < 32; ++n) cex(A[BMERGE16[n][0]], A[BMERGE16[n][1]]);
; }
; DI void peer_topk_phase(const bf16_t* __restrict__ qpk, const bf16_t* __restrict__ subk, int* __restrict__ eidx, float* __restrict__ gout) {
;     ...
; #pragma unroll
;             for (int n = 0; n < 63; ++n) { cex(g0[SORT16[n][0]], g0[SORT16[n][1]]); cex(g1[SORT16[n][0]], g1[SORT16[n][1]]); cex(g2[SORT16[n][0]], g2[SORT16[n][1]]); cex(g3[SORT16[n][0]], g3[SORT16[n][1]]); }
;             merge_top16(g0, g1); merge_top16(g2, g3); merge_top16(g0, g2);
	v_max_u32_e32 v49, v31, v33
	v_min_u32_e32 v31, v31, v33
	v_max_u32_e32 v33, v15, v17
	v_min_u32_e32 v15, v15, v17
	v_max_u32_e32 v17, v46, v48
	v_min_u32_e32 v46, v46, v48
	v_max_u32_e32 v48, v30, v32
	v_min_u32_e32 v30, v30, v32
	v_max_u32_e32 v32, v14, v16
	v_min_u32_e32 v14, v14, v16
	v_max_u32_e32 v16, v62, v64
	v_min_u32_e32 v62, v62, v64
	v_max_u32_e32 v64, v17, v12
	v_min_u32_e32 v12, v17, v12
	v_max_u32_e32 v17, v48, v47
	v_min_u32_e32 v47, v48, v47
	v_max_u32_e32 v48, v32, v31
	v_min_u32_e32 v31, v32, v31
	v_max_u32_e32 v32, v16, v15
	v_min_u32_e32 v15, v16, v15
	v_max_u32_e32 v16, v61, v65
	v_min_u32_e32 v61, v61, v65
	v_max_u32_e32 v65, v59, v63
	v_min_u32_e32 v59, v59, v63
	v_max_u32_e32 v63, v45, v49
	v_min_u32_e32 v45, v45, v49
	v_max_u32_e32 v49, v29, v33
	v_min_u32_e32 v29, v29, v33
	v_max_u32_e32 v33, v6, v12
	v_min_u32_e32 v6, v6, v12
	v_max_u32_e32 v12, v43, v47
	v_min_u32_e32 v43, v43, v47
	v_max_u32_e32 v47, v27, v31
	v_min_u32_e32 v27, v27, v31
	v_max_u32_e32 v31, v11, v15
	v_min_u32_e32 v11, v11, v15
	v_max_u32_e32 v15, v33, v61
	v_min_u32_e32 v33, v33, v61
	v_max_u32_e32 v61, v12, v59
	v_min_u32_e32 v12, v12, v59
	v_max_u32_e32 v59, v47, v45
	v_min_u32_e32 v45, v47, v45
	v_max_u32_e32 v47, v31, v29
	v_min_u32_e32 v29, v31, v29
	v_max_u32_e32 v31, v60, v64
	v_min_u32_e32 v60, v60, v64
	v_max_u32_e32 v64, v13, v17
	v_min_u32_e32 v13, v13, v17
	v_max_u32_e32 v17, v44, v48
	v_min_u32_e32 v44, v44, v48
	v_max_u32_e32 v48, v28, v32
	v_min_u32_e32 v28, v28, v32
	v_max_u32_e32 v32, v42, v46
	v_min_u32_e32 v42, v42, v46
	v_max_u32_e32 v46, v26, v30
	v_min_u32_e32 v26, v26, v30
	v_max_u32_e32 v30, v10, v14
	v_min_u32_e32 v10, v10, v14
	v_max_u32_e32 v14, v58, v62
	v_min_u32_e32 v58, v58, v62
	v_max_u32_e32 v62, v32, v60
	v_min_u32_e32 v32, v32, v60
	v_max_u32_e32 v60, v46, v13
	v_min_u32_e32 v13, v46, v13
	v_max_u32_e32 v46, v30, v44
	v_min_u32_e32 v30, v30, v44
	v_max_u32_e32 v44, v14, v28
	v_min_u32_e32 v14, v14, v28
	v_max_u32_e32 v28, v31, v15
	v_min_u32_e32 v15, v31, v15
	v_max_u32_e32 v31, v64, v61
	v_min_u32_e32 v61, v64, v61
	v_max_u32_e32 v64, v17, v59
	v_min_u32_e32 v17, v17, v59
	v_max_u32_e32 v59, v48, v47
	v_min_u32_e32 v47, v48, v47
	v_max_u32_e32 v48, v62, v33
	v_min_u32_e32 v33, v62, v33
	v_max_u32_e32 v62, v60, v12
	v_min_u32_e32 v12, v60, v12
	v_max_u32_e32 v60, v46, v45
	v_min_u32_e32 v45, v46, v45
	v_max_u32_e32 v46, v44, v29
	v_min_u32_e32 v29, v44, v29
	v_max_u32_e32 v44, v32, v6
	v_min_u32_e32 v6, v32, v6
	v_max_u32_e32 v32, v13, v43
	v_min_u32_e32 v13, v13, v43
	v_max_u32_e32 v43, v30, v27
	v_min_u32_e32 v27, v30, v27
	v_max_u32_e32 v30, v14, v11
	v_min_u32_e32 v11, v14, v11
	v_min_u32_e32 v14, v8, v16
	v_min_u32_e32 v67, v57, v65
	v_min_u32_e32 v68, v66, v63
	v_min_u32_e32 v69, v41, v49
	v_max_u32_e32 v70, v25, v33
	v_min_u32_e32 v25, v25, v33
	v_max_u32_e32 v33, v5, v12
	v_min_u32_e32 v5, v5, v12
	v_max_u32_e32 v12, v37, v45
	v_min_u32_e32 v37, v37, v45
	v_max_u32_e32 v45, v21, v29
	v_min_u32_e32 v21, v21, v29
	v_max_u32_e32 v29, v70, v14
	v_min_u32_e32 v14, v70, v14
	v_max_u32_e32 v70, v33, v67
	v_min_u32_e32 v33, v33, v67
	v_max_u32_e32 v67, v12, v68
	v_min_u32_e32 v12, v12, v68
	v_max_u32_e32 v68, v45, v69
	v_min_u32_e32 v45, v45, v69
	v_max_u32_e32 v69, v7, v15
	v_min_u32_e32 v7, v7, v15
	v_max_u32_e32 v15, v53, v61
	v_min_u32_e32 v53, v53, v61
	v_max_u32_e32 v61, v51, v17
	v_min_u32_e32 v17, v51, v17
	v_max_u32_e32 v51, v39, v47
	v_min_u32_e32 v39, v39, v47
	v_max_u32_e32 v47, v4, v6
	v_min_u32_e32 v4, v4, v6
	v_max_u32_e32 v6, v9, v13
	v_min_u32_e32 v9, v9, v13
	v_max_u32_e32 v13, v19, v27
	v_min_u32_e32 v19, v19, v27
	v_max_u32_e32 v27, v3, v11
	v_min_u32_e32 v3, v3, v11
	v_max_u32_e32 v11, v47, v7
	v_min_u32_e32 v7, v47, v7
	v_max_u32_e32 v47, v6, v53
	v_min_u32_e32 v6, v6, v53
	v_max_u32_e32 v53, v13, v17
	v_min_u32_e32 v13, v13, v17
	v_max_u32_e32 v17, v27, v39
	v_min_u32_e32 v27, v27, v39
	v_max_u32_e32 v39, v69, v29
	v_min_u32_e32 v29, v69, v29
	v_max_u32_e32 v69, v15, v70
	v_min_u32_e32 v15, v15, v70
	v_max_u32_e32 v70, v61, v67
	v_min_u32_e32 v61, v61, v67
	v_max_u32_e32 v67, v51, v68
	v_min_u32_e32 v51, v51, v68
	v_max_u32_e32 v68, v11, v14
	v_min_u32_e32 v11, v11, v14
	v_max_u32_e32 v14, v47, v33
	v_min_u32_e32 v33, v47, v33
	v_max_u32_e32 v47, v53, v12
	v_min_u32_e32 v12, v53, v12
	v_max_u32_e32 v53, v17, v45
	v_min_u32_e32 v17, v17, v45
	v_max_u32_e32 v45, v7, v25
	v_min_u32_e32 v7, v7, v25
	v_max_u32_e32 v25, v6, v5
	v_min_u32_e32 v5, v6, v5
	v_max_u32_e32 v6, v13, v37
	v_min_u32_e32 v13, v13, v37
	v_max_u32_e32 v37, v27, v21
	v_min_u32_e32 v21, v27, v21
	v_max_u32_e32 v27, v20, v28
	v_min_u32_e32 v20, v20, v28
	v_max_u32_e32 v28, v23, v31
	v_min_u32_e32 v23, v23, v31
	v_max_u32_e32 v31, v56, v64
	v_min_u32_e32 v56, v56, v64
	v_max_u32_e32 v64, v55, v59
	v_min_u32_e32 v55, v55, v59
	v_max_u32_e32 v59, v36, v44
	v_min_u32_e32 v36, v36, v44
	v_max_u32_e32 v44, v24, v32
	v_min_u32_e32 v24, v24, v32
	v_max_u32_e32 v32, v35, v43
	v_min_u32_e32 v35, v35, v43
	v_max_u32_e32 v43, v22, v30
	v_min_u32_e32 v22, v22, v30
	v_max_u32_e32 v30, v59, v20
	v_min_u32_e32 v20, v59, v20
	v_max_u32_e32 v59, v44, v23
	v_min_u32_e32 v23, v44, v23
	v_max_u32_e32 v44, v32, v56
	v_min_u32_e32 v32, v32, v56
	v_max_u32_e32 v56, v43, v55
	v_min_u32_e32 v43, v43, v55
	v_max_u32_e32 v55, v40, v48
	v_min_u32_e32 v40, v40, v48
	v_max_u32_e32 v48, v54, v62
	v_min_u32_e32 v54, v54, v62
	v_max_u32_e32 v62, v52, v60
	v_min_u32_e32 v52, v52, v60
	v_max_u32_e32 v60, v38, v46
	v_min_u32_e32 v38, v38, v46
	v_max_u32_e32 v46, v34, v42
	v_min_u32_e32 v34, v34, v42
	v_max_u32_e32 v42, v18, v26
	v_min_u32_e32 v18, v18, v26
; DI void merge_top16(unsigned (&A)[16], const unsigned (&B)[16]) {
; #pragma unroll
;     for (int i = 0; i < 16; ++i) A[i] = max(A[i], B[15 - i]);
; #pragma unroll
;     for (int n = 0; n < 32; ++n) cex(A[BMERGE16[n][0]], A[BMERGE16[n][1]]);
; }
; DI void peer_topk_phase(const bf16_t* __restrict__ qpk, const bf16_t* __restrict__ subk, int* __restrict__ eidx, float* __restrict__ gout) {
;     ...
;             merge_top16(g0, g1); merge_top16(g2, g3); merge_top16(g0, g2);
	v_max_u32_e32 v26, v2, v10
	v_min_u32_e32 v2, v2, v10
	v_max_u32_e32 v10, v50, v58
	v_min_u32_e32 v50, v50, v58
	v_max_u32_e32 v58, v46, v40
	v_min_u32_e32 v40, v46, v40
	v_max_u32_e32 v46, v42, v54
	v_min_u32_e32 v42, v42, v54
	v_max_u32_e32 v54, v26, v52
	v_min_u32_e32 v26, v26, v52
	v_max_u32_e32 v52, v10, v38
	v_min_u32_e32 v10, v10, v38
	v_max_u32_e32 v38, v55, v30
	v_min_u32_e32 v30, v55, v30
	v_max_u32_e32 v55, v48, v59
	v_min_u32_e32 v48, v48, v59
	v_max_u32_e32 v59, v62, v44
	v_min_u32_e32 v44, v62, v44
	v_max_u32_e32 v62, v60, v56
	v_min_u32_e32 v56, v60, v56
	v_max_u32_e32 v60, v58, v20
	v_min_u32_e32 v20, v58, v20
	v_max_u32_e32 v58, v46, v23
	v_min_u32_e32 v23, v46, v23
	v_max_u32_e32 v46, v54, v32
	v_min_u32_e32 v32, v54, v32
	v_max_u32_e32 v54, v52, v43
	v_min_u32_e32 v43, v52, v43
	v_max_u32_e32 v52, v40, v36
	v_min_u32_e32 v36, v40, v36
	v_max_u32_e32 v40, v42, v24
	v_min_u32_e32 v24, v42, v24
	v_max_u32_e32 v42, v26, v35
	v_min_u32_e32 v26, v26, v35
	v_max_u32_e32 v35, v10, v22
	v_min_u32_e32 v10, v10, v22
	v_min_u32_e32 v22, v27, v39
	v_min_u32_e32 v71, v28, v69
	v_min_u32_e32 v72, v31, v70
	v_min_u32_e32 v73, v64, v67
	v_min_u32_e32 v82, v38, v29
	v_min_u32_e32 v83, v55, v15
	v_min_u32_e32 v183, v59, v61
	v_min_u32_e32 v184, v62, v51
	v_min_u32_e32 v185, v30, v68
	v_min_u32_e32 v186, v48, v14
	v_min_u32_e32 v187, v44, v47
	v_min_u32_e32 v188, v56, v53
	v_min_u32_e32 v189, v60, v11
	v_min_u32_e32 v190, v58, v33
	v_min_u32_e32 v191, v46, v12
	v_min_u32_e32 v198, v54, v17
	v_min_u32_e32 v199, v20, v45
	v_min_u32_e32 v200, v23, v25
	v_min_u32_e32 v201, v32, v6
	v_min_u32_e32 v202, v43, v37
	v_min_u32_e32 v203, v52, v7
	v_min_u32_e32 v210, v40, v5
	v_min_u32_e32 v211, v42, v13
	v_min_u32_e32 v212, v35, v21
	v_min_u32_e32 v213, v36, v4
	v_min_u32_e32 v214, v24, v9
	v_min_u32_e32 v215, v26, v19
	v_min_u32_e32 v216, v10, v3
	v_max3_u32 v8, v8, v16, v18
	v_max3_u32 v16, v27, v39, v214
	v_max3_u32 v9, v22, v24, v9
	v_max3_u32 v18, v38, v29, v210
	v_max3_u32 v5, v82, v40, v5
	v_max3_u32 v22, v30, v68, v200
	v_max3_u32 v23, v185, v23, v25
	v_max3_u32 v11, v60, v11, v190
	v_max3_u32 v24, v189, v58, v33
	v_max3_u32 v20, v20, v45, v186
	v_max3_u32 v14, v199, v48, v14
	v_max3_u32 v7, v52, v7, v83
	v_max3_u32 v15, v203, v55, v15
	v_max3_u32 v4, v36, v4, v71
	v_max3_u32 v25, v213, v28, v69
	v_max3_u32 v27, v34, v57, v65
	v_max3_u32 v40, v66, v63, v50
	v_max3_u32 v31, v31, v70, v216
	v_max3_u32 v3, v72, v10, v3
	v_max3_u32 v10, v59, v61, v212
	v_max3_u32 v21, v183, v35, v21
	v_max3_u32 v35, v44, v47, v202
	v_max3_u32 v37, v187, v43, v37
	v_max3_u32 v12, v46, v12, v198
	v_max3_u32 v17, v191, v54, v17
	v_max3_u32 v6, v32, v6, v188
	v_max3_u32 v32, v201, v56, v53
	v_max3_u32 v13, v42, v13, v184
	v_max3_u32 v42, v211, v62, v51
	v_max3_u32 v19, v26, v19, v73
	v_max3_u32 v26, v215, v64, v67
	v_max3_u32 v2, v2, v41, v49
	v_max_u32_e32 v28, v8, v24
	v_min_u32_e32 v8, v8, v24
	v_max_u32_e32 v24, v16, v20
	v_min_u32_e32 v16, v16, v20
	v_max_u32_e32 v20, v9, v14
	v_min_u32_e32 v9, v9, v14
	v_max_u32_e32 v14, v18, v7
	v_min_u32_e32 v7, v18, v7
	v_max_u32_e32 v18, v5, v15
	v_min_u32_e32 v5, v5, v15
	v_max_u32_e32 v15, v22, v4
	v_min_u32_e32 v4, v22, v4
	v_max_u32_e32 v22, v23, v25
	v_min_u32_e32 v23, v23, v25
	v_max_u32_e32 v25, v11, v27
	v_min_u32_e32 v11, v11, v27
	v_max_u32_e32 v41, v40, v17
	v_min_u32_e32 v17, v40, v17
	v_max_u32_e32 v40, v31, v6
	v_min_u32_e32 v6, v31, v6
	v_max_u32_e32 v31, v3, v32
	v_min_u32_e32 v3, v3, v32
	v_max_u32_e32 v32, v10, v13
	v_min_u32_e32 v10, v10, v13
	v_max_u32_e32 v13, v21, v42
	v_min_u32_e32 v21, v21, v42
	v_max_u32_e32 v42, v35, v19
	v_min_u32_e32 v19, v35, v19
	v_max_u32_e32 v35, v37, v26
	v_min_u32_e32 v26, v37, v26
	v_max_u32_e32 v37, v12, v2
	v_min_u32_e32 v2, v12, v2
	v_max_u32_e32 v27, v28, v18
	v_min_u32_e32 v18, v28, v18
	v_max_u32_e32 v28, v24, v15
	v_min_u32_e32 v15, v24, v15
	v_max_u32_e32 v24, v20, v22
	v_min_u32_e32 v20, v20, v22
	v_max_u32_e32 v22, v14, v25
	v_min_u32_e32 v14, v14, v25
	v_max_u32_e32 v25, v8, v5
	v_min_u32_e32 v5, v8, v5
	v_max_u32_e32 v8, v16, v4
	v_min_u32_e32 v4, v16, v4
	v_max_u32_e32 v16, v9, v23
	v_min_u32_e32 v9, v9, v23
	v_max_u32_e32 v23, v7, v11
	v_min_u32_e32 v7, v7, v11
	v_max_u32_e32 v12, v41, v13
	v_min_u32_e32 v13, v41, v13
	v_max_u32_e32 v41, v40, v42
	v_min_u32_e32 v40, v40, v42
	v_max_u32_e32 v42, v31, v35
	v_min_u32_e32 v31, v31, v35
	v_max_u32_e32 v35, v32, v37
	v_min_u32_e32 v32, v32, v37
	v_max_u32_e32 v37, v17, v21
	v_min_u32_e32 v17, v17, v21
	v_max_u32_e32 v21, v6, v19
	v_min_u32_e32 v6, v6, v19
	v_max_u32_e32 v19, v3, v26
	v_min_u32_e32 v3, v3, v26
	v_max_u32_e32 v26, v10, v2
	v_min_u32_e32 v2, v10, v2
	v_max_u32_e32 v11, v27, v24
	v_min_u32_e32 v24, v27, v24
	v_max_u32_e32 v27, v28, v22
	v_min_u32_e32 v22, v28, v22
	v_max_u32_e32 v28, v18, v20
	v_min_u32_e32 v18, v18, v20
	v_max_u32_e32 v20, v15, v14
	v_min_u32_e32 v14, v15, v14
	v_max_u32_e32 v15, v25, v16
	v_min_u32_e32 v16, v25, v16
	v_max_u32_e32 v25, v8, v23
	v_min_u32_e32 v8, v8, v23
	v_max_u32_e32 v23, v5, v9
	v_min_u32_e32 v5, v5, v9
	v_max_u32_e32 v9, v4, v7
	v_min_u32_e32 v4, v4, v7
	v_max_u32_e32 v10, v12, v42
	v_min_u32_e32 v12, v12, v42
	v_max_u32_e32 v42, v41, v35
	v_min_u32_e32 v35, v41, v35
	v_max_u32_e32 v41, v13, v31
	v_min_u32_e32 v13, v13, v31
	v_max_u32_e32 v31, v40, v32
	v_min_u32_e32 v32, v40, v32
	v_max_u32_e32 v40, v37, v19
	v_min_u32_e32 v19, v37, v19
	v_max_u32_e32 v37, v21, v26
	v_min_u32_e32 v21, v21, v26
	v_max_u32_e32 v26, v17, v3
	v_min_u32_e32 v3, v17, v3
	v_max_u32_e32 v17, v6, v2
	v_min_u32_e32 v2, v6, v2
	v_min_u32_e32 v7, v11, v27
	v_min_u32_e32 v29, v24, v22
; DI float ord2f(unsigned o) { const unsigned u = (o & 0x80000000u) ? (o & 0x7fffffffu) : ~o; return __uint_as_float(u); }
; DI void merge_top16(unsigned (&A)[16], const unsigned (&B)[16]) {
; #pragma unroll
;     for (int i = 0; i < 16; ++i) A[i] = max(A[i], B[15 - i]);
; #pragma unroll
;     for (int n = 0; n < 32; ++n) cex(A[BMERGE16[n][0]], A[BMERGE16[n][1]]);
; }
; DI void peer_topk_phase(const bf16_t* __restrict__ qpk, const bf16_t* __restrict__ subk, int* __restrict__ eidx, float* __restrict__ gout) {
;     ...
;             merge_top16(g0, g1); merge_top16(g2, g3); merge_top16(g0, g2);
;             unsigned pb[16];
; #pragma unroll
;             for (int i = 0; i < 16; ++i) pb[i] = (unsigned)__shfl_xor((int)g0[i], 32);
;             merge_top16(g0, pb);
; #pragma unroll
;             for (int i = 0; i < 16; ++i) top[c][i] = g0[i];
;         }
;         unsigned ck[50];
; #pragma unroll
;         for (int a = 0; a < 16; ++a)
; #pragma unroll
;             for (int b = 0; b < 16 / (a + 1); ++b) {
;                 const float cv = ord2f(top[0][a] & ~127u) + ord2f(top[1][b] & ~127u);
	v_min_u32_e32 v30, v28, v20
	v_min_u32_e32 v33, v18, v14
	v_min_u32_e32 v34, v15, v25
	v_min_u32_e32 v36, v16, v8
	v_min_u32_e32 v38, v23, v9
	v_min_u32_e32 v39, v5, v4
	v_min_u32_e32 v6, v10, v42
	v_min_u32_e32 v43, v12, v35
	v_min_u32_e32 v44, v41, v31
	v_min_u32_e32 v45, v13, v32
	v_min_u32_e32 v46, v40, v37
	v_min_u32_e32 v47, v19, v21
	v_min_u32_e32 v48, v26, v17
	v_min_u32_e32 v49, v3, v2
	v_max3_u32 v11, v11, v27, v49
	v_max3_u32 v2, v7, v3, v2
	v_max3_u32 v3, v24, v22, v48
	v_max3_u32 v7, v29, v26, v17
	v_max3_u32 v17, v28, v20, v47
	v_max3_u32 v19, v30, v19, v21
	v_max3_u32 v14, v18, v14, v46
	v_max3_u32 v18, v33, v40, v37
	v_max3_u32 v15, v15, v25, v45
	v_max3_u32 v13, v34, v13, v32
	v_max3_u32 v8, v16, v8, v44
	v_max3_u32 v16, v36, v41, v31
	v_max3_u32 v9, v23, v9, v43
	v_max3_u32 v12, v38, v12, v35
	v_max3_u32 v4, v5, v4, v6
	v_max3_u32 v5, v39, v10, v42
	v_max_u32_e32 v6, v11, v15
	v_min_u32_e32 v10, v11, v15
	v_max_u32_e32 v11, v2, v13
	v_min_u32_e32 v2, v2, v13
	v_max_u32_e32 v13, v3, v8
	v_min_u32_e32 v3, v3, v8
	v_max_u32_e32 v8, v7, v16
	v_min_u32_e32 v7, v7, v16
	v_max_u32_e32 v15, v17, v9
	v_min_u32_e32 v9, v17, v9
	v_max_u32_e32 v16, v19, v12
	v_min_u32_e32 v12, v19, v12
	v_max_u32_e32 v17, v14, v4
	v_min_u32_e32 v4, v14, v4
	v_max_u32_e32 v14, v18, v5
	v_min_u32_e32 v5, v18, v5
	v_max_u32_e32 v18, v6, v15
	v_min_u32_e32 v6, v6, v15
	v_max_u32_e32 v15, v11, v16
	v_min_u32_e32 v11, v11, v16
	v_max_u32_e32 v16, v13, v17
	v_min_u32_e32 v13, v13, v17
	v_max_u32_e32 v17, v8, v14
	v_min_u32_e32 v8, v8, v14
	v_max_u32_e32 v14, v10, v9
	v_min_u32_e32 v9, v10, v9
	v_max_u32_e32 v10, v2, v12
	v_min_u32_e32 v2, v2, v12
	v_max_u32_e32 v12, v3, v4
	v_min_u32_e32 v3, v3, v4
	v_max_u32_e32 v4, v7, v5
	v_min_u32_e32 v5, v7, v5
	v_max_u32_e32 v7, v18, v16
	v_min_u32_e32 v16, v18, v16
	v_max_u32_e32 v18, v15, v17
	v_min_u32_e32 v15, v15, v17
	v_max_u32_e32 v17, v6, v13
	v_min_u32_e32 v6, v6, v13
	v_max_u32_e32 v13, v11, v8
	v_min_u32_e32 v8, v11, v8
	v_max_u32_e32 v11, v14, v12
	v_min_u32_e32 v12, v14, v12
	v_max_u32_e32 v14, v10, v4
	v_min_u32_e32 v4, v10, v4
	v_max_u32_e32 v10, v9, v3
	v_min_u32_e32 v3, v9, v3
	v_max_u32_e32 v9, v2, v5
	v_min_u32_e32 v2, v2, v5
	v_max_u32_e32 v5, v7, v18
	v_min_u32_e32 v7, v7, v18
	v_max_u32_e32 v18, v16, v15
	v_min_u32_e32 v15, v16, v15
	v_max_u32_e32 v16, v17, v13
	v_min_u32_e32 v13, v17, v13
	v_max_u32_e32 v17, v6, v8
	v_min_u32_e32 v6, v6, v8
	v_max_u32_e32 v8, v11, v14
	v_min_u32_e32 v11, v11, v14
	v_max_u32_e32 v14, v12, v4
	v_min_u32_e32 v4, v12, v4
	v_max_u32_e32 v12, v10, v9
	v_min_u32_e32 v9, v10, v9
	v_max_u32_e32 v10, v3, v2
	v_min_u32_e32 v2, v3, v2
	ds_bpermute_b32 v3, v173, v5
	ds_bpermute_b32 v19, v173, v7
	ds_bpermute_b32 v20, v173, v18
	ds_bpermute_b32 v21, v173, v15
	ds_bpermute_b32 v22, v173, v16
	ds_bpermute_b32 v23, v173, v13
	ds_bpermute_b32 v24, v173, v17
	ds_bpermute_b32 v25, v173, v6
	ds_bpermute_b32 v26, v173, v8
	ds_bpermute_b32 v27, v173, v11
	ds_bpermute_b32 v28, v173, v14
	ds_bpermute_b32 v29, v173, v4
	ds_bpermute_b32 v30, v173, v12
	ds_bpermute_b32 v31, v173, v9
	ds_bpermute_b32 v32, v173, v10
	ds_bpermute_b32 v33, v173, v2
	s_waitcnt lgkmcnt(4)
	v_max_u32_e32 v16, v16, v29
	s_waitcnt lgkmcnt(3)
	v_max_u32_e32 v15, v15, v30
	s_waitcnt lgkmcnt(2)
	v_max_u32_e32 v18, v18, v31
	s_waitcnt lgkmcnt(1)
	v_max_u32_e32 v7, v7, v32
	s_waitcnt lgkmcnt(0)
	v_max_u32_e32 v5, v5, v33
	v_max_u32_e32 v13, v13, v28
	v_max_u32_e32 v17, v17, v27
	v_max_u32_e32 v6, v6, v26
	v_max_u32_e32 v8, v8, v25
	v_max_u32_e32 v11, v11, v24
	v_max_u32_e32 v14, v14, v23
	v_max_u32_e32 v4, v4, v22
	v_max_u32_e32 v12, v12, v21
	v_max_u32_e32 v9, v9, v20
	v_max_u32_e32 v10, v10, v19
	v_max_u32_e32 v2, v2, v3
	v_max_u32_e32 v3, v5, v8
	v_min_u32_e32 v5, v5, v8
	v_max_u32_e32 v8, v7, v11
	v_min_u32_e32 v7, v7, v11
	v_max_u32_e32 v11, v18, v14
	v_min_u32_e32 v14, v18, v14
	v_max_u32_e32 v18, v15, v4
	v_min_u32_e32 v4, v15, v4
	v_max_u32_e32 v15, v16, v12
	v_min_u32_e32 v12, v16, v12
	v_max_u32_e32 v16, v13, v9
	v_min_u32_e32 v9, v13, v9
	v_max_u32_e32 v13, v17, v10
	v_min_u32_e32 v10, v17, v10
	v_max_u32_e32 v17, v6, v2
	v_min_u32_e32 v2, v6, v2
	v_max_u32_e32 v6, v3, v15
	v_min_u32_e32 v3, v3, v15
	v_max_u32_e32 v15, v8, v16
	v_min_u32_e32 v8, v8, v16
	v_max_u32_e32 v16, v11, v13
	v_min_u32_e32 v11, v11, v13
	v_max_u32_e32 v13, v18, v17
	v_min_u32_e32 v17, v18, v17
	v_max_u32_e32 v18, v5, v12
	v_min_u32_e32 v5, v5, v12
	v_max_u32_e32 v12, v7, v9
	v_min_u32_e32 v7, v7, v9
	v_max_u32_e32 v9, v14, v10
	v_min_u32_e32 v10, v14, v10
	v_max_u32_e32 v14, v4, v2
	v_min_u32_e32 v2, v4, v2
	v_max_u32_e32 v4, v6, v16
	v_min_u32_e32 v6, v6, v16
	v_max_u32_e32 v16, v15, v13
	v_min_u32_e32 v13, v15, v13
	v_max_u32_e32 v15, v3, v11
	v_min_u32_e32 v3, v3, v11
	v_max_u32_e32 v11, v8, v17
	v_min_u32_e32 v8, v8, v17
	v_max_u32_e32 v23, v18, v9
	v_min_u32_e32 v9, v18, v9
	v_max_u32_e32 v18, v15, v11
	v_min_u32_e32 v17, v15, v11
	v_max_u32_e32 v24, v12, v14
	v_min_u32_e32 v25, v12, v14
	v_max_u32_e32 v26, v5, v10
	v_min_u32_e32 v27, v5, v10
	v_max_u32_e32 v5, v7, v2
	v_min_u32_e32 v2, v7, v2
	v_max_u32_e32 v21, v6, v13
	v_min_u32_e32 v19, v6, v13
	v_and_b32_e32 v6, 0xffffff80, v18
	v_and_b32_e32 v7, 0xffffff80, v17
	v_max_u32_e32 v20, v4, v16
	v_min_u32_e32 v22, v4, v16
	v_max_u32_e32 v16, v3, v8
	v_min_u32_e32 v15, v3, v8
	v_max_u32_e32 v14, v23, v24
	v_min_u32_e32 v13, v23, v24
	v_max_u32_e32 v12, v9, v25
	v_min_u32_e32 v11, v9, v25
	v_max_u32_e32 v10, v26, v5
	v_min_u32_e32 v9, v26, v5
	v_max_u32_e32 v5, v27, v2
	v_min_u32_e32 v3, v27, v2
	v_cmp_gt_i32_e32 vcc, 0, v17
	v_cmp_gt_i32_e64 s[0:1], 0, v18
	v_and_b32_e32 v2, 0x7fffff80, v18
; DI unsigned f2ord(float f) { const unsigned u = __float_as_uint(f); return (u & 0x80000000u) ? ~u : (u | 0x80000000u); }
; DI float ord2f(unsigned o) { const unsigned u = (o & 0x80000000u) ? (o & 0x7fffffffu) : ~o; return __uint_as_float(u); }
; DI void peer_topk_phase(const bf16_t* __restrict__ qpk, const bf16_t* __restrict__ subk, int* __restrict__ eidx, float* __restrict__ gout) {
;     ...
; #pragma unroll
;         for (int a = 0; a < 16; ++a)
; #pragma unroll
;             for (int b = 0; b < 16 / (a + 1); ++b) {
;                 const float cv = ord2f(top[0][a] & ~127u) + ord2f(top[1][b] & ~127u);
;                 ck[combo_row_start(a) + b] = (f2ord(cv) & ~255u) | (unsigned)(((15 - a) << 4) | (15 - b));
;             }
	v_and_b32_e32 v4, 0x7fffff80, v17
	v_xor_b32_e32 v6, -1, v6
	v_xor_b32_e32 v8, -1, v7
	v_cndmask_b32_e64 v7, v6, v2, s[0:1]
	v_cndmask_b32_e32 v6, v8, v4, vcc
	v_cmp_gt_i32_e32 vcc, 0, v15
	v_and_b32_e32 v2, 0x7fffff80, v15
	v_bitop3_b32 v4, v15, s5, v15 bitop3:0xcf
	v_and_b32_e32 v8, 0xffffff80, v14
	v_and_b32_e32 v23, 0xffffff80, v13
	v_cndmask_b32_e32 v36, v4, v2, vcc
	v_cmp_gt_i32_e32 vcc, 0, v13
	v_cmp_gt_i32_e64 s[0:1], 0, v14
	v_and_b32_e32 v2, 0x7fffff80, v14
	v_and_b32_e32 v4, 0x7fffff80, v13
	v_xor_b32_e32 v8, -1, v8
	v_xor_b32_e32 v23, -1, v23
	v_cndmask_b32_e64 v27, v8, v2, s[0:1]
	v_cndmask_b32_e32 v26, v23, v4, vcc
	v_and_b32_e32 v8, 0xffffff80, v12
	v_and_b32_e32 v23, 0xffffff80, v11
	v_cmp_gt_i32_e32 vcc, 0, v11
	v_cmp_gt_i32_e64 s[0:1], 0, v12
	v_and_b32_e32 v2, 0x7fffff80, v12
	v_and_b32_e32 v4, 0x7fffff80, v11
	v_xor_b32_e32 v8, -1, v8
	v_xor_b32_e32 v23, -1, v23
	v_cndmask_b32_e64 v29, v8, v2, s[0:1]
	v_cndmask_b32_e32 v28, v23, v4, vcc
	v_and_b32_e32 v8, 0xffffff80, v10
	v_and_b32_e32 v23, 0xffffff80, v9
	v_cmp_gt_i32_e32 vcc, 0, v9
	v_cmp_gt_i32_e64 s[0:1], 0, v10
	v_and_b32_e32 v2, 0x7fffff80, v10
	v_and_b32_e32 v4, 0x7fffff80, v9
	v_xor_b32_e32 v8, -1, v8
	v_xor_b32_e32 v23, -1, v23
	v_cndmask_b32_e64 v31, v8, v2, s[0:1]
	v_cndmask_b32_e32 v30, v23, v4, vcc
	v_cmp_gt_i32_e32 vcc, 0, v5
	v_and_b32_e32 v2, 0x7fffff80, v5
	v_bitop3_b32 v4, v5, s5, v5 bitop3:0xcf
	v_and_b32_e32 v8, 0xffffff80, v3
	v_and_b32_e32 v23, 0xffffff80, v168
	v_cndmask_b32_e32 v33, v4, v2, vcc
	v_cmp_gt_i32_e32 vcc, 0, v168
	v_cmp_gt_i32_e64 s[0:1], 0, v3
	v_and_b32_e32 v2, 0x7fffff80, v3
	v_and_b32_e32 v4, 0x7fffff80, v168
	v_xor_b32_e32 v8, -1, v8
	v_xor_b32_e32 v23, -1, v23
	v_cndmask_b32_e64 v32, v8, v2, s[0:1]
	v_cndmask_b32_e32 v2, v23, v4, vcc
	v_pk_add_f32 v[24:25], v[2:3], v[6:7] op_sel_hi:[0,1]
	v_not_b32_e32 v4, v25
	v_or_b32_e32 v8, 0x80000000, v25
	v_cmp_gt_i32_e64 s[0:1], 0, v25
	v_cmp_gt_i32_e32 vcc, 0, v24
	v_pk_add_f32 v[34:35], v[2:3], v[26:27] op_sel_hi:[0,1]
	v_cndmask_b32_e64 v4, v8, v4, s[0:1]
	v_and_b32_e32 v4, 0xffffff00, v4
	v_or_b32_e32 v23, 0xfb, v4
	v_not_b32_e32 v4, v24
	v_or_b32_e32 v8, 0x80000000, v24
	v_cndmask_b32_e32 v4, v8, v4, vcc
	v_and_b32_e32 v4, 0xffffff00, v4
	v_or_b32_e32 v24, 0xfa, v4
	v_add_f32_e32 v4, v2, v36
	v_cmp_gt_i32_e32 vcc, 0, v4
	v_not_b32_e32 v8, v4
	v_or_b32_e32 v4, 0x80000000, v4
	v_cndmask_b32_e32 v4, v4, v8, vcc
	v_and_b32_e32 v4, 0xffffff00, v4
	v_or_b32_e32 v25, 0xf8, v4
	v_not_b32_e32 v4, v35
	v_or_b32_e32 v8, 0x80000000, v35
	v_cmp_gt_i32_e64 s[0:1], 0, v35
	v_cmp_gt_i32_e32 vcc, 0, v34
	v_and_b32_e32 v43, 0x7fffff80, v159
	v_cndmask_b32_e64 v4, v8, v4, s[0:1]
	v_and_b32_e32 v4, 0xffffff00, v4
	v_or_b32_e32 v26, 0xf7, v4
	v_not_b32_e32 v4, v34
	v_or_b32_e32 v8, 0x80000000, v34
	v_cndmask_b32_e32 v4, v8, v4, vcc
	v_and_b32_e32 v4, 0xffffff00, v4
	v_pk_add_f32 v[34:35], v[2:3], v[28:29] op_sel_hi:[0,1]
	v_or_b32_e32 v27, 0xf6, v4
	v_not_b32_e32 v4, v35
	v_or_b32_e32 v8, 0x80000000, v35
	v_cmp_gt_i32_e64 s[0:1], 0, v35
	v_cmp_gt_i32_e32 vcc, 0, v34
	v_and_b32_e32 v45, 0x7fffff80, v157
	v_cndmask_b32_e64 v4, v8, v4, s[0:1]
	v_and_b32_e32 v4, 0xffffff00, v4
	v_or_b32_e32 v28, 0xf5, v4
	v_not_b32_e32 v4, v34
	v_or_b32_e32 v8, 0x80000000, v34
	v_cndmask_b32_e32 v4, v8, v4, vcc
	v_and_b32_e32 v4, 0xffffff00, v4
	v_pk_add_f32 v[34:35], v[2:3], v[30:31] op_sel_hi:[0,1]
	v_or_b32_e32 v29, 0xf4, v4
	v_not_b32_e32 v4, v35
	v_or_b32_e32 v8, 0x80000000, v35
	v_cmp_gt_i32_e64 s[0:1], 0, v35
	v_cmp_gt_i32_e32 vcc, 0, v34
	v_and_b32_e32 v69, 0x7fffff80, v20
	v_cndmask_b32_e64 v4, v8, v4, s[0:1]
	v_and_b32_e32 v4, 0xffffff00, v4
	v_or_b32_e32 v30, 0xf3, v4
	v_not_b32_e32 v4, v34
	v_or_b32_e32 v8, 0x80000000, v34
	v_cndmask_b32_e32 v4, v8, v4, vcc
	v_and_b32_e32 v4, 0xffffff00, v4
	v_pk_add_f32 v[34:35], v[2:3], v[32:33] op_sel_hi:[0,1]
	v_or_b32_e32 v31, 0xf2, v4
	v_not_b32_e32 v4, v35
	v_or_b32_e32 v8, 0x80000000, v35
	v_cmp_gt_i32_e64 s[0:1], 0, v35
	v_cmp_gt_i32_e32 vcc, 0, v34
	v_and_b32_e32 v35, 0x7fffff80, v182
	v_cndmask_b32_e64 v4, v8, v4, s[0:1]
	v_and_b32_e32 v4, 0xffffff00, v4
	v_or_b32_e32 v32, 0xf1, v4
	v_not_b32_e32 v4, v34
	v_or_b32_e32 v8, 0x80000000, v34
	v_cndmask_b32_e32 v4, v8, v4, vcc
	v_and_b32_e32 v4, 0xffffff00, v4
	v_or_b32_e32 v33, 0xf0, v4
	v_and_b32_e32 v4, 0xffffff80, v16
	v_cmp_gt_i32_e32 vcc, 0, v16
	v_and_b32_e32 v34, 0x7fffff80, v16
	v_xor_b32_e32 v37, -1, v4
	v_and_b32_e32 v8, 0xffffff80, v182
	v_cndmask_b32_e32 v37, v37, v34, vcc
	v_xor_b32_e32 v4, -1, v8
	v_add_f32_e32 v8, v37, v2
	v_cmp_gt_i32_e64 s[0:1], 0, v182
	v_cmp_gt_i32_e32 vcc, 0, v8
	v_not_b32_e32 v34, v8
	v_or_b32_e32 v8, 0x80000000, v8
	v_cndmask_b32_e64 v4, v4, v35, s[0:1]
	v_cndmask_b32_e32 v8, v8, v34, vcc
	v_and_b32_e32 v8, 0xffffff00, v8
	v_pk_add_f32 v[38:39], v[4:5], v[6:7] op_sel_hi:[0,1]
	v_or_b32_e32 v34, 0xf9, v8
	v_not_b32_e32 v6, v39
	v_or_b32_e32 v8, 0x80000000, v39
	v_cmp_gt_i32_e64 s[0:1], 0, v39
	v_cmp_gt_i32_e32 vcc, 0, v38
	v_pk_add_f32 v[36:37], v[4:5], v[36:37] op_sel_hi:[0,1]
	v_cndmask_b32_e64 v6, v8, v6, s[0:1]
	v_and_b32_e32 v6, 0xffffff00, v6
	v_or_b32_e32 v47, 0xeb, v6
	v_not_b32_e32 v6, v38
	v_or_b32_e32 v8, 0x80000000, v38
	v_cndmask_b32_e32 v6, v8, v6, vcc
	v_and_b32_e32 v6, 0xffffff00, v6
	v_or_b32_e32 v48, 0xea, v6
	v_not_b32_e32 v6, v37
	v_or_b32_e32 v8, 0x80000000, v37
	v_cmp_gt_i32_e64 s[0:1], 0, v37
	v_cmp_gt_i32_e32 vcc, 0, v36
	v_and_b32_e32 v35, 0x7fffff80, v19
	v_cndmask_b32_e64 v6, v8, v6, s[0:1]
	v_and_b32_e32 v6, 0xffffff00, v6
	v_or_b32_e32 v49, 0xe9, v6
	v_not_b32_e32 v6, v36
	v_or_b32_e32 v8, 0x80000000, v36
	v_cndmask_b32_e32 v6, v8, v6, vcc
; DI unsigned f2ord(float f) { const unsigned u = __float_as_uint(f); return (u & 0x80000000u) ? ~u : (u | 0x80000000u); }
; DI float ord2f(unsigned o) { const unsigned u = (o & 0x80000000u) ? (o & 0x7fffffffu) : ~o; return __uint_as_float(u); }
; DI void peer_topk_phase(const bf16_t* __restrict__ qpk, const bf16_t* __restrict__ subk, int* __restrict__ eidx, float* __restrict__ gout) {
;     ...
; #pragma unroll
;         for (int a = 0; a < 16; ++a)
; #pragma unroll
;             for (int b = 0; b < 16 / (a + 1); ++b) {
;                 const float cv = ord2f(top[0][a] & ~127u) + ord2f(top[1][b] & ~127u);
;                 ck[combo_row_start(a) + b] = (f2ord(cv) & ~255u) | (unsigned)(((15 - a) << 4) | (15 - b));
;             }
	v_and_b32_e32 v6, 0xffffff00, v6
	v_or_b32_e32 v50, 0xe8, v6
	v_and_b32_e32 v6, 0xffffff80, v19
	v_and_b32_e32 v8, 0xffffff80, v169
	v_cmp_gt_i32_e64 s[0:1], 0, v19
	v_xor_b32_e32 v6, -1, v6
	v_cmp_gt_i32_e32 vcc, 0, v169
	v_and_b32_e32 v36, 0x7fffff80, v169
	v_xor_b32_e32 v8, -1, v8
	v_cndmask_b32_e64 v37, v6, v35, s[0:1]
	v_cndmask_b32_e32 v6, v8, v36, vcc
	v_add_f32_e32 v8, v37, v2
	v_cmp_gt_i32_e32 vcc, 0, v8
	v_not_b32_e32 v35, v8
	v_or_b32_e32 v8, 0x80000000, v8
	v_cndmask_b32_e32 v8, v8, v35, vcc
	v_and_b32_e32 v8, 0xffffff00, v8
	v_or_b32_e32 v35, 0xfc, v8
	v_add_f32_e32 v8, v37, v4
	v_not_b32_e32 v36, v8
	v_or_b32_e32 v38, 0x80000000, v8
	v_cmp_gt_i32_e32 vcc, 0, v8
	v_and_b32_e32 v70, 0x7fffff80, v74
	s_nop 0
	v_cndmask_b32_e32 v8, v38, v36, vcc
	v_mov_b32_e32 v36, v7
	v_and_b32_e32 v8, 0xffffff00, v8
	v_pk_add_f32 v[38:39], v[6:7], v[36:37] op_sel_hi:[0,1]
	v_or_b32_e32 v51, 0xec, v8
	v_not_b32_e32 v7, v39
	v_or_b32_e32 v8, 0x80000000, v39
	v_cmp_gt_i32_e64 s[0:1], 0, v39
	v_cmp_gt_i32_e32 vcc, 0, v38
	v_and_b32_e32 v36, 0x7fffff80, v21
	v_cndmask_b32_e64 v7, v8, v7, s[0:1]
	v_and_b32_e32 v7, 0xffffff00, v7
	v_or_b32_e32 v52, 0xdc, v7
	v_not_b32_e32 v7, v38
	v_or_b32_e32 v8, 0x80000000, v38
	v_cndmask_b32_e32 v7, v8, v7, vcc
	v_and_b32_e32 v7, 0xffffff00, v7
	v_or_b32_e32 v53, 0xdb, v7
	v_and_b32_e32 v7, 0xffffff80, v21
	v_cmp_gt_i32_e64 s[0:1], 0, v21
	v_xor_b32_e32 v7, -1, v7
	v_and_b32_e32 v8, 0xffffff80, v167
	v_cndmask_b32_e64 v39, v7, v36, s[0:1]
	v_cmp_gt_i32_e32 vcc, 0, v167
	v_and_b32_e32 v38, 0x7fffff80, v167
	v_xor_b32_e32 v8, -1, v8
	v_add_f32_e32 v7, v39, v2
	v_cndmask_b32_e32 v8, v8, v38, vcc
	v_cmp_gt_i32_e32 vcc, 0, v7
	v_not_b32_e32 v36, v7
	v_or_b32_e32 v7, 0x80000000, v7
	v_cndmask_b32_e32 v7, v7, v36, vcc
	v_add_f32_e32 v36, v39, v4
	v_not_b32_e32 v38, v36
	v_or_b32_e32 v40, 0x80000000, v36
	v_cmp_gt_i32_e32 vcc, 0, v36
	v_and_b32_e32 v7, 0xffffff00, v7
	v_or_b32_e32 v7, 0xfd, v7
	v_cndmask_b32_e32 v36, v40, v38, vcc
	v_and_b32_e32 v36, 0xffffff00, v36
	v_or_b32_e32 v54, 0xed, v36
	v_add_f32_e32 v36, v39, v6
	v_not_b32_e32 v38, v36
	v_or_b32_e32 v40, 0x80000000, v36
	v_cmp_gt_i32_e32 vcc, 0, v36
	s_nop 1
	v_cndmask_b32_e32 v36, v40, v38, vcc
	v_and_b32_e32 v36, 0xffffff00, v36
	v_mov_b32_e32 v38, v37
	v_or_b32_e32 v55, 0xdd, v36
	v_pk_add_f32 v[36:37], v[8:9], v[38:39] op_sel_hi:[0,1]
	v_not_b32_e32 v38, v37
	v_or_b32_e32 v40, 0x80000000, v37
	v_cmp_gt_i32_e64 s[0:1], 0, v37
	v_cmp_gt_i32_e32 vcc, 0, v36
	s_nop 0
	v_cndmask_b32_e64 v37, v40, v38, s[0:1]
	v_not_b32_e32 v38, v36
	v_or_b32_e32 v36, 0x80000000, v36
	v_cndmask_b32_e32 v36, v36, v38, vcc
	v_and_b32_e32 v36, 0xffffff00, v36
	v_or_b32_e32 v56, 0xcc, v36
	v_cmp_gt_i32_e32 vcc, 0, v166
	v_and_b32_e32 v36, 0x7fffff80, v166
	v_bitop3_b32 v38, v166, s5, v166 bitop3:0xcf
	v_cndmask_b32_e32 v57, v38, v36, vcc
	v_add_f32_e32 v36, v39, v57
	v_not_b32_e32 v38, v36
	v_or_b32_e32 v39, 0x80000000, v36
	v_cmp_gt_i32_e32 vcc, 0, v36
	v_cmp_gt_i32_e64 s[0:1], 0, v164
	v_and_b32_e32 v40, 0x7fffff80, v164
	v_cndmask_b32_e32 v36, v39, v38, vcc
	v_and_b32_e32 v36, 0xffffff00, v36
	v_or_b32_e32 v58, 0xbd, v36
	v_cmp_gt_i32_e32 vcc, 0, v165
	v_and_b32_e32 v36, 0x7fffff80, v165
	v_bitop3_b32 v38, v165, s5, v165 bitop3:0xcf
	v_cndmask_b32_e32 v59, v38, v36, vcc
	v_and_b32_e32 v36, 0xffffff80, v22
	v_and_b32_e32 v38, 0xffffff80, v164
	v_cmp_gt_i32_e32 vcc, 0, v22
	v_and_b32_e32 v39, 0x7fffff80, v22
	v_xor_b32_e32 v36, -1, v36
	v_xor_b32_e32 v38, -1, v38
	v_cndmask_b32_e64 v60, v38, v40, s[0:1]
	v_cndmask_b32_e32 v38, v36, v39, vcc
	v_add_f32_e32 v36, v38, v2
	v_cmp_gt_i32_e32 vcc, 0, v36
	v_not_b32_e32 v39, v36
	v_or_b32_e32 v36, 0x80000000, v36
	v_cndmask_b32_e32 v36, v36, v39, vcc
	v_add_f32_e32 v39, v38, v4
	v_not_b32_e32 v40, v39
	v_or_b32_e32 v41, 0x80000000, v39
	v_cmp_gt_i32_e32 vcc, 0, v39
	v_cmp_gt_i32_e64 s[0:1], 0, v162
	v_and_b32_e32 v37, 0xffffff00, v37
	v_cndmask_b32_e32 v39, v41, v40, vcc
	v_and_b32_e32 v39, 0xffffff00, v39
	v_or_b32_e32 v61, 0xee, v39
	v_add_f32_e32 v39, v38, v6
	v_not_b32_e32 v40, v39
	v_or_b32_e32 v41, 0x80000000, v39
	v_cmp_gt_i32_e32 vcc, 0, v39
	v_or_b32_e32 v37, 0xcd, v37
	v_and_b32_e32 v36, 0xffffff00, v36
	v_cndmask_b32_e32 v39, v41, v40, vcc
	v_and_b32_e32 v39, 0xffffff00, v39
	v_or_b32_e32 v62, 0xde, v39
	v_add_f32_e32 v39, v38, v8
	v_not_b32_e32 v40, v39
	v_or_b32_e32 v41, 0x80000000, v39
	v_cmp_gt_i32_e32 vcc, 0, v39
	v_or_b32_e32 v36, 0xfe, v36
	s_nop 0
	v_cndmask_b32_e32 v39, v41, v40, vcc
	v_and_b32_e32 v39, 0xffffff00, v39
	v_or_b32_e32 v63, 0xce, v39
	v_add_f32_e32 v39, v38, v57
	v_not_b32_e32 v40, v39
	v_or_b32_e32 v41, 0x80000000, v39
	v_cmp_gt_i32_e32 vcc, 0, v39
	s_nop 1
	v_cndmask_b32_e32 v39, v41, v40, vcc
	v_and_b32_e32 v39, 0xffffff00, v39
	v_or_b32_e32 v64, 0xbe, v39
	v_add_f32_e32 v39, v38, v59
	v_not_b32_e32 v40, v39
	v_or_b32_e32 v41, 0x80000000, v39
	v_cmp_gt_i32_e32 vcc, 0, v39
	s_nop 1
	v_cndmask_b32_e32 v39, v41, v40, vcc
	v_and_b32_e32 v39, 0xffffff00, v39
	v_or_b32_e32 v65, 0xae, v39
	v_add_f32_e32 v39, v38, v60
	v_not_b32_e32 v40, v39
	v_or_b32_e32 v41, 0x80000000, v39
	v_cmp_gt_i32_e32 vcc, 0, v39
	s_nop 1
	v_cndmask_b32_e32 v39, v41, v40, vcc
	v_and_b32_e32 v39, 0xffffff00, v39
	v_or_b32_e32 v66, 0x9e, v39
	v_cmp_gt_i32_e32 vcc, 0, v163
	v_and_b32_e32 v39, 0x7fffff80, v163
	v_bitop3_b32 v40, v163, s5, v163 bitop3:0xcf
	v_cndmask_b32_e32 v67, v40, v39, vcc
	v_add_f32_e32 v38, v38, v67
	v_not_b32_e32 v39, v38
	v_or_b32_e32 v40, 0x80000000, v38
	v_cmp_gt_i32_e32 vcc, 0, v38
	v_and_b32_e32 v41, 0x7fffff80, v161
	s_nop 0
	v_cndmask_b32_e32 v38, v40, v39, vcc
	v_and_b32_e32 v38, 0xffffff00, v38
; DI unsigned f2ord(float f) { const unsigned u = __float_as_uint(f); return (u & 0x80000000u) ? ~u : (u | 0x80000000u); }
; DI float ord2f(unsigned o) { const unsigned u = (o & 0x80000000u) ? (o & 0x7fffffffu) : ~o; return __uint_as_float(u); }
; DI void peer_topk_phase(const bf16_t* __restrict__ qpk, const bf16_t* __restrict__ subk, int* __restrict__ eidx, float* __restrict__ gout) {
;     ...
; #pragma unroll
;         for (int a = 0; a < 16; ++a)
; #pragma unroll
;             for (int b = 0; b < 16 / (a + 1); ++b) {
;                 const float cv = ord2f(top[0][a] & ~127u) + ord2f(top[1][b] & ~127u);
;                 ck[combo_row_start(a) + b] = (f2ord(cv) & ~255u) | (unsigned)(((15 - a) << 4) | (15 - b));
;             }
;         unsigned c0[16], c1[16], c2[16], c3[16];
; #pragma unroll
;         for (int i = 0; i < 16; ++i) { c0[i] = ck[i]; c1[i] = ck[16 + i]; c2[i] = ck[32 + i]; c3[i] = (i < 2) ? ck[48 + i] : 0u; }
; #pragma unroll
;         for (int n = 0; n < 63; ++n) { cex(c1[SORT16[n][0]], c1[SORT16[n][1]]); cex(c2[SORT16[n][0]], c2[SORT16[n][1]]); }
	v_or_b32_e32 v68, 0x8e, v38
	v_and_b32_e32 v38, 0xffffff80, v162
	v_and_b32_e32 v39, 0xffffff80, v161
	v_cmp_gt_i32_e32 vcc, 0, v161
	v_and_b32_e32 v40, 0x7fffff80, v162
	v_xor_b32_e32 v38, -1, v38
	v_xor_b32_e32 v42, -1, v39
	v_cndmask_b32_e64 v39, v38, v40, s[0:1]
	v_cndmask_b32_e32 v38, v42, v41, vcc
	v_and_b32_e32 v40, 0xffffff80, v160
	v_and_b32_e32 v41, 0xffffff80, v159
	v_cmp_gt_i32_e32 vcc, 0, v159
	v_cmp_gt_i32_e64 s[0:1], 0, v160
	v_and_b32_e32 v42, 0x7fffff80, v160
	v_xor_b32_e32 v40, -1, v40
	v_xor_b32_e32 v44, -1, v41
	v_cndmask_b32_e64 v41, v40, v42, s[0:1]
	v_cndmask_b32_e32 v40, v44, v43, vcc
	v_and_b32_e32 v42, 0xffffff80, v158
	v_and_b32_e32 v43, 0xffffff80, v157
	v_cmp_gt_i32_e32 vcc, 0, v157
	v_cmp_gt_i32_e64 s[0:1], 0, v158
	v_and_b32_e32 v44, 0x7fffff80, v158
	v_xor_b32_e32 v42, -1, v42
	v_xor_b32_e32 v46, -1, v43
	v_cndmask_b32_e64 v43, v42, v44, s[0:1]
	v_cndmask_b32_e32 v42, v46, v45, vcc
	v_cmp_gt_i32_e32 vcc, 0, v79
	v_and_b32_e32 v44, 0x7fffff80, v79
	v_bitop3_b32 v45, v79, s5, v79 bitop3:0xcf
	v_cndmask_b32_e32 v45, v45, v44, vcc
	v_and_b32_e32 v44, 0xffffff80, v20
	v_and_b32_e32 v46, 0xffffff80, v74
	v_cmp_gt_i32_e32 vcc, 0, v20
	v_xor_b32_e32 v71, -1, v44
	v_xor_b32_e32 v44, -1, v46
	v_cndmask_b32_e32 v46, v71, v69, vcc
	v_cmp_gt_i32_e64 s[0:1], 0, v74
	v_add_f32_e32 v2, v46, v2
	v_not_b32_e32 v69, v2
	v_cndmask_b32_e64 v44, v44, v70, s[0:1]
	v_or_b32_e32 v70, 0x80000000, v2
	v_cmp_gt_i32_e32 vcc, 0, v2
	v_add_f32_e32 v4, v46, v4
	v_add_f32_e32 v6, v46, v6
	v_cndmask_b32_e32 v2, v70, v69, vcc
	v_not_b32_e32 v69, v4
	v_or_b32_e32 v70, 0x80000000, v4
	v_cmp_gt_i32_e32 vcc, 0, v4
	v_add_f32_e32 v8, v46, v8
	v_add_f32_e32 v57, v46, v57
	v_cndmask_b32_e32 v4, v70, v69, vcc
	v_not_b32_e32 v69, v6
	v_or_b32_e32 v70, 0x80000000, v6
	v_cmp_gt_i32_e32 vcc, 0, v6
	v_add_f32_e32 v59, v46, v59
	v_add_f32_e32 v60, v46, v60
	v_cndmask_b32_e32 v6, v70, v69, vcc
	v_not_b32_e32 v69, v8
	v_or_b32_e32 v70, 0x80000000, v8
	v_cmp_gt_i32_e32 vcc, 0, v8
	v_add_f32_e32 v67, v46, v67
	v_pk_add_f32 v[38:39], v[46:47], v[38:39] op_sel_hi:[0,1]
	v_cndmask_b32_e32 v8, v70, v69, vcc
	v_not_b32_e32 v69, v57
	v_or_b32_e32 v70, 0x80000000, v57
	v_cmp_gt_i32_e32 vcc, 0, v57
	v_cmp_gt_i32_e64 s[0:1], 0, v39
	v_and_b32_e32 v4, 0xffffff00, v4
	v_cndmask_b32_e32 v57, v70, v69, vcc
	v_not_b32_e32 v69, v59
	v_or_b32_e32 v70, 0x80000000, v59
	v_cmp_gt_i32_e32 vcc, 0, v59
	v_and_b32_e32 v57, 0xffffff00, v57
	v_or_b32_e32 v4, 0xef, v4
	v_cndmask_b32_e32 v59, v70, v69, vcc
	v_not_b32_e32 v69, v60
	v_or_b32_e32 v70, 0x80000000, v60
	v_cmp_gt_i32_e32 vcc, 0, v60
	v_or_b32_e32 v57, 0xbf, v57
	v_and_b32_e32 v59, 0xffffff00, v59
	v_cndmask_b32_e32 v60, v70, v69, vcc
	v_not_b32_e32 v69, v67
	v_or_b32_e32 v70, 0x80000000, v67
	v_cmp_gt_i32_e32 vcc, 0, v67
	v_and_b32_e32 v60, 0xffffff00, v60
	v_or_b32_e32 v59, 0xaf, v59
	v_cndmask_b32_e32 v67, v70, v69, vcc
	v_not_b32_e32 v69, v39
	v_or_b32_e32 v70, 0x80000000, v39
	v_cndmask_b32_e64 v39, v70, v69, s[0:1]
	v_and_b32_e32 v39, 0xffffff00, v39
	v_cmp_gt_i32_e32 vcc, 0, v38
	v_or_b32_e32 v69, 0x7f, v39
	v_not_b32_e32 v39, v38
	v_or_b32_e32 v38, 0x80000000, v38
	v_cndmask_b32_e32 v38, v38, v39, vcc
	v_and_b32_e32 v38, 0xffffff00, v38
	v_or_b32_e32 v70, 0x6f, v38
	v_pk_add_f32 v[38:39], v[46:47], v[40:41] op_sel_hi:[0,1]
	v_not_b32_e32 v40, v39
	v_or_b32_e32 v41, 0x80000000, v39
	v_cmp_gt_i32_e64 s[0:1], 0, v39
	v_cmp_gt_i32_e32 vcc, 0, v38
	v_or_b32_e32 v60, 0x9f, v60
	v_cndmask_b32_e64 v39, v41, v40, s[0:1]
	v_and_b32_e32 v39, 0xffffff00, v39
	v_or_b32_e32 v40, 0x5f, v39
	v_not_b32_e32 v39, v38
	v_or_b32_e32 v38, 0x80000000, v38
	v_cndmask_b32_e32 v38, v38, v39, vcc
	v_and_b32_e32 v38, 0xffffff00, v38
	v_or_b32_e32 v41, 0x4f, v38
	v_pk_add_f32 v[38:39], v[46:47], v[42:43] op_sel_hi:[0,1]
	v_not_b32_e32 v42, v39
	v_or_b32_e32 v43, 0x80000000, v39
	v_cmp_gt_i32_e64 s[0:1], 0, v39
	v_cmp_gt_i32_e32 vcc, 0, v38
	v_and_b32_e32 v6, 0xffffff00, v6
	v_cndmask_b32_e64 v39, v43, v42, s[0:1]
	v_and_or_b32 v42, v39, s54, 63
	v_not_b32_e32 v39, v38
	v_or_b32_e32 v38, 0x80000000, v38
	v_cndmask_b32_e32 v38, v38, v39, vcc
	v_and_or_b32 v43, v38, s54, 47
	v_pk_add_f32 v[38:39], v[46:47], v[44:45] op_sel_hi:[0,1]
	v_not_b32_e32 v44, v39
	v_or_b32_e32 v45, 0x80000000, v39
	v_cmp_gt_i32_e64 s[0:1], 0, v39
	v_cmp_gt_i32_e32 vcc, 0, v38
	v_min_u32_e32 v46, v56, v57
	v_cndmask_b32_e64 v39, v45, v44, s[0:1]
	v_not_b32_e32 v44, v38
	v_or_b32_e32 v38, 0x80000000, v38
	v_cndmask_b32_e32 v38, v38, v44, vcc
	v_max_u32_e32 v44, v4, v61
	v_min_u32_e32 v4, v4, v61
	v_max_u32_e32 v45, v56, v57
	v_max_u32_e32 v56, v54, v51
	v_min_u32_e32 v51, v54, v51
	v_max_u32_e32 v54, v64, v58
	v_min_u32_e32 v57, v64, v58
	v_max_u32_e32 v58, v44, v56
	v_min_u32_e32 v44, v44, v56
	v_max_u32_e32 v56, v45, v54
	v_min_u32_e32 v45, v45, v54
	v_max_u32_e32 v54, v4, v51
	v_min_u32_e32 v4, v4, v51
	v_max_u32_e32 v51, v46, v57
	v_min_u32_e32 v46, v46, v57
	v_max_u32_e32 v57, v54, v44
	v_min_u32_e32 v44, v54, v44
	v_max_u32_e32 v54, v51, v45
	v_min_u32_e32 v45, v51, v45
	v_max_u32_e32 v51, v47, v48
	v_min_u32_e32 v47, v47, v48
	v_max_u32_e32 v48, v59, v65
	v_min_u32_e32 v59, v59, v65
	v_max_u32_e32 v61, v49, v50
	v_min_u32_e32 v49, v49, v50
	v_max_u32_e32 v50, v60, v66
	v_min_u32_e32 v60, v60, v66
	v_max_u32_e32 v64, v51, v61
	v_min_u32_e32 v51, v51, v61
	v_max_u32_e32 v61, v48, v50
	v_min_u32_e32 v48, v48, v50
	v_max_u32_e32 v50, v47, v49
	v_min_u32_e32 v47, v47, v49
	v_max_u32_e32 v49, v59, v60
	v_min_u32_e32 v59, v59, v60
	v_max_u32_e32 v60, v50, v51
	v_min_u32_e32 v50, v50, v51
	v_max_u32_e32 v51, v49, v48
	v_min_u32_e32 v48, v49, v48
	v_max_u32_e32 v49, v58, v64
; DI void merge_top16(unsigned (&A)[16], const unsigned (&B)[16]) {
; #pragma unroll
;     for (int i = 0; i < 16; ++i) A[i] = max(A[i], B[15 - i]);
; #pragma unroll
;     for (int n = 0; n < 32; ++n) cex(A[BMERGE16[n][0]], A[BMERGE16[n][1]]);
; }
; DI void peer_topk_phase(const bf16_t* __restrict__ qpk, const bf16_t* __restrict__ subk, int* __restrict__ eidx, float* __restrict__ gout) {
;     ...
;         unsigned c0[16], c1[16], c2[16], c3[16];
; #pragma unroll
;         for (int i = 0; i < 16; ++i) { c0[i] = ck[i]; c1[i] = ck[16 + i]; c2[i] = ck[32 + i]; c3[i] = (i < 2) ? ck[48 + i] : 0u; }
; #pragma unroll
;         for (int n = 0; n < 63; ++n) { cex(c1[SORT16[n][0]], c1[SORT16[n][1]]); cex(c2[SORT16[n][0]], c2[SORT16[n][1]]); }
;         merge_top16(c0, c1); merge_top16(c2, c3); merge_top16(c0, c2);
	v_min_u32_e32 v58, v58, v64
	v_max_u32_e32 v64, v56, v61
	v_min_u32_e32 v56, v56, v61
	v_max_u32_e32 v61, v44, v50
	v_min_u32_e32 v44, v44, v50
	v_max_u32_e32 v50, v45, v48
	v_and_b32_e32 v67, 0xffffff00, v67
	v_min_u32_e32 v45, v45, v48
	v_max_u32_e32 v48, v61, v58
	v_min_u32_e32 v58, v61, v58
	v_max_u32_e32 v61, v50, v56
	v_min_u32_e32 v50, v50, v56
	v_max_u32_e32 v56, v57, v60
	v_min_u32_e32 v57, v57, v60
	v_max_u32_e32 v60, v54, v51
	v_min_u32_e32 v51, v54, v51
	v_max_u32_e32 v54, v4, v47
	v_min_u32_e32 v4, v4, v47
	v_max_u32_e32 v47, v46, v59
	v_or_b32_e32 v6, 0xdf, v6
	v_or_b32_e32 v67, 0x8f, v67
	v_min_u32_e32 v46, v46, v59
	v_max_u32_e32 v59, v54, v57
	v_min_u32_e32 v54, v54, v57
	v_max_u32_e32 v57, v47, v51
	v_min_u32_e32 v47, v47, v51
	v_and_b32_e32 v8, 0xffffff00, v8
	v_max_u32_e32 v51, v56, v48
	v_min_u32_e32 v48, v56, v48
	v_max_u32_e32 v56, v60, v61
	v_min_u32_e32 v60, v60, v61
	v_max_u32_e32 v61, v59, v58
	v_min_u32_e32 v58, v59, v58
	v_max_u32_e32 v59, v57, v50
	v_min_u32_e32 v50, v57, v50
	v_max_u32_e32 v57, v54, v44
	v_min_u32_e32 v44, v54, v44
	v_max_u32_e32 v54, v47, v45
	v_min_u32_e32 v45, v47, v45
	v_max_u32_e32 v47, v6, v62
	v_min_u32_e32 v6, v6, v62
	v_max_u32_e32 v62, v67, v68
	v_min_u32_e32 v65, v67, v68
	v_max_u32_e32 v66, v55, v52
	v_min_u32_e32 v52, v55, v52
	v_max_u32_e32 v55, v69, v70
	v_min_u32_e32 v67, v69, v70
	v_or_b32_e32 v8, 0xcf, v8
	v_max_u32_e32 v68, v47, v66
	v_min_u32_e32 v47, v47, v66
	v_max_u32_e32 v66, v62, v55
	v_min_u32_e32 v55, v62, v55
	v_max_u32_e32 v62, v6, v52
	v_min_u32_e32 v6, v6, v52
	v_max_u32_e32 v52, v65, v67
	v_min_u32_e32 v65, v65, v67
	v_max_u32_e32 v67, v62, v47
	v_min_u32_e32 v47, v62, v47
	v_max_u32_e32 v62, v52, v55
	v_min_u32_e32 v52, v52, v55
	v_max_u32_e32 v55, v53, v8
	v_min_u32_e32 v8, v53, v8
	v_max_u32_e32 v53, v40, v41
	v_min_u32_e32 v40, v40, v41
	v_max_u32_e32 v41, v63, v37
	v_min_u32_e32 v37, v63, v37
	v_max_u32_e32 v63, v42, v43
	v_min_u32_e32 v42, v42, v43
	v_max_u32_e32 v43, v55, v41
	v_min_u32_e32 v41, v55, v41
	v_max_u32_e32 v55, v53, v63
	v_min_u32_e32 v53, v53, v63
	v_max_u32_e32 v63, v8, v37
	v_min_u32_e32 v8, v8, v37
	v_max_u32_e32 v37, v40, v42
	v_min_u32_e32 v40, v40, v42
	v_max_u32_e32 v42, v63, v41
	v_min_u32_e32 v41, v63, v41
	v_max_u32_e32 v63, v37, v53
	v_min_u32_e32 v37, v37, v53
	v_max_u32_e32 v53, v68, v43
	v_min_u32_e32 v43, v68, v43
	v_max_u32_e32 v68, v66, v55
	v_min_u32_e32 v55, v66, v55
	v_max_u32_e32 v66, v47, v41
	v_min_u32_e32 v41, v47, v41
	v_max_u32_e32 v47, v52, v37
	v_min_u32_e32 v37, v52, v37
	v_max_u32_e32 v52, v66, v43
	v_min_u32_e32 v43, v66, v43
	v_max_u32_e32 v66, v47, v55
	v_min_u32_e32 v47, v47, v55
	v_max_u32_e32 v55, v67, v42
	v_min_u32_e32 v42, v67, v42
	v_max_u32_e32 v67, v62, v63
	v_min_u32_e32 v62, v62, v63
	v_max_u32_e32 v63, v6, v8
	v_min_u32_e32 v6, v6, v8
	v_max_u32_e32 v8, v65, v40
	v_min_u32_e32 v40, v65, v40
	v_max_u32_e32 v65, v63, v42
	v_min_u32_e32 v42, v63, v42
	v_max_u32_e32 v63, v8, v62
	v_min_u32_e32 v8, v8, v62
	v_max_u32_e32 v62, v55, v52
	v_min_u32_e32 v52, v55, v52
	v_max_u32_e32 v55, v67, v66
	v_min_u32_e32 v66, v67, v66
	v_max_u32_e32 v67, v65, v43
	v_min_u32_e32 v43, v65, v43
	v_max_u32_e32 v65, v63, v47
	v_min_u32_e32 v47, v63, v47
	v_max_u32_e32 v63, v42, v41
	v_min_u32_e32 v41, v42, v41
	v_max_u32_e32 v42, v8, v37
	v_min_u32_e32 v8, v8, v37
	v_min_u32_e32 v37, v49, v53
	v_max_u32_e32 v69, v64, v68
	v_min_u32_e32 v64, v64, v68
	v_max_u32_e32 v68, v58, v43
	v_min_u32_e32 v43, v58, v43
	v_max_u32_e32 v58, v50, v47
	v_min_u32_e32 v47, v50, v47
	v_max_u32_e32 v50, v68, v37
	v_min_u32_e32 v37, v68, v37
	v_max_u32_e32 v68, v58, v64
	v_min_u32_e32 v58, v58, v64
	v_max_u32_e32 v64, v48, v52
	v_min_u32_e32 v48, v48, v52
	v_max_u32_e32 v52, v60, v66
	v_min_u32_e32 v60, v60, v66
	v_max_u32_e32 v66, v44, v41
	v_min_u32_e32 v41, v44, v41
	v_max_u32_e32 v44, v45, v8
	v_min_u32_e32 v8, v45, v8
	v_max_u32_e32 v45, v66, v48
	v_min_u32_e32 v48, v66, v48
	v_max_u32_e32 v66, v44, v60
	v_min_u32_e32 v44, v44, v60
	v_max_u32_e32 v60, v64, v50
	v_min_u32_e32 v50, v64, v50
	v_max_u32_e32 v64, v52, v68
	v_min_u32_e32 v52, v52, v68
	v_max_u32_e32 v68, v45, v37
	v_min_u32_e32 v37, v45, v37
	v_max_u32_e32 v45, v66, v58
	v_min_u32_e32 v58, v66, v58
	v_max_u32_e32 v66, v48, v43
	v_min_u32_e32 v43, v48, v43
	v_max_u32_e32 v48, v44, v47
	v_min_u32_e32 v44, v44, v47
	v_max_u32_e32 v47, v51, v62
	v_min_u32_e32 v51, v51, v62
	v_max_u32_e32 v62, v56, v55
	v_min_u32_e32 v55, v56, v55
	v_max_u32_e32 v56, v57, v63
	v_min_u32_e32 v57, v57, v63
	v_max_u32_e32 v63, v54, v42
	v_min_u32_e32 v42, v54, v42
	v_max_u32_e32 v54, v56, v51
	v_min_u32_e32 v51, v56, v51
	v_max_u32_e32 v56, v63, v55
	v_min_u32_e32 v55, v63, v55
	v_max_u32_e32 v63, v61, v67
	v_min_u32_e32 v61, v61, v67
	v_max_u32_e32 v67, v59, v65
	v_min_u32_e32 v59, v59, v65
	v_max_u32_e32 v65, v4, v6
	v_min_u32_e32 v4, v4, v6
	v_max_u32_e32 v6, v46, v40
	v_min_u32_e32 v40, v46, v40
	v_max_u32_e32 v46, v65, v61
	v_min_u32_e32 v61, v65, v61
	v_max_u32_e32 v65, v6, v59
	v_min_u32_e32 v6, v6, v59
	v_max_u32_e32 v59, v63, v54
	v_min_u32_e32 v54, v63, v54
	v_max_u32_e32 v63, v67, v56
	v_min_u32_e32 v56, v67, v56
	v_max_u32_e32 v67, v46, v51
	v_min_u32_e32 v46, v46, v51
	v_max_u32_e32 v51, v65, v55
	v_min_u32_e32 v55, v65, v55
	v_max_u32_e32 v65, v61, v57
	v_min_u32_e32 v57, v61, v57
	v_max_u32_e32 v61, v6, v42
	v_min_u32_e32 v6, v6, v42
	v_or_b32_e32 v2, 0xff, v2
	v_and_or_b32 v39, v39, s54, 31
	v_and_or_b32 v38, v38, s54, 15
	v_min_u32_e32 v42, v47, v60
	v_max_u32_e32 v70, v62, v64
	v_min_u32_e32 v62, v62, v64
	v_min_u32_e32 v64, v59, v50
	v_max_u32_e32 v71, v63, v52
	v_min_u32_e32 v52, v63, v52
; DI float ord2f(unsigned o) { const unsigned u = (o & 0x80000000u) ? (o & 0x7fffffffu) : ~o; return __uint_as_float(u); }
; DI void peer_topk_phase(const bf16_t* __restrict__ qpk, const bf16_t* __restrict__ subk, int* __restrict__ eidx, float* __restrict__ gout) {
;     ...
;         merge_top16(c0, c1); merge_top16(c2, c3); merge_top16(c0, c2);
;         float sv[16]; int se[16];
; #pragma unroll
;         for (int rd = 0; rd < 16; ++rd) {
;             const unsigned m = c0[rd];
;             const int asel = 15 - (int)((m >> 4) & 15u), bsel = 15 - (int)(m & 15u);
;             unsigned ka = top[0][0], kb = top[1][0];
; #pragma unroll
;             for (int i = 1; i < 16; ++i) { ka = (asel == i) ? top[0][i] : ka; kb = (bsel == i) ? top[1][i] : kb; }
;             sv[rd] = ord2f(ka & ~127u) + ord2f(kb & ~127u);
;             se[rd] = (127 - (int)(ka & 127u)) * 128 + (127 - (int)(kb & 127u));
;         }
	v_min_u32_e32 v63, v54, v68
	v_max_u32_e32 v72, v56, v45
	v_min_u32_e32 v45, v56, v45
	v_min_u32_e32 v56, v67, v37
	v_max_u32_e32 v73, v51, v58
	v_min_u32_e32 v51, v51, v58
	v_min_u32_e32 v58, v46, v66
	v_max_u32_e32 v82, v55, v48
	v_min_u32_e32 v48, v55, v48
	v_min_u32_e32 v55, v65, v43
	v_max_u32_e32 v83, v61, v44
	v_min_u32_e32 v44, v61, v44
	v_min_u32_e32 v61, v57, v41
	v_max_u32_e32 v183, v6, v8
	v_min_u32_e32 v6, v6, v8
	v_max_u32_e32 v2, v2, v4
	v_max_u32_e32 v4, v36, v61
	v_max3_u32 v7, v7, v57, v41
	v_max_u32_e32 v8, v35, v55
	v_max3_u32 v23, v23, v65, v43
	v_max_u32_e32 v24, v24, v58
	v_max3_u32 v34, v34, v46, v66
	v_max_u32_e32 v25, v25, v56
	v_max3_u32 v26, v26, v67, v37
	v_max_u32_e32 v27, v27, v63
	v_max3_u32 v28, v28, v54, v68
	v_max_u32_e32 v29, v29, v64
	v_max3_u32 v30, v30, v59, v50
	v_max_u32_e32 v31, v31, v42
	v_max3_u32 v32, v32, v47, v60
	v_max3_u32 v33, v33, v49, v53
	v_max_u32_e32 v6, v6, v38
	v_max_u32_e32 v38, v40, v39
	v_max_u32_e32 v35, v2, v26
	v_min_u32_e32 v2, v2, v26
	v_max_u32_e32 v26, v4, v27
	v_min_u32_e32 v4, v4, v27
	v_max_u32_e32 v27, v7, v28
	v_min_u32_e32 v7, v7, v28
	v_max_u32_e32 v28, v8, v29
	v_min_u32_e32 v8, v8, v29
	v_max_u32_e32 v29, v23, v30
	v_min_u32_e32 v23, v23, v30
	v_max_u32_e32 v30, v24, v31
	v_min_u32_e32 v24, v24, v31
	v_max_u32_e32 v31, v34, v32
	v_min_u32_e32 v32, v34, v32
	v_max_u32_e32 v34, v25, v33
	v_min_u32_e32 v25, v25, v33
	v_max_u32_e32 v39, v69, v51
	v_min_u32_e32 v40, v69, v51
	v_max_u32_e32 v49, v70, v82
	v_min_u32_e32 v50, v70, v82
	v_max_u32_e32 v51, v62, v48
	v_min_u32_e32 v48, v62, v48
	v_max_u32_e32 v53, v71, v83
	v_min_u32_e32 v54, v71, v83
	v_max_u32_e32 v55, v52, v44
	v_min_u32_e32 v44, v52, v44
	v_max_u32_e32 v52, v72, v183
	v_min_u32_e32 v56, v72, v183
	v_max_u32_e32 v57, v45, v6
	v_min_u32_e32 v6, v45, v6
	v_max_u32_e32 v45, v73, v38
	v_min_u32_e32 v38, v73, v38
	v_max_u32_e32 v33, v35, v29
	v_min_u32_e32 v29, v35, v29
	v_max_u32_e32 v35, v26, v30
	v_min_u32_e32 v26, v26, v30
	v_max_u32_e32 v30, v27, v31
	v_min_u32_e32 v27, v27, v31
	v_max_u32_e32 v31, v28, v34
	v_min_u32_e32 v28, v28, v34
	v_max_u32_e32 v34, v2, v23
	v_min_u32_e32 v2, v2, v23
	v_max_u32_e32 v23, v4, v24
	v_min_u32_e32 v4, v4, v24
	v_max_u32_e32 v24, v7, v32
	v_min_u32_e32 v7, v7, v32
	v_max_u32_e32 v32, v8, v25
	v_min_u32_e32 v8, v8, v25
	v_max_u32_e32 v58, v39, v55
	v_min_u32_e32 v39, v39, v55
	v_max_u32_e32 v55, v49, v52
	v_min_u32_e32 v49, v49, v52
	v_max_u32_e32 v52, v51, v57
	v_min_u32_e32 v51, v51, v57
	v_max_u32_e32 v57, v53, v45
	v_min_u32_e32 v45, v53, v45
	v_max_u32_e32 v53, v40, v44
	v_min_u32_e32 v40, v40, v44
	v_max_u32_e32 v44, v50, v56
	v_min_u32_e32 v50, v50, v56
	v_max_u32_e32 v56, v48, v6
	v_min_u32_e32 v6, v48, v6
	v_max_u32_e32 v48, v54, v38
	v_min_u32_e32 v38, v54, v38
	v_max_u32_e32 v25, v33, v30
	v_min_u32_e32 v30, v33, v30
	v_max_u32_e32 v33, v35, v31
	v_min_u32_e32 v31, v35, v31
	v_max_u32_e32 v35, v29, v27
	v_min_u32_e32 v27, v29, v27
	v_max_u32_e32 v29, v26, v28
	v_min_u32_e32 v26, v26, v28
	v_max_u32_e32 v28, v34, v24
	v_min_u32_e32 v24, v34, v24
	v_max_u32_e32 v34, v23, v32
	v_min_u32_e32 v23, v23, v32
	v_max_u32_e32 v32, v2, v7
	v_min_u32_e32 v2, v2, v7
	v_max_u32_e32 v7, v4, v8
	v_min_u32_e32 v4, v4, v8
	v_max_u32_e32 v54, v58, v52
	v_min_u32_e32 v52, v58, v52
	v_max_u32_e32 v58, v55, v57
	v_min_u32_e32 v55, v55, v57
	v_max_u32_e32 v57, v39, v51
	v_min_u32_e32 v39, v39, v51
	v_max_u32_e32 v51, v49, v45
	v_min_u32_e32 v45, v49, v45
	v_max_u32_e32 v49, v53, v56
	v_min_u32_e32 v53, v53, v56
	v_max_u32_e32 v56, v44, v48
	v_min_u32_e32 v44, v44, v48
	v_max_u32_e32 v48, v40, v6
	v_min_u32_e32 v6, v40, v6
	v_max_u32_e32 v40, v50, v38
	v_min_u32_e32 v38, v50, v38
	v_min_u32_e32 v8, v25, v33
	v_min_u32_e32 v36, v30, v31
	v_min_u32_e32 v37, v35, v29
	v_min_u32_e32 v41, v27, v26
	v_min_u32_e32 v42, v28, v34
	v_min_u32_e32 v43, v24, v23
	v_min_u32_e32 v46, v32, v7
	v_min_u32_e32 v47, v2, v4
	v_min_u32_e32 v50, v54, v58
	v_min_u32_e32 v59, v52, v55
	v_min_u32_e32 v60, v57, v51
	v_min_u32_e32 v61, v39, v45
	v_min_u32_e32 v62, v49, v56
	v_min_u32_e32 v63, v53, v44
	v_min_u32_e32 v64, v48, v40
	v_min_u32_e32 v65, v6, v38
	v_max3_u32 v25, v25, v33, v65
	v_max3_u32 v6, v8, v6, v38
	v_max3_u32 v8, v30, v31, v64
	v_max3_u32 v30, v36, v48, v40
	v_max3_u32 v29, v35, v29, v63
	v_max3_u32 v31, v37, v53, v44
	v_max3_u32 v26, v27, v26, v62
	v_max3_u32 v27, v41, v49, v56
	v_max3_u32 v28, v28, v34, v61
	v_max3_u32 v33, v42, v39, v45
	v_max3_u32 v23, v24, v23, v60
	v_max3_u32 v24, v43, v57, v51
	v_max3_u32 v7, v32, v7, v59
	v_max3_u32 v32, v46, v52, v55
	v_max3_u32 v2, v2, v4, v50
	v_max3_u32 v4, v47, v54, v58
	v_max_u32_e32 v34, v25, v28
	v_min_u32_e32 v25, v25, v28
	v_max_u32_e32 v28, v6, v33
	v_min_u32_e32 v6, v6, v33
	v_max_u32_e32 v33, v8, v23
	v_min_u32_e32 v8, v8, v23
	v_max_u32_e32 v23, v30, v24
	v_min_u32_e32 v24, v30, v24
	v_max_u32_e32 v30, v29, v7
	v_min_u32_e32 v7, v29, v7
	v_max_u32_e32 v29, v31, v32
	v_min_u32_e32 v31, v31, v32
	v_max_u32_e32 v32, v26, v2
	v_min_u32_e32 v2, v26, v2
	v_max_u32_e32 v26, v27, v4
	v_min_u32_e32 v4, v27, v4
	v_max_u32_e32 v27, v34, v30
	v_min_u32_e32 v30, v34, v30
	v_max_u32_e32 v34, v28, v29
	v_min_u32_e32 v28, v28, v29
	v_max_u32_e32 v29, v33, v32
	v_min_u32_e32 v32, v33, v32
	v_max_u32_e32 v33, v23, v26
	v_min_u32_e32 v23, v23, v26
	v_max_u32_e32 v26, v25, v7
	v_min_u32_e32 v7, v25, v7
	v_max_u32_e32 v25, v6, v31
	v_min_u32_e32 v6, v6, v31
	v_max_u32_e32 v31, v8, v2
	v_min_u32_e32 v2, v8, v2
	v_max_u32_e32 v8, v24, v4
	v_min_u32_e32 v4, v24, v4
	v_max_u32_e32 v24, v27, v29
	v_min_u32_e32 v27, v27, v29
	v_max_u32_e32 v29, v34, v33
	v_min_u32_e32 v33, v34, v33
	v_max_u32_e32 v34, v30, v32
	v_min_u32_e32 v30, v30, v32
	v_max_u32_e32 v32, v28, v23
	v_min_u32_e32 v23, v28, v23
	v_max_u32_e32 v28, v26, v31
	v_min_u32_e32 v26, v26, v31
	v_max_u32_e32 v31, v25, v8
	v_min_u32_e32 v8, v25, v8
	v_max_u32_e32 v25, v7, v2
	v_min_u32_e32 v7, v7, v2
	v_max_u32_e32 v35, v6, v4
	v_min_u32_e32 v4, v6, v4
	v_min_u32_e32 v6, v24, v29
	v_max_u32_e32 v2, v24, v29
	v_max_u32_e32 v29, v34, v32
	v_min_u32_e32 v32, v34, v32
	v_max_u32_e32 v38, v28, v31
	v_min_u32_e32 v39, v28, v31
	v_max_u32_e32 v34, v7, v4
	v_min_u32_e32 v31, v7, v4
	v_max_u32_e32 v42, v26, v8
	v_min_u32_e32 v41, v26, v8
	v_max_u32_e32 v24, v27, v33
	v_min_u32_e32 v27, v27, v33
	v_max_u32_e32 v33, v30, v23
	v_min_u32_e32 v36, v30, v23
	v_max_u32_e32 v40, v25, v35
	v_min_u32_e32 v37, v25, v35
	v_lshrrev_b32_e32 v48, 6, v174
	v_lshlrev_b32_e32 v48, 13, v48
	v_lshl_or_b32 v48, v172, 2, v48
	v_mov_b32_e32 v49, 0xf00
	ds_write_b32 v48, v74
	ds_write_b32 v48, v79 offset:256
	ds_write_b32 v48, v157 offset:512
	ds_write_b32 v48, v158 offset:768
	ds_write_b32 v48, v159 offset:1024
	ds_write_b32 v48, v160 offset:1280
	ds_write_b32 v48, v161 offset:1536
	ds_write_b32 v48, v162 offset:1792
	s_waitcnt lgkmcnt(7)
; DI float ord2f(unsigned o) { const unsigned u = (o & 0x80000000u) ? (o & 0x7fffffffu) : ~o; return __uint_as_float(u); }
; DI void peer_topk_phase(const bf16_t* __restrict__ qpk, const bf16_t* __restrict__ subk, int* __restrict__ eidx, float* __restrict__ gout) {
;     ...
;         float sv[16]; int se[16];
; #pragma unroll
;         for (int rd = 0; rd < 16; ++rd) {
;             const unsigned m = c0[rd];
;             const int asel = 15 - (int)((m >> 4) & 15u), bsel = 15 - (int)(m & 15u);
;             unsigned ka = top[0][0], kb = top[1][0];
; #pragma unroll
;             for (int i = 1; i < 16; ++i) { ka = (asel == i) ? top[0][i] : ka; kb = (bsel == i) ? top[1][i] : kb; }
;             sv[rd] = ord2f(ka & ~127u) + ord2f(kb & ~127u);
;             se[rd] = (127 - (int)(ka & 127u)) * 128 + (127 - (int)(kb & 127u));
;         }
	ds_write_b32 v48, v163 offset:2048
	ds_write_b32 v48, v164 offset:2304
	ds_write_b32 v48, v165 offset:2560
	ds_write_b32 v48, v166 offset:2816
	ds_write_b32 v48, v167 offset:3072
	ds_write_b32 v48, v169 offset:3328
	ds_write_b32 v48, v182 offset:3584
	ds_write_b32 v48, v168 offset:3840
	s_waitcnt lgkmcnt(7)
	ds_write_b32 v48, v3 offset:4096
	ds_write_b32 v48, v5 offset:4352
	ds_write_b32 v48, v9 offset:4608
	ds_write_b32 v48, v10 offset:4864
	ds_write_b32 v48, v11 offset:5120
	ds_write_b32 v48, v12 offset:5376
	ds_write_b32 v48, v13 offset:5632
	ds_write_b32 v48, v14 offset:5888
	s_waitcnt lgkmcnt(7)
	ds_write_b32 v48, v15 offset:6144
	ds_write_b32 v48, v16 offset:6400
	ds_write_b32 v48, v17 offset:6656
	ds_write_b32 v48, v18 offset:6912
	ds_write_b32 v48, v19 offset:7168
	ds_write_b32 v48, v21 offset:7424
	ds_write_b32 v48, v22 offset:7680
	ds_write_b32 v48, v20 offset:7936
	s_waitcnt lgkmcnt(7)
	s_waitcnt lgkmcnt(0)
	v_lshlrev_b32_e32 v4, 8, v6
	v_and_or_b32 v4, v4, v49, v48
	ds_read_b32 v4, v4 offset:4096
	v_lshlrev_b32_e32 v6, 4, v6
	v_and_or_b32 v6, v6, v49, v48
	ds_read_b32 v6, v6
	v_lshlrev_b32_e32 v8, 4, v24
	v_and_or_b32 v8, v8, v49, v48
	ds_read_b32 v8, v8
	v_lshlrev_b32_e32 v7, 8, v24
	v_and_or_b32 v7, v7, v49, v48
	ds_read_b32 v7, v7 offset:4096
	v_lshlrev_b32_e32 v24, 4, v27
	v_and_or_b32 v24, v24, v49, v48
	ds_read_b32 v24, v24
	v_lshlrev_b32_e32 v23, 8, v27
	v_and_or_b32 v23, v23, v49, v48
	ds_read_b32 v23, v23 offset:4096
	v_lshlrev_b32_e32 v26, 4, v29
	v_and_or_b32 v26, v26, v49, v48
	ds_read_b32 v26, v26
	v_lshlrev_b32_e32 v25, 8, v29
	v_and_or_b32 v25, v25, v49, v48
	ds_read_b32 v25, v25 offset:4096
	s_waitcnt lgkmcnt(7)
	v_lshlrev_b32_e32 v28, 4, v32
	v_and_or_b32 v28, v28, v49, v48
	ds_read_b32 v28, v28
	v_lshlrev_b32_e32 v27, 8, v32
	v_and_or_b32 v27, v27, v49, v48
	ds_read_b32 v27, v27 offset:4096
	v_lshlrev_b32_e32 v30, 4, v33
	v_and_or_b32 v30, v30, v49, v48
	ds_read_b32 v30, v30
	v_lshlrev_b32_e32 v29, 8, v33
	v_and_or_b32 v29, v29, v49, v48
	ds_read_b32 v29, v29 offset:4096
	v_lshlrev_b32_e32 v33, 4, v36
	v_and_or_b32 v33, v33, v49, v48
	ds_read_b32 v33, v33
	v_lshlrev_b32_e32 v32, 8, v36
	v_and_or_b32 v32, v32, v49, v48
	ds_read_b32 v32, v32 offset:4096
	v_lshlrev_b32_e32 v36, 4, v38
	v_and_or_b32 v36, v36, v49, v48
	ds_read_b32 v36, v36
	v_lshlrev_b32_e32 v35, 8, v38
	v_and_or_b32 v35, v35, v49, v48
	ds_read_b32 v35, v35 offset:4096
	s_waitcnt lgkmcnt(7)
	v_lshlrev_b32_e32 v38, 8, v39
	v_and_or_b32 v38, v38, v49, v48
	ds_read_b32 v38, v38 offset:4096
	v_lshlrev_b32_e32 v39, 4, v39
	v_and_or_b32 v39, v39, v49, v48
	ds_read_b32 v39, v39
	v_lshlrev_b32_e32 v43, 4, v42
	v_and_or_b32 v43, v43, v49, v48
	ds_read_b32 v43, v43
	v_lshlrev_b32_e32 v42, 8, v42
	v_and_or_b32 v42, v42, v49, v48
	ds_read_b32 v42, v42 offset:4096
	v_lshlrev_b32_e32 v44, 4, v41
	v_and_or_b32 v44, v44, v49, v48
	ds_read_b32 v44, v44
	v_lshlrev_b32_e32 v41, 8, v41
	v_and_or_b32 v41, v41, v49, v48
	ds_read_b32 v41, v41 offset:4096
	v_lshlrev_b32_e32 v45, 4, v40
	v_and_or_b32 v45, v45, v49, v48
	ds_read_b32 v45, v45
	v_lshlrev_b32_e32 v40, 8, v40
	v_and_or_b32 v40, v40, v49, v48
	ds_read_b32 v40, v40 offset:4096
	s_waitcnt lgkmcnt(7)
	v_lshlrev_b32_e32 v46, 4, v37
	v_and_or_b32 v46, v46, v49, v48
	ds_read_b32 v46, v46
	v_lshlrev_b32_e32 v37, 8, v37
	v_and_or_b32 v37, v37, v49, v48
	ds_read_b32 v37, v37 offset:4096
	v_lshlrev_b32_e32 v47, 4, v34
	v_and_or_b32 v47, v47, v49, v48
	ds_read_b32 v47, v47
	v_lshlrev_b32_e32 v34, 8, v34
	v_and_or_b32 v34, v34, v49, v48
	ds_read_b32 v34, v34 offset:4096
	v_lshlrev_b32_e32 v10, 4, v2
	v_and_or_b32 v10, v10, v49, v48
	ds_read_b32 v10, v10
	v_lshlrev_b32_e32 v11, 8, v2
	v_and_or_b32 v11, v11, v49, v48
	ds_read_b32 v11, v11 offset:4096
	v_lshlrev_b32_e32 v5, 4, v31
	v_and_or_b32 v5, v5, v49, v48
	ds_read_b32 v5, v5
	v_lshlrev_b32_e32 v9, 8, v31
	v_and_or_b32 v9, v9, v49, v48
	ds_read_b32 v9, v9 offset:4096
	s_waitcnt lgkmcnt(7)
	s_waitcnt lgkmcnt(0)
	v_lshlrev_b64 v[2:3], 7, v[80:81]
	v_lshl_or_b32 v2, v156, 4, v2
	s_and_saveexec_b64 s[0:1], s[10:11]
	s_xor_b64 s[0:1], exec, s[0:1]
	s_cbranch_execz .LBB0_468
	v_and_b32_e32 v12, 0x7fffff80, v47
	v_bitop3_b32 v13, v47, s5, v47 bitop3:0xcf
	v_cmp_gt_i32_e32 vcc, 0, v47
	v_bitop3_b32 v14, v34, s5, v34 bitop3:0xcf
	v_bitop3_b32 v21, v32, s5, v32 bitop3:0xcf
	v_cndmask_b32_e32 v12, v13, v12, vcc
	v_and_b32_e32 v13, 0x7fffff80, v34
	v_cmp_gt_i32_e32 vcc, 0, v34
	v_bitop3_b32 v22, v29, s5, v29 bitop3:0xcf
	s_nop 0
	v_cndmask_b32_e32 v13, v14, v13, vcc
	v_add_f32_e32 v20, v13, v12
	v_and_b32_e32 v12, 0x7fffff80, v46
	v_bitop3_b32 v13, v46, s5, v46 bitop3:0xcf
	v_cmp_gt_i32_e32 vcc, 0, v46
	v_bitop3_b32 v14, v37, s5, v37 bitop3:0xcf
	s_nop 0
	v_cndmask_b32_e32 v12, v13, v12, vcc
	v_and_b32_e32 v13, 0x7fffff80, v37
	v_cmp_gt_i32_e32 vcc, 0, v37
	s_nop 1
	v_cndmask_b32_e32 v13, v14, v13, vcc
	v_add_f32_e32 v19, v13, v12
	v_and_b32_e32 v12, 0x7fffff80, v45
	v_bitop3_b32 v13, v45, s5, v45 bitop3:0xcf
	v_cmp_gt_i32_e32 vcc, 0, v45
	v_bitop3_b32 v14, v40, s5, v40 bitop3:0xcf
	s_nop 0
	v_cndmask_b32_e32 v12, v13, v12, vcc
	v_and_b32_e32 v13, 0x7fffff80, v40
	v_cmp_gt_i32_e32 vcc, 0, v40
	s_nop 1
	v_cndmask_b32_e32 v13, v14, v13, vcc
	v_add_f32_e32 v18, v13, v12
	v_and_b32_e32 v12, 0x7fffff80, v44
	v_bitop3_b32 v13, v44, s5, v44 bitop3:0xcf
	v_cmp_gt_i32_e32 vcc, 0, v44
	v_bitop3_b32 v14, v41, s5, v41 bitop3:0xcf
	s_nop 0
	v_cndmask_b32_e32 v12, v13, v12, vcc
	v_and_b32_e32 v13, 0x7fffff80, v41
	v_cmp_gt_i32_e32 vcc, 0, v41
	s_nop 1
	v_cndmask_b32_e32 v13, v14, v13, vcc
	v_add_f32_e32 v17, v13, v12
	v_and_b32_e32 v12, 0x7fffff80, v43
	v_bitop3_b32 v13, v43, s5, v43 bitop3:0xcf
; DI float ord2f(unsigned o) { const unsigned u = (o & 0x80000000u) ? (o & 0x7fffffffu) : ~o; return __uint_as_float(u); }
; DI void peer_topk_phase(const bf16_t* __restrict__ qpk, const bf16_t* __restrict__ subk, int* __restrict__ eidx, float* __restrict__ gout) {
;     ...
;             sv[rd] = ord2f(ka & ~127u) + ord2f(kb & ~127u);
;             se[rd] = (127 - (int)(ka & 127u)) * 128 + (127 - (int)(kb & 127u));
;         }
;         float den = 0.f;
;         const float mx0 = sv[0];
; #pragma unroll
;         for (int i = 0; i < 16; ++i) { sv[i] = __expf(sv[i] - mx0); den += sv[i]; }
;         const float inv = 1.0f / den;
;         const size_t ob = (size_t)(t0 + r) * 128 + hh * 16;
;         if (h == 0) {
; #pragma unroll
;             for (int i = 0; i < 4; ++i) { int4 v = make_int4(se[4 * i], se[4 * i + 1], se[4 * i + 2], se[4 * i + 3]); *(int4*)(eidx + ob + 4 * i) = v; }
;         } else {
; #pragma unroll
;             for (int i = 0; i < 4; ++i) { f32x4 v = {sv[4 * i] * inv, sv[4 * i + 1] * inv, sv[4 * i + 2] * inv, sv[4 * i + 3] * inv}; *(f32x4*)(gout + ob + 4 * i) = v; }
;         }
	v_cmp_gt_i32_e32 vcc, 0, v43
	v_bitop3_b32 v14, v42, s5, v42 bitop3:0xcf
	s_nop 0
	v_cndmask_b32_e32 v12, v13, v12, vcc
	v_and_b32_e32 v13, 0x7fffff80, v42
	v_cmp_gt_i32_e32 vcc, 0, v42
	s_nop 1
	v_cndmask_b32_e32 v13, v14, v13, vcc
	v_add_f32_e32 v16, v13, v12
	v_and_b32_e32 v12, 0x7fffff80, v39
	v_bitop3_b32 v13, v39, s5, v39 bitop3:0xcf
	v_cmp_gt_i32_e32 vcc, 0, v39
	v_bitop3_b32 v14, v38, s5, v38 bitop3:0xcf
	s_nop 0
	v_cndmask_b32_e32 v12, v13, v12, vcc
	v_and_b32_e32 v13, 0x7fffff80, v38
	v_cmp_gt_i32_e32 vcc, 0, v38
	s_nop 1
	v_cndmask_b32_e32 v13, v14, v13, vcc
	v_add_f32_e32 v15, v13, v12
	v_and_b32_e32 v12, 0x7fffff80, v36
	v_bitop3_b32 v13, v36, s5, v36 bitop3:0xcf
	v_cmp_gt_i32_e32 vcc, 0, v36
	v_bitop3_b32 v14, v35, s5, v35 bitop3:0xcf
	s_nop 0
	v_cndmask_b32_e32 v12, v13, v12, vcc
	v_and_b32_e32 v13, 0x7fffff80, v35
	v_cmp_gt_i32_e32 vcc, 0, v35
	s_nop 1
	v_cndmask_b32_e32 v13, v14, v13, vcc
	v_add_f32_e32 v14, v13, v12
	v_and_b32_e32 v12, 0x7fffff80, v33
	v_bitop3_b32 v13, v33, s5, v33 bitop3:0xcf
	v_cmp_gt_i32_e32 vcc, 0, v33
	s_nop 1
	v_cndmask_b32_e32 v12, v13, v12, vcc
	v_and_b32_e32 v13, 0x7fffff80, v32
	v_cmp_gt_i32_e32 vcc, 0, v32
	s_nop 1
	v_cndmask_b32_e32 v13, v21, v13, vcc
	v_add_f32_e32 v13, v13, v12
	v_and_b32_e32 v12, 0x7fffff80, v30
	v_bitop3_b32 v21, v30, s5, v30 bitop3:0xcf
	v_cmp_gt_i32_e32 vcc, 0, v30
	s_nop 1
	v_cndmask_b32_e32 v12, v21, v12, vcc
	v_and_b32_e32 v21, 0x7fffff80, v29
	v_cmp_gt_i32_e32 vcc, 0, v29
	v_and_b32_e32 v29, 0xffffff80, v9
	s_nop 0
	v_cndmask_b32_e32 v21, v22, v21, vcc
	v_add_f32_e32 v12, v21, v12
	v_and_b32_e32 v21, 0x7fffff80, v28
	v_bitop3_b32 v22, v28, s5, v28 bitop3:0xcf
	v_cmp_gt_i32_e32 vcc, 0, v28
	v_bitop3_b32 v28, v27, s5, v27 bitop3:0xcf
	s_nop 0
	v_cndmask_b32_e32 v21, v22, v21, vcc
	v_and_b32_e32 v22, 0x7fffff80, v27
	v_cmp_gt_i32_e32 vcc, 0, v27
	v_bitop3_b32 v27, v26, s5, v26 bitop3:0xcf
	s_nop 0
	v_cndmask_b32_e32 v22, v28, v22, vcc
	v_add_f32_e32 v21, v22, v21
	v_and_b32_e32 v22, 0x7fffff80, v26
	v_cmp_gt_i32_e32 vcc, 0, v26
	v_and_b32_e32 v26, 0x7fffff80, v25
	v_and_b32_e32 v28, 0xffffff80, v11
	v_cndmask_b32_e32 v22, v27, v22, vcc
	v_bitop3_b32 v27, v25, s5, v25 bitop3:0xcf
	v_cmp_gt_i32_e32 vcc, 0, v25
	s_nop 1
	v_cndmask_b32_e32 v25, v27, v26, vcc
	v_add_f32_e32 v22, v25, v22
	v_and_b32_e32 v25, 0x7fffff80, v24
	v_bitop3_b32 v26, v24, s5, v24 bitop3:0xcf
	v_cmp_gt_i32_e32 vcc, 0, v24
	v_and_b32_e32 v27, 0x7fffff80, v9
	s_nop 0
	v_cndmask_b32_e32 v24, v26, v25, vcc
	v_and_b32_e32 v25, 0x7fffff80, v23
	v_bitop3_b32 v26, v23, s5, v23 bitop3:0xcf
	v_cmp_gt_i32_e32 vcc, 0, v23
	s_nop 1
	v_cndmask_b32_e32 v23, v26, v25, vcc
	v_add_f32_e32 v23, v23, v24
	v_and_b32_e32 v24, 0x7fffff80, v8
	v_bitop3_b32 v25, v8, s5, v8 bitop3:0xcf
	v_cmp_gt_i32_e32 vcc, 0, v8
	v_and_b32_e32 v26, 0x7fffff80, v11
	s_nop 0
	v_cndmask_b32_e32 v8, v25, v24, vcc
	v_and_b32_e32 v24, 0x7fffff80, v7
	v_bitop3_b32 v25, v7, s5, v7 bitop3:0xcf
	v_cmp_gt_i32_e32 vcc, 0, v7
	s_nop 1
	v_cndmask_b32_e32 v7, v25, v24, vcc
	v_add_f32_e32 v8, v7, v8
	v_and_b32_e32 v7, 0x7fffff80, v6
	v_bitop3_b32 v24, v6, s5, v6 bitop3:0xcf
	v_cmp_gt_i32_e32 vcc, 0, v6
	v_and_b32_e32 v25, 0xffffff80, v5
	v_xor_b32_e32 v25, -1, v25
	v_cndmask_b32_e32 v6, v24, v7, vcc
	v_and_b32_e32 v7, 0x7fffff80, v4
	v_bitop3_b32 v24, v4, s5, v4 bitop3:0xcf
	v_cmp_gt_i32_e32 vcc, 0, v4
	s_nop 1
	v_cndmask_b32_e32 v4, v24, v7, vcc
	v_and_b32_e32 v7, 0xffffff80, v10
	v_add_f32_e32 v24, v4, v6
	v_and_b32_e32 v4, 0x7fffff80, v10
	v_xor_b32_e32 v7, -1, v7
	v_cmp_gt_i32_e32 vcc, 0, v10
	v_and_b32_e32 v6, 0x7fffff80, v5
	v_xor_b32_e32 v10, -1, v29
	v_cndmask_b32_e32 v7, v7, v4, vcc
	v_cmp_gt_i32_e32 vcc, 0, v5
	v_xor_b32_e32 v4, -1, v28
	s_nop 0
	v_cndmask_b32_e32 v6, v25, v6, vcc
	v_cmp_gt_i32_e32 vcc, 0, v11
	s_nop 1
	v_cndmask_b32_e32 v5, v4, v26, vcc
	v_cmp_gt_i32_e32 vcc, 0, v9
	s_nop 1
	v_cndmask_b32_e32 v4, v10, v27, vcc
	v_pk_add_f32 v[4:5], v[4:5], v[6:7]
	s_nop 0
	v_sub_f32_e32 v6, v5, v5
	v_mul_f32_e32 v6, 0x3fb8aa3b, v6
	v_sub_f32_e32 v7, v24, v5
	v_exp_f32_e32 v6, v6
	v_mul_f32_e32 v7, 0x3fb8aa3b, v7
	v_sub_f32_e32 v8, v8, v5
	v_exp_f32_e32 v7, v7
	v_mul_f32_e32 v8, 0x3fb8aa3b, v8
	v_sub_f32_e32 v9, v23, v5
	v_exp_f32_e32 v8, v8
	v_mul_f32_e32 v9, 0x3fb8aa3b, v9
	v_exp_f32_e32 v9, v9
	v_add_f32_e32 v10, 0, v6
	v_add_f32_e32 v10, v7, v10
	v_add_f32_e32 v10, v8, v10
	v_add_f32_e32 v23, v9, v10
	v_sub_f32_e32 v10, v22, v5
	v_mul_f32_e32 v10, 0x3fb8aa3b, v10
	v_sub_f32_e32 v11, v21, v5
	v_exp_f32_e32 v10, v10
	v_mul_f32_e32 v11, 0x3fb8aa3b, v11
	v_sub_f32_e32 v12, v12, v5
	v_exp_f32_e32 v11, v11
	v_mul_f32_e32 v12, 0x3fb8aa3b, v12
	v_sub_f32_e32 v13, v13, v5
	v_exp_f32_e32 v12, v12
	v_mul_f32_e32 v13, 0x3fb8aa3b, v13
	v_sub_f32_e32 v14, v14, v5
	v_exp_f32_e32 v13, v13
	v_mul_f32_e32 v14, 0x3fb8aa3b, v14
	v_sub_f32_e32 v15, v15, v5
	v_add_f32_e32 v21, v10, v23
	v_exp_f32_e32 v14, v14
	v_mul_f32_e32 v15, 0x3fb8aa3b, v15
	v_sub_f32_e32 v16, v16, v5
	v_add_f32_e32 v21, v11, v21
	v_exp_f32_e32 v15, v15
	v_mul_f32_e32 v16, 0x3fb8aa3b, v16
	v_sub_f32_e32 v17, v17, v5
	v_add_f32_e32 v21, v12, v21
	v_exp_f32_e32 v16, v16
	v_mul_f32_e32 v17, 0x3fb8aa3b, v17
	v_sub_f32_e32 v18, v18, v5
	v_add_f32_e32 v21, v13, v21
	v_exp_f32_e32 v17, v17
	v_mul_f32_e32 v18, 0x3fb8aa3b, v18
	v_sub_f32_e32 v19, v19, v5
	v_add_f32_e32 v21, v14, v21
	v_exp_f32_e32 v18, v18
	v_mul_f32_e32 v19, 0x3fb8aa3b, v19
	v_sub_f32_e32 v20, v20, v5
	v_add_f32_e32 v21, v15, v21
	v_exp_f32_e32 v19, v19
	v_mul_f32_e32 v20, 0x3fb8aa3b, v20
	v_sub_f32_e32 v4, v4, v5
	v_add_f32_e32 v21, v16, v21
	v_exp_f32_e32 v20, v20
	v_mul_f32_e32 v4, 0x3fb8aa3b, v4
	v_add_f32_e32 v22, v17, v21
	v_exp_f32_e32 v21, v4
	v_add_f32_e32 v4, v18, v22
	v_add_f32_e32 v4, v19, v4
	v_add_f32_e32 v4, v20, v4
	v_add_f32_e32 v4, v21, v4
	v_div_scale_f32 v5, s[12:13], v4, v4, 1.0
	v_rcp_f32_e32 v22, v5
	v_readlane_b32 s12, v253, 18
	v_readlane_b32 s13, v253, 19
	v_fma_f32 v23, -v5, v22, 1.0
	v_fmac_f32_e32 v22, v23, v22
	v_div_scale_f32 v23, vcc, 1.0, v4, 1.0
	v_mul_f32_e32 v24, v23, v22
	v_fma_f32 v25, -v5, v24, v23
	v_fmac_f32_e32 v24, v25, v22
	v_fma_f32 v5, -v5, v24, v23
	v_div_fmas_f32 v5, v5, v22, v24
	v_div_fixup_f32 v22, v5, v4, 1.0
	v_lshl_add_u64 v[24:25], v[2:3], 2, s[12:13]
	v_pk_mul_f32 v[4:5], v[8:9], v[22:23] op_sel_hi:[1,0]
	v_pk_mul_f32 v[2:3], v[6:7], v[22:23] op_sel_hi:[1,0]
	global_store_dwordx4 v[24:25], v[2:5], off
	s_nop 1
	v_pk_mul_f32 v[4:5], v[12:13], v[22:23] op_sel_hi:[1,0]
	v_pk_mul_f32 v[2:3], v[10:11], v[22:23] op_sel_hi:[1,0]
	global_store_dwordx4 v[24:25], v[2:5], off offset:16
	s_nop 1
	v_pk_mul_f32 v[4:5], v[16:17], v[22:23] op_sel_hi:[1,0]
	v_pk_mul_f32 v[2:3], v[14:15], v[22:23] op_sel_hi:[1,0]
	global_store_dwordx4 v[24:25], v[2:5], off offset:32
	s_nop 1
	v_pk_mul_f32 v[4:5], v[20:21], v[22:23] op_sel_hi:[1,0]
	v_pk_mul_f32 v[2:3], v[18:19], v[22:23] op_sel_hi:[1,0]
	global_store_dwordx4 v[24:25], v[2:5], off offset:48

; #define MFMA(a, b, c) __builtin_amdgcn_mfma_f32_32x32x16_bf16((a), (b), (c), 0, 0, 0)
; DI unsigned f2ord(float f) { const unsigned u = __float_as_uint(f); return (u & 0x80000000u) ? ~u : (u | 0x80000000u); }
; DI void peer_topk_phase(const bf16_t* __restrict__ qpk, const bf16_t* __restrict__ subk, int* __restrict__ eidx, float* __restrict__ gout) {
;     ...
;         const int tt = item >> 3, hh = item & 7, t0 = tt * 32;
;         unsigned top[2][16];
; #pragma unroll
;         for (int c = 0; c < 2; ++c) {
;             f32x16 acc[4];
; #pragma unroll
;             for (int nb = 0; nb < 4; ++nb)
; #pragma unroll
;                 for (int i = 0; i < 16; ++i) acc[nb][i] = 0.f;
;             const bf16_t* qp = qpk + (size_t)(t0 + r) * 1024 + hh * 128 + c * 64 + h * 8;
;             const bf16_t* kp = subk + ((size_t)(hh * 2 + c) * 128 + r) * 64 + h * 8;
; #pragma unroll
;             for (int ks = 0; ks < 4; ++ks) {
;                 const bf16x8 qfr = *(const bf16x8*)(qp + ks * 16);
; #pragma unroll
;                 for (int nb = 0; nb < 4; ++nb) {
;                     const bf16x8 kf = *(const bf16x8*)(kp + nb * 32 * 64 + ks * 16);
;                     acc[nb] = MFMA(kf, qfr, acc[nb]);
;                 }
;             }
;             unsigned key[64];
; #pragma unroll
;             for (int nb = 0; nb < 4; ++nb)
; #pragma unroll
;                 for (int i = 0; i < 16; ++i) {
;                     const int n = nb * 32 + (i & 3) + 8 * (i >> 2) + 4 * h;
;                     key[nb * 16 + i] = (f2ord(acc[nb][i]) & ~127u) | (unsigned)(127 - n);
.LBB0_1164:
	v_and_or_b32 v86, v169, s13, v99
	v_ashrrev_i32_e32 v87, 31, v86
	v_and_b32_e32 v179, 7, v98
	v_lshlrev_b64 v[0:1], 11, v[86:87]
	v_lshl_add_u64 v[0:1], s[36:37], 0, v[0:1]
	v_lshlrev_b32_e32 v80, 8, v179
	v_lshl_add_u64 v[4:5], v[0:1], 0, v[80:81]
	v_lshl_or_b32 v80, v179, 15, v178
	v_lshl_add_u64 v[90:91], v[82:83], 0, v[80:81]
	v_mov_b32_e32 v85, v81
	v_add_co_u32_e32 v92, vcc, s15, v90
	v_lshl_add_u64 v[88:89], v[4:5], 0, v[84:85]
	s_nop 0
	v_addc_co_u32_e32 v93, vcc, 0, v91, vcc
	global_load_dwordx4 v[0:3], v[90:91], off
	global_load_dwordx4 v[16:19], v[88:89], off
	global_load_dwordx4 v[64:67], v[88:89], off offset:32
	global_load_dwordx4 v[68:71], v[90:91], off offset:32
	global_load_dwordx4 v[20:23], v[92:93], off offset:-4096
	global_load_dwordx4 v[180:183], v[92:93], off offset:32
	v_add_co_u32_e32 v94, vcc, s20, v90
	s_waitcnt vmcnt(4)
	v_mfma_f32_32x32x16_bf16 v[0:15], v[0:3], v[16:19], 0
	v_addc_co_u32_e32 v95, vcc, 0, v91, vcc
	global_load_dwordx4 v[72:75], v[94:95], off offset:96
	v_add_co_u32_e32 v96, vcc, s10, v90
	s_nop 1
	v_addc_co_u32_e32 v97, vcc, 0, v91, vcc
	s_waitcnt vmcnt(2)
	v_mfma_f32_32x32x16_bf16 v[48:63], v[20:23], v[16:19], 0
	global_load_dwordx4 v[20:23], v[92:93], off
	v_add_co_u32_e32 v184, vcc, s14, v90
	s_nop 1
	v_addc_co_u32_e32 v185, vcc, 0, v91, vcc
	v_add_co_u32_e32 v206, vcc, s16, v90
	v_mfma_f32_32x32x16_bf16 v[0:15], v[68:71], v[64:67], v[0:15]
	s_nop 0
	v_addc_co_u32_e32 v207, vcc, 0, v91, vcc
	s_waitcnt vmcnt(0)
	v_mfma_f32_32x32x16_bf16 v[32:47], v[20:23], v[16:19], 0
	global_load_dwordx4 v[20:23], v[96:97], off offset:-4096
	global_load_dwordx4 v[76:79], v[96:97], off
	global_load_dwordx4 v[68:71], v[184:185], off offset:32
	global_load_dwordx4 v[188:191], v[184:185], off offset:64
	v_mfma_f32_32x32x16_bf16 v[32:47], v[180:183], v[64:67], v[32:47]
	s_waitcnt vmcnt(1)
	v_mfma_f32_32x32x16_bf16 v[48:63], v[68:71], v[64:67], v[48:63]
	global_load_dwordx4 v[68:71], v[206:207], off offset:32
	global_load_dwordx4 v[180:183], v[90:91], off offset:64
	global_load_dwordx4 v[198:201], v[184:185], off offset:96
	v_mfma_f32_32x32x16_bf16 v[16:31], v[20:23], v[16:19], 0
	s_waitcnt vmcnt(2)
	v_mfma_f32_32x32x16_bf16 v[16:31], v[68:71], v[64:67], v[16:31]
	global_load_dwordx4 v[64:67], v[88:89], off offset:64
	global_load_dwordx4 v[68:71], v[88:89], off offset:96
	global_load_dwordx4 v[202:205], v[90:91], off offset:96
	s_waitcnt vmcnt(2)
	v_mfma_f32_32x32x16_bf16 v[0:15], v[180:183], v[64:67], v[0:15]
	v_mfma_f32_32x32x16_bf16 v[48:63], v[188:191], v[64:67], v[48:63]
	global_load_dwordx4 v[180:183], v[92:93], off offset:64
	global_load_dwordx4 v[188:191], v[92:93], off offset:96
	s_waitcnt vmcnt(2)
	v_mfma_f32_32x32x16_bf16 v[0:15], v[202:205], v[68:71], v[0:15]
	v_mfma_f32_32x32x16_bf16 v[48:63], v[198:201], v[68:71], v[48:63]
	s_nop 10
	v_cmp_gt_i32_e32 vcc, 0, v0
	v_not_b32_e32 v80, v2
	v_or_b32_e32 v85, 0x80000000, v2
	v_not_b32_e32 v92, v3
	v_or_b32_e32 v93, 0x80000000, v3
	v_not_b32_e32 v184, v6
	v_or_b32_e32 v185, 0x80000000, v6
	v_not_b32_e32 v187, v7
	v_or_b32_e32 v198, 0x80000000, v9
	v_not_b32_e32 v199, v10
	v_or_b32_e32 v200, 0x80000000, v10
	v_not_b32_e32 v201, v11
	v_or_b32_e32 v202, 0x80000000, v11
	s_waitcnt vmcnt(1)
	v_mfma_f32_32x32x16_bf16 v[32:47], v[180:183], v[64:67], v[32:47]
	global_load_dwordx4 v[180:183], v[206:207], off offset:64
	s_nop 0
	global_load_dwordx4 v[206:209], v[206:207], off offset:96
	s_nop 0
	global_load_dwordx4 v[214:217], v[88:89], off offset:224
	s_waitcnt vmcnt(2)
	v_mfma_f32_32x32x16_bf16 v[16:31], v[180:183], v[64:67], v[16:31]
	v_not_b32_e32 v64, v0
	v_or_b32_e32 v65, 0x80000000, v0
	v_not_b32_e32 v66, v1
	v_or_b32_e32 v67, 0x80000000, v1
	v_cndmask_b32_e32 v0, v65, v64, vcc
	v_cmp_gt_i32_e32 vcc, 0, v1
	v_not_b32_e32 v180, v4
	v_or_b32_e32 v181, 0x80000000, v4
	v_cndmask_b32_e32 v1, v67, v66, vcc
	v_cmp_gt_i32_e32 vcc, 0, v2
	v_not_b32_e32 v182, v5
	v_or_b32_e32 v183, 0x80000000, v5
	v_cndmask_b32_e32 v2, v85, v80, vcc
	v_cmp_gt_i32_e32 vcc, 0, v3
	v_mfma_f32_32x32x16_bf16 v[32:47], v[188:191], v[68:71], v[32:47]
	v_or_b32_e32 v188, 0x80000000, v7
	v_cndmask_b32_e32 v3, v93, v92, vcc
	v_cmp_gt_i32_e32 vcc, 0, v4
	v_not_b32_e32 v189, v8
	v_or_b32_e32 v190, 0x80000000, v8
	v_cndmask_b32_e32 v4, v181, v180, vcc
	v_cmp_gt_i32_e32 vcc, 0, v5
	v_not_b32_e32 v191, v9
	v_not_b32_e32 v64, v12
	v_cndmask_b32_e32 v5, v183, v182, vcc
	v_cmp_gt_i32_e32 vcc, 0, v6
	v_or_b32_e32 v65, 0x80000000, v12
	s_waitcnt vmcnt(1)
; DI unsigned f2ord(float f) { const unsigned u = __float_as_uint(f); return (u & 0x80000000u) ? ~u : (u | 0x80000000u); }
; DI void peer_topk_phase(const bf16_t* __restrict__ qpk, const bf16_t* __restrict__ subk, int* __restrict__ eidx, float* __restrict__ gout) {
;     ...
; #pragma unroll
;             for (int nb = 0; nb < 4; ++nb)
; #pragma unroll
;                 for (int i = 0; i < 16; ++i) {
;                     const int n = nb * 32 + (i & 3) + 8 * (i >> 2) + 4 * h;
;                     key[nb * 16 + i] = (f2ord(acc[nb][i]) & ~127u) | (unsigned)(127 - n);
;                 }
;             unsigned g0[16], g1[16], g2[16], g3[16];
; #pragma unroll
;             for (int i = 0; i < 16; ++i) { g0[i] = key[i]; g1[i] = key[16 + i]; g2[i] = key[32 + i]; g3[i] = key[48 + i]; }
; #pragma unroll
;             for (int n = 0; n < 63; ++n) { cex(g0[SORT16[n][0]], g0[SORT16[n][1]]); cex(g1[SORT16[n][0]], g1[SORT16[n][1]]); cex(g2[SORT16[n][0]], g2[SORT16[n][1]]); cex(g3[SORT16[n][0]], g3[SORT16[n][1]]); }
	v_mfma_f32_32x32x16_bf16 v[16:31], v[206:209], v[68:71], v[16:31]
	v_cndmask_b32_e32 v6, v185, v184, vcc
	v_cmp_gt_i32_e32 vcc, 0, v7
	v_and_or_b32 v0, v0, s17, v100
	v_and_or_b32 v1, v1, s17, v101
	v_cndmask_b32_e32 v7, v188, v187, vcc
	v_cmp_gt_i32_e32 vcc, 0, v8
	v_and_or_b32 v2, v2, s17, v102
	v_and_or_b32 v3, v3, s17, v103
	v_cndmask_b32_e32 v8, v190, v189, vcc
	v_cmp_gt_i32_e32 vcc, 0, v9
	v_and_or_b32 v4, v4, s17, v104
	v_and_or_b32 v5, v5, s17, v105
	v_cndmask_b32_e32 v9, v198, v191, vcc
	v_cmp_gt_i32_e32 vcc, 0, v10
	v_and_or_b32 v6, v6, s17, v106
	v_and_or_b32 v7, v7, s17, v107
	v_cndmask_b32_e32 v10, v200, v199, vcc
	v_cmp_gt_i32_e32 vcc, 0, v11
	v_and_or_b32 v8, v8, s17, v108
	v_and_or_b32 v9, v9, s17, v109
	v_cndmask_b32_e32 v11, v202, v201, vcc
	v_cmp_gt_i32_e32 vcc, 0, v12
	v_and_or_b32 v10, v10, s17, v110
	v_and_or_b32 v11, v11, s17, v111
	v_cndmask_b32_e32 v12, v65, v64, vcc
	v_not_b32_e32 v64, v13
	v_or_b32_e32 v65, 0x80000000, v13
	v_cmp_gt_i32_e32 vcc, 0, v13
	v_and_or_b32 v12, v12, s17, v112
	s_nop 0
	v_cndmask_b32_e32 v13, v65, v64, vcc
	v_not_b32_e32 v64, v14
	v_or_b32_e32 v65, 0x80000000, v14
	v_cmp_gt_i32_e32 vcc, 0, v14
	v_and_or_b32 v13, v13, s17, v113
	s_nop 0
	v_cndmask_b32_e32 v14, v65, v64, vcc
	v_not_b32_e32 v64, v15
	v_or_b32_e32 v65, 0x80000000, v15
	v_cmp_gt_i32_e32 vcc, 0, v15
	v_and_or_b32 v14, v14, s17, v114
	s_nop 0
	v_cndmask_b32_e32 v15, v65, v64, vcc
	v_not_b32_e32 v64, v48
	v_or_b32_e32 v65, 0x80000000, v48
	v_cmp_gt_i32_e32 vcc, 0, v48
	v_and_or_b32 v15, v15, s17, v115
	s_nop 0
	v_cndmask_b32_e32 v48, v65, v64, vcc
	v_not_b32_e32 v64, v49
	v_or_b32_e32 v65, 0x80000000, v49
	v_cmp_gt_i32_e32 vcc, 0, v49
	v_and_or_b32 v48, v48, s17, v116
	s_nop 0
	v_cndmask_b32_e32 v49, v65, v64, vcc
	v_not_b32_e32 v64, v50
	v_or_b32_e32 v65, 0x80000000, v50
	v_cmp_gt_i32_e32 vcc, 0, v50
	v_and_or_b32 v49, v49, s17, v117
	s_nop 0
	v_cndmask_b32_e32 v50, v65, v64, vcc
	v_not_b32_e32 v64, v51
	v_or_b32_e32 v65, 0x80000000, v51
	v_cmp_gt_i32_e32 vcc, 0, v51
	v_and_or_b32 v50, v50, s17, v118
	s_nop 0
	v_cndmask_b32_e32 v51, v65, v64, vcc
	v_not_b32_e32 v64, v52
	v_or_b32_e32 v65, 0x80000000, v52
	v_cmp_gt_i32_e32 vcc, 0, v52
	v_and_or_b32 v51, v51, s17, v119
	s_nop 0
	v_cndmask_b32_e32 v52, v65, v64, vcc
	v_not_b32_e32 v64, v53
	v_or_b32_e32 v65, 0x80000000, v53
	v_cmp_gt_i32_e32 vcc, 0, v53
	v_and_or_b32 v52, v52, s17, v120
	s_nop 0
	v_cndmask_b32_e32 v53, v65, v64, vcc
	v_not_b32_e32 v64, v54
	v_or_b32_e32 v65, 0x80000000, v54
	v_cmp_gt_i32_e32 vcc, 0, v54
	v_and_or_b32 v53, v53, s17, v121
	s_nop 0
	v_cndmask_b32_e32 v54, v65, v64, vcc
	v_not_b32_e32 v64, v55
	v_or_b32_e32 v65, 0x80000000, v55
	v_cmp_gt_i32_e32 vcc, 0, v55
	v_and_or_b32 v54, v54, s17, v122
	s_nop 0
	v_cndmask_b32_e32 v55, v65, v64, vcc
	v_not_b32_e32 v64, v56
	v_or_b32_e32 v65, 0x80000000, v56
	v_cmp_gt_i32_e32 vcc, 0, v56
	v_and_or_b32 v55, v55, s17, v123
	s_nop 0
	v_cndmask_b32_e32 v56, v65, v64, vcc
	v_not_b32_e32 v64, v57
	v_or_b32_e32 v65, 0x80000000, v57
	v_cmp_gt_i32_e32 vcc, 0, v57
	v_and_or_b32 v56, v56, s17, v124
	s_nop 0
	v_cndmask_b32_e32 v57, v65, v64, vcc
	v_not_b32_e32 v64, v58
	v_or_b32_e32 v65, 0x80000000, v58
	v_cmp_gt_i32_e32 vcc, 0, v58
	v_and_or_b32 v57, v57, s17, v125
	s_nop 0
	v_cndmask_b32_e32 v58, v65, v64, vcc
	v_not_b32_e32 v64, v59
	v_or_b32_e32 v65, 0x80000000, v59
	v_cmp_gt_i32_e32 vcc, 0, v59
	v_and_or_b32 v58, v58, s17, v126
	s_nop 0
	v_cndmask_b32_e32 v59, v65, v64, vcc
	v_not_b32_e32 v64, v60
	v_or_b32_e32 v65, 0x80000000, v60
	v_cmp_gt_i32_e32 vcc, 0, v60
	v_and_or_b32 v59, v59, s17, v127
	s_nop 0
	v_cndmask_b32_e32 v60, v65, v64, vcc
	v_not_b32_e32 v64, v61
	v_or_b32_e32 v65, 0x80000000, v61
	v_cmp_gt_i32_e32 vcc, 0, v61
	v_and_or_b32 v60, v60, s17, v128
	s_nop 0
	v_cndmask_b32_e32 v61, v65, v64, vcc
	v_not_b32_e32 v64, v62
	v_or_b32_e32 v65, 0x80000000, v62
	v_cmp_gt_i32_e32 vcc, 0, v62
	v_and_or_b32 v61, v61, s17, v129
	s_nop 0
	v_cndmask_b32_e32 v62, v65, v64, vcc
	v_not_b32_e32 v64, v63
	v_or_b32_e32 v65, 0x80000000, v63
	v_cmp_gt_i32_e32 vcc, 0, v63
	v_and_or_b32 v62, v62, s17, v130
	s_nop 0
	v_cndmask_b32_e32 v63, v65, v64, vcc
	v_not_b32_e32 v64, v32
	v_or_b32_e32 v65, 0x80000000, v32
	v_cmp_gt_i32_e32 vcc, 0, v32
	v_and_or_b32 v63, v63, s17, v131
	s_nop 0
	v_cndmask_b32_e32 v32, v65, v64, vcc
	v_not_b32_e32 v64, v33
	v_or_b32_e32 v65, 0x80000000, v33
	v_cmp_gt_i32_e32 vcc, 0, v33
	v_and_or_b32 v32, v32, s17, v132
	s_nop 0
	v_cndmask_b32_e32 v33, v65, v64, vcc
	v_not_b32_e32 v64, v34
	v_or_b32_e32 v65, 0x80000000, v34
	v_cmp_gt_i32_e32 vcc, 0, v34
	v_and_or_b32 v33, v33, s17, v133
	s_nop 0
	v_cndmask_b32_e32 v34, v65, v64, vcc
	v_not_b32_e32 v64, v35
	v_or_b32_e32 v65, 0x80000000, v35
	v_cmp_gt_i32_e32 vcc, 0, v35
	v_and_or_b32 v34, v34, s17, v134
	s_nop 0
	v_cndmask_b32_e32 v35, v65, v64, vcc
	v_not_b32_e32 v64, v36
	v_or_b32_e32 v65, 0x80000000, v36
	v_cmp_gt_i32_e32 vcc, 0, v36
	v_and_or_b32 v35, v35, s17, v135
	s_nop 0
	v_cndmask_b32_e32 v36, v65, v64, vcc
	v_not_b32_e32 v64, v37
	v_or_b32_e32 v65, 0x80000000, v37
	v_cmp_gt_i32_e32 vcc, 0, v37
	v_and_or_b32 v36, v36, s17, v136
	s_nop 0
	v_cndmask_b32_e32 v37, v65, v64, vcc
	v_not_b32_e32 v64, v38
	v_or_b32_e32 v65, 0x80000000, v38
	v_cmp_gt_i32_e32 vcc, 0, v38
	v_and_or_b32 v37, v37, s17, v137
	s_nop 0
	v_cndmask_b32_e32 v38, v65, v64, vcc
	v_not_b32_e32 v64, v39
	v_or_b32_e32 v65, 0x80000000, v39
	v_cmp_gt_i32_e32 vcc, 0, v39
	v_and_or_b32 v38, v38, s17, v138
	s_nop 0
	v_cndmask_b32_e32 v39, v65, v64, vcc
	v_not_b32_e32 v64, v40
	v_or_b32_e32 v65, 0x80000000, v40
	v_cmp_gt_i32_e32 vcc, 0, v40
	v_and_or_b32 v39, v39, s17, v139
	s_nop 0
; DI unsigned f2ord(float f) { const unsigned u = __float_as_uint(f); return (u & 0x80000000u) ? ~u : (u | 0x80000000u); }
; DI void peer_topk_phase(const bf16_t* __restrict__ qpk, const bf16_t* __restrict__ subk, int* __restrict__ eidx, float* __restrict__ gout) {
;     ...
;             for (int nb = 0; nb < 4; ++nb)
; #pragma unroll
;                 for (int i = 0; i < 16; ++i) {
;                     const int n = nb * 32 + (i & 3) + 8 * (i >> 2) + 4 * h;
;                     key[nb * 16 + i] = (f2ord(acc[nb][i]) & ~127u) | (unsigned)(127 - n);
;                 }
;             unsigned g0[16], g1[16], g2[16], g3[16];
; #pragma unroll
;             for (int i = 0; i < 16; ++i) { g0[i] = key[i]; g1[i] = key[16 + i]; g2[i] = key[32 + i]; g3[i] = key[48 + i]; }
; #pragma unroll
;             for (int n = 0; n < 63; ++n) { cex(g0[SORT16[n][0]], g0[SORT16[n][1]]); cex(g1[SORT16[n][0]], g1[SORT16[n][1]]); cex(g2[SORT16[n][0]], g2[SORT16[n][1]]); cex(g3[SORT16[n][0]], g3[SORT16[n][1]]); }
	v_cndmask_b32_e32 v40, v65, v64, vcc
	v_not_b32_e32 v64, v41
	v_or_b32_e32 v65, 0x80000000, v41
	v_cmp_gt_i32_e32 vcc, 0, v41
	v_and_or_b32 v40, v40, s17, v140
	s_nop 0
	v_cndmask_b32_e32 v41, v65, v64, vcc
	v_not_b32_e32 v64, v42
	v_or_b32_e32 v65, 0x80000000, v42
	v_cmp_gt_i32_e32 vcc, 0, v42
	v_and_or_b32 v41, v41, s17, v141
	s_nop 0
	v_cndmask_b32_e32 v42, v65, v64, vcc
	v_not_b32_e32 v64, v43
	v_or_b32_e32 v65, 0x80000000, v43
	v_cmp_gt_i32_e32 vcc, 0, v43
	v_and_or_b32 v42, v42, s17, v142
	s_nop 0
	v_cndmask_b32_e32 v43, v65, v64, vcc
	v_not_b32_e32 v64, v44
	v_or_b32_e32 v65, 0x80000000, v44
	v_cmp_gt_i32_e32 vcc, 0, v44
	v_and_or_b32 v43, v43, s17, v143
	s_nop 0
	v_cndmask_b32_e32 v44, v65, v64, vcc
	v_not_b32_e32 v64, v45
	v_or_b32_e32 v65, 0x80000000, v45
	v_cmp_gt_i32_e32 vcc, 0, v45
	v_and_or_b32 v44, v44, s17, v149
	s_nop 0
	v_cndmask_b32_e32 v45, v65, v64, vcc
	v_not_b32_e32 v64, v46
	v_or_b32_e32 v65, 0x80000000, v46
	v_cmp_gt_i32_e32 vcc, 0, v46
	v_and_or_b32 v45, v45, s17, v150
	s_nop 0
	v_cndmask_b32_e32 v46, v65, v64, vcc
	v_not_b32_e32 v64, v47
	v_or_b32_e32 v65, 0x80000000, v47
	v_cmp_gt_i32_e32 vcc, 0, v47
	v_and_or_b32 v46, v46, s17, v151
	s_nop 0
	v_cndmask_b32_e32 v47, v65, v64, vcc
	v_not_b32_e32 v64, v16
	v_or_b32_e32 v65, 0x80000000, v16
	v_cmp_gt_i32_e32 vcc, 0, v16
	v_and_or_b32 v47, v47, s17, v152
	s_nop 0
	v_cndmask_b32_e32 v16, v65, v64, vcc
	v_not_b32_e32 v64, v17
	v_or_b32_e32 v65, 0x80000000, v17
	v_cmp_gt_i32_e32 vcc, 0, v17
	v_and_or_b32 v16, v16, s17, v153
	s_nop 0
	v_cndmask_b32_e32 v17, v65, v64, vcc
	v_not_b32_e32 v64, v18
	v_or_b32_e32 v65, 0x80000000, v18
	v_cmp_gt_i32_e32 vcc, 0, v18
	v_and_or_b32 v17, v17, s17, v154
	s_nop 0
	v_cndmask_b32_e32 v18, v65, v64, vcc
	v_not_b32_e32 v64, v19
	v_or_b32_e32 v65, 0x80000000, v19
	v_cmp_gt_i32_e32 vcc, 0, v19
	v_and_or_b32 v18, v18, s17, v155
	s_nop 0
	v_cndmask_b32_e32 v19, v65, v64, vcc
	v_not_b32_e32 v64, v20
	v_or_b32_e32 v65, 0x80000000, v20
	v_cmp_gt_i32_e32 vcc, 0, v20
	v_and_or_b32 v19, v19, s17, v156
	s_nop 0
	v_cndmask_b32_e32 v20, v65, v64, vcc
	v_not_b32_e32 v64, v21
	v_or_b32_e32 v65, 0x80000000, v21
	v_cmp_gt_i32_e32 vcc, 0, v21
	v_and_or_b32 v20, v20, s17, v157
	s_nop 0
	v_cndmask_b32_e32 v21, v65, v64, vcc
	v_not_b32_e32 v64, v22
	v_or_b32_e32 v65, 0x80000000, v22
	v_cmp_gt_i32_e32 vcc, 0, v22
	v_and_or_b32 v21, v21, s17, v158
	s_nop 0
	v_cndmask_b32_e32 v22, v65, v64, vcc
	v_not_b32_e32 v64, v23
	v_or_b32_e32 v65, 0x80000000, v23
	v_cmp_gt_i32_e32 vcc, 0, v23
	v_and_or_b32 v22, v22, s17, v159
	s_nop 0
	v_cndmask_b32_e32 v23, v65, v64, vcc
	v_not_b32_e32 v64, v24
	v_or_b32_e32 v65, 0x80000000, v24
	v_cmp_gt_i32_e32 vcc, 0, v24
	v_and_or_b32 v23, v23, s17, v160
	s_nop 0
	v_cndmask_b32_e32 v24, v65, v64, vcc
	v_not_b32_e32 v64, v25
	v_or_b32_e32 v65, 0x80000000, v25
	v_cmp_gt_i32_e32 vcc, 0, v25
	v_and_or_b32 v24, v24, s17, v161
	s_nop 0
	v_cndmask_b32_e32 v25, v65, v64, vcc
	v_not_b32_e32 v64, v26
	v_or_b32_e32 v65, 0x80000000, v26
	v_cmp_gt_i32_e32 vcc, 0, v26
	v_and_or_b32 v25, v25, s17, v162
	s_nop 0
	v_cndmask_b32_e32 v26, v65, v64, vcc
	v_not_b32_e32 v64, v27
	v_or_b32_e32 v65, 0x80000000, v27
	v_cmp_gt_i32_e32 vcc, 0, v27
	v_and_or_b32 v26, v26, s17, v163
	s_nop 0
	v_cndmask_b32_e32 v27, v65, v64, vcc
	v_not_b32_e32 v64, v28
	v_or_b32_e32 v65, 0x80000000, v28
	v_cmp_gt_i32_e32 vcc, 0, v28
	v_and_or_b32 v27, v27, s17, v164
	s_nop 0
	v_cndmask_b32_e32 v28, v65, v64, vcc
	v_not_b32_e32 v64, v29
	v_or_b32_e32 v65, 0x80000000, v29
	v_cmp_gt_i32_e32 vcc, 0, v29
	v_and_or_b32 v28, v28, s17, v165
	s_nop 0
	v_cndmask_b32_e32 v29, v65, v64, vcc
	v_not_b32_e32 v64, v30
	v_or_b32_e32 v65, 0x80000000, v30
	v_cmp_gt_i32_e32 vcc, 0, v30
	v_and_or_b32 v29, v29, s17, v166
	s_nop 0
	v_cndmask_b32_e32 v30, v65, v64, vcc
	v_not_b32_e32 v64, v31
	v_or_b32_e32 v65, 0x80000000, v31
	v_cmp_gt_i32_e32 vcc, 0, v31
	v_and_or_b32 v30, v30, s17, v167
	s_nop 0
	v_cndmask_b32_e32 v31, v65, v64, vcc
	v_max_u32_e32 v64, v0, v1
	v_min_u32_e32 v0, v0, v1
	v_max_u32_e32 v1, v48, v49
	v_min_u32_e32 v48, v48, v49
	v_max_u32_e32 v49, v32, v33
	v_min_u32_e32 v32, v32, v33
	v_max_u32_e32 v33, v16, v17
	v_min_u32_e32 v16, v16, v17
	v_max_u32_e32 v17, v2, v3
	v_min_u32_e32 v2, v2, v3
	v_max_u32_e32 v3, v50, v51
	v_min_u32_e32 v50, v50, v51
	v_max_u32_e32 v51, v34, v35
	v_min_u32_e32 v34, v34, v35
	v_max_u32_e32 v35, v18, v19
	v_min_u32_e32 v18, v18, v19
	v_max_u32_e32 v19, v64, v17
	v_min_u32_e32 v17, v64, v17
	v_max_u32_e32 v64, v1, v3
	v_min_u32_e32 v1, v1, v3
	v_max_u32_e32 v3, v49, v51
	v_min_u32_e32 v49, v49, v51
	v_max_u32_e32 v51, v33, v35
	v_min_u32_e32 v33, v33, v35
	v_max_u32_e32 v35, v0, v2
	v_min_u32_e32 v0, v0, v2
	v_max_u32_e32 v2, v48, v50
	v_min_u32_e32 v48, v48, v50
	v_max_u32_e32 v50, v32, v34
	v_min_u32_e32 v32, v32, v34
	v_max_u32_e32 v34, v16, v18
	v_min_u32_e32 v16, v16, v18
	v_max_u32_e32 v18, v35, v17
	v_min_u32_e32 v17, v35, v17
	v_max_u32_e32 v35, v2, v1
	v_min_u32_e32 v1, v2, v1
	v_max_u32_e32 v2, v50, v49
	v_min_u32_e32 v49, v50, v49
	v_max_u32_e32 v50, v34, v33
	v_min_u32_e32 v33, v34, v33
	v_max_u32_e32 v34, v4, v5
	v_min_u32_e32 v4, v4, v5
	v_max_u32_e32 v5, v52, v53
	v_min_u32_e32 v52, v52, v53
	v_max_u32_e32 v53, v36, v37
	v_min_u32_e32 v36, v36, v37
	v_max_u32_e32 v37, v20, v21
	v_min_u32_e32 v20, v20, v21
	v_max_u32_e32 v21, v6, v7
	v_min_u32_e32 v6, v6, v7
	v_max_u32_e32 v7, v54, v55
	v_min_u32_e32 v54, v54, v55
	v_max_u32_e32 v55, v38, v39
	v_min_u32_e32 v38, v38, v39
	v_max_u32_e32 v39, v22, v23
	v_min_u32_e32 v22, v22, v23
	v_max_u32_e32 v23, v34, v21
	v_min_u32_e32 v21, v34, v21
	v_max_u32_e32 v34, v5, v7
	v_min_u32_e32 v5, v5, v7
; DI void peer_topk_phase(const bf16_t* __restrict__ qpk, const bf16_t* __restrict__ subk, int* __restrict__ eidx, float* __restrict__ gout) {
;     ...
;             unsigned g0[16], g1[16], g2[16], g3[16];
; #pragma unroll
;             for (int i = 0; i < 16; ++i) { g0[i] = key[i]; g1[i] = key[16 + i]; g2[i] = key[32 + i]; g3[i] = key[48 + i]; }
; #pragma unroll
;             for (int n = 0; n < 63; ++n) { cex(g0[SORT16[n][0]], g0[SORT16[n][1]]); cex(g1[SORT16[n][0]], g1[SORT16[n][1]]); cex(g2[SORT16[n][0]], g2[SORT16[n][1]]); cex(g3[SORT16[n][0]], g3[SORT16[n][1]]); }
;             merge_top16(g0, g1); merge_top16(g2, g3); merge_top16(g0, g2);
	v_max_u32_e32 v7, v53, v55
	v_min_u32_e32 v53, v53, v55
	v_max_u32_e32 v55, v37, v39
	v_min_u32_e32 v37, v37, v39
	v_max_u32_e32 v39, v4, v6
	v_min_u32_e32 v4, v4, v6
	v_max_u32_e32 v6, v52, v54
	v_min_u32_e32 v52, v52, v54
	v_max_u32_e32 v54, v36, v38
	v_min_u32_e32 v36, v36, v38
	v_max_u32_e32 v38, v20, v22
	v_min_u32_e32 v20, v20, v22
	v_max_u32_e32 v22, v39, v21
	v_min_u32_e32 v21, v39, v21
	v_max_u32_e32 v39, v6, v5
	v_min_u32_e32 v5, v6, v5
	v_max_u32_e32 v6, v54, v53
	v_min_u32_e32 v53, v54, v53
	v_max_u32_e32 v54, v38, v37
	v_min_u32_e32 v37, v38, v37
	v_max_u32_e32 v38, v19, v23
	v_min_u32_e32 v19, v19, v23
	v_max_u32_e32 v23, v64, v34
	v_min_u32_e32 v34, v64, v34
	v_max_u32_e32 v64, v3, v7
	v_min_u32_e32 v3, v3, v7
	v_max_u32_e32 v7, v51, v55
	v_min_u32_e32 v51, v51, v55
	v_max_u32_e32 v55, v17, v21
	v_min_u32_e32 v17, v17, v21
	v_max_u32_e32 v21, v1, v5
	v_min_u32_e32 v1, v1, v5
	v_max_u32_e32 v5, v49, v53
	v_min_u32_e32 v49, v49, v53
	v_max_u32_e32 v53, v33, v37
	v_min_u32_e32 v33, v33, v37
	v_max_u32_e32 v37, v55, v19
	v_min_u32_e32 v19, v55, v19
	v_max_u32_e32 v55, v21, v34
	v_min_u32_e32 v21, v21, v34
	v_max_u32_e32 v34, v5, v3
	v_min_u32_e32 v3, v5, v3
	v_max_u32_e32 v5, v53, v51
	v_min_u32_e32 v51, v53, v51
	v_max_u32_e32 v53, v18, v22
	v_min_u32_e32 v18, v18, v22
	v_max_u32_e32 v22, v35, v39
	v_min_u32_e32 v35, v35, v39
	v_max_u32_e32 v39, v2, v6
	v_min_u32_e32 v2, v2, v6
	v_max_u32_e32 v6, v50, v54
	v_min_u32_e32 v50, v50, v54
	v_max_u32_e32 v54, v0, v4
	v_min_u32_e32 v0, v0, v4
	v_max_u32_e32 v4, v48, v52
	v_min_u32_e32 v48, v48, v52
	v_max_u32_e32 v52, v32, v36
	v_min_u32_e32 v32, v32, v36
	v_max_u32_e32 v36, v16, v20
	v_min_u32_e32 v16, v16, v20
	v_max_u32_e32 v20, v54, v18
	v_min_u32_e32 v18, v54, v18
	v_max_u32_e32 v54, v4, v35
	v_min_u32_e32 v4, v4, v35
	v_max_u32_e32 v35, v52, v2
	v_min_u32_e32 v2, v52, v2
	v_max_u32_e32 v52, v36, v50
	v_min_u32_e32 v36, v36, v50
	v_max_u32_e32 v50, v53, v37
	v_min_u32_e32 v37, v53, v37
	v_max_u32_e32 v53, v22, v55
	v_min_u32_e32 v22, v22, v55
	v_max_u32_e32 v55, v39, v34
	v_min_u32_e32 v34, v39, v34
	v_max_u32_e32 v39, v6, v5
	v_min_u32_e32 v5, v6, v5
	v_max_u32_e32 v6, v20, v19
	v_min_u32_e32 v19, v20, v19
	v_max_u32_e32 v20, v54, v21
	v_min_u32_e32 v21, v54, v21
	v_max_u32_e32 v54, v35, v3
	v_min_u32_e32 v3, v35, v3
	v_max_u32_e32 v35, v52, v51
	v_min_u32_e32 v51, v52, v51
	v_max_u32_e32 v52, v18, v17
	v_min_u32_e32 v17, v18, v17
	v_max_u32_e32 v18, v4, v1
	v_min_u32_e32 v1, v4, v1
	v_max_u32_e32 v4, v2, v49
	v_min_u32_e32 v2, v2, v49
	v_max_u32_e32 v49, v36, v33
	v_min_u32_e32 v33, v36, v33
	v_max_u32_e32 v36, v8, v9
	v_min_u32_e32 v8, v8, v9
	v_max_u32_e32 v9, v56, v57
	v_min_u32_e32 v56, v56, v57
	v_max_u32_e32 v57, v40, v41
	v_min_u32_e32 v40, v40, v41
	v_max_u32_e32 v41, v24, v25
	v_min_u32_e32 v24, v24, v25
	v_max_u32_e32 v25, v10, v11
	v_min_u32_e32 v10, v10, v11
	v_max_u32_e32 v11, v58, v59
	v_min_u32_e32 v58, v58, v59
	v_max_u32_e32 v59, v42, v43
	v_min_u32_e32 v42, v42, v43
	v_max_u32_e32 v43, v26, v27
	v_min_u32_e32 v26, v26, v27
	v_and_or_b32 v31, v31, s17, v168
	v_max_u32_e32 v27, v36, v25
	v_min_u32_e32 v25, v36, v25
	v_max_u32_e32 v36, v9, v11
	v_min_u32_e32 v9, v9, v11
	v_max_u32_e32 v11, v57, v59
	v_min_u32_e32 v57, v57, v59
	v_max_u32_e32 v59, v41, v43
	v_min_u32_e32 v41, v41, v43
	v_max_u32_e32 v43, v8, v10
	v_min_u32_e32 v8, v8, v10
	v_max_u32_e32 v10, v56, v58
	v_min_u32_e32 v56, v56, v58
	v_max_u32_e32 v58, v40, v42
	v_min_u32_e32 v40, v40, v42
	v_max_u32_e32 v42, v24, v26
	v_min_u32_e32 v24, v24, v26
	v_max_u32_e32 v26, v43, v25
	v_min_u32_e32 v25, v43, v25
	v_max_u32_e32 v43, v10, v9
	v_min_u32_e32 v9, v10, v9
	v_max_u32_e32 v10, v58, v57
	v_min_u32_e32 v57, v58, v57
	v_max_u32_e32 v58, v42, v41
	v_min_u32_e32 v41, v42, v41
	v_max_u32_e32 v42, v12, v13
	v_min_u32_e32 v12, v12, v13
	v_max_u32_e32 v13, v60, v61
	v_min_u32_e32 v60, v60, v61
	v_max_u32_e32 v61, v44, v45
	v_min_u32_e32 v44, v44, v45
	v_max_u32_e32 v45, v28, v29
	v_min_u32_e32 v28, v28, v29
	v_max_u32_e32 v29, v14, v15
	v_min_u32_e32 v14, v14, v15
	v_max_u32_e32 v15, v62, v63
	v_min_u32_e32 v62, v62, v63
	v_max_u32_e32 v63, v46, v47
	v_min_u32_e32 v46, v46, v47
	v_max_u32_e32 v47, v30, v31
	v_min_u32_e32 v30, v30, v31
	v_max_u32_e32 v31, v42, v29
	v_min_u32_e32 v29, v42, v29
	v_max_u32_e32 v42, v13, v15
	v_min_u32_e32 v13, v13, v15
	v_max_u32_e32 v15, v61, v63
	v_min_u32_e32 v61, v61, v63
	v_max_u32_e32 v63, v45, v47
	v_min_u32_e32 v45, v45, v47
	v_max_u32_e32 v47, v12, v14
	v_min_u32_e32 v12, v12, v14
	v_max_u32_e32 v14, v60, v62
	v_min_u32_e32 v60, v60, v62
	v_max_u32_e32 v62, v44, v46
	v_min_u32_e32 v44, v44, v46
	v_max_u32_e32 v46, v28, v30
	v_min_u32_e32 v28, v28, v30
	v_max_u32_e32 v30, v47, v29
	v_min_u32_e32 v29, v47, v29
	v_max_u32_e32 v47, v14, v13
	v_min_u32_e32 v13, v14, v13
	v_max_u32_e32 v14, v62, v61
	v_min_u32_e32 v61, v62, v61
	v_max_u32_e32 v62, v46, v45
	v_min_u32_e32 v45, v46, v45
	v_max_u32_e32 v46, v27, v31
	v_min_u32_e32 v27, v27, v31
	v_max_u32_e32 v31, v36, v42
	v_min_u32_e32 v36, v36, v42
	v_max_u32_e32 v42, v11, v15
	v_min_u32_e32 v11, v11, v15
	v_max_u32_e32 v15, v59, v63
	v_min_u32_e32 v59, v59, v63
	v_max_u32_e32 v63, v25, v29
	v_min_u32_e32 v25, v25, v29
	v_max_u32_e32 v29, v9, v13
	v_min_u32_e32 v9, v9, v13
	v_max_u32_e32 v13, v57, v61
	v_min_u32_e32 v57, v57, v61
	v_max_u32_e32 v61, v41, v45
	v_min_u32_e32 v41, v41, v45
	v_max_u32_e32 v45, v63, v27
	v_min_u32_e32 v27, v63, v27
	v_max_u32_e32 v63, v29, v36
	v_min_u32_e32 v29, v29, v36
	v_max_u32_e32 v36, v13, v11
	v_min_u32_e32 v11, v13, v11
	v_max_u32_e32 v13, v61, v59
	v_min_u32_e32 v59, v61, v59
; DI void peer_topk_phase(const bf16_t* __restrict__ qpk, const bf16_t* __restrict__ subk, int* __restrict__ eidx, float* __restrict__ gout) {
;     ...
; #pragma unroll
;             for (int n = 0; n < 63; ++n) { cex(g0[SORT16[n][0]], g0[SORT16[n][1]]); cex(g1[SORT16[n][0]], g1[SORT16[n][1]]); cex(g2[SORT16[n][0]], g2[SORT16[n][1]]); cex(g3[SORT16[n][0]], g3[SORT16[n][1]]); }
;             merge_top16(g0, g1); merge_top16(g2, g3); merge_top16(g0, g2);
;             unsigned pb[16];
; #pragma unroll
;             for (int i = 0; i < 16; ++i) pb[i] = (unsigned)__shfl_xor((int)g0[i], 32);
;             merge_top16(g0, pb);
	v_max_u32_e32 v61, v26, v30
	v_min_u32_e32 v26, v26, v30
	v_max_u32_e32 v30, v43, v47
	v_min_u32_e32 v43, v43, v47
	v_max_u32_e32 v47, v10, v14
	v_min_u32_e32 v10, v10, v14
	v_max_u32_e32 v14, v58, v62
	v_min_u32_e32 v58, v58, v62
	v_max_u32_e32 v62, v8, v12
	v_min_u32_e32 v8, v8, v12
	v_max_u32_e32 v12, v56, v60
	v_min_u32_e32 v56, v56, v60
	v_max_u32_e32 v60, v40, v44
	v_min_u32_e32 v40, v40, v44
	v_max_u32_e32 v44, v24, v28
	v_min_u32_e32 v24, v24, v28
	v_max_u32_e32 v28, v62, v26
	v_min_u32_e32 v26, v62, v26
	v_max_u32_e32 v62, v12, v43
	v_min_u32_e32 v12, v12, v43
	v_max_u32_e32 v43, v60, v10
	v_min_u32_e32 v10, v60, v10
	v_max_u32_e32 v60, v44, v58
	v_min_u32_e32 v44, v44, v58
	v_max_u32_e32 v58, v61, v45
	v_min_u32_e32 v45, v61, v45
	v_max_u32_e32 v61, v30, v63
	v_min_u32_e32 v30, v30, v63
	v_max_u32_e32 v63, v47, v36
	v_min_u32_e32 v36, v47, v36
	v_max_u32_e32 v47, v14, v13
	v_min_u32_e32 v13, v14, v13
	v_max_u32_e32 v14, v28, v27
	v_min_u32_e32 v27, v28, v27
	v_max_u32_e32 v28, v62, v29
	v_min_u32_e32 v29, v62, v29
	v_max_u32_e32 v62, v43, v11
	v_min_u32_e32 v11, v43, v11
	v_max_u32_e32 v43, v60, v59
	v_min_u32_e32 v59, v60, v59
	v_max_u32_e32 v60, v26, v25
	v_min_u32_e32 v25, v26, v25
	v_max_u32_e32 v26, v12, v9
	v_min_u32_e32 v9, v12, v9
	v_max_u32_e32 v12, v10, v57
	v_min_u32_e32 v10, v10, v57
	v_max_u32_e32 v57, v44, v41
	v_min_u32_e32 v41, v44, v41
	v_min_u32_e32 v44, v38, v46
	v_min_u32_e32 v65, v23, v31
	v_min_u32_e32 v66, v64, v42
	v_min_u32_e32 v67, v7, v15
	v_max_u32_e32 v68, v19, v27
	v_min_u32_e32 v19, v19, v27
	v_max_u32_e32 v27, v21, v29
	v_min_u32_e32 v21, v21, v29
	v_max_u32_e32 v29, v3, v11
	v_min_u32_e32 v3, v3, v11
	v_max_u32_e32 v11, v51, v59
	v_min_u32_e32 v51, v51, v59
	v_max_u32_e32 v59, v68, v44
	v_min_u32_e32 v44, v68, v44
	v_max_u32_e32 v68, v27, v65
	v_min_u32_e32 v27, v27, v65
	v_max_u32_e32 v65, v29, v66
	v_min_u32_e32 v29, v29, v66
	v_max_u32_e32 v66, v11, v67
	v_min_u32_e32 v11, v11, v67
	v_max_u32_e32 v67, v37, v45
	v_min_u32_e32 v37, v37, v45
	v_max_u32_e32 v45, v22, v30
	v_min_u32_e32 v22, v22, v30
	v_max_u32_e32 v30, v34, v36
	v_min_u32_e32 v34, v34, v36
	v_max_u32_e32 v36, v5, v13
	v_min_u32_e32 v5, v5, v13
	v_max_u32_e32 v13, v17, v25
	v_min_u32_e32 v17, v17, v25
	v_max_u32_e32 v25, v1, v9
	v_min_u32_e32 v1, v1, v9
	v_max_u32_e32 v9, v2, v10
	v_min_u32_e32 v2, v2, v10
	v_max_u32_e32 v10, v33, v41
	v_min_u32_e32 v33, v33, v41
	v_max_u32_e32 v41, v13, v37
	v_min_u32_e32 v13, v13, v37
	v_max_u32_e32 v37, v25, v22
	v_min_u32_e32 v22, v25, v22
	v_max_u32_e32 v25, v9, v34
	v_min_u32_e32 v9, v9, v34
	v_max_u32_e32 v34, v10, v5
	v_min_u32_e32 v5, v10, v5
	v_max_u32_e32 v10, v67, v59
	v_min_u32_e32 v59, v67, v59
	v_max_u32_e32 v67, v45, v68
	v_min_u32_e32 v45, v45, v68
	v_max_u32_e32 v68, v30, v65
	v_min_u32_e32 v30, v30, v65
	v_max_u32_e32 v65, v36, v66
	v_min_u32_e32 v36, v36, v66
	v_max_u32_e32 v66, v41, v44
	v_min_u32_e32 v41, v41, v44
	v_max_u32_e32 v44, v37, v27
	v_min_u32_e32 v27, v37, v27
	v_max_u32_e32 v37, v25, v29
	v_min_u32_e32 v25, v25, v29
	v_max_u32_e32 v29, v34, v11
	v_min_u32_e32 v11, v34, v11
	v_max_u32_e32 v34, v13, v19
	v_min_u32_e32 v13, v13, v19
	v_max_u32_e32 v19, v22, v21
	v_min_u32_e32 v21, v22, v21
	v_max_u32_e32 v22, v9, v3
	v_min_u32_e32 v3, v9, v3
	v_max_u32_e32 v9, v5, v51
	v_min_u32_e32 v5, v5, v51
	v_max_u32_e32 v51, v50, v58
	v_min_u32_e32 v50, v50, v58
	v_max_u32_e32 v58, v53, v61
	v_min_u32_e32 v53, v53, v61
	v_max_u32_e32 v61, v55, v63
	v_min_u32_e32 v55, v55, v63
	v_max_u32_e32 v63, v39, v47
	v_min_u32_e32 v39, v39, v47
	v_max_u32_e32 v47, v52, v60
	v_min_u32_e32 v52, v52, v60
	v_max_u32_e32 v60, v18, v26
	v_min_u32_e32 v18, v18, v26
	v_max_u32_e32 v26, v4, v12
	v_min_u32_e32 v4, v4, v12
	v_max_u32_e32 v12, v49, v57
	v_min_u32_e32 v49, v49, v57
	v_max_u32_e32 v57, v47, v50
	v_min_u32_e32 v47, v47, v50
	v_max_u32_e32 v50, v60, v53
	v_min_u32_e32 v53, v60, v53
	v_max_u32_e32 v60, v26, v55
	v_min_u32_e32 v26, v26, v55
	v_max_u32_e32 v55, v12, v39
	v_min_u32_e32 v12, v12, v39
	v_max_u32_e32 v39, v6, v14
	v_min_u32_e32 v6, v6, v14
	v_max_u32_e32 v14, v20, v28
	v_min_u32_e32 v20, v20, v28
	v_max_u32_e32 v28, v54, v62
	v_min_u32_e32 v54, v54, v62
	v_max_u32_e32 v62, v35, v43
	v_min_u32_e32 v35, v35, v43
	v_max_u32_e32 v43, v0, v8
	v_min_u32_e32 v0, v0, v8
	v_max_u32_e32 v8, v48, v56
	v_min_u32_e32 v48, v48, v56
	v_max_u32_e32 v56, v32, v40
	v_min_u32_e32 v32, v32, v40
	v_max_u32_e32 v40, v16, v24
	v_min_u32_e32 v16, v16, v24
	v_max_u32_e32 v24, v43, v6
	v_min_u32_e32 v6, v43, v6
	v_max_u32_e32 v43, v8, v20
	v_min_u32_e32 v8, v8, v20
	v_max_u32_e32 v20, v56, v54
	v_min_u32_e32 v54, v56, v54
	v_max_u32_e32 v56, v40, v35
	v_min_u32_e32 v35, v40, v35
	v_max_u32_e32 v40, v39, v57
	v_min_u32_e32 v39, v39, v57
	v_max_u32_e32 v57, v14, v50
	v_min_u32_e32 v14, v14, v50
	v_max_u32_e32 v50, v28, v60
	v_min_u32_e32 v28, v28, v60
	v_max_u32_e32 v60, v62, v55
	v_min_u32_e32 v55, v62, v55
	v_max_u32_e32 v62, v24, v47
	v_min_u32_e32 v24, v24, v47
	v_max_u32_e32 v47, v43, v53
	v_min_u32_e32 v43, v43, v53
	v_max_u32_e32 v53, v20, v26
	v_min_u32_e32 v20, v20, v26
	v_max_u32_e32 v26, v56, v12
	v_min_u32_e32 v12, v56, v12
	v_max_u32_e32 v56, v6, v52
	v_min_u32_e32 v6, v6, v52
	v_max_u32_e32 v52, v8, v18
	v_min_u32_e32 v8, v8, v18
	v_max_u32_e32 v18, v54, v4
	v_min_u32_e32 v4, v54, v4
	v_max_u32_e32 v54, v35, v49
	v_min_u32_e32 v35, v35, v49
	v_min_u32_e32 v49, v51, v10
	v_min_u32_e32 v69, v58, v67
	v_min_u32_e32 v70, v61, v68
	v_min_u32_e32 v71, v63, v65
	v_min_u32_e32 v80, v40, v59
	v_min_u32_e32 v85, v57, v45
	v_min_u32_e32 v92, v50, v30
	v_min_u32_e32 v93, v60, v36
	v_min_u32_e32 v180, v39, v66
; #define MFMA(a, b, c) __builtin_amdgcn_mfma_f32_32x32x16_bf16((a), (b), (c), 0, 0, 0)
; DI unsigned f2ord(float f) { const unsigned u = __float_as_uint(f); return (u & 0x80000000u) ? ~u : (u | 0x80000000u); }
; DI void peer_topk_phase(const bf16_t* __restrict__ qpk, const bf16_t* __restrict__ subk, int* __restrict__ eidx, float* __restrict__ gout) {
;     ...
;         for (int c = 0; c < 2; ++c) {
;             f32x16 acc[4];
; #pragma unroll
;             for (int nb = 0; nb < 4; ++nb)
; #pragma unroll
;                 for (int i = 0; i < 16; ++i) acc[nb][i] = 0.f;
;             const bf16_t* qp = qpk + (size_t)(t0 + r) * 1024 + hh * 128 + c * 64 + h * 8;
;             const bf16_t* kp = subk + ((size_t)(hh * 2 + c) * 128 + r) * 64 + h * 8;
; #pragma unroll
;             for (int ks = 0; ks < 4; ++ks) {
;                 const bf16x8 qfr = *(const bf16x8*)(qp + ks * 16);
; #pragma unroll
;                 for (int nb = 0; nb < 4; ++nb) {
;                     const bf16x8 kf = *(const bf16x8*)(kp + nb * 32 * 64 + ks * 16);
;                     acc[nb] = MFMA(kf, qfr, acc[nb]);
;                 }
;             }
;             unsigned key[64];
; #pragma unroll
;             for (int nb = 0; nb < 4; ++nb)
; #pragma unroll
;                 for (int i = 0; i < 16; ++i) {
;                     const int n = nb * 32 + (i & 3) + 8 * (i >> 2) + 4 * h;
;                     key[nb * 16 + i] = (f2ord(acc[nb][i]) & ~127u) | (unsigned)(127 - n);
;                 }
;             unsigned g0[16], g1[16], g2[16], g3[16];
; #pragma unroll
;             for (int i = 0; i < 16; ++i) { g0[i] = key[i]; g1[i] = key[16 + i]; g2[i] = key[32 + i]; g3[i] = key[48 + i]; }
; #pragma unroll
;             for (int n = 0; n < 63; ++n) { cex(g0[SORT16[n][0]], g0[SORT16[n][1]]); cex(g1[SORT16[n][0]], g1[SORT16[n][1]]); cex(g2[SORT16[n][0]], g2[SORT16[n][1]]); cex(g3[SORT16[n][0]], g3[SORT16[n][1]]); }
;             merge_top16(g0, g1); merge_top16(g2, g3); merge_top16(g0, g2);
;             unsigned pb[16];
; #pragma unroll
;             for (int i = 0; i < 16; ++i) pb[i] = (unsigned)__shfl_xor((int)g0[i], 32);
;             merge_top16(g0, pb);
	v_min_u32_e32 v181, v14, v44
	v_min_u32_e32 v182, v28, v37
	v_min_u32_e32 v183, v55, v29
	v_min_u32_e32 v184, v62, v41
	v_min_u32_e32 v185, v47, v27
	v_min_u32_e32 v187, v53, v25
	v_min_u32_e32 v188, v26, v11
	v_min_u32_e32 v189, v24, v34
	v_min_u32_e32 v190, v43, v19
	v_min_u32_e32 v191, v20, v22
	v_min_u32_e32 v198, v12, v9
	v_min_u32_e32 v199, v56, v13
	v_min_u32_e32 v200, v52, v21
	v_min_u32_e32 v201, v18, v3
	v_min_u32_e32 v202, v54, v5
	v_min_u32_e32 v203, v6, v17
	v_min_u32_e32 v204, v8, v1
	v_min_u32_e32 v205, v4, v2
	v_min_u32_e32 v206, v35, v33
	v_max3_u32 v38, v38, v46, v48
	v_max3_u32 v10, v51, v10, v204
	v_max3_u32 v1, v49, v8, v1
	v_max3_u32 v8, v40, v59, v200
	v_max3_u32 v21, v80, v52, v21
	v_max3_u32 v39, v39, v66, v190
	v_max3_u32 v19, v180, v43, v19
	v_max3_u32 v40, v62, v41, v185
	v_max3_u32 v27, v184, v47, v27
	v_max3_u32 v24, v24, v34, v181
	v_max3_u32 v14, v189, v14, v44
	v_max3_u32 v13, v56, v13, v85
	v_max3_u32 v34, v199, v57, v45
	v_max3_u32 v6, v6, v17, v69
	v_max3_u32 v17, v203, v58, v67
	v_max3_u32 v0, v0, v23, v31
	v_max3_u32 v16, v64, v42, v16
	v_max3_u32 v42, v61, v68, v206
	v_max3_u32 v33, v70, v35, v33
	v_max3_u32 v30, v50, v30, v202
	v_max3_u32 v5, v92, v54, v5
	v_max3_u32 v28, v28, v37, v198
	v_max3_u32 v9, v182, v12, v9
	v_max3_u32 v12, v53, v25, v188
	v_max3_u32 v11, v187, v26, v11
	v_max3_u32 v20, v20, v22, v183
	v_max3_u32 v22, v191, v55, v29
	v_max3_u32 v3, v18, v3, v93
	v_max3_u32 v18, v201, v60, v36
	v_max3_u32 v2, v4, v2, v71
	v_max3_u32 v4, v205, v63, v65
	v_max3_u32 v7, v32, v7, v15
	v_max_u32_e32 v23, v38, v27
	v_min_u32_e32 v27, v38, v27
	v_max_u32_e32 v31, v10, v24
	v_min_u32_e32 v10, v10, v24
	v_max_u32_e32 v24, v1, v14
	v_min_u32_e32 v1, v1, v14
	v_max_u32_e32 v14, v8, v13
	v_min_u32_e32 v8, v8, v13
	v_max_u32_e32 v13, v21, v34
	v_min_u32_e32 v21, v21, v34
	v_max_u32_e32 v34, v39, v6
	v_min_u32_e32 v6, v39, v6
	v_max_u32_e32 v38, v19, v17
	v_min_u32_e32 v17, v19, v17
	v_max_u32_e32 v19, v40, v0
	v_min_u32_e32 v0, v40, v0
	v_max_u32_e32 v15, v16, v11
	v_min_u32_e32 v11, v16, v11
	v_max_u32_e32 v16, v42, v20
	v_min_u32_e32 v20, v42, v20
	v_max_u32_e32 v25, v33, v22
	v_min_u32_e32 v22, v33, v22
	v_max_u32_e32 v26, v30, v3
	v_min_u32_e32 v3, v30, v3
	v_max_u32_e32 v29, v5, v18
	v_min_u32_e32 v5, v5, v18
	v_max_u32_e32 v18, v28, v2
	v_min_u32_e32 v2, v28, v2
	v_max_u32_e32 v28, v9, v4
	v_min_u32_e32 v4, v9, v4
	v_max_u32_e32 v9, v12, v7
	v_min_u32_e32 v7, v12, v7
	v_max_u32_e32 v39, v23, v13
	v_min_u32_e32 v13, v23, v13
	v_max_u32_e32 v23, v31, v34
	v_min_u32_e32 v31, v31, v34
	v_max_u32_e32 v34, v24, v38
	v_min_u32_e32 v24, v24, v38
	v_max_u32_e32 v38, v14, v19
	v_min_u32_e32 v14, v14, v19
	v_max_u32_e32 v19, v27, v21
	v_min_u32_e32 v21, v27, v21
	v_max_u32_e32 v27, v10, v6
	v_min_u32_e32 v6, v10, v6
	v_max_u32_e32 v10, v1, v17
	v_min_u32_e32 v1, v1, v17
	v_max_u32_e32 v17, v8, v0
	v_min_u32_e32 v0, v8, v0
	v_max_u32_e32 v12, v15, v29
	v_min_u32_e32 v15, v15, v29
	v_max_u32_e32 v29, v16, v18
	v_min_u32_e32 v16, v16, v18
	v_max_u32_e32 v18, v25, v28
	v_min_u32_e32 v25, v25, v28
	v_max_u32_e32 v28, v26, v9
	v_min_u32_e32 v9, v26, v9
	v_max_u32_e32 v26, v11, v5
	v_min_u32_e32 v5, v11, v5
	v_max_u32_e32 v11, v20, v2
	v_min_u32_e32 v2, v20, v2
	v_max_u32_e32 v20, v22, v4
	v_min_u32_e32 v4, v22, v4
	v_max_u32_e32 v22, v3, v7
	v_min_u32_e32 v3, v3, v7
	v_max_u32_e32 v8, v39, v34
	v_min_u32_e32 v34, v39, v34
	v_max_u32_e32 v39, v23, v38
	v_min_u32_e32 v23, v23, v38
	v_max_u32_e32 v38, v13, v24
	v_min_u32_e32 v13, v13, v24
	v_max_u32_e32 v24, v31, v14
	v_min_u32_e32 v14, v31, v14
	v_max_u32_e32 v31, v19, v10
	v_min_u32_e32 v10, v19, v10
	v_max_u32_e32 v19, v27, v17
	v_min_u32_e32 v17, v27, v17
	v_max_u32_e32 v27, v21, v1
	v_min_u32_e32 v1, v21, v1
	v_max_u32_e32 v21, v6, v0
	v_max_u32_e32 v30, v12, v18
	v_min_u32_e32 v7, v12, v18
	v_max_u32_e32 v12, v29, v28
	v_min_u32_e32 v18, v29, v28
	v_max_u32_e32 v28, v15, v25
	v_min_u32_e32 v15, v15, v25
	v_max_u32_e32 v25, v16, v9
	v_min_u32_e32 v9, v16, v9
	v_max_u32_e32 v16, v26, v20
	v_min_u32_e32 v20, v26, v20
	v_max_u32_e32 v26, v11, v22
	v_min_u32_e32 v11, v11, v22
	v_max_u32_e32 v22, v5, v4
	v_min_u32_e32 v4, v5, v4
	v_max_u32_e32 v5, v2, v3
	v_min_u32_e32 v2, v2, v3
	v_min_u32_e32 v0, v6, v0
	v_min_u32_e32 v6, v8, v39
	v_min_u32_e32 v46, v27, v21
	v_min_u32_e32 v3, v30, v12
	v_min_u32_e32 v32, v28, v25
	v_min_u32_e32 v42, v4, v2
	v_min_u32_e32 v45, v10, v17
	v_min_u32_e32 v47, v1, v0
	v_min_u32_e32 v29, v7, v18
	v_max3_u32 v8, v8, v39, v42
	v_max3_u32 v39, v6, v4, v2
	v_max3_u32 v10, v10, v17, v32
	v_max3_u32 v17, v46, v7, v18
	v_max3_u32 v18, v1, v0, v3
	global_load_dwordx4 v[0:3], v[88:89], off offset:128
	global_load_dwordx4 v[68:71], v[88:89], off offset:160
	v_min_u32_e32 v40, v34, v23
	v_min_u32_e32 v41, v38, v24
	v_min_u32_e32 v44, v31, v19
	v_min_u32_e32 v33, v15, v9
	v_min_u32_e32 v35, v16, v26
	v_min_u32_e32 v36, v20, v11
	v_min_u32_e32 v37, v22, v5
	v_add_co_u32_e32 v184, vcc, s19, v90
	v_min_u32_e32 v43, v13, v14
	v_max3_u32 v23, v34, v23, v37
	v_max3_u32 v22, v40, v22, v5
	v_max3_u32 v24, v38, v24, v36
	v_max3_u32 v20, v41, v20, v11
	v_max3_u32 v13, v13, v14, v35
	v_max3_u32 v11, v31, v19, v33
	v_max3_u32 v9, v44, v15, v9
	v_max3_u32 v14, v45, v28, v25
	v_max3_u32 v15, v27, v21, v29
	v_addc_co_u32_e32 v185, vcc, 0, v91, vcc
	v_max3_u32 v16, v43, v16, v26
	global_load_dwordx4 v[4:7], v[184:185], off offset:-4096
	global_load_dwordx4 v[198:201], v[96:97], off offset:64
	v_max3_u32 v19, v47, v30, v12
	v_max_u32_e32 v21, v8, v11
	v_min_u32_e32 v25, v8, v11
	v_max_u32_e32 v26, v39, v9
	v_min_u32_e32 v27, v39, v9
	v_max_u32_e32 v28, v23, v10
	v_min_u32_e32 v23, v23, v10
	global_load_dwordx4 v[8:11], v[184:185], off
	v_max_u32_e32 v29, v22, v14
	v_min_u32_e32 v22, v22, v14
	v_max_u32_e32 v30, v24, v15
	v_min_u32_e32 v24, v24, v15
	v_max_u32_e32 v31, v20, v17
	v_min_u32_e32 v17, v20, v17
	v_max_u32_e32 v20, v13, v18
	v_min_u32_e32 v18, v13, v18
	global_load_dwordx4 v[12:15], v[94:95], off
	global_load_dwordx4 v[188:191], v[94:95], off offset:32
	global_load_dwordx4 v[64:67], v[96:97], off offset:32
	global_load_dwordx4 v[202:205], v[88:89], off offset:192
	v_add_co_u32_e32 v218, vcc, s18, v90
	s_waitcnt vmcnt(8)
; #define MFMA(a, b, c) __builtin_amdgcn_mfma_f32_32x32x16_bf16((a), (b), (c), 0, 0, 0)
; DI unsigned f2ord(float f) { const unsigned u = __float_as_uint(f); return (u & 0x80000000u) ? ~u : (u | 0x80000000u); }
; DI void peer_topk_phase(const bf16_t* __restrict__ qpk, const bf16_t* __restrict__ subk, int* __restrict__ eidx, float* __restrict__ gout) {
;     ...
;         for (int c = 0; c < 2; ++c) {
;             f32x16 acc[4];
; #pragma unroll
;             for (int nb = 0; nb < 4; ++nb)
; #pragma unroll
;                 for (int i = 0; i < 16; ++i) acc[nb][i] = 0.f;
;             const bf16_t* qp = qpk + (size_t)(t0 + r) * 1024 + hh * 128 + c * 64 + h * 8;
;             const bf16_t* kp = subk + ((size_t)(hh * 2 + c) * 128 + r) * 64 + h * 8;
; #pragma unroll
;             for (int ks = 0; ks < 4; ++ks) {
;                 const bf16x8 qfr = *(const bf16x8*)(qp + ks * 16);
; #pragma unroll
;                 for (int nb = 0; nb < 4; ++nb) {
;                     const bf16x8 kf = *(const bf16x8*)(kp + nb * 32 * 64 + ks * 16);
;                     acc[nb] = MFMA(kf, qfr, acc[nb]);
;                 }
;             }
;             unsigned key[64];
; #pragma unroll
;             for (int nb = 0; nb < 4; ++nb)
; #pragma unroll
;                 for (int i = 0; i < 16; ++i) {
;                     const int n = nb * 32 + (i & 3) + 8 * (i >> 2) + 4 * h;
;                     key[nb * 16 + i] = (f2ord(acc[nb][i]) & ~127u) | (unsigned)(127 - n);
;                 }
;             unsigned g0[16], g1[16], g2[16], g3[16];
; #pragma unroll
;             for (int i = 0; i < 16; ++i) { g0[i] = key[i]; g1[i] = key[16 + i]; g2[i] = key[32 + i]; g3[i] = key[48 + i]; }
; #pragma unroll
;             for (int n = 0; n < 63; ++n) { cex(g0[SORT16[n][0]], g0[SORT16[n][1]]); cex(g1[SORT16[n][0]], g1[SORT16[n][1]]); cex(g2[SORT16[n][0]], g2[SORT16[n][1]]); cex(g3[SORT16[n][0]], g3[SORT16[n][1]]); }
;             merge_top16(g0, g1); merge_top16(g2, g3); merge_top16(g0, g2);
;             unsigned pb[16];
; #pragma unroll
;             for (int i = 0; i < 16; ++i) pb[i] = (unsigned)__shfl_xor((int)g0[i], 32);
;             merge_top16(g0, pb);
; #pragma unroll
;             for (int i = 0; i < 16; ++i) top[c][i] = g0[i];
	v_mfma_f32_32x32x16_bf16 v[48:63], v[76:79], v[0:3], 0
	v_addc_co_u32_e32 v219, vcc, 0, v91, vcc
	global_load_dwordx4 v[90:93], v[218:219], off offset:32
	global_load_dwordx4 v[222:225], v[184:185], off offset:96
	global_load_dwordx4 v[76:79], v[94:95], off offset:64
	global_load_dwordx4 v[206:209], v[218:219], off offset:64
	global_load_dwordx4 v[180:183], v[184:185], off offset:32
	global_load_dwordx4 v[210:213], v[184:185], off offset:64
	v_max_u32_e32 v32, v16, v19
	global_load_dwordx4 v[94:97], v[96:97], off offset:96
	v_min_u32_e32 v16, v16, v19
	global_load_dwordx4 v[218:221], v[218:219], off offset:96
	v_max_u32_e32 v19, v21, v30
	v_min_u32_e32 v21, v21, v30
	v_max_u32_e32 v30, v26, v31
	v_min_u32_e32 v26, v26, v31
	v_max_u32_e32 v31, v28, v20
	v_min_u32_e32 v20, v28, v20
	v_max_u32_e32 v28, v29, v32
	v_min_u32_e32 v29, v29, v32
	v_max_u32_e32 v32, v25, v24
	v_min_u32_e32 v24, v25, v24
	v_max_u32_e32 v25, v27, v17
	v_min_u32_e32 v17, v27, v17
	v_max_u32_e32 v27, v23, v18
	v_min_u32_e32 v18, v23, v18
	v_max_u32_e32 v23, v22, v16
	v_min_u32_e32 v16, v22, v16
	v_max_u32_e32 v22, v19, v31
	v_min_u32_e32 v19, v19, v31
	v_max_u32_e32 v31, v30, v28
	v_min_u32_e32 v28, v30, v28
	v_max_u32_e32 v30, v21, v20
	v_min_u32_e32 v20, v21, v20
	v_max_u32_e32 v21, v26, v29
	v_min_u32_e32 v26, v26, v29
	v_max_u32_e32 v29, v32, v27
	v_min_u32_e32 v27, v32, v27
	v_max_u32_e32 v32, v25, v23
	v_min_u32_e32 v23, v25, v23
	v_max_u32_e32 v25, v24, v18
	v_min_u32_e32 v18, v24, v18
	v_max_u32_e32 v24, v17, v16
	v_min_u32_e32 v16, v17, v16
	v_max_u32_e32 v80, v22, v31
	v_min_u32_e32 v85, v22, v31
	v_max_u32_e32 v187, v19, v28
	v_min_u32_e32 v226, v19, v28
	v_max_u32_e32 v227, v30, v21
	v_min_u32_e32 v228, v30, v21
	v_max_u32_e32 v229, v20, v26
	v_min_u32_e32 v230, v20, v26
	v_max_u32_e32 v231, v29, v32
	v_min_u32_e32 v232, v29, v32
	v_max_u32_e32 v233, v27, v23
	v_min_u32_e32 v234, v27, v23
	v_max_u32_e32 v235, v25, v24
	v_min_u32_e32 v236, v25, v24
	v_max_u32_e32 v237, v18, v16
	v_min_u32_e32 v238, v18, v16
	s_waitcnt vmcnt(14)
	v_mfma_f32_32x32x16_bf16 v[32:47], v[4:7], v[0:3], 0
	ds_bpermute_b32 v239, v173, v80
	ds_bpermute_b32 v240, v173, v85
	ds_bpermute_b32 v241, v173, v187
	ds_bpermute_b32 v242, v173, v226
	ds_bpermute_b32 v243, v173, v227
	ds_bpermute_b32 v244, v173, v228
	ds_bpermute_b32 v245, v173, v229
	s_waitcnt vmcnt(12)
	v_mfma_f32_32x32x16_bf16 v[16:31], v[8:11], v[0:3], 0
	ds_bpermute_b32 v88, v173, v230
	ds_bpermute_b32 v89, v173, v231
	ds_bpermute_b32 v246, v173, v232
	ds_bpermute_b32 v247, v173, v233
	ds_bpermute_b32 v248, v173, v234
	ds_bpermute_b32 v249, v173, v238
	ds_bpermute_b32 v250, v173, v237
	s_waitcnt vmcnt(11)
	v_mfma_f32_32x32x16_bf16 v[0:15], v[12:15], v[0:3], 0
	ds_bpermute_b32 v251, v173, v236
	ds_bpermute_b32 v252, v173, v235
	s_waitcnt lgkmcnt(3)
	v_max_u32_e32 v80, v80, v249
	s_waitcnt lgkmcnt(2)
	v_max_u32_e32 v85, v85, v250
	v_max_u32_e32 v89, v230, v89
	s_waitcnt lgkmcnt(1)
	v_max_u32_e32 v184, v187, v251
	v_max_u32_e32 v88, v231, v88
	s_waitcnt vmcnt(9)
	v_mfma_f32_32x32x16_bf16 v[48:63], v[64:67], v[68:71], v[48:63]
	s_waitcnt lgkmcnt(0)
	v_max_u32_e32 v64, v226, v252
	v_max_u32_e32 v65, v227, v248
	v_max_u32_e32 v66, v228, v247
	v_max_u32_e32 v67, v229, v246
	v_max_u32_e32 v185, v232, v245
	v_max_u32_e32 v187, v237, v240
	v_max_u32_e32 v226, v238, v239
	v_mfma_f32_32x32x16_bf16 v[0:15], v[188:191], v[68:71], v[0:15]
	v_max_u32_e32 v227, v80, v88
	v_min_u32_e32 v80, v80, v88
	v_max_u32_e32 v88, v85, v185
	v_min_u32_e32 v85, v85, v185
	s_waitcnt vmcnt(8)
	v_mfma_f32_32x32x16_bf16 v[48:63], v[198:201], v[202:205], v[48:63]
	s_waitcnt vmcnt(7)
	v_mfma_f32_32x32x16_bf16 v[32:47], v[90:93], v[68:71], v[32:47]
	v_max_u32_e32 v90, v233, v244
	v_max_u32_e32 v91, v234, v243
	v_max_u32_e32 v92, v235, v242
	v_max_u32_e32 v93, v236, v241
	s_waitcnt vmcnt(5)
	v_mfma_f32_32x32x16_bf16 v[0:15], v[76:79], v[202:205], v[0:15]
	s_waitcnt vmcnt(1)
	v_mfma_f32_32x32x16_bf16 v[48:63], v[94:97], v[214:217], v[48:63]
	v_mfma_f32_32x32x16_bf16 v[32:47], v[206:209], v[202:205], v[32:47]
	s_nop 10
	v_cmp_gt_i32_e32 vcc, 0, v48
	v_mfma_f32_32x32x16_bf16 v[0:15], v[72:75], v[214:217], v[0:15]
	v_not_b32_e32 v72, v48
	v_or_b32_e32 v73, 0x80000000, v48
	v_cndmask_b32_e32 v48, v73, v72, vcc
	v_not_b32_e32 v72, v49
	v_or_b32_e32 v73, 0x80000000, v49
	v_cmp_gt_i32_e32 vcc, 0, v49
	v_and_or_b32 v48, v48, s17, v100
	v_mfma_f32_32x32x16_bf16 v[16:31], v[180:183], v[68:71], v[16:31]
	v_cndmask_b32_e32 v49, v73, v72, vcc
	v_not_b32_e32 v72, v50
	v_or_b32_e32 v73, 0x80000000, v50
	v_cmp_gt_i32_e32 vcc, 0, v50
	v_and_or_b32 v49, v49, s17, v101
	v_max_u32_e32 v180, v184, v90
	v_cndmask_b32_e32 v50, v73, v72, vcc
	v_not_b32_e32 v72, v51
	v_or_b32_e32 v73, 0x80000000, v51
	v_cmp_gt_i32_e32 vcc, 0, v51
	s_waitcnt vmcnt(0)
; DI unsigned f2ord(float f) { const unsigned u = __float_as_uint(f); return (u & 0x80000000u) ? ~u : (u | 0x80000000u); }
; DI void peer_topk_phase(const bf16_t* __restrict__ qpk, const bf16_t* __restrict__ subk, int* __restrict__ eidx, float* __restrict__ gout) {
;     ...
;             for (int nb = 0; nb < 4; ++nb)
; #pragma unroll
;                 for (int i = 0; i < 16; ++i) {
;                     const int n = nb * 32 + (i & 3) + 8 * (i >> 2) + 4 * h;
;                     key[nb * 16 + i] = (f2ord(acc[nb][i]) & ~127u) | (unsigned)(127 - n);
;                 }
;             unsigned g0[16], g1[16], g2[16], g3[16];
; #pragma unroll
;             for (int i = 0; i < 16; ++i) { g0[i] = key[i]; g1[i] = key[16 + i]; g2[i] = key[32 + i]; g3[i] = key[48 + i]; }
; #pragma unroll
;             for (int n = 0; n < 63; ++n) { cex(g0[SORT16[n][0]], g0[SORT16[n][1]]); cex(g1[SORT16[n][0]], g1[SORT16[n][1]]); cex(g2[SORT16[n][0]], g2[SORT16[n][1]]); cex(g3[SORT16[n][0]], g3[SORT16[n][1]]); }
;             merge_top16(g0, g1); merge_top16(g2, g3); merge_top16(g0, g2);
	v_mfma_f32_32x32x16_bf16 v[32:47], v[218:221], v[214:217], v[32:47]
	v_and_or_b32 v50, v50, s17, v102
	v_cndmask_b32_e32 v51, v73, v72, vcc
	v_not_b32_e32 v72, v52
	v_or_b32_e32 v73, 0x80000000, v52
	v_cmp_gt_i32_e32 vcc, 0, v52
	v_and_or_b32 v51, v51, s17, v103
	v_min_u32_e32 v90, v184, v90
	v_cndmask_b32_e32 v52, v73, v72, vcc
	v_not_b32_e32 v72, v53
	v_or_b32_e32 v73, 0x80000000, v53
	v_cmp_gt_i32_e32 vcc, 0, v53
	v_mfma_f32_32x32x16_bf16 v[16:31], v[210:213], v[202:205], v[16:31]
	v_and_or_b32 v52, v52, s17, v104
	v_cndmask_b32_e32 v53, v73, v72, vcc
	v_not_b32_e32 v72, v54
	v_or_b32_e32 v73, 0x80000000, v54
	v_cmp_gt_i32_e32 vcc, 0, v54
	v_and_or_b32 v53, v53, s17, v105
	v_max_u32_e32 v181, v64, v91
	v_cndmask_b32_e32 v54, v73, v72, vcc
	v_not_b32_e32 v72, v55
	v_or_b32_e32 v73, 0x80000000, v55
	v_cmp_gt_i32_e32 vcc, 0, v55
	v_mfma_f32_32x32x16_bf16 v[16:31], v[222:225], v[214:217], v[16:31]
	v_and_or_b32 v54, v54, s17, v106
	v_cndmask_b32_e32 v55, v73, v72, vcc
	v_not_b32_e32 v72, v56
	v_or_b32_e32 v73, 0x80000000, v56
	v_cmp_gt_i32_e32 vcc, 0, v56
	v_and_or_b32 v55, v55, s17, v107
	v_min_u32_e32 v64, v64, v91
	v_cndmask_b32_e32 v56, v73, v72, vcc
	v_not_b32_e32 v72, v57
	v_or_b32_e32 v73, 0x80000000, v57
	v_cmp_gt_i32_e32 vcc, 0, v57
	v_and_or_b32 v56, v56, s17, v108
	v_max_u32_e32 v68, v65, v92
	v_cndmask_b32_e32 v57, v73, v72, vcc
	v_not_b32_e32 v72, v58
	v_or_b32_e32 v73, 0x80000000, v58
	v_cmp_gt_i32_e32 vcc, 0, v58
	v_and_or_b32 v57, v57, s17, v109
	v_min_u32_e32 v65, v65, v92
	v_cndmask_b32_e32 v58, v73, v72, vcc
	v_not_b32_e32 v72, v59
	v_or_b32_e32 v73, 0x80000000, v59
	v_cmp_gt_i32_e32 vcc, 0, v59
	v_and_or_b32 v58, v58, s17, v110
	v_max_u32_e32 v69, v66, v93
	v_cndmask_b32_e32 v59, v73, v72, vcc
	v_not_b32_e32 v72, v60
	v_or_b32_e32 v73, 0x80000000, v60
	v_cmp_gt_i32_e32 vcc, 0, v60
	v_and_or_b32 v59, v59, s17, v111
	v_min_u32_e32 v66, v66, v93
	v_cndmask_b32_e32 v60, v73, v72, vcc
	v_not_b32_e32 v72, v61
	v_or_b32_e32 v73, 0x80000000, v61
	v_cmp_gt_i32_e32 vcc, 0, v61
	v_and_or_b32 v60, v60, s17, v112
	v_max_u32_e32 v70, v67, v187
	v_cndmask_b32_e32 v61, v73, v72, vcc
	v_not_b32_e32 v72, v62
	v_or_b32_e32 v73, 0x80000000, v62
	v_cmp_gt_i32_e32 vcc, 0, v62
	v_and_or_b32 v61, v61, s17, v113
	v_min_u32_e32 v67, v67, v187
	v_cndmask_b32_e32 v62, v73, v72, vcc
	v_not_b32_e32 v72, v63
	v_or_b32_e32 v73, 0x80000000, v63
	v_cmp_gt_i32_e32 vcc, 0, v63
	v_and_or_b32 v62, v62, s17, v114
	v_max_u32_e32 v71, v89, v226
	v_cndmask_b32_e32 v63, v73, v72, vcc
	v_not_b32_e32 v72, v32
	v_or_b32_e32 v73, 0x80000000, v32
	v_cmp_gt_i32_e32 vcc, 0, v32
	v_and_or_b32 v63, v63, s17, v115
	v_min_u32_e32 v89, v89, v226
	v_cndmask_b32_e32 v32, v73, v72, vcc
	v_not_b32_e32 v72, v33
	v_or_b32_e32 v73, 0x80000000, v33
	v_cmp_gt_i32_e32 vcc, 0, v33
	v_and_or_b32 v32, v32, s17, v116
	v_max_u32_e32 v91, v227, v68
	v_cndmask_b32_e32 v33, v73, v72, vcc
	v_not_b32_e32 v72, v34
	v_or_b32_e32 v73, 0x80000000, v34
	v_cmp_gt_i32_e32 vcc, 0, v34
	v_and_or_b32 v33, v33, s17, v117
	v_min_u32_e32 v68, v227, v68
	v_cndmask_b32_e32 v34, v73, v72, vcc
	v_not_b32_e32 v72, v35
	v_or_b32_e32 v73, 0x80000000, v35
	v_cmp_gt_i32_e32 vcc, 0, v35
	v_and_or_b32 v34, v34, s17, v118
	v_max_u32_e32 v92, v88, v69
	v_cndmask_b32_e32 v35, v73, v72, vcc
	v_not_b32_e32 v72, v36
	v_or_b32_e32 v73, 0x80000000, v36
	v_cmp_gt_i32_e32 vcc, 0, v36
	v_and_or_b32 v35, v35, s17, v119
	v_min_u32_e32 v69, v88, v69
	v_cndmask_b32_e32 v36, v73, v72, vcc
	v_not_b32_e32 v72, v37
	v_or_b32_e32 v73, 0x80000000, v37
	v_cmp_gt_i32_e32 vcc, 0, v37
	v_and_or_b32 v36, v36, s17, v120
	v_max_u32_e32 v88, v180, v70
	v_cndmask_b32_e32 v37, v73, v72, vcc
	v_not_b32_e32 v72, v38
	v_or_b32_e32 v73, 0x80000000, v38
	v_cmp_gt_i32_e32 vcc, 0, v38
	v_and_or_b32 v37, v37, s17, v121
	v_min_u32_e32 v70, v180, v70
	v_cndmask_b32_e32 v38, v73, v72, vcc
	v_not_b32_e32 v72, v39
	v_or_b32_e32 v73, 0x80000000, v39
	v_cmp_gt_i32_e32 vcc, 0, v39
	v_and_or_b32 v38, v38, s17, v122
	v_max_u32_e32 v93, v181, v71
	v_cndmask_b32_e32 v39, v73, v72, vcc
	v_not_b32_e32 v72, v40
	v_or_b32_e32 v73, 0x80000000, v40
	v_cmp_gt_i32_e32 vcc, 0, v40
	v_and_or_b32 v39, v39, s17, v123
	v_min_u32_e32 v71, v181, v71
	v_cndmask_b32_e32 v40, v73, v72, vcc
	v_not_b32_e32 v72, v41
	v_or_b32_e32 v73, 0x80000000, v41
	v_cmp_gt_i32_e32 vcc, 0, v41
	v_and_or_b32 v40, v40, s17, v124
	v_max_u32_e32 v180, v80, v65
	v_cndmask_b32_e32 v41, v73, v72, vcc
	v_not_b32_e32 v72, v42
	v_or_b32_e32 v73, 0x80000000, v42
	v_cmp_gt_i32_e32 vcc, 0, v42
	v_and_or_b32 v41, v41, s17, v125
	v_min_u32_e32 v65, v80, v65
	v_cndmask_b32_e32 v42, v73, v72, vcc
	v_not_b32_e32 v72, v43
	v_or_b32_e32 v73, 0x80000000, v43
	v_cmp_gt_i32_e32 vcc, 0, v43
	v_and_or_b32 v42, v42, s17, v126
	v_max_u32_e32 v80, v85, v66
	v_cndmask_b32_e32 v43, v73, v72, vcc
	v_not_b32_e32 v72, v44
	v_or_b32_e32 v73, 0x80000000, v44
	v_cmp_gt_i32_e32 vcc, 0, v44
	v_and_or_b32 v43, v43, s17, v127
	v_min_u32_e32 v66, v85, v66
	v_cndmask_b32_e32 v44, v73, v72, vcc
	v_not_b32_e32 v72, v45
	v_or_b32_e32 v73, 0x80000000, v45
	v_cmp_gt_i32_e32 vcc, 0, v45
	v_and_or_b32 v44, v44, s17, v128
	v_max_u32_e32 v85, v90, v67
	v_cndmask_b32_e32 v45, v73, v72, vcc
	v_not_b32_e32 v72, v46
	v_or_b32_e32 v73, 0x80000000, v46
	v_cmp_gt_i32_e32 vcc, 0, v46
	v_and_or_b32 v45, v45, s17, v129
	v_min_u32_e32 v67, v90, v67
	v_cndmask_b32_e32 v46, v73, v72, vcc
	v_not_b32_e32 v72, v47
	v_or_b32_e32 v73, 0x80000000, v47
	v_cmp_gt_i32_e32 vcc, 0, v47
	v_and_or_b32 v46, v46, s17, v130
	v_max_u32_e32 v90, v64, v89
	v_cndmask_b32_e32 v47, v73, v72, vcc
	v_not_b32_e32 v72, v16
	v_or_b32_e32 v73, 0x80000000, v16
	v_cmp_gt_i32_e32 vcc, 0, v16
; DI unsigned f2ord(float f) { const unsigned u = __float_as_uint(f); return (u & 0x80000000u) ? ~u : (u | 0x80000000u); }
; DI void peer_topk_phase(const bf16_t* __restrict__ qpk, const bf16_t* __restrict__ subk, int* __restrict__ eidx, float* __restrict__ gout) {
;     ...
;             for (int nb = 0; nb < 4; ++nb)
; #pragma unroll
;                 for (int i = 0; i < 16; ++i) {
;                     const int n = nb * 32 + (i & 3) + 8 * (i >> 2) + 4 * h;
;                     key[nb * 16 + i] = (f2ord(acc[nb][i]) & ~127u) | (unsigned)(127 - n);
;                 }
;             unsigned g0[16], g1[16], g2[16], g3[16];
; #pragma unroll
;             for (int i = 0; i < 16; ++i) { g0[i] = key[i]; g1[i] = key[16 + i]; g2[i] = key[32 + i]; g3[i] = key[48 + i]; }
; #pragma unroll
;             for (int n = 0; n < 63; ++n) { cex(g0[SORT16[n][0]], g0[SORT16[n][1]]); cex(g1[SORT16[n][0]], g1[SORT16[n][1]]); cex(g2[SORT16[n][0]], g2[SORT16[n][1]]); cex(g3[SORT16[n][0]], g3[SORT16[n][1]]); }
;             merge_top16(g0, g1); merge_top16(g2, g3); merge_top16(g0, g2);
	v_and_or_b32 v47, v47, s17, v131
	v_min_u32_e32 v64, v64, v89
	v_cndmask_b32_e32 v16, v73, v72, vcc
	v_not_b32_e32 v72, v17
	v_or_b32_e32 v73, 0x80000000, v17
	v_cmp_gt_i32_e32 vcc, 0, v17
	v_and_or_b32 v16, v16, s17, v132
	v_max_u32_e32 v89, v91, v88
	v_cndmask_b32_e32 v17, v73, v72, vcc
	v_not_b32_e32 v72, v18
	v_or_b32_e32 v73, 0x80000000, v18
	v_cmp_gt_i32_e32 vcc, 0, v18
	v_and_or_b32 v17, v17, s17, v133
	v_min_u32_e32 v91, v91, v88
	v_cndmask_b32_e32 v18, v73, v72, vcc
	v_not_b32_e32 v72, v19
	v_or_b32_e32 v73, 0x80000000, v19
	v_cmp_gt_i32_e32 vcc, 0, v19
	v_and_or_b32 v18, v18, s17, v134
	v_max_u32_e32 v88, v92, v93
	v_cndmask_b32_e32 v19, v73, v72, vcc
	v_not_b32_e32 v72, v20
	v_or_b32_e32 v73, 0x80000000, v20
	v_cmp_gt_i32_e32 vcc, 0, v20
	v_and_or_b32 v19, v19, s17, v135
	v_min_u32_e32 v92, v92, v93
	v_cndmask_b32_e32 v20, v73, v72, vcc
	v_not_b32_e32 v72, v21
	v_or_b32_e32 v73, 0x80000000, v21
	v_cmp_gt_i32_e32 vcc, 0, v21
	v_and_or_b32 v20, v20, s17, v136
	v_max_u32_e32 v76, v68, v70
	v_cndmask_b32_e32 v21, v73, v72, vcc
	v_not_b32_e32 v72, v22
	v_or_b32_e32 v73, 0x80000000, v22
	v_cmp_gt_i32_e32 vcc, 0, v22
	v_and_or_b32 v21, v21, s17, v137
	v_min_u32_e32 v68, v68, v70
	v_cndmask_b32_e32 v22, v73, v72, vcc
	v_not_b32_e32 v72, v23
	v_or_b32_e32 v73, 0x80000000, v23
	v_cmp_gt_i32_e32 vcc, 0, v23
	v_and_or_b32 v22, v22, s17, v138
	v_max_u32_e32 v70, v69, v71
	v_cndmask_b32_e32 v23, v73, v72, vcc
	v_not_b32_e32 v72, v24
	v_or_b32_e32 v73, 0x80000000, v24
	v_cmp_gt_i32_e32 vcc, 0, v24
	v_and_or_b32 v23, v23, s17, v139
	v_min_u32_e32 v69, v69, v71
	v_cndmask_b32_e32 v24, v73, v72, vcc
	v_not_b32_e32 v72, v25
	v_or_b32_e32 v73, 0x80000000, v25
	v_cmp_gt_i32_e32 vcc, 0, v25
	v_and_or_b32 v24, v24, s17, v140
	v_max_u32_e32 v93, v180, v85
	v_cndmask_b32_e32 v25, v73, v72, vcc
	v_not_b32_e32 v72, v26
	v_or_b32_e32 v73, 0x80000000, v26
	v_cmp_gt_i32_e32 vcc, 0, v26
	v_and_or_b32 v25, v25, s17, v141
	v_min_u32_e32 v180, v180, v85
	v_cndmask_b32_e32 v26, v73, v72, vcc
	v_not_b32_e32 v72, v27
	v_or_b32_e32 v73, 0x80000000, v27
	v_cmp_gt_i32_e32 vcc, 0, v27
	v_and_or_b32 v26, v26, s17, v142
	v_max_u32_e32 v181, v80, v90
	v_cndmask_b32_e32 v27, v73, v72, vcc
	v_not_b32_e32 v72, v28
	v_or_b32_e32 v73, 0x80000000, v28
	v_cmp_gt_i32_e32 vcc, 0, v28
	v_and_or_b32 v27, v27, s17, v143
	v_min_u32_e32 v90, v80, v90
	v_cndmask_b32_e32 v28, v73, v72, vcc
	v_not_b32_e32 v72, v29
	v_or_b32_e32 v73, 0x80000000, v29
	v_cmp_gt_i32_e32 vcc, 0, v29
	v_and_or_b32 v28, v28, s17, v149
	v_max_u32_e32 v79, v76, v70
	v_cndmask_b32_e32 v29, v73, v72, vcc
	v_not_b32_e32 v72, v30
	v_or_b32_e32 v73, 0x80000000, v30
	v_cmp_gt_i32_e32 vcc, 0, v30
	v_and_or_b32 v29, v29, s17, v150
	v_min_u32_e32 v78, v76, v70
	v_cndmask_b32_e32 v30, v73, v72, vcc
	v_not_b32_e32 v72, v31
	v_or_b32_e32 v73, 0x80000000, v31
	v_cmp_gt_i32_e32 vcc, 0, v31
	v_and_or_b32 v30, v30, s17, v151
	v_max_u32_e32 v77, v68, v69
	v_cndmask_b32_e32 v31, v73, v72, vcc
	v_not_b32_e32 v72, v0
	v_or_b32_e32 v73, 0x80000000, v0
	v_cmp_gt_i32_e32 vcc, 0, v0
	v_and_or_b32 v31, v31, s17, v152
	v_min_u32_e32 v76, v68, v69
	v_cndmask_b32_e32 v0, v73, v72, vcc
	v_not_b32_e32 v72, v1
	v_or_b32_e32 v73, 0x80000000, v1
	v_cmp_gt_i32_e32 vcc, 0, v1
	v_and_or_b32 v0, v0, s17, v153
	v_max_u32_e32 v69, v180, v90
	v_cndmask_b32_e32 v1, v73, v72, vcc
	v_not_b32_e32 v72, v2
	v_or_b32_e32 v73, 0x80000000, v2
	v_cmp_gt_i32_e32 vcc, 0, v2
	v_and_or_b32 v1, v1, s17, v154
	v_min_u32_e32 v68, v180, v90
	v_cndmask_b32_e32 v2, v73, v72, vcc
	v_not_b32_e32 v72, v3
	v_or_b32_e32 v73, 0x80000000, v3
	v_cmp_gt_i32_e32 vcc, 0, v3
	v_and_or_b32 v2, v2, s17, v155
	v_max_u32_e32 v94, v65, v67
	v_cndmask_b32_e32 v3, v73, v72, vcc
	v_not_b32_e32 v72, v4
	v_or_b32_e32 v73, 0x80000000, v4
	v_cmp_gt_i32_e32 vcc, 0, v4
	v_and_or_b32 v3, v3, s17, v156
	v_min_u32_e32 v95, v65, v67
	v_cndmask_b32_e32 v4, v73, v72, vcc
	v_not_b32_e32 v72, v5
	v_or_b32_e32 v73, 0x80000000, v5
	v_cmp_gt_i32_e32 vcc, 0, v5
	v_and_or_b32 v4, v4, s17, v157
	v_max_u32_e32 v65, v66, v64
	v_cndmask_b32_e32 v5, v73, v72, vcc
	v_not_b32_e32 v72, v6
	v_or_b32_e32 v73, 0x80000000, v6
	v_cmp_gt_i32_e32 vcc, 0, v6
	v_and_or_b32 v5, v5, s17, v158
	v_min_u32_e32 v64, v66, v64
	v_cndmask_b32_e32 v6, v73, v72, vcc
	v_not_b32_e32 v72, v7
	v_or_b32_e32 v73, 0x80000000, v7
	v_cmp_gt_i32_e32 vcc, 0, v7
	v_and_or_b32 v6, v6, s17, v159
	v_max_u32_e32 v80, v89, v88
	v_cndmask_b32_e32 v7, v73, v72, vcc
	v_not_b32_e32 v72, v8
	v_or_b32_e32 v73, 0x80000000, v8
	v_cmp_gt_i32_e32 vcc, 0, v8
	v_and_or_b32 v7, v7, s17, v160
	v_min_u32_e32 v88, v89, v88
	v_cndmask_b32_e32 v8, v73, v72, vcc
	v_not_b32_e32 v72, v9
	v_or_b32_e32 v73, 0x80000000, v9
	v_cmp_gt_i32_e32 vcc, 0, v9
	v_and_or_b32 v8, v8, s17, v161
	v_max_u32_e32 v89, v91, v92
	v_cndmask_b32_e32 v9, v73, v72, vcc
	v_not_b32_e32 v72, v10
	v_or_b32_e32 v73, 0x80000000, v10
	v_cmp_gt_i32_e32 vcc, 0, v10
	v_and_or_b32 v9, v9, s17, v162
	v_min_u32_e32 v85, v91, v92
	v_cndmask_b32_e32 v10, v73, v72, vcc
	v_not_b32_e32 v72, v11
	v_or_b32_e32 v73, 0x80000000, v11
	v_cmp_gt_i32_e32 vcc, 0, v11
	v_and_or_b32 v10, v10, s17, v163
	v_max_u32_e32 v71, v93, v181
	v_cndmask_b32_e32 v11, v73, v72, vcc
	v_not_b32_e32 v72, v12
	v_or_b32_e32 v73, 0x80000000, v12
	v_cmp_gt_i32_e32 vcc, 0, v12
	v_and_or_b32 v11, v11, s17, v164
	v_min_u32_e32 v70, v93, v181
	v_cndmask_b32_e32 v12, v73, v72, vcc
	v_not_b32_e32 v72, v13
	v_or_b32_e32 v73, 0x80000000, v13
	v_cmp_gt_i32_e32 vcc, 0, v13
	v_and_or_b32 v12, v12, s17, v165
	v_max_u32_e32 v67, v94, v65
	v_cndmask_b32_e32 v13, v73, v72, vcc
	v_not_b32_e32 v72, v14
	v_or_b32_e32 v73, 0x80000000, v14
	v_cmp_gt_i32_e32 vcc, 0, v14
; DI void peer_topk_phase(const bf16_t* __restrict__ qpk, const bf16_t* __restrict__ subk, int* __restrict__ eidx, float* __restrict__ gout) {
;     ...
;             unsigned g0[16], g1[16], g2[16], g3[16];
; #pragma unroll
;             for (int i = 0; i < 16; ++i) { g0[i] = key[i]; g1[i] = key[16 + i]; g2[i] = key[32 + i]; g3[i] = key[48 + i]; }
; #pragma unroll
;             for (int n = 0; n < 63; ++n) { cex(g0[SORT16[n][0]], g0[SORT16[n][1]]); cex(g1[SORT16[n][0]], g1[SORT16[n][1]]); cex(g2[SORT16[n][0]], g2[SORT16[n][1]]); cex(g3[SORT16[n][0]], g3[SORT16[n][1]]); }
;             merge_top16(g0, g1); merge_top16(g2, g3); merge_top16(g0, g2);
	v_and_or_b32 v13, v13, s17, v166
	v_min_u32_e32 v66, v94, v65
	v_cndmask_b32_e32 v14, v73, v72, vcc
	v_not_b32_e32 v72, v15
	v_or_b32_e32 v73, 0x80000000, v15
	v_cmp_gt_i32_e32 vcc, 0, v15
	v_and_or_b32 v14, v14, s17, v167
	v_max_u32_e32 v65, v95, v64
	v_cndmask_b32_e32 v15, v73, v72, vcc
	v_max_u32_e32 v72, v48, v49
	v_min_u32_e32 v48, v48, v49
	v_max_u32_e32 v49, v32, v33
	v_min_u32_e32 v32, v32, v33
	v_max_u32_e32 v33, v16, v17
	v_min_u32_e32 v16, v16, v17
	v_max_u32_e32 v17, v0, v1
	v_min_u32_e32 v0, v0, v1
	v_max_u32_e32 v1, v50, v51
	v_min_u32_e32 v50, v50, v51
	v_max_u32_e32 v51, v34, v35
	v_min_u32_e32 v34, v34, v35
	v_max_u32_e32 v35, v18, v19
	v_min_u32_e32 v18, v18, v19
	v_max_u32_e32 v19, v2, v3
	v_min_u32_e32 v2, v2, v3
	v_max_u32_e32 v3, v72, v1
	v_min_u32_e32 v1, v72, v1
	v_max_u32_e32 v72, v49, v51
	v_min_u32_e32 v49, v49, v51
	v_max_u32_e32 v51, v33, v35
	v_min_u32_e32 v33, v33, v35
	v_max_u32_e32 v35, v17, v19
	v_min_u32_e32 v17, v17, v19
	v_max_u32_e32 v19, v48, v50
	v_min_u32_e32 v48, v48, v50
	v_max_u32_e32 v50, v32, v34
	v_min_u32_e32 v32, v32, v34
	v_max_u32_e32 v34, v16, v18
	v_min_u32_e32 v16, v16, v18
	v_max_u32_e32 v18, v0, v2
	v_min_u32_e32 v0, v0, v2
	v_max_u32_e32 v2, v19, v1
	v_min_u32_e32 v1, v19, v1
	v_max_u32_e32 v19, v50, v49
	v_min_u32_e32 v49, v50, v49
	v_max_u32_e32 v50, v34, v33
	v_min_u32_e32 v33, v34, v33
	v_max_u32_e32 v34, v18, v17
	v_min_u32_e32 v17, v18, v17
	v_max_u32_e32 v18, v52, v53
	v_min_u32_e32 v52, v52, v53
	v_max_u32_e32 v53, v36, v37
	v_min_u32_e32 v36, v36, v37
	v_max_u32_e32 v37, v20, v21
	v_min_u32_e32 v20, v20, v21
	v_max_u32_e32 v21, v4, v5
	v_min_u32_e32 v4, v4, v5
	v_max_u32_e32 v5, v54, v55
	v_min_u32_e32 v54, v54, v55
	v_max_u32_e32 v55, v38, v39
	v_min_u32_e32 v38, v38, v39
	v_max_u32_e32 v39, v22, v23
	v_min_u32_e32 v22, v22, v23
	v_max_u32_e32 v23, v6, v7
	v_min_u32_e32 v6, v6, v7
	v_max_u32_e32 v7, v18, v5
	v_min_u32_e32 v5, v18, v5
	v_max_u32_e32 v18, v53, v55
	v_min_u32_e32 v53, v53, v55
	v_max_u32_e32 v55, v37, v39
	v_min_u32_e32 v37, v37, v39
	v_max_u32_e32 v39, v21, v23
	v_min_u32_e32 v21, v21, v23
	v_max_u32_e32 v23, v52, v54
	v_min_u32_e32 v52, v52, v54
	v_max_u32_e32 v54, v36, v38
	v_min_u32_e32 v36, v36, v38
	v_max_u32_e32 v38, v20, v22
	v_min_u32_e32 v20, v20, v22
	v_max_u32_e32 v22, v4, v6
	v_min_u32_e32 v4, v4, v6
	v_max_u32_e32 v6, v23, v5
	v_min_u32_e32 v5, v23, v5
	v_max_u32_e32 v23, v54, v53
	v_min_u32_e32 v53, v54, v53
	v_max_u32_e32 v54, v38, v37
	v_min_u32_e32 v37, v38, v37
	v_max_u32_e32 v38, v22, v21
	v_min_u32_e32 v21, v22, v21
	v_max_u32_e32 v22, v3, v7
	v_min_u32_e32 v3, v3, v7
	v_max_u32_e32 v7, v72, v18
	v_min_u32_e32 v18, v72, v18
	v_max_u32_e32 v72, v51, v55
	v_min_u32_e32 v51, v51, v55
	v_max_u32_e32 v55, v35, v39
	v_min_u32_e32 v35, v35, v39
	v_max_u32_e32 v39, v1, v5
	v_min_u32_e32 v1, v1, v5
	v_max_u32_e32 v5, v49, v53
	v_min_u32_e32 v49, v49, v53
	v_max_u32_e32 v53, v33, v37
	v_min_u32_e32 v33, v33, v37
	v_max_u32_e32 v37, v17, v21
	v_min_u32_e32 v17, v17, v21
	v_max_u32_e32 v21, v39, v3
	v_min_u32_e32 v3, v39, v3
	v_max_u32_e32 v39, v5, v18
	v_min_u32_e32 v5, v5, v18
	v_max_u32_e32 v18, v53, v51
	v_min_u32_e32 v51, v53, v51
	v_max_u32_e32 v53, v37, v35
	v_min_u32_e32 v35, v37, v35
	v_max_u32_e32 v37, v2, v6
	v_min_u32_e32 v2, v2, v6
	v_max_u32_e32 v6, v19, v23
	v_min_u32_e32 v19, v19, v23
	v_max_u32_e32 v23, v50, v54
	v_min_u32_e32 v50, v50, v54
	v_max_u32_e32 v54, v34, v38
	v_min_u32_e32 v34, v34, v38
	v_max_u32_e32 v38, v48, v52
	v_min_u32_e32 v48, v48, v52
	v_max_u32_e32 v52, v32, v36
	v_min_u32_e32 v32, v32, v36
	v_max_u32_e32 v36, v16, v20
	v_min_u32_e32 v16, v16, v20
	v_max_u32_e32 v20, v0, v4
	v_min_u32_e32 v0, v0, v4
	v_max_u32_e32 v4, v38, v2
	v_min_u32_e32 v2, v38, v2
	v_max_u32_e32 v38, v52, v19
	v_min_u32_e32 v19, v52, v19
	v_max_u32_e32 v52, v36, v50
	v_min_u32_e32 v36, v36, v50
	v_max_u32_e32 v50, v20, v34
	v_min_u32_e32 v20, v20, v34
	v_max_u32_e32 v34, v37, v21
	v_min_u32_e32 v21, v37, v21
	v_max_u32_e32 v37, v6, v39
	v_min_u32_e32 v6, v6, v39
	v_max_u32_e32 v39, v23, v18
	v_min_u32_e32 v18, v23, v18
	v_max_u32_e32 v23, v54, v53
	v_min_u32_e32 v53, v54, v53
	v_max_u32_e32 v54, v4, v3
	v_min_u32_e32 v3, v4, v3
	v_max_u32_e32 v4, v38, v5
	v_min_u32_e32 v5, v38, v5
	v_max_u32_e32 v38, v52, v51
	v_min_u32_e32 v51, v52, v51
	v_max_u32_e32 v52, v50, v35
	v_min_u32_e32 v35, v50, v35
	v_max_u32_e32 v50, v2, v1
	v_min_u32_e32 v1, v2, v1
	v_max_u32_e32 v2, v19, v49
	v_min_u32_e32 v19, v19, v49
	v_max_u32_e32 v49, v36, v33
	v_min_u32_e32 v33, v36, v33
	v_max_u32_e32 v36, v20, v17
	v_min_u32_e32 v17, v20, v17
	v_max_u32_e32 v20, v56, v57
	v_min_u32_e32 v56, v56, v57
	v_max_u32_e32 v57, v40, v41
	v_min_u32_e32 v40, v40, v41
	v_max_u32_e32 v41, v24, v25
	v_min_u32_e32 v24, v24, v25
	v_max_u32_e32 v25, v8, v9
	v_min_u32_e32 v8, v8, v9
	v_max_u32_e32 v9, v58, v59
	v_min_u32_e32 v58, v58, v59
	v_max_u32_e32 v59, v42, v43
	v_min_u32_e32 v42, v42, v43
	v_max_u32_e32 v43, v26, v27
	v_min_u32_e32 v26, v26, v27
	v_max_u32_e32 v27, v10, v11
	v_min_u32_e32 v10, v10, v11
	v_and_or_b32 v15, v15, s17, v168
	v_max_u32_e32 v11, v20, v9
	v_min_u32_e32 v9, v20, v9
	v_max_u32_e32 v20, v57, v59
	v_min_u32_e32 v57, v57, v59
	v_max_u32_e32 v59, v41, v43
	v_min_u32_e32 v41, v41, v43
	v_max_u32_e32 v43, v25, v27
	v_min_u32_e32 v25, v25, v27
	v_max_u32_e32 v27, v56, v58
	v_min_u32_e32 v56, v56, v58
	v_max_u32_e32 v58, v40, v42
	v_min_u32_e32 v40, v40, v42
	v_max_u32_e32 v42, v24, v26
	v_min_u32_e32 v24, v24, v26
	v_max_u32_e32 v26, v8, v10
	v_min_u32_e32 v8, v8, v10
	v_max_u32_e32 v10, v27, v9
	v_min_u32_e32 v9, v27, v9
	v_max_u32_e32 v27, v58, v57
; DI void peer_topk_phase(const bf16_t* __restrict__ qpk, const bf16_t* __restrict__ subk, int* __restrict__ eidx, float* __restrict__ gout) {
;     ...
; #pragma unroll
;             for (int n = 0; n < 63; ++n) { cex(g0[SORT16[n][0]], g0[SORT16[n][1]]); cex(g1[SORT16[n][0]], g1[SORT16[n][1]]); cex(g2[SORT16[n][0]], g2[SORT16[n][1]]); cex(g3[SORT16[n][0]], g3[SORT16[n][1]]); }
;             merge_top16(g0, g1); merge_top16(g2, g3); merge_top16(g0, g2);
;             unsigned pb[16];
; #pragma unroll
;             for (int i = 0; i < 16; ++i) pb[i] = (unsigned)__shfl_xor((int)g0[i], 32);
;             merge_top16(g0, pb);
	v_min_u32_e32 v57, v58, v57
	v_max_u32_e32 v58, v42, v41
	v_min_u32_e32 v41, v42, v41
	v_max_u32_e32 v42, v26, v25
	v_min_u32_e32 v25, v26, v25
	v_max_u32_e32 v26, v60, v61
	v_min_u32_e32 v60, v60, v61
	v_max_u32_e32 v61, v44, v45
	v_min_u32_e32 v44, v44, v45
	v_max_u32_e32 v45, v28, v29
	v_min_u32_e32 v28, v28, v29
	v_max_u32_e32 v29, v12, v13
	v_min_u32_e32 v12, v12, v13
	v_max_u32_e32 v13, v62, v63
	v_min_u32_e32 v62, v62, v63
	v_max_u32_e32 v63, v46, v47
	v_min_u32_e32 v46, v46, v47
	v_max_u32_e32 v47, v30, v31
	v_min_u32_e32 v30, v30, v31
	v_max_u32_e32 v31, v14, v15
	v_min_u32_e32 v14, v14, v15
	v_max_u32_e32 v15, v26, v13
	v_min_u32_e32 v13, v26, v13
	v_max_u32_e32 v26, v61, v63
	v_min_u32_e32 v61, v61, v63
	v_max_u32_e32 v63, v45, v47
	v_min_u32_e32 v45, v45, v47
	v_max_u32_e32 v47, v29, v31
	v_min_u32_e32 v29, v29, v31
	v_max_u32_e32 v31, v60, v62
	v_min_u32_e32 v60, v60, v62
	v_max_u32_e32 v62, v44, v46
	v_min_u32_e32 v44, v44, v46
	v_max_u32_e32 v46, v28, v30
	v_min_u32_e32 v28, v28, v30
	v_max_u32_e32 v30, v12, v14
	v_min_u32_e32 v12, v12, v14
	v_max_u32_e32 v14, v31, v13
	v_min_u32_e32 v13, v31, v13
	v_max_u32_e32 v31, v62, v61
	v_min_u32_e32 v61, v62, v61
	v_max_u32_e32 v62, v46, v45
	v_min_u32_e32 v45, v46, v45
	v_max_u32_e32 v46, v30, v29
	v_min_u32_e32 v29, v30, v29
	v_max_u32_e32 v30, v11, v15
	v_min_u32_e32 v11, v11, v15
	v_max_u32_e32 v15, v20, v26
	v_min_u32_e32 v20, v20, v26
	v_max_u32_e32 v26, v59, v63
	v_min_u32_e32 v59, v59, v63
	v_max_u32_e32 v63, v43, v47
	v_min_u32_e32 v43, v43, v47
	v_max_u32_e32 v47, v9, v13
	v_min_u32_e32 v9, v9, v13
	v_max_u32_e32 v13, v57, v61
	v_min_u32_e32 v57, v57, v61
	v_max_u32_e32 v61, v41, v45
	v_min_u32_e32 v41, v41, v45
	v_max_u32_e32 v45, v25, v29
	v_min_u32_e32 v25, v25, v29
	v_max_u32_e32 v29, v47, v11
	v_min_u32_e32 v11, v47, v11
	v_max_u32_e32 v47, v13, v20
	v_min_u32_e32 v13, v13, v20
	v_max_u32_e32 v20, v61, v59
	v_min_u32_e32 v59, v61, v59
	v_max_u32_e32 v61, v45, v43
	v_min_u32_e32 v43, v45, v43
	v_max_u32_e32 v45, v10, v14
	v_min_u32_e32 v10, v10, v14
	v_max_u32_e32 v14, v27, v31
	v_min_u32_e32 v27, v27, v31
	v_max_u32_e32 v31, v58, v62
	v_min_u32_e32 v58, v58, v62
	v_max_u32_e32 v62, v42, v46
	v_min_u32_e32 v42, v42, v46
	v_max_u32_e32 v46, v56, v60
	v_min_u32_e32 v56, v56, v60
	v_max_u32_e32 v60, v40, v44
	v_min_u32_e32 v40, v40, v44
	v_max_u32_e32 v44, v24, v28
	v_min_u32_e32 v24, v24, v28
	v_max_u32_e32 v28, v8, v12
	v_min_u32_e32 v8, v8, v12
	v_max_u32_e32 v12, v46, v10
	v_min_u32_e32 v10, v46, v10
	v_max_u32_e32 v46, v60, v27
	v_min_u32_e32 v27, v60, v27
	v_max_u32_e32 v60, v44, v58
	v_min_u32_e32 v44, v44, v58
	v_max_u32_e32 v58, v28, v42
	v_min_u32_e32 v28, v28, v42
	v_max_u32_e32 v42, v45, v29
	v_min_u32_e32 v29, v45, v29
	v_max_u32_e32 v45, v14, v47
	v_min_u32_e32 v14, v14, v47
	v_max_u32_e32 v47, v31, v20
	v_min_u32_e32 v20, v31, v20
	v_max_u32_e32 v31, v62, v61
	v_min_u32_e32 v61, v62, v61
	v_max_u32_e32 v62, v12, v11
	v_min_u32_e32 v11, v12, v11
	v_max_u32_e32 v12, v46, v13
	v_min_u32_e32 v13, v46, v13
	v_max_u32_e32 v46, v60, v59
	v_min_u32_e32 v59, v60, v59
	v_max_u32_e32 v60, v58, v43
	v_min_u32_e32 v43, v58, v43
	v_max_u32_e32 v58, v10, v9
	v_min_u32_e32 v9, v10, v9
	v_max_u32_e32 v10, v27, v57
	v_min_u32_e32 v27, v27, v57
	v_max_u32_e32 v57, v44, v41
	v_min_u32_e32 v41, v44, v41
	v_max_u32_e32 v44, v28, v25
	v_min_u32_e32 v25, v28, v25
	v_min_u32_e32 v28, v22, v30
	v_min_u32_e32 v73, v7, v15
	v_min_u32_e32 v74, v72, v26
	v_min_u32_e32 v75, v55, v63
	v_max_u32_e32 v90, v3, v11
	v_min_u32_e32 v3, v3, v11
	v_max_u32_e32 v11, v5, v13
	v_min_u32_e32 v5, v5, v13
	v_max_u32_e32 v13, v51, v59
	v_min_u32_e32 v51, v51, v59
	v_max_u32_e32 v59, v35, v43
	v_min_u32_e32 v35, v35, v43
	v_max_u32_e32 v43, v90, v28
	v_min_u32_e32 v28, v90, v28
	v_max_u32_e32 v90, v11, v73
	v_min_u32_e32 v11, v11, v73
	v_max_u32_e32 v73, v13, v74
	v_min_u32_e32 v13, v13, v74
	v_max_u32_e32 v74, v59, v75
	v_min_u32_e32 v59, v59, v75
	v_max_u32_e32 v75, v21, v29
	v_min_u32_e32 v21, v21, v29
	v_max_u32_e32 v29, v6, v14
	v_min_u32_e32 v6, v6, v14
	v_max_u32_e32 v14, v18, v20
	v_min_u32_e32 v18, v18, v20
	v_max_u32_e32 v20, v53, v61
	v_min_u32_e32 v53, v53, v61
	v_max_u32_e32 v61, v1, v9
	v_min_u32_e32 v1, v1, v9
	v_max_u32_e32 v9, v19, v27
	v_min_u32_e32 v19, v19, v27
	v_max_u32_e32 v27, v33, v41
	v_min_u32_e32 v33, v33, v41
	v_max_u32_e32 v41, v17, v25
	v_min_u32_e32 v17, v17, v25
	v_max_u32_e32 v25, v61, v21
	v_min_u32_e32 v21, v61, v21
	v_max_u32_e32 v61, v9, v6
	v_min_u32_e32 v6, v9, v6
	v_max_u32_e32 v9, v27, v18
	v_min_u32_e32 v18, v27, v18
	v_max_u32_e32 v27, v41, v53
	v_min_u32_e32 v41, v41, v53
	v_max_u32_e32 v53, v75, v43
	v_min_u32_e32 v43, v75, v43
	v_max_u32_e32 v75, v29, v90
	v_min_u32_e32 v29, v29, v90
	v_max_u32_e32 v90, v14, v73
	v_min_u32_e32 v14, v14, v73
	v_max_u32_e32 v73, v20, v74
	v_min_u32_e32 v20, v20, v74
	v_max_u32_e32 v74, v25, v28
	v_min_u32_e32 v25, v25, v28
	v_max_u32_e32 v28, v61, v11
	v_min_u32_e32 v11, v61, v11
	v_max_u32_e32 v61, v9, v13
	v_min_u32_e32 v9, v9, v13
	v_max_u32_e32 v13, v27, v59
	v_min_u32_e32 v27, v27, v59
	v_max_u32_e32 v59, v21, v3
	v_min_u32_e32 v3, v21, v3
	v_max_u32_e32 v21, v6, v5
	v_min_u32_e32 v5, v6, v5
	v_max_u32_e32 v6, v18, v51
	v_min_u32_e32 v18, v18, v51
	v_max_u32_e32 v51, v41, v35
	v_min_u32_e32 v35, v41, v35
	v_max_u32_e32 v41, v34, v42
	v_min_u32_e32 v34, v34, v42
	v_max_u32_e32 v42, v37, v45
	v_min_u32_e32 v37, v37, v45
	v_max_u32_e32 v45, v39, v47
	v_min_u32_e32 v39, v39, v47
	v_max_u32_e32 v47, v23, v31
	v_min_u32_e32 v23, v23, v31
	v_max_u32_e32 v31, v50, v58
	v_min_u32_e32 v50, v50, v58
	v_max_u32_e32 v58, v2, v10
; DI void peer_topk_phase(const bf16_t* __restrict__ qpk, const bf16_t* __restrict__ subk, int* __restrict__ eidx, float* __restrict__ gout) {
;     ...
;             merge_top16(g0, g1); merge_top16(g2, g3); merge_top16(g0, g2);
;             unsigned pb[16];
; #pragma unroll
;             for (int i = 0; i < 16; ++i) pb[i] = (unsigned)__shfl_xor((int)g0[i], 32);
;             merge_top16(g0, pb);
	v_min_u32_e32 v2, v2, v10
	v_max_u32_e32 v10, v49, v57
	v_min_u32_e32 v49, v49, v57
	v_max_u32_e32 v57, v36, v44
	v_min_u32_e32 v36, v36, v44
	v_max_u32_e32 v44, v31, v34
	v_min_u32_e32 v31, v31, v34
	v_max_u32_e32 v34, v58, v37
	v_min_u32_e32 v37, v58, v37
	v_max_u32_e32 v58, v10, v39
	v_min_u32_e32 v10, v10, v39
	v_max_u32_e32 v39, v57, v23
	v_min_u32_e32 v23, v57, v23
	v_max_u32_e32 v57, v54, v62
	v_min_u32_e32 v54, v54, v62
	v_max_u32_e32 v62, v4, v12
	v_min_u32_e32 v4, v4, v12
	v_max_u32_e32 v12, v38, v46
	v_min_u32_e32 v38, v38, v46
	v_max_u32_e32 v46, v52, v60
	v_min_u32_e32 v52, v52, v60
	v_max_u32_e32 v60, v48, v56
	v_min_u32_e32 v48, v48, v56
	v_max_u32_e32 v56, v32, v40
	v_min_u32_e32 v32, v32, v40
	v_max_u32_e32 v40, v16, v24
	v_min_u32_e32 v16, v16, v24
	v_max_u32_e32 v24, v0, v8
	v_min_u32_e32 v0, v0, v8
	v_max_u32_e32 v8, v60, v54
	v_min_u32_e32 v54, v60, v54
	v_max_u32_e32 v60, v56, v4
	v_min_u32_e32 v4, v56, v4
	v_max_u32_e32 v56, v40, v38
	v_min_u32_e32 v38, v40, v38
	v_max_u32_e32 v40, v24, v52
	v_min_u32_e32 v24, v24, v52
	v_max_u32_e32 v52, v57, v44
	v_min_u32_e32 v44, v57, v44
	v_max_u32_e32 v57, v62, v34
	v_min_u32_e32 v34, v62, v34
	v_max_u32_e32 v62, v12, v58
	v_min_u32_e32 v12, v12, v58
	v_max_u32_e32 v58, v46, v39
	v_min_u32_e32 v39, v46, v39
	v_max_u32_e32 v46, v8, v31
	v_min_u32_e32 v8, v8, v31
	v_max_u32_e32 v31, v60, v37
	v_min_u32_e32 v37, v60, v37
	v_max_u32_e32 v60, v56, v10
	v_min_u32_e32 v10, v56, v10
	v_max_u32_e32 v56, v40, v23
	v_min_u32_e32 v23, v40, v23
	v_max_u32_e32 v40, v54, v50
	v_min_u32_e32 v50, v54, v50
	v_max_u32_e32 v54, v4, v2
	v_min_u32_e32 v2, v4, v2
	v_max_u32_e32 v4, v38, v49
	v_min_u32_e32 v38, v38, v49
	v_max_u32_e32 v49, v24, v36
	v_min_u32_e32 v24, v24, v36
	v_min_u32_e32 v64, v95, v64
	v_min_u32_e32 v36, v41, v53
	v_min_u32_e32 v91, v42, v75
	v_min_u32_e32 v92, v45, v90
	v_min_u32_e32 v93, v47, v73
	v_min_u32_e32 v94, v52, v43
	v_min_u32_e32 v95, v57, v29
	v_min_u32_e32 v96, v62, v14
	v_min_u32_e32 v97, v58, v20
	v_min_u32_e32 v180, v44, v74
	v_min_u32_e32 v181, v34, v28
	v_min_u32_e32 v182, v12, v61
	v_min_u32_e32 v183, v39, v13
	v_min_u32_e32 v184, v46, v25
	v_min_u32_e32 v185, v31, v11
	v_min_u32_e32 v187, v60, v9
	v_min_u32_e32 v188, v56, v27
	v_min_u32_e32 v189, v8, v59
	v_min_u32_e32 v190, v37, v21
	v_min_u32_e32 v191, v10, v6
	v_min_u32_e32 v198, v23, v51
	v_min_u32_e32 v199, v40, v3
	v_min_u32_e32 v200, v54, v5
	v_min_u32_e32 v201, v4, v18
	v_min_u32_e32 v202, v49, v35
	v_min_u32_e32 v203, v50, v1
	v_min_u32_e32 v204, v2, v19
	v_min_u32_e32 v205, v38, v33
	v_min_u32_e32 v206, v24, v17
	v_max3_u32 v22, v22, v30, v32
	v_max3_u32 v30, v41, v53, v204
	v_max3_u32 v2, v36, v2, v19
	v_max3_u32 v19, v52, v43, v200
	v_max3_u32 v5, v94, v54, v5
	v_max3_u32 v32, v44, v74, v190
	v_max3_u32 v21, v180, v37, v21
	v_max3_u32 v25, v46, v25, v185
	v_max3_u32 v11, v184, v31, v11
	v_max3_u32 v8, v8, v59, v181
	v_max3_u32 v28, v189, v34, v28
	v_max3_u32 v3, v40, v3, v95
	v_max3_u32 v29, v199, v57, v29
	v_max3_u32 v1, v50, v1, v91
	v_max3_u32 v31, v203, v42, v75
	v_max3_u32 v7, v48, v7, v15
	v_max3_u32 v0, v72, v26, v0
	v_max3_u32 v26, v45, v90, v206
	v_max3_u32 v17, v92, v24, v17
	v_max3_u32 v14, v62, v14, v202
	v_max3_u32 v24, v96, v49, v35
	v_max3_u32 v12, v12, v61, v198
	v_max3_u32 v23, v182, v23, v51
	v_max3_u32 v9, v60, v9, v188
	v_max3_u32 v27, v187, v56, v27
	v_max3_u32 v6, v10, v6, v183
	v_max3_u32 v10, v191, v39, v13
	v_max3_u32 v4, v4, v18, v97
	v_max3_u32 v13, v201, v58, v20
	v_max3_u32 v18, v38, v33, v93
	v_max3_u32 v20, v205, v47, v73
	v_max3_u32 v16, v16, v55, v63
	v_max_u32_e32 v15, v22, v11
	v_min_u32_e32 v11, v22, v11
	v_max_u32_e32 v22, v30, v8
	v_min_u32_e32 v8, v30, v8
	v_max_u32_e32 v30, v2, v28
	v_min_u32_e32 v2, v2, v28
	v_max_u32_e32 v28, v19, v3
	v_min_u32_e32 v3, v19, v3
	v_max_u32_e32 v19, v5, v29
	v_min_u32_e32 v5, v5, v29
	v_max_u32_e32 v29, v32, v1
	v_min_u32_e32 v1, v32, v1
	v_max_u32_e32 v32, v21, v31
	v_min_u32_e32 v21, v21, v31
	v_max_u32_e32 v31, v25, v7
	v_min_u32_e32 v7, v25, v7
	v_max_u32_e32 v33, v0, v27
	v_min_u32_e32 v0, v0, v27
	v_max_u32_e32 v27, v26, v6
	v_min_u32_e32 v6, v26, v6
	v_max_u32_e32 v26, v17, v10
	v_min_u32_e32 v10, v17, v10
	v_max_u32_e32 v17, v14, v4
	v_min_u32_e32 v4, v14, v4
	v_max_u32_e32 v14, v24, v13
	v_min_u32_e32 v13, v24, v13
	v_max_u32_e32 v24, v12, v18
	v_min_u32_e32 v12, v12, v18
	v_max_u32_e32 v18, v23, v20
	v_min_u32_e32 v20, v23, v20
	v_max_u32_e32 v23, v9, v16
	v_min_u32_e32 v9, v9, v16
	v_max_u32_e32 v25, v15, v19
	v_min_u32_e32 v15, v15, v19
	v_max_u32_e32 v19, v22, v29
	v_min_u32_e32 v22, v22, v29
	v_max_u32_e32 v29, v30, v32
	v_min_u32_e32 v30, v30, v32
	v_max_u32_e32 v32, v28, v31
	v_min_u32_e32 v28, v28, v31
	v_max_u32_e32 v31, v11, v5
	v_min_u32_e32 v5, v11, v5
	v_max_u32_e32 v11, v8, v1
	v_min_u32_e32 v1, v8, v1
	v_max_u32_e32 v8, v2, v21
	v_min_u32_e32 v2, v2, v21
	v_max_u32_e32 v21, v3, v7
	v_min_u32_e32 v3, v3, v7
	v_max_u32_e32 v16, v33, v14
	v_min_u32_e32 v14, v33, v14
	v_max_u32_e32 v33, v27, v24
	v_min_u32_e32 v24, v27, v24
	v_max_u32_e32 v27, v26, v18
	v_min_u32_e32 v18, v26, v18
	v_max_u32_e32 v26, v17, v23
	v_min_u32_e32 v17, v17, v23
	v_max_u32_e32 v23, v0, v13
	v_min_u32_e32 v0, v0, v13
	v_max_u32_e32 v13, v6, v12
	v_min_u32_e32 v6, v6, v12
	v_max_u32_e32 v12, v10, v20
	v_min_u32_e32 v10, v10, v20
	v_max_u32_e32 v20, v4, v9
	v_min_u32_e32 v4, v4, v9
	v_max_u32_e32 v7, v25, v29
	v_min_u32_e32 v25, v25, v29
	v_max_u32_e32 v29, v19, v32
	v_min_u32_e32 v19, v19, v32
	v_max_u32_e32 v32, v15, v30
	v_min_u32_e32 v15, v15, v30
	v_max_u32_e32 v30, v22, v28
	v_min_u32_e32 v22, v22, v28
	v_max_u32_e32 v28, v31, v8
; DI void peer_topk_phase(const bf16_t* __restrict__ qpk, const bf16_t* __restrict__ subk, int* __restrict__ eidx, float* __restrict__ gout) {
;     ...
;             merge_top16(g0, g1); merge_top16(g2, g3); merge_top16(g0, g2);
;             unsigned pb[16];
; #pragma unroll
;             for (int i = 0; i < 16; ++i) pb[i] = (unsigned)__shfl_xor((int)g0[i], 32);
;             merge_top16(g0, pb);
; #pragma unroll
;             for (int i = 0; i < 16; ++i) top[c][i] = g0[i];
	v_min_u32_e32 v8, v31, v8
	v_max_u32_e32 v31, v11, v21
	v_min_u32_e32 v11, v11, v21
	v_max_u32_e32 v21, v5, v2
	v_min_u32_e32 v2, v5, v2
	v_max_u32_e32 v5, v1, v3
	v_min_u32_e32 v1, v1, v3
	v_max_u32_e32 v9, v16, v27
	v_min_u32_e32 v16, v16, v27
	v_max_u32_e32 v27, v33, v26
	v_min_u32_e32 v26, v33, v26
	v_max_u32_e32 v33, v14, v18
	v_min_u32_e32 v14, v14, v18
	v_max_u32_e32 v18, v24, v17
	v_min_u32_e32 v17, v24, v17
	v_max_u32_e32 v24, v23, v12
	v_min_u32_e32 v12, v23, v12
	v_max_u32_e32 v23, v13, v20
	v_min_u32_e32 v13, v13, v20
	v_max_u32_e32 v20, v0, v10
	v_min_u32_e32 v0, v0, v10
	v_max_u32_e32 v10, v6, v4
	v_min_u32_e32 v4, v6, v4
	v_min_u32_e32 v3, v7, v29
	v_min_u32_e32 v34, v25, v19
	v_min_u32_e32 v36, v32, v30
	v_min_u32_e32 v37, v15, v22
	v_min_u32_e32 v40, v28, v31
	v_min_u32_e32 v41, v8, v11
	v_min_u32_e32 v42, v21, v5
	v_min_u32_e32 v43, v2, v1
	v_min_u32_e32 v6, v9, v27
	v_min_u32_e32 v35, v16, v26
	v_min_u32_e32 v38, v33, v18
	v_min_u32_e32 v39, v14, v17
	v_min_u32_e32 v44, v24, v23
	v_min_u32_e32 v45, v12, v13
	v_min_u32_e32 v46, v20, v10
	v_min_u32_e32 v47, v0, v4
	v_max3_u32 v7, v7, v29, v47
	v_max3_u32 v0, v3, v0, v4
	v_max3_u32 v3, v25, v19, v46
	v_max3_u32 v4, v34, v20, v10
	v_max3_u32 v10, v32, v30, v45
	v_max3_u32 v12, v36, v12, v13
	v_max3_u32 v13, v15, v22, v44
	v_max3_u32 v15, v37, v24, v23
	v_max3_u32 v19, v28, v31, v39
	v_max3_u32 v14, v40, v14, v17
	v_max3_u32 v8, v8, v11, v38
	v_max3_u32 v11, v41, v33, v18
	v_max3_u32 v5, v21, v5, v35
	v_max3_u32 v16, v42, v16, v26
	v_max3_u32 v1, v2, v1, v6
	v_max3_u32 v2, v43, v9, v27
	v_max_u32_e32 v6, v7, v19
	v_min_u32_e32 v7, v7, v19
	v_max_u32_e32 v9, v0, v14
	v_min_u32_e32 v0, v0, v14
	v_max_u32_e32 v14, v3, v8
	v_min_u32_e32 v3, v3, v8
	v_max_u32_e32 v8, v4, v11
	v_min_u32_e32 v4, v4, v11
	v_max_u32_e32 v11, v10, v5
	v_min_u32_e32 v5, v10, v5
	v_max_u32_e32 v10, v12, v16
	v_min_u32_e32 v12, v12, v16
	v_max_u32_e32 v16, v13, v1
	v_min_u32_e32 v1, v13, v1
	v_max_u32_e32 v13, v15, v2
	v_min_u32_e32 v2, v15, v2
	v_max_u32_e32 v15, v6, v11
	v_min_u32_e32 v6, v6, v11
	v_max_u32_e32 v11, v9, v10
	v_min_u32_e32 v9, v9, v10
	v_max_u32_e32 v10, v14, v16
	v_min_u32_e32 v14, v14, v16
	v_max_u32_e32 v16, v8, v13
	v_min_u32_e32 v8, v8, v13
	v_max_u32_e32 v13, v7, v5
	v_min_u32_e32 v5, v7, v5
	v_max_u32_e32 v7, v0, v12
	v_min_u32_e32 v0, v0, v12
	v_max_u32_e32 v12, v3, v1
	v_min_u32_e32 v1, v3, v1
	v_max_u32_e32 v3, v4, v2
	v_min_u32_e32 v2, v4, v2
	v_max_u32_e32 v4, v15, v10
	v_min_u32_e32 v10, v15, v10
	v_max_u32_e32 v15, v11, v16
	v_min_u32_e32 v11, v11, v16
	v_max_u32_e32 v16, v6, v14
	v_min_u32_e32 v6, v6, v14
	v_max_u32_e32 v14, v9, v8
	v_min_u32_e32 v8, v9, v8
	v_max_u32_e32 v9, v13, v12
	v_min_u32_e32 v12, v13, v12
	v_max_u32_e32 v13, v7, v3
	v_min_u32_e32 v3, v7, v3
	v_max_u32_e32 v7, v5, v1
	v_min_u32_e32 v1, v5, v1
	v_max_u32_e32 v5, v0, v2
	v_min_u32_e32 v0, v0, v2
	v_max_u32_e32 v2, v4, v15
	v_min_u32_e32 v4, v4, v15
	v_max_u32_e32 v15, v10, v11
	v_min_u32_e32 v10, v10, v11
	v_max_u32_e32 v11, v16, v14
	v_min_u32_e32 v14, v16, v14
	v_max_u32_e32 v16, v6, v8
	v_min_u32_e32 v6, v6, v8
	v_max_u32_e32 v8, v9, v13
	v_min_u32_e32 v9, v9, v13
	v_max_u32_e32 v13, v12, v3
	v_min_u32_e32 v3, v12, v3
	v_max_u32_e32 v12, v7, v5
	v_min_u32_e32 v5, v7, v5
	v_max_u32_e32 v7, v1, v0
	v_min_u32_e32 v0, v1, v0
	ds_bpermute_b32 v1, v173, v2
	ds_bpermute_b32 v17, v173, v4
	ds_bpermute_b32 v18, v173, v15
	ds_bpermute_b32 v19, v173, v10
	ds_bpermute_b32 v20, v173, v11
	ds_bpermute_b32 v21, v173, v14
	ds_bpermute_b32 v22, v173, v16
	ds_bpermute_b32 v23, v173, v6
	ds_bpermute_b32 v24, v173, v8
	ds_bpermute_b32 v25, v173, v9
	ds_bpermute_b32 v26, v173, v13
	ds_bpermute_b32 v27, v173, v0
	ds_bpermute_b32 v28, v173, v7
	ds_bpermute_b32 v29, v173, v5
	ds_bpermute_b32 v30, v173, v12
	ds_bpermute_b32 v31, v173, v3
	s_waitcnt lgkmcnt(4)
	v_max_u32_e32 v2, v2, v27
	s_waitcnt lgkmcnt(3)
	v_max_u32_e32 v4, v4, v28
	s_waitcnt lgkmcnt(2)
	v_max_u32_e32 v15, v15, v29
	s_waitcnt lgkmcnt(1)
	v_max_u32_e32 v10, v10, v30
	s_waitcnt lgkmcnt(0)
	v_max_u32_e32 v11, v11, v31
	v_max_u32_e32 v14, v14, v26
	v_max_u32_e32 v16, v16, v25
	v_max_u32_e32 v6, v6, v24
	v_max_u32_e32 v8, v8, v23
	v_max_u32_e32 v9, v9, v22
	v_max_u32_e32 v13, v13, v21
	v_max_u32_e32 v3, v3, v20
	v_max_u32_e32 v12, v12, v19
	v_max_u32_e32 v5, v5, v18
	v_max_u32_e32 v7, v7, v17
	v_max_u32_e32 v0, v0, v1
	v_max_u32_e32 v1, v2, v8
	v_min_u32_e32 v2, v2, v8
	v_max_u32_e32 v8, v4, v9
	v_min_u32_e32 v4, v4, v9
	v_max_u32_e32 v9, v15, v13
	v_min_u32_e32 v13, v15, v13
	v_max_u32_e32 v15, v10, v3
	v_min_u32_e32 v3, v10, v3
	v_max_u32_e32 v10, v11, v12
	v_min_u32_e32 v11, v11, v12
	v_max_u32_e32 v12, v14, v5
	v_min_u32_e32 v5, v14, v5
	v_max_u32_e32 v14, v16, v7
	v_min_u32_e32 v7, v16, v7
	v_max_u32_e32 v16, v6, v0
	v_min_u32_e32 v0, v6, v0
	v_max_u32_e32 v6, v1, v10
	v_min_u32_e32 v1, v1, v10
	v_max_u32_e32 v10, v8, v12
	v_min_u32_e32 v8, v8, v12
	v_max_u32_e32 v12, v9, v14
	v_min_u32_e32 v9, v9, v14
	v_max_u32_e32 v14, v15, v16
	v_min_u32_e32 v15, v15, v16
	v_max_u32_e32 v16, v2, v11
	v_min_u32_e32 v2, v2, v11
	v_max_u32_e32 v11, v4, v5
	v_min_u32_e32 v4, v4, v5
	v_max_u32_e32 v5, v13, v7
	v_min_u32_e32 v7, v13, v7
	v_max_u32_e32 v13, v3, v0
	v_max_u32_e32 v18, v1, v9
	v_min_u32_e32 v1, v1, v9
	v_max_u32_e32 v9, v8, v15
	v_min_u32_e32 v0, v3, v0
	v_max_u32_e32 v3, v6, v12
	v_min_u32_e32 v6, v6, v12
	v_max_u32_e32 v12, v10, v14
	v_max_u32_e32 v20, v11, v13
	v_min_u32_e32 v21, v11, v13
	v_max_u32_e32 v13, v18, v9
	v_min_u32_e32 v10, v10, v14
	v_min_u32_e32 v8, v8, v15
	v_max_u32_e32 v19, v16, v5
	v_max_u32_e32 v22, v2, v7
	v_min_u32_e32 v2, v2, v7
; DI unsigned f2ord(float f) { const unsigned u = __float_as_uint(f); return (u & 0x80000000u) ? ~u : (u | 0x80000000u); }
; DI float ord2f(unsigned o) { const unsigned u = (o & 0x80000000u) ? (o & 0x7fffffffu) : ~o; return __uint_as_float(u); }
; DI void peer_topk_phase(const bf16_t* __restrict__ qpk, const bf16_t* __restrict__ subk, int* __restrict__ eidx, float* __restrict__ gout) {
;     ...
;         unsigned ck[50];
; #pragma unroll
;         for (int a = 0; a < 16; ++a)
; #pragma unroll
;             for (int b = 0; b < 16 / (a + 1); ++b) {
;                 const float cv = ord2f(top[0][a] & ~127u) + ord2f(top[1][b] & ~127u);
;                 ck[combo_row_start(a) + b] = (f2ord(cv) & ~255u) | (unsigned)(((15 - a) << 4) | (15 - b));
;             }
	v_max_u32_e32 v23, v4, v0
	v_min_u32_e32 v0, v4, v0
	v_max_u32_e32 v15, v3, v12
	v_min_u32_e32 v17, v3, v12
	v_min_u32_e32 v12, v18, v9
	v_and_b32_e32 v18, 0xffffff80, v13
	v_min_u32_e32 v5, v16, v5
	v_max_u32_e32 v16, v6, v10
	v_min_u32_e32 v14, v6, v10
	v_max_u32_e32 v11, v1, v8
	v_min_u32_e32 v10, v1, v8
	v_max_u32_e32 v9, v19, v20
	v_min_u32_e32 v8, v19, v20
	v_max_u32_e32 v3, v2, v0
	v_min_u32_e32 v1, v2, v0
	v_and_b32_e32 v0, 0x7fffff80, v13
	v_and_b32_e32 v19, 0xffffff80, v12
	v_xor_b32_e32 v18, -1, v18
	v_cmp_gt_i32_e32 vcc, 0, v13
	v_and_b32_e32 v2, 0x7fffff80, v12
	v_xor_b32_e32 v19, -1, v19
	v_cndmask_b32_e32 v31, v18, v0, vcc
	v_cmp_gt_i32_e32 vcc, 0, v12
	v_and_b32_e32 v0, 0x7fffff80, v10
	v_and_b32_e32 v18, 0xffffff80, v9
	v_cndmask_b32_e32 v30, v19, v2, vcc
	v_bitop3_b32 v2, v10, s11, v10 bitop3:0xcf
	v_cmp_gt_i32_e32 vcc, 0, v10
	v_max_u32_e32 v7, v5, v21
	v_and_b32_e32 v19, 0xffffff80, v8
	v_cndmask_b32_e32 v32, v2, v0, vcc
	v_and_b32_e32 v0, 0x7fffff80, v9
	v_xor_b32_e32 v18, -1, v18
	v_cmp_gt_i32_e32 vcc, 0, v9
	v_min_u32_e32 v6, v5, v21
	v_max_u32_e32 v5, v22, v23
	v_min_u32_e32 v4, v22, v23
	v_and_b32_e32 v2, 0x7fffff80, v8
	v_xor_b32_e32 v19, -1, v19
	v_cndmask_b32_e32 v23, v18, v0, vcc
	v_cmp_gt_i32_e32 vcc, 0, v8
	v_and_b32_e32 v18, 0xffffff80, v7
	v_and_b32_e32 v0, 0x7fffff80, v7
	v_cndmask_b32_e32 v22, v19, v2, vcc
	v_and_b32_e32 v19, 0xffffff80, v6
	v_xor_b32_e32 v18, -1, v18
	v_cmp_gt_i32_e32 vcc, 0, v7
	v_and_b32_e32 v2, 0x7fffff80, v6
	v_xor_b32_e32 v19, -1, v19
	v_cndmask_b32_e32 v25, v18, v0, vcc
	v_cmp_gt_i32_e32 vcc, 0, v6
	v_and_b32_e32 v18, 0xffffff80, v5
	v_and_b32_e32 v0, 0x7fffff80, v5
	v_cndmask_b32_e32 v24, v19, v2, vcc
	v_and_b32_e32 v19, 0xffffff80, v4
	v_xor_b32_e32 v18, -1, v18
	v_cmp_gt_i32_e32 vcc, 0, v5
	v_and_b32_e32 v2, 0x7fffff80, v4
	v_xor_b32_e32 v19, -1, v19
	v_cndmask_b32_e32 v27, v18, v0, vcc
	v_cmp_gt_i32_e32 vcc, 0, v4
	v_and_b32_e32 v0, 0x7fffff80, v3
	v_and_b32_e32 v18, 0xffffff80, v1
	v_cndmask_b32_e32 v26, v19, v2, vcc
	v_bitop3_b32 v2, v3, s11, v3 bitop3:0xcf
	v_cmp_gt_i32_e32 vcc, 0, v3
	v_and_b32_e32 v19, 0xffffff80, v80
	v_xor_b32_e32 v18, -1, v18
	v_cndmask_b32_e32 v29, v2, v0, vcc
	v_and_b32_e32 v0, 0x7fffff80, v1
	v_cmp_gt_i32_e32 vcc, 0, v1
	v_and_b32_e32 v2, 0x7fffff80, v80
	v_xor_b32_e32 v19, -1, v19
	v_cndmask_b32_e32 v28, v18, v0, vcc
	v_cmp_gt_i32_e32 vcc, 0, v80
	v_and_b32_e32 v34, 0x7fffff80, v88
	v_and_b32_e32 v33, 0x7fffff80, v11
	v_cndmask_b32_e32 v0, v19, v2, vcc
	v_pk_add_f32 v[20:21], v[0:1], v[30:31] op_sel_hi:[0,1]
	v_not_b32_e32 v2, v21
	v_or_b32_e32 v18, 0x80000000, v21
	v_cmp_gt_i32_e32 vcc, 0, v21
	v_or_b32_e32 v19, 0x80000000, v20
	v_pk_add_f32 v[22:23], v[0:1], v[22:23] op_sel_hi:[0,1]
	v_cndmask_b32_e32 v2, v18, v2, vcc
	v_and_b32_e32 v2, 0xffffff00, v2
	v_or_b32_e32 v18, 0xfb, v2
	v_not_b32_e32 v2, v20
	v_cmp_gt_i32_e32 vcc, 0, v20
	v_pk_add_f32 v[24:25], v[0:1], v[24:25] op_sel_hi:[0,1]
	v_pk_add_f32 v[26:27], v[0:1], v[26:27] op_sel_hi:[0,1]
	v_cndmask_b32_e32 v2, v19, v2, vcc
	v_and_b32_e32 v2, 0xffffff00, v2
	v_or_b32_e32 v19, 0xfa, v2
	v_add_f32_e32 v2, v0, v32
	v_not_b32_e32 v20, v2
	v_or_b32_e32 v21, 0x80000000, v2
	v_cmp_gt_i32_e32 vcc, 0, v2
	v_pk_add_f32 v[28:29], v[0:1], v[28:29] op_sel_hi:[0,1]
	v_and_b32_e32 v38, 0x7fffff80, v85
	v_cndmask_b32_e32 v2, v21, v20, vcc
	v_and_b32_e32 v2, 0xffffff00, v2
	v_or_b32_e32 v20, 0xf8, v2
	v_not_b32_e32 v2, v23
	v_or_b32_e32 v21, 0x80000000, v23
	v_cmp_gt_i32_e32 vcc, 0, v23
	v_or_b32_e32 v23, 0x80000000, v22
	v_and_b32_e32 v41, 0x7fffff80, v68
	v_cndmask_b32_e32 v2, v21, v2, vcc
	v_and_b32_e32 v2, 0xffffff00, v2
	v_or_b32_e32 v21, 0xf7, v2
	v_not_b32_e32 v2, v22
	v_cmp_gt_i32_e32 vcc, 0, v22
	v_and_b32_e32 v43, 0x7fffff80, v66
	v_and_b32_e32 v90, 0x7fffff80, v64
	v_cndmask_b32_e32 v2, v23, v2, vcc
	v_and_b32_e32 v2, 0xffffff00, v2
	v_or_b32_e32 v22, 0xf6, v2
	v_not_b32_e32 v2, v25
	v_or_b32_e32 v23, 0x80000000, v25
	v_cmp_gt_i32_e32 vcc, 0, v25
	v_or_b32_e32 v25, 0x80000000, v24
	v_and_b32_e32 v75, 0x7fffff80, v15
	v_cndmask_b32_e32 v2, v23, v2, vcc
	v_and_b32_e32 v2, 0xffffff00, v2
	v_or_b32_e32 v23, 0xf5, v2
	v_not_b32_e32 v2, v24
	v_cmp_gt_i32_e32 vcc, 0, v24
	s_nop 1
	v_cndmask_b32_e32 v2, v25, v2, vcc
	v_and_b32_e32 v2, 0xffffff00, v2
	v_or_b32_e32 v24, 0xf4, v2
	v_not_b32_e32 v2, v27
	v_or_b32_e32 v25, 0x80000000, v27
	v_cmp_gt_i32_e32 vcc, 0, v27
	v_or_b32_e32 v27, 0x80000000, v26
	s_nop 0
	v_cndmask_b32_e32 v2, v25, v2, vcc
	v_and_b32_e32 v2, 0xffffff00, v2
	v_or_b32_e32 v25, 0xf3, v2
	v_not_b32_e32 v2, v26
	v_cmp_gt_i32_e32 vcc, 0, v26
	s_nop 1
	v_cndmask_b32_e32 v2, v27, v2, vcc
	v_and_b32_e32 v2, 0xffffff00, v2
	v_or_b32_e32 v26, 0xf2, v2
	v_not_b32_e32 v2, v29
	v_or_b32_e32 v27, 0x80000000, v29
	v_cmp_gt_i32_e32 vcc, 0, v29
	v_or_b32_e32 v29, 0x80000000, v28
	s_nop 0
	v_cndmask_b32_e32 v2, v27, v2, vcc
	v_and_b32_e32 v2, 0xffffff00, v2
	v_or_b32_e32 v27, 0xf1, v2
	v_not_b32_e32 v2, v28
	v_cmp_gt_i32_e32 vcc, 0, v28
	s_nop 1
	v_cndmask_b32_e32 v2, v29, v2, vcc
	v_and_b32_e32 v2, 0xffffff00, v2
	v_or_b32_e32 v28, 0xf0, v2
	v_and_b32_e32 v2, 0xffffff80, v11
	v_and_b32_e32 v29, 0xffffff80, v88
	v_xor_b32_e32 v35, -1, v2
	v_xor_b32_e32 v2, -1, v29
	v_cmp_gt_i32_e32 vcc, 0, v88
	s_nop 1
	v_cndmask_b32_e32 v2, v2, v34, vcc
	v_cmp_gt_i32_e32 vcc, 0, v11
	s_nop 1
	v_cndmask_b32_e32 v33, v35, v33, vcc
	v_add_f32_e32 v29, v33, v0
	v_not_b32_e32 v34, v29
	v_or_b32_e32 v35, 0x80000000, v29
	v_cmp_gt_i32_e32 vcc, 0, v29
	v_pk_add_f32 v[32:33], v[2:3], v[32:33] op_sel_hi:[0,1]
	s_nop 0
	v_cndmask_b32_e32 v29, v35, v34, vcc
	v_pk_add_f32 v[34:35], v[2:3], v[30:31] op_sel_hi:[0,1]
	v_not_b32_e32 v30, v35
; DI unsigned f2ord(float f) { const unsigned u = __float_as_uint(f); return (u & 0x80000000u) ? ~u : (u | 0x80000000u); }
; DI float ord2f(unsigned o) { const unsigned u = (o & 0x80000000u) ? (o & 0x7fffffffu) : ~o; return __uint_as_float(u); }
; DI void peer_topk_phase(const bf16_t* __restrict__ qpk, const bf16_t* __restrict__ subk, int* __restrict__ eidx, float* __restrict__ gout) {
;     ...
;         unsigned ck[50];
; #pragma unroll
;         for (int a = 0; a < 16; ++a)
; #pragma unroll
;             for (int b = 0; b < 16 / (a + 1); ++b) {
;                 const float cv = ord2f(top[0][a] & ~127u) + ord2f(top[1][b] & ~127u);
;                 ck[combo_row_start(a) + b] = (f2ord(cv) & ~255u) | (unsigned)(((15 - a) << 4) | (15 - b));
;             }
	v_or_b32_e32 v36, 0x80000000, v35
	v_cmp_gt_i32_e32 vcc, 0, v35
	v_and_b32_e32 v29, 0xffffff00, v29
	v_or_b32_e32 v29, 0xf9, v29
	v_cndmask_b32_e32 v30, v36, v30, vcc
	v_and_b32_e32 v30, 0xffffff00, v30
	v_or_b32_e32 v35, 0xeb, v30
	v_not_b32_e32 v30, v34
	v_or_b32_e32 v36, 0x80000000, v34
	v_cmp_gt_i32_e32 vcc, 0, v34
	v_or_b32_e32 v34, 0x80000000, v33
	s_nop 0
	v_cndmask_b32_e32 v30, v36, v30, vcc
	v_and_b32_e32 v30, 0xffffff00, v30
	v_or_b32_e32 v45, 0xea, v30
	v_not_b32_e32 v30, v33
	v_cmp_gt_i32_e32 vcc, 0, v33
	v_or_b32_e32 v33, 0x80000000, v32
	s_nop 0
	v_cndmask_b32_e32 v30, v34, v30, vcc
	v_and_b32_e32 v30, 0xffffff00, v30
	v_or_b32_e32 v46, 0xe9, v30
	v_not_b32_e32 v30, v32
	v_cmp_gt_i32_e32 vcc, 0, v32
	v_and_b32_e32 v32, 0xffffff80, v89
	v_and_b32_e32 v34, 0x7fffff80, v89
	v_cndmask_b32_e32 v30, v33, v30, vcc
	v_and_b32_e32 v30, 0xffffff00, v30
	v_or_b32_e32 v47, 0xe8, v30
	v_and_b32_e32 v30, 0xffffff80, v14
	v_and_b32_e32 v33, 0x7fffff80, v14
	v_xor_b32_e32 v30, -1, v30
	v_cmp_gt_i32_e32 vcc, 0, v14
	v_xor_b32_e32 v32, -1, v32
	s_nop 0
	v_cndmask_b32_e32 v33, v30, v33, vcc
	v_cmp_gt_i32_e32 vcc, 0, v89
	v_add_f32_e32 v30, v33, v0
	v_or_b32_e32 v36, 0x80000000, v30
	v_cndmask_b32_e32 v34, v32, v34, vcc
	v_not_b32_e32 v32, v30
	v_cmp_gt_i32_e32 vcc, 0, v30
	s_nop 1
	v_cndmask_b32_e32 v30, v36, v32, vcc
	v_add_f32_e32 v32, v33, v2
	v_not_b32_e32 v36, v32
	v_or_b32_e32 v37, 0x80000000, v32
	v_cmp_gt_i32_e32 vcc, 0, v32
	v_and_b32_e32 v30, 0xffffff00, v30
	v_or_b32_e32 v30, 0xfc, v30
	v_cndmask_b32_e32 v32, v37, v36, vcc
	v_and_b32_e32 v32, 0xffffff00, v32
	v_or_b32_e32 v48, 0xec, v32
	v_mov_b32_e32 v32, v31
	v_pk_add_f32 v[36:37], v[34:35], v[32:33] op_sel_hi:[0,1]
	v_not_b32_e32 v31, v37
	v_or_b32_e32 v32, 0x80000000, v37
	v_cmp_gt_i32_e32 vcc, 0, v37
	s_nop 1
	v_cndmask_b32_e32 v31, v32, v31, vcc
	v_and_b32_e32 v31, 0xffffff00, v31
	v_or_b32_e32 v49, 0xdc, v31
	v_not_b32_e32 v31, v36
	v_or_b32_e32 v32, 0x80000000, v36
	v_cmp_gt_i32_e32 vcc, 0, v36
	v_and_b32_e32 v36, 0x7fffff80, v16
	s_nop 0
	v_cndmask_b32_e32 v31, v32, v31, vcc
	v_and_b32_e32 v31, 0xffffff00, v31
	v_or_b32_e32 v50, 0xdb, v31
	v_and_b32_e32 v31, 0xffffff80, v16
	v_xor_b32_e32 v31, -1, v31
	v_cmp_gt_i32_e32 vcc, 0, v16
	v_and_b32_e32 v32, 0xffffff80, v85
	v_xor_b32_e32 v32, -1, v32
	v_cndmask_b32_e32 v37, v31, v36, vcc
	v_cmp_gt_i32_e32 vcc, 0, v85
	v_add_f32_e32 v31, v37, v0
	v_not_b32_e32 v36, v31
	v_cndmask_b32_e32 v32, v32, v38, vcc
	v_or_b32_e32 v38, 0x80000000, v31
	v_cmp_gt_i32_e32 vcc, 0, v31
	s_nop 1
	v_cndmask_b32_e32 v31, v38, v36, vcc
	v_add_f32_e32 v36, v37, v2
	v_not_b32_e32 v38, v36
	v_or_b32_e32 v39, 0x80000000, v36
	v_cmp_gt_i32_e32 vcc, 0, v36
	v_and_b32_e32 v31, 0xffffff00, v31
	v_or_b32_e32 v31, 0xfd, v31
	v_cndmask_b32_e32 v36, v39, v38, vcc
	v_and_b32_e32 v36, 0xffffff00, v36
	v_or_b32_e32 v51, 0xed, v36
	v_add_f32_e32 v36, v37, v34
	v_not_b32_e32 v38, v36
	v_or_b32_e32 v39, 0x80000000, v36
	v_cmp_gt_i32_e32 vcc, 0, v36
	s_nop 1
	v_cndmask_b32_e32 v36, v39, v38, vcc
	v_and_b32_e32 v36, 0xffffff00, v36
	v_or_b32_e32 v52, 0xdd, v36
	v_mov_b32_e32 v36, v33
	v_pk_add_f32 v[38:39], v[32:33], v[36:37] op_sel_hi:[0,1]
	v_not_b32_e32 v33, v39
	v_or_b32_e32 v36, 0x80000000, v39
	v_cmp_gt_i32_e32 vcc, 0, v39
	v_and_b32_e32 v39, 0x7fffff80, v77
	s_nop 0
	v_cndmask_b32_e32 v33, v36, v33, vcc
	v_and_b32_e32 v33, 0xffffff00, v33
	v_or_b32_e32 v53, 0xcd, v33
	v_not_b32_e32 v33, v38
	v_or_b32_e32 v36, 0x80000000, v38
	v_cmp_gt_i32_e32 vcc, 0, v38
	s_nop 1
	v_cndmask_b32_e32 v33, v36, v33, vcc
	v_and_b32_e32 v33, 0xffffff00, v33
	v_or_b32_e32 v54, 0xcc, v33
	v_and_b32_e32 v33, 0x7fffff80, v79
	v_bitop3_b32 v36, v79, s11, v79 bitop3:0xcf
	v_cmp_gt_i32_e32 vcc, 0, v79
	s_nop 1
	v_cndmask_b32_e32 v33, v36, v33, vcc
	v_add_f32_e32 v36, v37, v33
	v_not_b32_e32 v37, v36
	v_or_b32_e32 v38, 0x80000000, v36
	v_cmp_gt_i32_e32 vcc, 0, v36
	s_nop 1
	v_cndmask_b32_e32 v36, v38, v37, vcc
	v_and_b32_e32 v36, 0xffffff00, v36
	v_or_b32_e32 v55, 0xbd, v36
	v_and_b32_e32 v36, 0x7fffff80, v78
	v_bitop3_b32 v37, v78, s11, v78 bitop3:0xcf
	v_cmp_gt_i32_e32 vcc, 0, v78
	v_and_b32_e32 v38, 0x7fffff80, v17
	s_nop 0
	v_cndmask_b32_e32 v56, v37, v36, vcc
	v_and_b32_e32 v37, 0xffffff80, v77
	v_and_b32_e32 v36, 0xffffff80, v17
	v_xor_b32_e32 v37, -1, v37
	v_cmp_gt_i32_e32 vcc, 0, v77
	v_xor_b32_e32 v36, -1, v36
	s_nop 0
	v_cndmask_b32_e32 v57, v37, v39, vcc
	v_cmp_gt_i32_e32 vcc, 0, v17
	s_nop 1
	v_cndmask_b32_e32 v36, v36, v38, vcc
	v_add_f32_e32 v37, v36, v0
	v_not_b32_e32 v38, v37
	v_or_b32_e32 v39, 0x80000000, v37
	v_cmp_gt_i32_e32 vcc, 0, v37
	s_nop 1
	v_cndmask_b32_e32 v37, v39, v38, vcc
	v_and_b32_e32 v37, 0xffffff00, v37
	v_or_b32_e32 v58, 0xfe, v37
	v_add_f32_e32 v37, v36, v2
	v_not_b32_e32 v38, v37
	v_or_b32_e32 v39, 0x80000000, v37
	v_cmp_gt_i32_e32 vcc, 0, v37
	s_nop 1
	v_cndmask_b32_e32 v37, v39, v38, vcc
	v_and_b32_e32 v37, 0xffffff00, v37
	v_or_b32_e32 v59, 0xee, v37
	v_add_f32_e32 v37, v36, v34
	v_not_b32_e32 v38, v37
	v_or_b32_e32 v39, 0x80000000, v37
	v_cmp_gt_i32_e32 vcc, 0, v37
	s_nop 1
	v_cndmask_b32_e32 v37, v39, v38, vcc
	v_and_b32_e32 v37, 0xffffff00, v37
	v_or_b32_e32 v60, 0xde, v37
	v_add_f32_e32 v37, v36, v32
	v_not_b32_e32 v38, v37
	v_or_b32_e32 v39, 0x80000000, v37
	v_cmp_gt_i32_e32 vcc, 0, v37
	s_nop 1
	v_cndmask_b32_e32 v37, v39, v38, vcc
	v_and_b32_e32 v37, 0xffffff00, v37
	v_or_b32_e32 v61, 0xce, v37
	v_add_f32_e32 v37, v36, v33
	v_not_b32_e32 v38, v37
	v_or_b32_e32 v39, 0x80000000, v37
	v_cmp_gt_i32_e32 vcc, 0, v37
	s_nop 1
	v_cndmask_b32_e32 v37, v39, v38, vcc
	v_and_b32_e32 v37, 0xffffff00, v37
	v_or_b32_e32 v62, 0xbe, v37
	v_add_f32_e32 v37, v36, v56
; DI unsigned f2ord(float f) { const unsigned u = __float_as_uint(f); return (u & 0x80000000u) ? ~u : (u | 0x80000000u); }
; DI float ord2f(unsigned o) { const unsigned u = (o & 0x80000000u) ? (o & 0x7fffffffu) : ~o; return __uint_as_float(u); }
; DI void peer_topk_phase(const bf16_t* __restrict__ qpk, const bf16_t* __restrict__ subk, int* __restrict__ eidx, float* __restrict__ gout) {
;     ...
;         unsigned ck[50];
; #pragma unroll
;         for (int a = 0; a < 16; ++a)
; #pragma unroll
;             for (int b = 0; b < 16 / (a + 1); ++b) {
;                 const float cv = ord2f(top[0][a] & ~127u) + ord2f(top[1][b] & ~127u);
;                 ck[combo_row_start(a) + b] = (f2ord(cv) & ~255u) | (unsigned)(((15 - a) << 4) | (15 - b));
;             }
;         unsigned c0[16], c1[16], c2[16], c3[16];
; #pragma unroll
;         for (int i = 0; i < 16; ++i) { c0[i] = ck[i]; c1[i] = ck[16 + i]; c2[i] = ck[32 + i]; c3[i] = (i < 2) ? ck[48 + i] : 0u; }
; #pragma unroll
;         for (int n = 0; n < 63; ++n) { cex(c1[SORT16[n][0]], c1[SORT16[n][1]]); cex(c2[SORT16[n][0]], c2[SORT16[n][1]]); }
	v_not_b32_e32 v38, v37
	v_or_b32_e32 v39, 0x80000000, v37
	v_cmp_gt_i32_e32 vcc, 0, v37
	s_nop 1
	v_cndmask_b32_e32 v37, v39, v38, vcc
	v_and_b32_e32 v37, 0xffffff00, v37
	v_or_b32_e32 v63, 0xae, v37
	v_add_f32_e32 v37, v36, v57
	v_not_b32_e32 v38, v37
	v_or_b32_e32 v39, 0x80000000, v37
	v_cmp_gt_i32_e32 vcc, 0, v37
	s_nop 1
	v_cndmask_b32_e32 v37, v39, v38, vcc
	v_and_b32_e32 v37, 0xffffff00, v37
	v_or_b32_e32 v72, 0x9e, v37
	v_and_b32_e32 v37, 0x7fffff80, v76
	v_bitop3_b32 v38, v76, s11, v76 bitop3:0xcf
	v_cmp_gt_i32_e32 vcc, 0, v76
	v_and_b32_e32 v39, 0x7fffff80, v70
	s_nop 0
	v_cndmask_b32_e32 v73, v38, v37, vcc
	v_add_f32_e32 v36, v36, v73
	v_not_b32_e32 v37, v36
	v_or_b32_e32 v38, 0x80000000, v36
	v_cmp_gt_i32_e32 vcc, 0, v36
	s_nop 1
	v_cndmask_b32_e32 v36, v38, v37, vcc
	v_and_b32_e32 v36, 0xffffff00, v36
	v_or_b32_e32 v74, 0x8e, v36
	v_and_b32_e32 v36, 0xffffff80, v71
	v_and_b32_e32 v37, 0xffffff80, v70
	v_and_b32_e32 v38, 0x7fffff80, v71
	v_xor_b32_e32 v36, -1, v36
	v_cmp_gt_i32_e32 vcc, 0, v71
	v_xor_b32_e32 v40, -1, v37
	s_nop 0
	v_cndmask_b32_e32 v37, v36, v38, vcc
	v_cmp_gt_i32_e32 vcc, 0, v70
	v_and_b32_e32 v38, 0xffffff80, v69
	v_xor_b32_e32 v38, -1, v38
	v_cndmask_b32_e32 v36, v40, v39, vcc
	v_and_b32_e32 v39, 0xffffff80, v68
	v_and_b32_e32 v40, 0x7fffff80, v69
	v_cmp_gt_i32_e32 vcc, 0, v69
	v_xor_b32_e32 v42, -1, v39
	s_nop 0
	v_cndmask_b32_e32 v39, v38, v40, vcc
	v_cmp_gt_i32_e32 vcc, 0, v68
	v_and_b32_e32 v40, 0xffffff80, v67
	v_xor_b32_e32 v40, -1, v40
	v_cndmask_b32_e32 v38, v42, v41, vcc
	v_and_b32_e32 v41, 0xffffff80, v66
	v_and_b32_e32 v42, 0x7fffff80, v67
	v_cmp_gt_i32_e32 vcc, 0, v67
	v_xor_b32_e32 v44, -1, v41
	s_nop 0
	v_cndmask_b32_e32 v41, v40, v42, vcc
	v_cmp_gt_i32_e32 vcc, 0, v66
	v_and_b32_e32 v42, 0x7fffff80, v65
	s_nop 0
	v_cndmask_b32_e32 v40, v44, v43, vcc
	v_bitop3_b32 v43, v65, s11, v65 bitop3:0xcf
	v_cmp_gt_i32_e32 vcc, 0, v65
	v_and_b32_e32 v44, 0xffffff80, v64
	s_nop 0
	v_cndmask_b32_e32 v43, v43, v42, vcc
	v_and_b32_e32 v42, 0xffffff80, v15
	v_xor_b32_e32 v91, -1, v42
	v_xor_b32_e32 v42, -1, v44
	v_cmp_gt_i32_e32 vcc, 0, v64
	s_nop 1
	v_cndmask_b32_e32 v42, v42, v90, vcc
	v_cmp_gt_i32_e32 vcc, 0, v15
	s_nop 1
	v_cndmask_b32_e32 v44, v91, v75, vcc
	v_add_f32_e32 v0, v44, v0
	v_not_b32_e32 v75, v0
	v_or_b32_e32 v90, 0x80000000, v0
	v_cmp_gt_i32_e32 vcc, 0, v0
	v_add_f32_e32 v2, v44, v2
	v_add_f32_e32 v34, v44, v34
	v_cndmask_b32_e32 v0, v90, v75, vcc
	v_not_b32_e32 v75, v2
	v_or_b32_e32 v90, 0x80000000, v2
	v_cmp_gt_i32_e32 vcc, 0, v2
	v_add_f32_e32 v32, v44, v32
	v_or_b32_e32 v0, 0xff, v0
	v_cndmask_b32_e32 v2, v90, v75, vcc
	v_not_b32_e32 v75, v34
	v_or_b32_e32 v90, 0x80000000, v34
	v_cmp_gt_i32_e32 vcc, 0, v34
	v_and_b32_e32 v2, 0xffffff00, v2
	v_or_b32_e32 v2, 0xef, v2
	v_cndmask_b32_e32 v34, v90, v75, vcc
	v_not_b32_e32 v75, v32
	v_or_b32_e32 v90, 0x80000000, v32
	v_cmp_gt_i32_e32 vcc, 0, v32
	v_and_b32_e32 v34, 0xffffff00, v34
	v_or_b32_e32 v34, 0xdf, v34
	v_cndmask_b32_e32 v32, v90, v75, vcc
	v_and_b32_e32 v32, 0xffffff00, v32
	v_or_b32_e32 v75, 0xcf, v32
	v_add_f32_e32 v32, v44, v33
	v_not_b32_e32 v33, v32
	v_or_b32_e32 v90, 0x80000000, v32
	v_cmp_gt_i32_e32 vcc, 0, v32
	s_nop 1
	v_cndmask_b32_e32 v32, v90, v33, vcc
	v_and_b32_e32 v32, 0xffffff00, v32
	v_or_b32_e32 v90, 0xbf, v32
	v_add_f32_e32 v32, v44, v56
	v_not_b32_e32 v33, v32
	v_or_b32_e32 v56, 0x80000000, v32
	v_cmp_gt_i32_e32 vcc, 0, v32
	s_nop 1
	v_cndmask_b32_e32 v32, v56, v33, vcc
	v_and_b32_e32 v32, 0xffffff00, v32
	v_or_b32_e32 v56, 0xaf, v32
	v_add_f32_e32 v32, v44, v57
	v_not_b32_e32 v33, v32
	v_or_b32_e32 v57, 0x80000000, v32
	v_cmp_gt_i32_e32 vcc, 0, v32
	s_nop 1
	v_cndmask_b32_e32 v32, v57, v33, vcc
	v_and_b32_e32 v32, 0xffffff00, v32
	v_or_b32_e32 v57, 0x9f, v32
	v_add_f32_e32 v32, v44, v73
	v_not_b32_e32 v33, v32
	v_or_b32_e32 v73, 0x80000000, v32
	v_cmp_gt_i32_e32 vcc, 0, v32
	s_nop 1
	v_cndmask_b32_e32 v32, v73, v33, vcc
	v_and_b32_e32 v32, 0xffffff00, v32
	v_or_b32_e32 v73, 0x8f, v32
	v_pk_add_f32 v[32:33], v[44:45], v[36:37] op_sel_hi:[0,1]
	v_not_b32_e32 v36, v33
	v_or_b32_e32 v37, 0x80000000, v33
	v_cmp_gt_i32_e32 vcc, 0, v33
	s_nop 1
	v_cndmask_b32_e32 v33, v37, v36, vcc
	v_and_b32_e32 v33, 0xffffff00, v33
	v_or_b32_e32 v36, 0x7f, v33
	v_not_b32_e32 v33, v32
	v_or_b32_e32 v37, 0x80000000, v32
	v_cmp_gt_i32_e32 vcc, 0, v32
	s_nop 1
	v_cndmask_b32_e32 v32, v37, v33, vcc
	v_and_b32_e32 v32, 0xffffff00, v32
	v_or_b32_e32 v37, 0x6f, v32
	v_pk_add_f32 v[32:33], v[44:45], v[38:39] op_sel_hi:[0,1]
	v_not_b32_e32 v38, v33
	v_or_b32_e32 v39, 0x80000000, v33
	v_cmp_gt_i32_e32 vcc, 0, v33
	s_nop 1
	v_cndmask_b32_e32 v33, v39, v38, vcc
	v_and_b32_e32 v33, 0xffffff00, v33
	v_or_b32_e32 v38, 0x5f, v33
	v_not_b32_e32 v33, v32
	v_or_b32_e32 v39, 0x80000000, v32
	v_cmp_gt_i32_e32 vcc, 0, v32
	s_nop 1
	v_cndmask_b32_e32 v32, v39, v33, vcc
	v_and_b32_e32 v32, 0xffffff00, v32
	v_or_b32_e32 v39, 0x4f, v32
	v_pk_add_f32 v[32:33], v[44:45], v[40:41] op_sel_hi:[0,1]
	v_not_b32_e32 v40, v33
	v_or_b32_e32 v41, 0x80000000, v33
	v_cmp_gt_i32_e32 vcc, 0, v33
	s_nop 1
	v_cndmask_b32_e32 v33, v41, v40, vcc
	v_and_or_b32 v40, v33, s21, 63
	v_not_b32_e32 v33, v32
	v_or_b32_e32 v41, 0x80000000, v32
	v_cmp_gt_i32_e32 vcc, 0, v32
	s_nop 1
	v_cndmask_b32_e32 v32, v41, v33, vcc
	v_and_or_b32 v41, v32, s21, 47
	v_pk_add_f32 v[32:33], v[44:45], v[42:43] op_sel_hi:[0,1]
	v_not_b32_e32 v42, v33
	v_or_b32_e32 v43, 0x80000000, v33
	v_cmp_gt_i32_e32 vcc, 0, v33
	v_min_u32_e32 v44, v54, v90
	s_nop 0
	v_cndmask_b32_e32 v33, v43, v42, vcc
	v_not_b32_e32 v42, v32
	v_or_b32_e32 v43, 0x80000000, v32
	v_cmp_gt_i32_e32 vcc, 0, v32
	v_and_or_b32 v33, v33, s21, 31
; DI void peer_topk_phase(const bf16_t* __restrict__ qpk, const bf16_t* __restrict__ subk, int* __restrict__ eidx, float* __restrict__ gout) {
;     ...
;         unsigned c0[16], c1[16], c2[16], c3[16];
; #pragma unroll
;         for (int i = 0; i < 16; ++i) { c0[i] = ck[i]; c1[i] = ck[16 + i]; c2[i] = ck[32 + i]; c3[i] = (i < 2) ? ck[48 + i] : 0u; }
; #pragma unroll
;         for (int n = 0; n < 63; ++n) { cex(c1[SORT16[n][0]], c1[SORT16[n][1]]); cex(c2[SORT16[n][0]], c2[SORT16[n][1]]); }
	s_nop 0
	v_cndmask_b32_e32 v32, v43, v42, vcc
	v_max_u32_e32 v42, v2, v59
	v_min_u32_e32 v2, v2, v59
	v_max_u32_e32 v43, v54, v90
	v_max_u32_e32 v54, v51, v48
	v_min_u32_e32 v48, v51, v48
	v_max_u32_e32 v51, v62, v55
	v_min_u32_e32 v55, v62, v55
	v_max_u32_e32 v59, v42, v54
	v_min_u32_e32 v42, v42, v54
	v_max_u32_e32 v54, v43, v51
	v_min_u32_e32 v43, v43, v51
	v_max_u32_e32 v51, v2, v48
	v_min_u32_e32 v2, v2, v48
	v_max_u32_e32 v48, v44, v55
	v_min_u32_e32 v44, v44, v55
	v_max_u32_e32 v55, v51, v42
	v_min_u32_e32 v42, v51, v42
	v_max_u32_e32 v51, v48, v43
	v_min_u32_e32 v43, v48, v43
	v_max_u32_e32 v48, v35, v45
	v_min_u32_e32 v35, v35, v45
	v_max_u32_e32 v45, v56, v63
	v_min_u32_e32 v56, v56, v63
	v_max_u32_e32 v62, v46, v47
	v_min_u32_e32 v46, v46, v47
	v_max_u32_e32 v47, v57, v72
	v_min_u32_e32 v57, v57, v72
	v_max_u32_e32 v63, v48, v62
	v_min_u32_e32 v48, v48, v62
	v_max_u32_e32 v62, v45, v47
	v_min_u32_e32 v45, v45, v47
	v_max_u32_e32 v47, v35, v46
	v_min_u32_e32 v35, v35, v46
	v_max_u32_e32 v46, v56, v57
	v_min_u32_e32 v56, v56, v57
	v_max_u32_e32 v57, v47, v48
	v_min_u32_e32 v47, v47, v48
	v_max_u32_e32 v48, v46, v45
	v_min_u32_e32 v45, v46, v45
	v_max_u32_e32 v46, v59, v63
	v_min_u32_e32 v59, v59, v63
	v_max_u32_e32 v63, v54, v62
	v_min_u32_e32 v54, v54, v62
	v_max_u32_e32 v62, v42, v47
	v_min_u32_e32 v42, v42, v47
	v_max_u32_e32 v47, v43, v45
	v_min_u32_e32 v43, v43, v45
	v_max_u32_e32 v45, v62, v59
	v_min_u32_e32 v59, v62, v59
	v_max_u32_e32 v62, v47, v54
	v_min_u32_e32 v47, v47, v54
	v_max_u32_e32 v54, v55, v57
	v_min_u32_e32 v55, v55, v57
	v_max_u32_e32 v57, v51, v48
	v_min_u32_e32 v48, v51, v48
	v_max_u32_e32 v51, v2, v35
	v_min_u32_e32 v2, v2, v35
	v_max_u32_e32 v35, v44, v56
	v_min_u32_e32 v44, v44, v56
	v_max_u32_e32 v56, v51, v55
	v_min_u32_e32 v51, v51, v55
	v_max_u32_e32 v55, v35, v48
	v_min_u32_e32 v35, v35, v48
	v_max_u32_e32 v48, v54, v45
	v_min_u32_e32 v45, v54, v45
	v_max_u32_e32 v54, v57, v62
	v_min_u32_e32 v57, v57, v62
	v_max_u32_e32 v62, v56, v59
	v_min_u32_e32 v56, v56, v59
	v_max_u32_e32 v59, v55, v47
	v_min_u32_e32 v47, v55, v47
	v_max_u32_e32 v55, v51, v42
	v_min_u32_e32 v42, v51, v42
	v_max_u32_e32 v51, v35, v43
	v_min_u32_e32 v35, v35, v43
	v_max_u32_e32 v43, v34, v60
	v_min_u32_e32 v34, v34, v60
	v_max_u32_e32 v60, v73, v74
	v_min_u32_e32 v72, v73, v74
	v_max_u32_e32 v73, v52, v49
	v_min_u32_e32 v49, v52, v49
	v_max_u32_e32 v52, v36, v37
	v_min_u32_e32 v36, v36, v37
	v_max_u32_e32 v37, v43, v73
	v_min_u32_e32 v43, v43, v73
	v_max_u32_e32 v73, v60, v52
	v_min_u32_e32 v52, v60, v52
	v_max_u32_e32 v60, v34, v49
	v_min_u32_e32 v34, v34, v49
	v_max_u32_e32 v49, v72, v36
	v_min_u32_e32 v36, v72, v36
	v_max_u32_e32 v72, v60, v43
	v_min_u32_e32 v43, v60, v43
	v_max_u32_e32 v60, v49, v52
	v_min_u32_e32 v49, v49, v52
	v_max_u32_e32 v52, v50, v75
	v_min_u32_e32 v50, v50, v75
	v_max_u32_e32 v74, v38, v39
	v_min_u32_e32 v38, v38, v39
	v_max_u32_e32 v39, v61, v53
	v_min_u32_e32 v53, v61, v53
	v_max_u32_e32 v61, v40, v41
	v_min_u32_e32 v40, v40, v41
	v_max_u32_e32 v41, v52, v39
	v_min_u32_e32 v39, v52, v39
	v_max_u32_e32 v52, v74, v61
	v_min_u32_e32 v61, v74, v61
	v_max_u32_e32 v74, v50, v53
	v_min_u32_e32 v50, v50, v53
	v_max_u32_e32 v53, v38, v40
	v_min_u32_e32 v38, v38, v40
	v_max_u32_e32 v40, v74, v39
	v_min_u32_e32 v39, v74, v39
	v_max_u32_e32 v74, v53, v61
	v_min_u32_e32 v53, v53, v61
	v_max_u32_e32 v61, v37, v41
	v_min_u32_e32 v37, v37, v41
	v_max_u32_e32 v41, v73, v52
	v_min_u32_e32 v52, v73, v52
	v_max_u32_e32 v73, v43, v39
	v_min_u32_e32 v39, v43, v39
	v_max_u32_e32 v43, v49, v53
	v_min_u32_e32 v49, v49, v53
	v_max_u32_e32 v53, v73, v37
	v_min_u32_e32 v37, v73, v37
	v_max_u32_e32 v73, v43, v52
	v_min_u32_e32 v43, v43, v52
	v_max_u32_e32 v52, v72, v40
	v_min_u32_e32 v40, v72, v40
	v_max_u32_e32 v72, v60, v74
	v_min_u32_e32 v60, v60, v74
	v_max_u32_e32 v74, v34, v50
	v_min_u32_e32 v34, v34, v50
	v_max_u32_e32 v50, v36, v38
	v_min_u32_e32 v36, v36, v38
	v_max_u32_e32 v38, v74, v40
	v_min_u32_e32 v40, v74, v40
	v_max_u32_e32 v74, v50, v60
	v_min_u32_e32 v50, v50, v60
	v_max_u32_e32 v60, v52, v53
	v_min_u32_e32 v52, v52, v53
	v_max_u32_e32 v53, v72, v73
	v_min_u32_e32 v72, v72, v73
	v_max_u32_e32 v73, v38, v37
	v_min_u32_e32 v37, v38, v37
	v_max_u32_e32 v38, v74, v43
	v_min_u32_e32 v43, v74, v43
	v_max_u32_e32 v74, v40, v39
	v_min_u32_e32 v39, v40, v39
	v_max_u32_e32 v40, v50, v49
	v_min_u32_e32 v49, v50, v49
	v_min_u32_e32 v50, v46, v61
	v_max_u32_e32 v75, v63, v41
	v_min_u32_e32 v41, v63, v41
	v_max_u32_e32 v63, v56, v37
	v_min_u32_e32 v37, v56, v37
	v_max_u32_e32 v56, v47, v43
	v_min_u32_e32 v43, v47, v43
	v_max_u32_e32 v47, v63, v50
	v_min_u32_e32 v50, v63, v50
	v_max_u32_e32 v63, v56, v41
	v_min_u32_e32 v41, v56, v41
	v_max_u32_e32 v56, v45, v52
	v_min_u32_e32 v45, v45, v52
	v_max_u32_e32 v52, v57, v72
	v_min_u32_e32 v57, v57, v72
	v_max_u32_e32 v72, v42, v39
	v_min_u32_e32 v39, v42, v39
	v_max_u32_e32 v42, v35, v49
	v_min_u32_e32 v35, v35, v49
	v_max_u32_e32 v49, v72, v45
	v_min_u32_e32 v45, v72, v45
	v_max_u32_e32 v72, v42, v57
	v_min_u32_e32 v42, v42, v57
	v_max_u32_e32 v57, v56, v47
	v_min_u32_e32 v47, v56, v47
	v_max_u32_e32 v56, v52, v63
	v_min_u32_e32 v52, v52, v63
	v_max_u32_e32 v63, v49, v50
	v_min_u32_e32 v49, v49, v50
	v_max_u32_e32 v50, v72, v41
	v_min_u32_e32 v41, v72, v41
	v_max_u32_e32 v72, v45, v37
	v_min_u32_e32 v37, v45, v37
	v_max_u32_e32 v45, v42, v43
	v_min_u32_e32 v42, v42, v43
	v_max_u32_e32 v43, v48, v60
	v_min_u32_e32 v48, v48, v60
	v_max_u32_e32 v60, v54, v53
	v_min_u32_e32 v53, v54, v53
	v_max_u32_e32 v54, v55, v74
	v_min_u32_e32 v55, v55, v74
	v_max_u32_e32 v74, v51, v40
; DI void merge_top16(unsigned (&A)[16], const unsigned (&B)[16]) {
; #pragma unroll
;     for (int i = 0; i < 16; ++i) A[i] = max(A[i], B[15 - i]);
; #pragma unroll
;     for (int n = 0; n < 32; ++n) cex(A[BMERGE16[n][0]], A[BMERGE16[n][1]]);
; }
; DI void peer_topk_phase(const bf16_t* __restrict__ qpk, const bf16_t* __restrict__ subk, int* __restrict__ eidx, float* __restrict__ gout) {
;     ...
;         for (int n = 0; n < 63; ++n) { cex(c1[SORT16[n][0]], c1[SORT16[n][1]]); cex(c2[SORT16[n][0]], c2[SORT16[n][1]]); }
;         merge_top16(c0, c1); merge_top16(c2, c3); merge_top16(c0, c2);
	v_min_u32_e32 v40, v51, v40
	v_max_u32_e32 v51, v54, v48
	v_min_u32_e32 v48, v54, v48
	v_max_u32_e32 v54, v74, v53
	v_min_u32_e32 v53, v74, v53
	v_max_u32_e32 v74, v62, v73
	v_min_u32_e32 v62, v62, v73
	v_max_u32_e32 v73, v59, v38
	v_min_u32_e32 v38, v59, v38
	v_max_u32_e32 v59, v2, v34
	v_min_u32_e32 v2, v2, v34
	v_max_u32_e32 v34, v44, v36
	v_min_u32_e32 v36, v44, v36
	v_max_u32_e32 v44, v59, v62
	v_min_u32_e32 v59, v59, v62
	v_max_u32_e32 v62, v34, v38
	v_min_u32_e32 v34, v34, v38
	v_max_u32_e32 v38, v74, v51
	v_min_u32_e32 v51, v74, v51
	v_max_u32_e32 v74, v73, v54
	v_min_u32_e32 v54, v73, v54
	v_max_u32_e32 v73, v44, v48
	v_min_u32_e32 v44, v44, v48
	v_max_u32_e32 v48, v62, v53
	v_min_u32_e32 v53, v62, v53
	v_max_u32_e32 v62, v59, v55
	v_min_u32_e32 v55, v59, v55
	v_max_u32_e32 v59, v34, v40
	v_min_u32_e32 v34, v34, v40
	v_and_or_b32 v32, v32, s21, 15
	v_min_u32_e32 v40, v43, v57
	v_max_u32_e32 v90, v60, v56
	v_min_u32_e32 v56, v60, v56
	v_min_u32_e32 v60, v38, v47
	v_max_u32_e32 v91, v74, v52
	v_min_u32_e32 v52, v74, v52
	v_min_u32_e32 v74, v51, v63
	v_max_u32_e32 v92, v54, v50
	v_min_u32_e32 v50, v54, v50
	v_min_u32_e32 v54, v73, v49
	v_max_u32_e32 v93, v48, v41
	v_min_u32_e32 v41, v48, v41
	v_min_u32_e32 v48, v44, v72
	v_max_u32_e32 v94, v53, v45
	v_min_u32_e32 v45, v53, v45
	v_min_u32_e32 v53, v62, v37
	v_max_u32_e32 v95, v59, v42
	v_min_u32_e32 v42, v59, v42
	v_min_u32_e32 v59, v55, v39
	v_max_u32_e32 v96, v34, v35
	v_min_u32_e32 v34, v34, v35
	v_max_u32_e32 v0, v0, v2
	v_max_u32_e32 v2, v58, v59
	v_max3_u32 v31, v31, v55, v39
	v_max_u32_e32 v30, v30, v53
	v_max3_u32 v18, v18, v62, v37
	v_max_u32_e32 v19, v19, v48
	v_max3_u32 v29, v29, v44, v72
	v_max_u32_e32 v20, v20, v54
	v_max3_u32 v21, v21, v73, v49
	v_max_u32_e32 v22, v22, v74
	v_max3_u32 v23, v23, v51, v63
	v_max_u32_e32 v24, v24, v60
	v_max3_u32 v25, v25, v38, v47
	v_max_u32_e32 v26, v26, v40
	v_max3_u32 v27, v27, v43, v57
	v_max3_u32 v28, v28, v46, v61
	v_max_u32_e32 v32, v34, v32
	v_max_u32_e32 v33, v36, v33
	v_max_u32_e32 v35, v0, v21
	v_min_u32_e32 v0, v0, v21
	v_max_u32_e32 v21, v2, v22
	v_min_u32_e32 v2, v2, v22
	v_max_u32_e32 v22, v31, v23
	v_min_u32_e32 v23, v31, v23
	v_max_u32_e32 v31, v30, v24
	v_min_u32_e32 v24, v30, v24
	v_max_u32_e32 v30, v18, v25
	v_min_u32_e32 v18, v18, v25
	v_max_u32_e32 v25, v19, v26
	v_min_u32_e32 v19, v19, v26
	v_max_u32_e32 v26, v29, v27
	v_min_u32_e32 v27, v29, v27
	v_max_u32_e32 v29, v20, v28
	v_min_u32_e32 v20, v20, v28
	v_max_u32_e32 v34, v75, v41
	v_min_u32_e32 v36, v75, v41
	v_max_u32_e32 v41, v90, v94
	v_min_u32_e32 v47, v90, v94
	v_max_u32_e32 v48, v56, v45
	v_min_u32_e32 v45, v56, v45
	v_max_u32_e32 v49, v91, v95
	v_min_u32_e32 v51, v91, v95
	v_max_u32_e32 v53, v52, v42
	v_min_u32_e32 v42, v52, v42
	v_max_u32_e32 v52, v92, v96
	v_min_u32_e32 v54, v92, v96
	v_max_u32_e32 v55, v50, v32
	v_min_u32_e32 v32, v50, v32
	v_max_u32_e32 v50, v93, v33
	v_min_u32_e32 v33, v93, v33
	v_max_u32_e32 v28, v35, v30
	v_min_u32_e32 v30, v35, v30
	v_max_u32_e32 v35, v21, v25
	v_min_u32_e32 v21, v21, v25
	v_max_u32_e32 v25, v22, v26
	v_min_u32_e32 v22, v22, v26
	v_max_u32_e32 v26, v31, v29
	v_min_u32_e32 v29, v31, v29
	v_max_u32_e32 v31, v0, v18
	v_min_u32_e32 v0, v0, v18
	v_max_u32_e32 v18, v2, v19
	v_min_u32_e32 v2, v2, v19
	v_max_u32_e32 v19, v23, v27
	v_min_u32_e32 v23, v23, v27
	v_max_u32_e32 v27, v24, v20
	v_min_u32_e32 v20, v24, v20
	v_max_u32_e32 v56, v34, v53
	v_min_u32_e32 v34, v34, v53
	v_max_u32_e32 v53, v41, v52
	v_min_u32_e32 v41, v41, v52
	v_max_u32_e32 v52, v48, v55
	v_min_u32_e32 v48, v48, v55
	v_max_u32_e32 v55, v49, v50
	v_min_u32_e32 v49, v49, v50
	v_max_u32_e32 v50, v36, v42
	v_min_u32_e32 v36, v36, v42
	v_max_u32_e32 v42, v47, v54
	v_min_u32_e32 v47, v47, v54
	v_max_u32_e32 v54, v45, v32
	v_min_u32_e32 v32, v45, v32
	v_max_u32_e32 v45, v51, v33
	v_min_u32_e32 v33, v51, v33
	v_max_u32_e32 v24, v28, v25
	v_min_u32_e32 v25, v28, v25
	v_max_u32_e32 v28, v35, v26
	v_min_u32_e32 v26, v35, v26
	v_max_u32_e32 v35, v30, v22
	v_min_u32_e32 v22, v30, v22
	v_max_u32_e32 v30, v21, v29
	v_min_u32_e32 v21, v21, v29
	v_max_u32_e32 v29, v31, v19
	v_min_u32_e32 v19, v31, v19
	v_max_u32_e32 v31, v18, v27
	v_min_u32_e32 v18, v18, v27
	v_max_u32_e32 v27, v0, v23
	v_min_u32_e32 v0, v0, v23
	v_max_u32_e32 v23, v2, v20
	v_min_u32_e32 v2, v2, v20
	v_max_u32_e32 v51, v56, v52
	v_min_u32_e32 v52, v56, v52
	v_max_u32_e32 v56, v53, v55
	v_min_u32_e32 v53, v53, v55
	v_max_u32_e32 v55, v34, v48
	v_min_u32_e32 v34, v34, v48
	v_max_u32_e32 v48, v41, v49
	v_min_u32_e32 v41, v41, v49
	v_max_u32_e32 v49, v50, v54
	v_min_u32_e32 v50, v50, v54
	v_max_u32_e32 v54, v42, v45
	v_min_u32_e32 v42, v42, v45
	v_max_u32_e32 v45, v36, v32
	v_min_u32_e32 v32, v36, v32
	v_max_u32_e32 v36, v47, v33
	v_min_u32_e32 v33, v47, v33
	v_min_u32_e32 v20, v24, v28
	v_min_u32_e32 v37, v25, v26
	v_min_u32_e32 v38, v35, v30
	v_min_u32_e32 v39, v22, v21
	v_min_u32_e32 v40, v29, v31
	v_min_u32_e32 v43, v19, v18
	v_min_u32_e32 v44, v27, v23
	v_min_u32_e32 v46, v0, v2
	v_min_u32_e32 v47, v51, v56
	v_min_u32_e32 v57, v52, v53
	v_min_u32_e32 v58, v55, v48
	v_min_u32_e32 v59, v34, v41
	v_min_u32_e32 v60, v49, v54
	v_min_u32_e32 v61, v50, v42
	v_min_u32_e32 v62, v45, v36
	v_min_u32_e32 v63, v32, v33
	v_max3_u32 v24, v24, v28, v63
	v_max3_u32 v20, v20, v32, v33
	v_max3_u32 v25, v25, v26, v62
	v_max3_u32 v26, v37, v45, v36
	v_max3_u32 v28, v35, v30, v61
	v_max3_u32 v30, v38, v50, v42
	v_max3_u32 v21, v22, v21, v60
	v_max3_u32 v22, v39, v49, v54
	v_max3_u32 v29, v29, v31, v59
	v_max3_u32 v31, v40, v34, v41
	v_max3_u32 v18, v19, v18, v58
	v_max3_u32 v19, v43, v55, v48
	v_max3_u32 v23, v27, v23, v57
; DI float ord2f(unsigned o) { const unsigned u = (o & 0x80000000u) ? (o & 0x7fffffffu) : ~o; return __uint_as_float(u); }
; DI void peer_topk_phase(const bf16_t* __restrict__ qpk, const bf16_t* __restrict__ subk, int* __restrict__ eidx, float* __restrict__ gout) {
;     ...
;         merge_top16(c0, c1); merge_top16(c2, c3); merge_top16(c0, c2);
;         float sv[16]; int se[16];
; #pragma unroll
;         for (int rd = 0; rd < 16; ++rd) {
;             const unsigned m = c0[rd];
;             const int asel = 15 - (int)((m >> 4) & 15u), bsel = 15 - (int)(m & 15u);
;             unsigned ka = top[0][0], kb = top[1][0];
; #pragma unroll
;             for (int i = 1; i < 16; ++i) { ka = (asel == i) ? top[0][i] : ka; kb = (bsel == i) ? top[1][i] : kb; }
;             sv[rd] = ord2f(ka & ~127u) + ord2f(kb & ~127u);
;             se[rd] = (127 - (int)(ka & 127u)) * 128 + (127 - (int)(kb & 127u));
;         }
	v_max3_u32 v27, v44, v52, v53
	v_max3_u32 v0, v0, v2, v47
	v_max3_u32 v2, v46, v51, v56
	v_max_u32_e32 v32, v24, v29
	v_min_u32_e32 v24, v24, v29
	v_max_u32_e32 v29, v20, v31
	v_min_u32_e32 v20, v20, v31
	v_max_u32_e32 v31, v25, v18
	v_min_u32_e32 v18, v25, v18
	v_max_u32_e32 v25, v26, v19
	v_min_u32_e32 v19, v26, v19
	v_max_u32_e32 v26, v28, v23
	v_min_u32_e32 v23, v28, v23
	v_max_u32_e32 v28, v30, v27
	v_min_u32_e32 v27, v30, v27
	v_max_u32_e32 v30, v21, v0
	v_min_u32_e32 v0, v21, v0
	v_max_u32_e32 v21, v22, v2
	v_min_u32_e32 v2, v22, v2
	v_max_u32_e32 v22, v32, v26
	v_min_u32_e32 v26, v32, v26
	v_max_u32_e32 v32, v29, v28
	v_min_u32_e32 v28, v29, v28
	v_max_u32_e32 v29, v31, v30
	v_min_u32_e32 v30, v31, v30
	v_max_u32_e32 v31, v25, v21
	v_min_u32_e32 v21, v25, v21
	v_max_u32_e32 v25, v24, v23
	v_min_u32_e32 v23, v24, v23
	v_max_u32_e32 v24, v20, v27
	v_min_u32_e32 v20, v20, v27
	v_max_u32_e32 v27, v18, v0
	v_min_u32_e32 v0, v18, v0
	v_max_u32_e32 v18, v19, v2
	v_min_u32_e32 v2, v19, v2
	v_max_u32_e32 v19, v22, v29
	v_min_u32_e32 v22, v22, v29
	v_max_u32_e32 v29, v32, v31
	v_min_u32_e32 v31, v32, v31
	v_max_u32_e32 v32, v26, v30
	v_min_u32_e32 v26, v26, v30
	v_max_u32_e32 v30, v28, v21
	v_min_u32_e32 v21, v28, v21
	v_max_u32_e32 v28, v25, v27
	v_min_u32_e32 v25, v25, v27
	v_max_u32_e32 v27, v24, v18
	v_min_u32_e32 v18, v24, v18
	v_max_u32_e32 v24, v23, v0
	v_min_u32_e32 v23, v23, v0
	v_max_u32_e32 v33, v20, v2
	v_min_u32_e32 v2, v20, v2
	v_max_u32_e32 v0, v19, v29
	v_min_u32_e32 v19, v19, v29
	v_max_u32_e32 v20, v22, v31
	v_min_u32_e32 v22, v22, v31
	v_max_u32_e32 v29, v32, v30
	v_min_u32_e32 v31, v32, v30
	v_max_u32_e32 v35, v28, v27
	v_min_u32_e32 v37, v28, v27
	v_max_u32_e32 v30, v23, v2
	v_min_u32_e32 v27, v23, v2
	v_max_u32_e32 v40, v25, v18
	v_min_u32_e32 v39, v25, v18
	v_max_u32_e32 v32, v26, v21
	v_min_u32_e32 v34, v26, v21
	v_max_u32_e32 v36, v24, v33
	v_min_u32_e32 v33, v24, v33
	v_lshrrev_b32_e32 v46, 6, v174
	v_lshlrev_b32_e32 v46, 13, v46
	v_lshl_or_b32 v46, v172, 2, v46
	v_mov_b32_e32 v47, 0xf00
	ds_write_b32 v46, v64
	ds_write_b32 v46, v65 offset:256
	ds_write_b32 v46, v66 offset:512
	ds_write_b32 v46, v67 offset:768
	ds_write_b32 v46, v68 offset:1024
	ds_write_b32 v46, v69 offset:1280
	ds_write_b32 v46, v70 offset:1536
	ds_write_b32 v46, v71 offset:1792
	s_waitcnt lgkmcnt(7)
	ds_write_b32 v46, v76 offset:2048
	ds_write_b32 v46, v77 offset:2304
	ds_write_b32 v46, v78 offset:2560
	ds_write_b32 v46, v79 offset:2816
	ds_write_b32 v46, v85 offset:3072
	ds_write_b32 v46, v89 offset:3328
	ds_write_b32 v46, v88 offset:3584
	ds_write_b32 v46, v80 offset:3840
	s_waitcnt lgkmcnt(7)
	ds_write_b32 v46, v1 offset:4096
	ds_write_b32 v46, v3 offset:4352
	ds_write_b32 v46, v4 offset:4608
	ds_write_b32 v46, v5 offset:4864
	ds_write_b32 v46, v6 offset:5120
	ds_write_b32 v46, v7 offset:5376
	ds_write_b32 v46, v8 offset:5632
	ds_write_b32 v46, v9 offset:5888
	s_waitcnt lgkmcnt(7)
	ds_write_b32 v46, v10 offset:6144
	ds_write_b32 v46, v11 offset:6400
	ds_write_b32 v46, v12 offset:6656
	ds_write_b32 v46, v13 offset:6912
	ds_write_b32 v46, v14 offset:7168
	ds_write_b32 v46, v16 offset:7424
	ds_write_b32 v46, v17 offset:7680
	ds_write_b32 v46, v15 offset:7936
	s_waitcnt lgkmcnt(7)
	s_waitcnt lgkmcnt(0)
	v_lshlrev_b32_e32 v18, 4, v19
	v_and_or_b32 v18, v18, v47, v46
	ds_read_b32 v18, v18
	v_lshlrev_b32_e32 v2, 8, v19
	v_and_or_b32 v2, v2, v47, v46
	ds_read_b32 v2, v2 offset:4096
	v_lshlrev_b32_e32 v19, 8, v20
	v_and_or_b32 v19, v19, v47, v46
	ds_read_b32 v19, v19 offset:4096
	v_lshlrev_b32_e32 v20, 4, v20
	v_and_or_b32 v20, v20, v47, v46
	ds_read_b32 v20, v20
	v_lshlrev_b32_e32 v21, 8, v22
	v_and_or_b32 v21, v21, v47, v46
	ds_read_b32 v21, v21 offset:4096
	v_lshlrev_b32_e32 v22, 4, v22
	v_and_or_b32 v22, v22, v47, v46
	ds_read_b32 v22, v22
	v_lshlrev_b32_e32 v24, 4, v29
	v_and_or_b32 v24, v24, v47, v46
	ds_read_b32 v24, v24
	v_lshlrev_b32_e32 v23, 8, v29
	v_and_or_b32 v23, v23, v47, v46
	ds_read_b32 v23, v23 offset:4096
	s_waitcnt lgkmcnt(7)
	v_lshlrev_b32_e32 v26, 4, v31
	v_and_or_b32 v26, v26, v47, v46
	ds_read_b32 v26, v26
	v_lshlrev_b32_e32 v25, 8, v31
	v_and_or_b32 v25, v25, v47, v46
	ds_read_b32 v25, v25 offset:4096
	v_lshlrev_b32_e32 v29, 4, v32
	v_and_or_b32 v29, v29, v47, v46
	ds_read_b32 v29, v29
	v_lshlrev_b32_e32 v28, 8, v32
	v_and_or_b32 v28, v28, v47, v46
	ds_read_b32 v28, v28 offset:4096
	v_lshlrev_b32_e32 v32, 4, v34
	v_and_or_b32 v32, v32, v47, v46
	ds_read_b32 v32, v32
	v_lshlrev_b32_e32 v31, 8, v34
	v_and_or_b32 v31, v31, v47, v46
	ds_read_b32 v31, v31 offset:4096
	v_lshlrev_b32_e32 v34, 8, v35
	v_and_or_b32 v34, v34, v47, v46
	ds_read_b32 v34, v34 offset:4096
	v_lshlrev_b32_e32 v35, 4, v35
	v_and_or_b32 v35, v35, v47, v46
	ds_read_b32 v35, v35
	s_waitcnt lgkmcnt(7)
	v_lshlrev_b32_e32 v38, 4, v37
	v_and_or_b32 v38, v38, v47, v46
	ds_read_b32 v38, v38
	v_lshlrev_b32_e32 v37, 8, v37
	v_and_or_b32 v37, v37, v47, v46
	ds_read_b32 v37, v37 offset:4096
	v_lshlrev_b32_e32 v41, 4, v40
	v_and_or_b32 v41, v41, v47, v46
	ds_read_b32 v41, v41
	v_lshlrev_b32_e32 v40, 8, v40
	v_and_or_b32 v40, v40, v47, v46
	ds_read_b32 v40, v40 offset:4096
	v_lshlrev_b32_e32 v42, 4, v39
	v_and_or_b32 v42, v42, v47, v46
	ds_read_b32 v42, v42
	v_lshlrev_b32_e32 v39, 8, v39
	v_and_or_b32 v39, v39, v47, v46
	ds_read_b32 v39, v39 offset:4096
	v_lshlrev_b32_e32 v43, 4, v36
	v_and_or_b32 v43, v43, v47, v46
	ds_read_b32 v43, v43
	v_lshlrev_b32_e32 v36, 8, v36
	v_and_or_b32 v36, v36, v47, v46
	ds_read_b32 v36, v36 offset:4096
	s_waitcnt lgkmcnt(7)
	v_lshlrev_b32_e32 v44, 4, v33
	v_and_or_b32 v44, v44, v47, v46
	ds_read_b32 v44, v44
	v_lshlrev_b32_e32 v33, 8, v33
	v_and_or_b32 v33, v33, v47, v46
	ds_read_b32 v33, v33 offset:4096
	v_lshlrev_b32_e32 v45, 4, v30
	v_and_or_b32 v45, v45, v47, v46
	ds_read_b32 v45, v45
	v_lshlrev_b32_e32 v30, 8, v30
	v_and_or_b32 v30, v30, v47, v46
	ds_read_b32 v30, v30 offset:4096
	v_lshlrev_b32_e32 v6, 4, v0
	v_and_or_b32 v6, v6, v47, v46
	ds_read_b32 v6, v6
	v_lshlrev_b32_e32 v5, 8, v0
	v_and_or_b32 v5, v5, v47, v46
	ds_read_b32 v5, v5 offset:4096
	v_lshlrev_b32_e32 v4, 4, v27
	v_and_or_b32 v4, v4, v47, v46
	ds_read_b32 v4, v4
	v_lshlrev_b32_e32 v3, 8, v27
	v_and_or_b32 v3, v3, v47, v46
	ds_read_b32 v3, v3 offset:4096
	s_waitcnt lgkmcnt(7)
	s_waitcnt lgkmcnt(0)
	v_lshlrev_b64 v[0:1], 7, v[86:87]
	v_lshl_or_b32 v0, v179, 4, v0
	s_and_saveexec_b64 s[8:9], s[6:7]
	s_xor_b64 s[8:9], exec, s[8:9]
	s_cbranch_execz .LBB0_1166
; DI float ord2f(unsigned o) { const unsigned u = (o & 0x80000000u) ? (o & 0x7fffffffu) : ~o; return __uint_as_float(u); }
; DI void peer_topk_phase(const bf16_t* __restrict__ qpk, const bf16_t* __restrict__ subk, int* __restrict__ eidx, float* __restrict__ gout) {
;     ...
;             sv[rd] = ord2f(ka & ~127u) + ord2f(kb & ~127u);
;     ...
;         for (int i = 0; i < 16; ++i) { sv[i] = __expf(sv[i] - mx0); den += sv[i]; }
	v_and_b32_e32 v7, 0x7fffff80, v45
	v_bitop3_b32 v8, v45, s11, v45 bitop3:0xcf
	v_cmp_gt_i32_e32 vcc, 0, v45
	v_bitop3_b32 v9, v30, s11, v30 bitop3:0xcf
	s_nop 0
	v_cndmask_b32_e32 v7, v8, v7, vcc
	v_and_b32_e32 v8, 0x7fffff80, v30
	v_cmp_gt_i32_e32 vcc, 0, v30
	s_nop 1
	v_cndmask_b32_e32 v8, v9, v8, vcc
	v_add_f32_e32 v27, v8, v7
	v_and_b32_e32 v7, 0x7fffff80, v44
	v_bitop3_b32 v8, v44, s11, v44 bitop3:0xcf
	v_cmp_gt_i32_e32 vcc, 0, v44
	v_bitop3_b32 v9, v33, s11, v33 bitop3:0xcf
	s_nop 0
	v_cndmask_b32_e32 v7, v8, v7, vcc
	v_and_b32_e32 v8, 0x7fffff80, v33
	v_cmp_gt_i32_e32 vcc, 0, v33
	s_nop 1
	v_cndmask_b32_e32 v8, v9, v8, vcc
	v_add_f32_e32 v17, v8, v7
	v_and_b32_e32 v7, 0x7fffff80, v43
	v_bitop3_b32 v8, v43, s11, v43 bitop3:0xcf
	v_cmp_gt_i32_e32 vcc, 0, v43
	v_bitop3_b32 v9, v36, s11, v36 bitop3:0xcf
	s_nop 0
	v_cndmask_b32_e32 v7, v8, v7, vcc
	v_and_b32_e32 v8, 0x7fffff80, v36
	v_cmp_gt_i32_e32 vcc, 0, v36
	s_nop 1
	v_cndmask_b32_e32 v8, v9, v8, vcc
	v_add_f32_e32 v16, v8, v7
	v_and_b32_e32 v7, 0x7fffff80, v42
	v_bitop3_b32 v8, v42, s11, v42 bitop3:0xcf
	v_cmp_gt_i32_e32 vcc, 0, v42
	v_bitop3_b32 v9, v39, s11, v39 bitop3:0xcf
	s_nop 0
	v_cndmask_b32_e32 v7, v8, v7, vcc
	v_and_b32_e32 v8, 0x7fffff80, v39
	v_cmp_gt_i32_e32 vcc, 0, v39
	s_nop 1
	v_cndmask_b32_e32 v8, v9, v8, vcc
	v_add_f32_e32 v15, v8, v7
	v_and_b32_e32 v7, 0x7fffff80, v41
	v_bitop3_b32 v8, v41, s11, v41 bitop3:0xcf
	v_cmp_gt_i32_e32 vcc, 0, v41
	v_bitop3_b32 v9, v40, s11, v40 bitop3:0xcf
	s_nop 0
	v_cndmask_b32_e32 v7, v8, v7, vcc
	v_and_b32_e32 v8, 0x7fffff80, v40
	v_cmp_gt_i32_e32 vcc, 0, v40
	s_nop 1
	v_cndmask_b32_e32 v8, v9, v8, vcc
	v_add_f32_e32 v14, v8, v7
	v_and_b32_e32 v7, 0x7fffff80, v38
	v_bitop3_b32 v8, v38, s11, v38 bitop3:0xcf
	v_cmp_gt_i32_e32 vcc, 0, v38
	v_bitop3_b32 v9, v37, s11, v37 bitop3:0xcf
	s_nop 0
	v_cndmask_b32_e32 v7, v8, v7, vcc
	v_and_b32_e32 v8, 0x7fffff80, v37
	v_cmp_gt_i32_e32 vcc, 0, v37
	s_nop 1
	v_cndmask_b32_e32 v8, v9, v8, vcc
	v_add_f32_e32 v13, v8, v7
	v_and_b32_e32 v7, 0x7fffff80, v35
	v_bitop3_b32 v8, v35, s11, v35 bitop3:0xcf
	v_cmp_gt_i32_e32 vcc, 0, v35
	v_bitop3_b32 v9, v34, s11, v34 bitop3:0xcf
	s_nop 0
	v_cndmask_b32_e32 v7, v8, v7, vcc
	v_and_b32_e32 v8, 0x7fffff80, v34
	v_cmp_gt_i32_e32 vcc, 0, v34
	s_nop 1
	v_cndmask_b32_e32 v8, v9, v8, vcc
	v_add_f32_e32 v12, v8, v7
	v_and_b32_e32 v7, 0x7fffff80, v32
	v_bitop3_b32 v8, v32, s11, v32 bitop3:0xcf
	v_cmp_gt_i32_e32 vcc, 0, v32
	v_bitop3_b32 v9, v31, s11, v31 bitop3:0xcf
	s_nop 0
	v_cndmask_b32_e32 v7, v8, v7, vcc
	v_and_b32_e32 v8, 0x7fffff80, v31
	v_cmp_gt_i32_e32 vcc, 0, v31
	s_nop 1
	v_cndmask_b32_e32 v8, v9, v8, vcc
	v_add_f32_e32 v11, v8, v7
	v_and_b32_e32 v7, 0x7fffff80, v29
	v_bitop3_b32 v8, v29, s11, v29 bitop3:0xcf
	v_cmp_gt_i32_e32 vcc, 0, v29
	v_bitop3_b32 v9, v28, s11, v28 bitop3:0xcf
	s_nop 0
	v_cndmask_b32_e32 v7, v8, v7, vcc
	v_and_b32_e32 v8, 0x7fffff80, v28
	v_cmp_gt_i32_e32 vcc, 0, v28
	s_nop 1
	v_cndmask_b32_e32 v8, v9, v8, vcc
	v_add_f32_e32 v10, v8, v7
	v_and_b32_e32 v7, 0x7fffff80, v26
	v_bitop3_b32 v8, v26, s11, v26 bitop3:0xcf
	v_cmp_gt_i32_e32 vcc, 0, v26
	v_bitop3_b32 v9, v25, s11, v25 bitop3:0xcf
	v_and_b32_e32 v26, 0xffffff80, v3
	v_cndmask_b32_e32 v7, v8, v7, vcc
	v_and_b32_e32 v8, 0x7fffff80, v25
	v_cmp_gt_i32_e32 vcc, 0, v25
	v_and_b32_e32 v25, 0xffffff80, v5
	s_nop 0
	v_cndmask_b32_e32 v8, v9, v8, vcc
	v_add_f32_e32 v9, v8, v7
	v_and_b32_e32 v7, 0x7fffff80, v24
	v_bitop3_b32 v8, v24, s11, v24 bitop3:0xcf
	v_cmp_gt_i32_e32 vcc, 0, v24
	v_bitop3_b32 v24, v23, s11, v23 bitop3:0xcf
	s_nop 0
	v_cndmask_b32_e32 v7, v8, v7, vcc
	v_and_b32_e32 v8, 0x7fffff80, v23
	v_cmp_gt_i32_e32 vcc, 0, v23
	v_bitop3_b32 v23, v22, s11, v22 bitop3:0xcf
	s_nop 0
	v_cndmask_b32_e32 v8, v24, v8, vcc
	v_add_f32_e32 v8, v8, v7
	v_and_b32_e32 v7, 0x7fffff80, v22
	v_cmp_gt_i32_e32 vcc, 0, v22
	v_and_b32_e32 v22, 0x7fffff80, v21
	v_and_b32_e32 v24, 0x7fffff80, v3
	v_cndmask_b32_e32 v7, v23, v7, vcc
	v_bitop3_b32 v23, v21, s11, v21 bitop3:0xcf
	v_cmp_gt_i32_e32 vcc, 0, v21
	s_nop 1
	v_cndmask_b32_e32 v21, v23, v22, vcc
	v_add_f32_e32 v21, v21, v7
	v_and_b32_e32 v7, 0x7fffff80, v20
	v_bitop3_b32 v22, v20, s11, v20 bitop3:0xcf
; DI void peer_topk_phase(const bf16_t* __restrict__ qpk, const bf16_t* __restrict__ subk, int* __restrict__ eidx, float* __restrict__ gout) {
;     ...
;         float den = 0.f;
;         const float mx0 = sv[0];
; #pragma unroll
;         for (int i = 0; i < 16; ++i) { sv[i] = __expf(sv[i] - mx0); den += sv[i]; }
;         const float inv = 1.0f / den;
;         const size_t ob = (size_t)(t0 + r) * 128 + hh * 16;
;         if (h == 0) {
; #pragma unroll
;             for (int i = 0; i < 4; ++i) { int4 v = make_int4(se[4 * i], se[4 * i + 1], se[4 * i + 2], se[4 * i + 3]); *(int4*)(eidx + ob + 4 * i) = v; }
;         } else {
; #pragma unroll
;             for (int i = 0; i < 4; ++i) { f32x4 v = {sv[4 * i] * inv, sv[4 * i + 1] * inv, sv[4 * i + 2] * inv, sv[4 * i + 3] * inv}; *(f32x4*)(gout + ob + 4 * i) = v; }
;         }
	v_cmp_gt_i32_e32 vcc, 0, v20
	v_and_b32_e32 v20, 0x7fffff80, v19
	v_and_b32_e32 v23, 0x7fffff80, v5
	v_cndmask_b32_e32 v7, v22, v7, vcc
	v_bitop3_b32 v22, v19, s11, v19 bitop3:0xcf
	v_cmp_gt_i32_e32 vcc, 0, v19
	s_nop 1
	v_cndmask_b32_e32 v19, v22, v20, vcc
	v_add_f32_e32 v19, v19, v7
	v_and_b32_e32 v7, 0x7fffff80, v18
	v_bitop3_b32 v20, v18, s11, v18 bitop3:0xcf
	v_cmp_gt_i32_e32 vcc, 0, v18
	v_and_b32_e32 v18, 0x7fffff80, v2
	v_and_b32_e32 v22, 0xffffff80, v4
	v_cndmask_b32_e32 v7, v20, v7, vcc
	v_bitop3_b32 v20, v2, s11, v2 bitop3:0xcf
	v_cmp_gt_i32_e32 vcc, 0, v2
	v_xor_b32_e32 v22, -1, v22
	s_nop 0
	v_cndmask_b32_e32 v2, v20, v18, vcc
	v_add_f32_e32 v18, v2, v7
	v_and_b32_e32 v7, 0xffffff80, v6
	v_and_b32_e32 v2, 0x7fffff80, v6
	v_xor_b32_e32 v7, -1, v7
	v_cmp_gt_i32_e32 vcc, 0, v6
	v_and_b32_e32 v20, 0x7fffff80, v4
	s_nop 0
	v_cndmask_b32_e32 v7, v7, v2, vcc
	v_cmp_gt_i32_e32 vcc, 0, v4
	v_xor_b32_e32 v2, -1, v25
	v_xor_b32_e32 v4, -1, v26
	v_cndmask_b32_e32 v6, v22, v20, vcc
	v_cmp_gt_i32_e32 vcc, 0, v5
	s_nop 1
	v_cndmask_b32_e32 v5, v2, v23, vcc
	v_cmp_gt_i32_e32 vcc, 0, v3
	s_nop 1
	v_cndmask_b32_e32 v4, v4, v24, vcc
	v_pk_add_f32 v[2:3], v[4:5], v[6:7]
	s_nop 0
	v_sub_f32_e32 v4, v3, v3
	v_mul_f32_e32 v4, 0x3fb8aa3b, v4
	v_sub_f32_e32 v5, v18, v3
	v_exp_f32_e32 v4, v4
	v_mul_f32_e32 v5, 0x3fb8aa3b, v5
	v_sub_f32_e32 v6, v19, v3
	v_exp_f32_e32 v5, v5
	v_mul_f32_e32 v6, 0x3fb8aa3b, v6
	v_sub_f32_e32 v7, v21, v3
	v_exp_f32_e32 v6, v6
	v_mul_f32_e32 v7, 0x3fb8aa3b, v7
	v_sub_f32_e32 v8, v8, v3
	v_exp_f32_e32 v7, v7
	v_mul_f32_e32 v8, 0x3fb8aa3b, v8
	v_sub_f32_e32 v9, v9, v3
	v_add_f32_e32 v18, 0, v4
	v_exp_f32_e32 v8, v8
	v_mul_f32_e32 v9, 0x3fb8aa3b, v9
	v_sub_f32_e32 v10, v10, v3
	v_add_f32_e32 v18, v5, v18
	v_exp_f32_e32 v9, v9
	v_mul_f32_e32 v10, 0x3fb8aa3b, v10
	v_sub_f32_e32 v11, v11, v3
	v_add_f32_e32 v18, v6, v18
	v_exp_f32_e32 v10, v10
	v_mul_f32_e32 v11, 0x3fb8aa3b, v11
	v_sub_f32_e32 v12, v12, v3
	v_add_f32_e32 v18, v7, v18
	v_exp_f32_e32 v11, v11
	v_mul_f32_e32 v12, 0x3fb8aa3b, v12
	v_sub_f32_e32 v13, v13, v3
	v_add_f32_e32 v18, v8, v18
	v_exp_f32_e32 v12, v12
	v_mul_f32_e32 v13, 0x3fb8aa3b, v13
	v_sub_f32_e32 v14, v14, v3
	v_add_f32_e32 v18, v9, v18
	v_exp_f32_e32 v13, v13
	v_mul_f32_e32 v14, 0x3fb8aa3b, v14
	v_sub_f32_e32 v15, v15, v3
	v_add_f32_e32 v18, v10, v18
	v_exp_f32_e32 v14, v14
	v_mul_f32_e32 v15, 0x3fb8aa3b, v15
	v_add_f32_e32 v18, v11, v18
	v_exp_f32_e32 v15, v15
	v_add_f32_e32 v18, v12, v18
	v_add_f32_e32 v18, v13, v18
	v_sub_f32_e32 v16, v16, v3
	v_add_f32_e32 v18, v14, v18
	v_mul_f32_e32 v16, 0x3fb8aa3b, v16
	v_sub_f32_e32 v17, v17, v3
	v_add_f32_e32 v20, v15, v18
	v_exp_f32_e32 v16, v16
	v_mul_f32_e32 v17, 0x3fb8aa3b, v17
	v_sub_f32_e32 v18, v27, v3
	v_exp_f32_e32 v17, v17
	v_mul_f32_e32 v18, 0x3fb8aa3b, v18
	v_sub_f32_e32 v2, v2, v3
	v_exp_f32_e32 v18, v18
	v_mul_f32_e32 v2, 0x3fb8aa3b, v2
	v_exp_f32_e32 v19, v2
	v_add_f32_e32 v2, v16, v20
	v_add_f32_e32 v2, v17, v2
	v_add_f32_e32 v2, v18, v2
	v_add_f32_e32 v2, v19, v2
	v_div_scale_f32 v3, s[24:25], v2, v2, 1.0
	v_rcp_f32_e32 v20, v3
	v_readlane_b32 s24, v253, 18
	v_readlane_b32 s25, v253, 19
	v_fma_f32 v21, -v3, v20, 1.0
	v_fmac_f32_e32 v20, v21, v20
	v_div_scale_f32 v21, vcc, 1.0, v2, 1.0
	v_mul_f32_e32 v22, v21, v20
	v_fma_f32 v23, -v3, v22, v21
	v_fmac_f32_e32 v22, v23, v20
	v_fma_f32 v3, -v3, v22, v21
	v_div_fmas_f32 v3, v3, v20, v22
	v_div_fixup_f32 v20, v3, v2, 1.0
	v_lshl_add_u64 v[22:23], v[0:1], 2, s[24:25]
	v_pk_mul_f32 v[2:3], v[6:7], v[20:21] op_sel_hi:[1,0]
	v_pk_mul_f32 v[0:1], v[4:5], v[20:21] op_sel_hi:[1,0]
	global_store_dwordx4 v[22:23], v[0:3], off
	s_nop 1
	v_pk_mul_f32 v[2:3], v[10:11], v[20:21] op_sel_hi:[1,0]
	v_pk_mul_f32 v[0:1], v[8:9], v[20:21] op_sel_hi:[1,0]
	global_store_dwordx4 v[22:23], v[0:3], off offset:16
	s_nop 1
	v_pk_mul_f32 v[2:3], v[14:15], v[20:21] op_sel_hi:[1,0]
	v_pk_mul_f32 v[0:1], v[12:13], v[20:21] op_sel_hi:[1,0]
	global_store_dwordx4 v[22:23], v[0:3], off offset:32
	s_nop 1
	v_pk_mul_f32 v[2:3], v[18:19], v[20:21] op_sel_hi:[1,0]
	v_pk_mul_f32 v[0:1], v[16:17], v[20:21] op_sel_hi:[1,0]
	global_store_dwordx4 v[22:23], v[0:3], off offset:48
